# gather loop rewrite on both instances + SGPR-base LDS-DMA issue in all six GEMM K-loops
# speedup vs baseline: 1.0099x; 1.0099x over previous
; DEV int bid_() { int t = blockIdx.x; asm volatile("" : "+s"(t)); return t; }
; DEV int gdim_() { int t = gridDim.x; asm volatile("" : "+s"(t)); return t; }
; #define P (*launderP(lp))
; __device__ __forceinline__ void phase_peer_gather(PREF P, int slab, int tbeg, int tend) {
;     ...
;   for (int t = tbeg + bid_() * 4 + wid; t < tend; t += gdim_() * 4) {
;     const u16* hrow = P.hb + (size_t)t * 2048 + lane * 16;
;     int xq[8];
;     float sh;
;     {
;       float hv[32];
;       ld16bf(hrow, hv);
;       ld16bf(hrow + 1024, hv + 16);
;       float am = 0.f;
; #pragma unroll
;       for (int e = 0; e < 32; ++e) am = fmaxf(am, fabsf(hv[e]));
;       am = wmax(am);
;       sh = am > 0.f ? am * (1.f / 127.f) : 1.f;
;       const float inv = 1.f / sh;
; #pragma unroll
;       for (int w = 0; w < 8; ++w) xq[w] = (int)q4(hv[w * 4], hv[w * 4 + 1], hv[w * 4 + 2], hv[w * 4 + 3], inv, 0);
;     }
;     float acc[32];
; #pragma unroll
;     for (int e = 0; e < 32; ++e) acc[e] = 0.f;
.LBB0_154:
	ds_read2_b64 v[0:3], v53 offset0:43 offset1:48
	v_ashrrev_i32_e32 v49, 31, v48
	v_lshlrev_b64 v[4:5], 12, v[48:49]
	v_mov_b32_e32 v55, 0
	v_lshlrev_b64 v[100:101], 7, v[48:49]
	s_waitcnt lgkmcnt(0)
	v_lshl_add_u64 v[0:1], v[0:1], 0, v[4:5]
	v_lshl_add_u64 v[0:1], v[0:1], 0, v[180:181]
	flat_load_dwordx4 v[4:7], v[0:1]
	flat_load_dwordx4 v[8:11], v[0:1] offset:16
	flat_load_dwordx4 v[12:15], v[0:1] offset:2048
	flat_load_dwordx4 v[16:19], v[0:1] offset:2064
	v_or_b32_e32 v100, v100, v52
	s_mov_b64 s[40:41], -1
	s_mov_b64 s[42:43], 0
	v_mov_b32_e32 v134, 0
	v_mov_b32_e32 v135, v55
	v_mov_b32_e32 v132, 0
	v_mov_b32_e32 v133, v55
	v_mov_b32_e32 v130, 0
	v_mov_b32_e32 v131, v55
	v_mov_b32_e32 v128, 0
	v_mov_b32_e32 v129, v55
	v_mov_b32_e32 v126, 0
	v_mov_b32_e32 v127, v55
	v_mov_b32_e32 v124, 0
	v_mov_b32_e32 v125, v55
	v_mov_b32_e32 v122, 0
	v_mov_b32_e32 v123, v55
	v_mov_b32_e32 v120, 0
	v_mov_b32_e32 v121, v55
	v_mov_b32_e32 v118, 0
	v_mov_b32_e32 v119, v55
	v_mov_b32_e32 v116, 0
	v_mov_b32_e32 v117, v55
	v_mov_b32_e32 v114, 0
	v_mov_b32_e32 v115, v55
	v_mov_b32_e32 v112, 0
	v_mov_b32_e32 v113, v55
	v_mov_b32_e32 v110, 0
	v_mov_b32_e32 v111, v55
	v_mov_b32_e32 v108, 0
	v_mov_b32_e32 v109, v55
	v_mov_b32_e32 v106, 0
	v_mov_b32_e32 v107, v55
	v_mov_b32_e32 v136, 0
	v_mov_b32_e32 v137, v55
	s_waitcnt vmcnt(0) lgkmcnt(0)
	v_lshlrev_b32_e32 v68, 16, v4
	v_and_b32_e32 v69, 0xffff0000, v4
	v_lshlrev_b32_e32 v70, 16, v5
	v_and_b32_e32 v71, 0xffff0000, v5
	v_max3_f32 v0, |v68|, 0, |v69|
	v_lshlrev_b32_e32 v72, 16, v6
	v_and_b32_e32 v73, 0xffff0000, v6
	v_max3_f32 v0, v0, |v70|, |v71|
	v_lshlrev_b32_e32 v74, 16, v7
	v_and_b32_e32 v75, 0xffff0000, v7
	v_max3_f32 v0, v0, |v72|, |v73|
	v_lshlrev_b32_e32 v76, 16, v8
	v_and_b32_e32 v77, 0xffff0000, v8
	v_max3_f32 v0, v0, |v74|, |v75|
	v_lshlrev_b32_e32 v78, 16, v9
	v_and_b32_e32 v79, 0xffff0000, v9
	v_max3_f32 v0, v0, |v76|, |v77|
	v_lshlrev_b32_e32 v80, 16, v10
	v_and_b32_e32 v81, 0xffff0000, v10
	v_max3_f32 v0, v0, |v78|, |v79|
	v_lshlrev_b32_e32 v82, 16, v11
	v_and_b32_e32 v83, 0xffff0000, v11
	v_max3_f32 v0, v0, |v80|, |v81|
	v_lshlrev_b32_e32 v84, 16, v12
	v_and_b32_e32 v85, 0xffff0000, v12
	v_max3_f32 v0, v0, |v82|, |v83|
	v_lshlrev_b32_e32 v86, 16, v13
	v_and_b32_e32 v87, 0xffff0000, v13
	v_max3_f32 v0, v0, |v84|, |v85|
	v_lshlrev_b32_e32 v88, 16, v14
	v_and_b32_e32 v89, 0xffff0000, v14
	v_max3_f32 v0, v0, |v86|, |v87|
	v_lshlrev_b32_e32 v90, 16, v15
	v_and_b32_e32 v91, 0xffff0000, v15
	v_max3_f32 v0, v0, |v88|, |v89|
	v_lshlrev_b32_e32 v92, 16, v16
	v_and_b32_e32 v93, 0xffff0000, v16
	v_max3_f32 v0, v0, |v90|, |v91|
	v_lshlrev_b32_e32 v94, 16, v17
	v_and_b32_e32 v95, 0xffff0000, v17
	v_max3_f32 v0, v0, |v92|, |v93|
	v_lshlrev_b32_e32 v96, 16, v18
	v_and_b32_e32 v97, 0xffff0000, v18
	v_max3_f32 v0, v0, |v94|, |v95|
	v_lshlrev_b32_e32 v98, 16, v19
	v_and_b32_e32 v99, 0xffff0000, v19
	v_max3_f32 v0, v0, |v96|, |v97|
	v_max3_f32 v0, v0, |v98|, |v99|
	ds_bpermute_b32 v1, v138, v0
	s_waitcnt lgkmcnt(0)
	v_max_f32_e32 v1, v1, v1
	v_max_f32_e32 v0, v0, v1
	ds_bpermute_b32 v1, v139, v0
	s_waitcnt lgkmcnt(0)
	v_max_f32_e32 v1, v1, v1
	v_max_f32_e32 v0, v0, v1
	ds_bpermute_b32 v1, v140, v0
	s_waitcnt lgkmcnt(0)
	v_max_f32_e32 v1, v1, v1
	v_max_f32_e32 v0, v0, v1
	ds_bpermute_b32 v1, v141, v0
	s_waitcnt lgkmcnt(0)
	v_max_f32_e32 v1, v1, v1
	v_max_f32_e32 v0, v0, v1
	ds_bpermute_b32 v1, v142, v0
	s_waitcnt lgkmcnt(0)
	v_max_f32_e32 v1, v1, v1
	v_max_f32_e32 v0, v0, v1
	ds_bpermute_b32 v1, v143, v0
	s_waitcnt lgkmcnt(0)
	v_max_f32_e32 v1, v1, v1
	v_max_f32_e32 v0, v0, v1
	v_mul_f32_e32 v1, 0x3c010204, v0
	v_cmp_lt_f32_e32 vcc, 0, v0
	s_nop 1
	v_cndmask_b32_e32 v61, 1.0, v1, vcc
	v_div_scale_f32 v4, s[14:15], v61, v61, 1.0
	v_rcp_f32_e32 v5, v4
	v_div_scale_f32 v6, vcc, 1.0, v61, 1.0
	v_lshlrev_b64 v[0:1], 11, v[48:49]
	v_fma_f32 v7, -v4, v5, 1.0
	v_fmac_f32_e32 v5, v7, v5
	v_mul_f32_e32 v7, v6, v5
	v_fma_f32 v8, -v4, v7, v6
	v_fmac_f32_e32 v7, v8, v5
	v_fma_f32 v4, -v4, v7, v6
	v_div_fmas_f32 v4, v4, v5, v7
	v_div_fixup_f32 v4, v4, v61, 1.0
	v_mul_f32_e32 v6, v4, v69
	v_mul_f32_e32 v7, v4, v70
	v_mul_f32_e32 v5, v4, v68
	v_mul_f32_e32 v8, v4, v71
	v_rndne_f32_e32 v6, v6
	v_rndne_f32_e32 v7, v7
	v_rndne_f32_e32 v5, v5
	v_rndne_f32_e32 v8, v8
	v_cvt_i32_f32_e32 v6, v6
	v_cvt_i32_f32_e32 v7, v7
	v_mul_f32_e32 v10, v4, v73
	v_mul_f32_e32 v11, v4, v74
	v_cvt_i32_f32_e32 v5, v5
	v_cvt_i32_f32_e32 v8, v8
	v_mul_f32_e32 v9, v4, v72
	v_mul_f32_e32 v12, v4, v75
	v_rndne_f32_e32 v10, v10
	v_rndne_f32_e32 v11, v11
	v_rndne_f32_e32 v9, v9
	v_rndne_f32_e32 v12, v12
	v_cvt_i32_f32_e32 v10, v10
	v_cvt_i32_f32_e32 v11, v11
	v_mul_f32_e32 v18, v4, v81
	v_mul_f32_e32 v19, v4, v82
	v_cvt_i32_f32_e32 v9, v9
	v_cvt_i32_f32_e32 v12, v12
	v_med3_i32 v6, v6, s29, v189
	v_med3_i32 v7, v7, s29, v189
	v_mul_f32_e32 v17, v4, v80
	v_mul_f32_e32 v20, v4, v83
	v_rndne_f32_e32 v18, v18
	v_rndne_f32_e32 v19, v19
	v_med3_i32 v5, v5, s29, v189
	v_med3_i32 v8, v8, s29, v189
	v_lshlrev_b32_e32 v6, 8, v6
	v_lshlrev_b32_e32 v7, 16, v7
	v_rndne_f32_e32 v17, v17
	v_rndne_f32_e32 v20, v20
	v_cvt_i32_f32_e32 v18, v18
	v_cvt_i32_f32_e32 v19, v19
	v_perm_b32 v5, v8, v5, s33
	v_and_b32_e32 v6, 0xff00, v6
	v_and_b32_e32 v7, 0xff0000, v7
	v_cvt_i32_f32_e32 v17, v17
	v_med3_i32 v10, v10, s29, v189
	v_med3_i32 v11, v11, s29, v189
	v_or3_b32 v63, v5, v6, v7
	v_cvt_i32_f32_e32 v5, v20
	v_med3_i32 v9, v9, s29, v189
	v_med3_i32 v12, v12, s29, v189
	v_lshlrev_b32_e32 v8, 8, v10
	v_lshlrev_b32_e32 v10, 16, v11
	v_perm_b32 v9, v12, v9, s33
	v_and_b32_e32 v8, 0xff00, v8
	v_and_b32_e32 v10, 0xff0000, v10
	v_or3_b32 v65, v9, v8, v10
	v_med3_i32 v7, v18, s29, v189
; #define P (*launderP(lp))
; __device__ __forceinline__ void phase_peer_gather(PREF P, int slab, int tbeg, int tend) {
;     ...
;       for (int w = 0; w < 8; ++w) xq[w] = (int)q4(hv[w * 4], hv[w * 4 + 1], hv[w * 4 + 2], hv[w * 4 + 3], inv, 0);
;     }
;     float acc[32];
; #pragma unroll
;     for (int e = 0; e < 32; ++e) acc[e] = 0.f;
;     float csum = 0.f;
; #pragma unroll 1
;     for (int half = 0; half < 2; ++half) {
;       const int ev = P.eidx[(size_t)t * 128 + half * 64 + lane];
;       const int gv = __float_as_int(P.gw[(size_t)t * 128 + half * 64 + lane]);
;       const int suv = __float_as_int(P.su[ev]);
;       const int svv = __float_as_int(P.sv[ev]);
; #pragma unroll 1
;       for (int e = 0; e < 64; e += 4) {
;         u32x4 ua[4][2], va[4][2];
;         float cg[4], csu[4], csv[4];
; #pragma unroll
;         for (int k = 0; k < 4; ++k) {
;           const int ix = __builtin_amdgcn_readlane(ev, e + k);
;           cg[k] = __int_as_float(__builtin_amdgcn_readlane(gv, e + k));
;           csu[k] = __int_as_float(__builtin_amdgcn_readlane(suv, e + k));
;           csv[k] = __int_as_float(__builtin_amdgcn_readlane(svv, e + k));
;           typedef const __attribute__((address_space(1))) u32x4* gvec_t;
;           gbytes_t up = U8 + (size_t)ix * 2048 + lane * 16;
;           gbytes_t vp = V8 + (size_t)ix * 2048 + lane * 16;
;           ua[k][0] = *(gvec_t)up; ua[k][1] = *(gvec_t)(up + 1024);
;           va[k][0] = *(gvec_t)vp; va[k][1] = *(gvec_t)(vp + 1024);
;         }
	v_med3_i32 v8, v19, s29, v189
	v_med3_i32 v6, v17, s29, v189
	v_med3_i32 v5, v5, s29, v189
	v_lshlrev_b32_e32 v7, 8, v7
	v_lshlrev_b32_e32 v8, 16, v8
	v_and_b32_e32 v7, 0xff00, v7
	v_and_b32_e32 v8, 0xff0000, v8
	v_perm_b32 v5, v5, v6, s33
	v_or3_b32 v144, v5, v7, v8
	v_mul_f32_e32 v6, v4, v85
	v_mul_f32_e32 v7, v4, v86
	v_mul_f32_e32 v5, v4, v84
	v_rndne_f32_e32 v6, v6
	v_rndne_f32_e32 v7, v7
	v_mul_f32_e32 v8, v4, v87
	v_rndne_f32_e32 v5, v5
	v_cvt_i32_f32_e32 v6, v6
	v_cvt_i32_f32_e32 v7, v7
	v_rndne_f32_e32 v8, v8
	v_cvt_i32_f32_e32 v5, v5
	v_cvt_i32_f32_e32 v8, v8
	v_med3_i32 v6, v6, s29, v189
	v_med3_i32 v7, v7, s29, v189
	v_med3_i32 v5, v5, s29, v189
	v_med3_i32 v8, v8, s29, v189
	v_lshlrev_b32_e32 v6, 8, v6
	v_lshlrev_b32_e32 v7, 16, v7
	v_and_b32_e32 v6, 0xff00, v6
	v_and_b32_e32 v7, 0xff0000, v7
	v_perm_b32 v5, v8, v5, s33
	v_or3_b32 v145, v5, v6, v7
	v_mul_f32_e32 v6, v4, v89
	v_mul_f32_e32 v7, v4, v90
	v_mul_f32_e32 v5, v4, v88
	v_rndne_f32_e32 v6, v6
	v_rndne_f32_e32 v7, v7
	v_mul_f32_e32 v8, v4, v91
	v_rndne_f32_e32 v5, v5
	v_cvt_i32_f32_e32 v6, v6
	v_cvt_i32_f32_e32 v7, v7
	v_rndne_f32_e32 v8, v8
	v_cvt_i32_f32_e32 v5, v5
	v_cvt_i32_f32_e32 v8, v8
	v_med3_i32 v6, v6, s29, v189
	v_med3_i32 v7, v7, s29, v189
	v_med3_i32 v5, v5, s29, v189
	v_med3_i32 v8, v8, s29, v189
	v_lshlrev_b32_e32 v6, 8, v6
	v_lshlrev_b32_e32 v7, 16, v7
	v_and_b32_e32 v6, 0xff00, v6
	v_and_b32_e32 v7, 0xff0000, v7
	v_perm_b32 v5, v8, v5, s33
	v_or3_b32 v146, v5, v6, v7
	v_mul_f32_e32 v6, v4, v93
	v_mul_f32_e32 v7, v4, v94
	v_mul_f32_e32 v5, v4, v92
	v_rndne_f32_e32 v6, v6
	v_rndne_f32_e32 v7, v7
	v_mul_f32_e32 v8, v4, v95
	v_rndne_f32_e32 v5, v5
	v_cvt_i32_f32_e32 v6, v6
	v_cvt_i32_f32_e32 v7, v7
	v_rndne_f32_e32 v8, v8
	v_cvt_i32_f32_e32 v5, v5
	v_cvt_i32_f32_e32 v8, v8
	v_med3_i32 v6, v6, s29, v189
	v_med3_i32 v7, v7, s29, v189
	v_med3_i32 v5, v5, s29, v189
	v_med3_i32 v8, v8, s29, v189
	v_lshlrev_b32_e32 v6, 8, v6
	v_lshlrev_b32_e32 v7, 16, v7
	v_and_b32_e32 v6, 0xff00, v6
	v_and_b32_e32 v7, 0xff0000, v7
	v_perm_b32 v5, v8, v5, s33
	v_or3_b32 v147, v5, v6, v7
	v_mul_f32_e32 v6, v4, v97
	v_mul_f32_e32 v7, v4, v98
	v_mul_f32_e32 v13, v4, v76
	v_mul_f32_e32 v14, v4, v77
	v_mul_f32_e32 v15, v4, v78
	v_mul_f32_e32 v16, v4, v79
	v_mul_f32_e32 v5, v4, v96
	v_rndne_f32_e32 v6, v6
	v_rndne_f32_e32 v7, v7
	v_mul_f32_e32 v4, v4, v99
	v_rndne_f32_e32 v5, v5
	v_cvt_i32_f32_e32 v6, v6
	v_cvt_i32_f32_e32 v7, v7
	v_rndne_f32_e32 v4, v4
	v_cvt_i32_f32_e32 v5, v5
	v_cvt_i32_f32_e32 v4, v4
	v_rndne_f32_e32 v14, v14
	v_rndne_f32_e32 v15, v15
	v_rndne_f32_e32 v13, v13
	v_rndne_f32_e32 v16, v16
	v_cvt_i32_f32_e32 v14, v14
	v_cvt_i32_f32_e32 v15, v15
	v_med3_i32 v6, v6, s29, v189
	v_med3_i32 v7, v7, s29, v189
	v_cvt_i32_f32_e32 v13, v13
	v_cvt_i32_f32_e32 v16, v16
	v_med3_i32 v5, v5, s29, v189
	v_med3_i32 v4, v4, s29, v189
	v_lshlrev_b32_e32 v6, 8, v6
	v_lshlrev_b32_e32 v7, 16, v7
	v_and_b32_e32 v6, 0xff00, v6
	v_and_b32_e32 v7, 0xff0000, v7
	v_perm_b32 v4, v4, v5, s33
	v_or3_b32 v148, v4, v6, v7
	ds_read_b64 v[102:103], v53 offset:520
	ds_read2_b64 v[4:7], v53 offset0:50 offset1:51
	v_med3_i32 v14, v14, s29, v189
	v_med3_i32 v15, v15, s29, v189
	v_med3_i32 v13, v13, s29, v189
	v_med3_i32 v16, v16, s29, v189
	v_lshlrev_b32_e32 v11, 8, v14
	v_lshlrev_b32_e32 v12, 16, v15
	v_perm_b32 v13, v16, v13, s33
	v_and_b32_e32 v11, 0xff00, v11
	v_and_b32_e32 v12, 0xff0000, v12
	v_or3_b32 v67, v13, v11, v12
	s_branch .LBB0_156
.LBB0_156:
	s_waitcnt lgkmcnt(0)
	v_lshlrev_b64 v[8:9], 2, v[100:101]
	v_readlane_b32 s68, v4, 0
	v_readlane_b32 s69, v5, 0
	v_lshl_add_u64 v[10:11], v[102:103], 0, v[8:9]
	v_lshl_add_u64 v[12:13], v[2:3], 0, v[8:9]
	global_load_dword v104, v[10:11], off
	global_load_dword v105, v[10:11], off offset:256
	global_load_dword v49, v[12:13], off
	global_load_dword v149, v[12:13], off offset:256
	v_readlane_b32 s70, v6, 0
	v_readlane_b32 s71, v7, 0
	v_readlane_b32 s62, v56, 0
	v_readlane_b32 s63, v57, 0
	v_readlane_b32 s64, v58, 0
	v_readlane_b32 s65, v59, 0
	v_mov_b32_e32 v186, 0
	s_mov_b32 s77, 0
	s_waitcnt vmcnt(2)
	v_lshlrev_b32_e32 v2, 2, v104
	v_lshlrev_b32_e32 v3, 2, v105
	v_mov_b32_e32 v174, v104
	s_mov_b32 s66, s62
	s_mov_b32 s67, s63
	global_load_dword v102, v2, s[68:69]
	global_load_dword v103, v3, s[68:69]
	global_load_dword v100, v2, s[70:71]
	global_load_dword v101, v3, s[70:71]
	v_readlane_b32 s74, v174, 0
	s_lshl_b32 s74, s74, 11
	s_add_u32 s72, s66, s74
	s_addc_u32 s73, s67, 0
	global_load_dwordx4 v[8:11], v54, s[72:73]
	global_load_dwordx4 v[12:15], v54, s[72:73] offset:1024
	v_readlane_b32 s74, v174, 1
	s_lshl_b32 s74, s74, 11
	s_add_u32 s72, s66, s74
	s_addc_u32 s73, s67, 0
	global_load_dwordx4 v[16:19], v54, s[72:73]
	global_load_dwordx4 v[20:23], v54, s[72:73] offset:1024
	v_readlane_b32 s74, v174, 2
	s_lshl_b32 s74, s74, 11
	s_add_u32 s72, s66, s74
	s_addc_u32 s73, s67, 0
	global_load_dwordx4 v[24:27], v54, s[72:73]
	global_load_dwordx4 v[28:31], v54, s[72:73] offset:1024
	v_readlane_b32 s74, v174, 3
	s_lshl_b32 s74, s74, 11
	s_add_u32 s72, s66, s74
	s_addc_u32 s73, s67, 0
	global_load_dwordx4 v[32:35], v54, s[72:73]
	global_load_dwordx4 v[36:39], v54, s[72:73] offset:1024
	v_readlane_b32 s74, v174, 4
	s_lshl_b32 s74, s74, 11
	s_add_u32 s72, s66, s74
	s_addc_u32 s73, s67, 0
	global_load_dwordx4 v[40:43], v54, s[72:73]
	global_load_dwordx4 v[44:47], v54, s[72:73] offset:1024
	v_readlane_b32 s74, v174, 5
	s_lshl_b32 s74, s74, 11
	s_add_u32 s72, s66, s74
	s_addc_u32 s73, s67, 0
	global_load_dwordx4 v[150:153], v54, s[72:73]
	global_load_dwordx4 v[154:157], v54, s[72:73] offset:1024
	v_readlane_b32 s74, v174, 6
	s_lshl_b32 s74, s74, 11
	s_add_u32 s72, s66, s74
	s_addc_u32 s73, s67, 0
	global_load_dwordx4 v[158:161], v54, s[72:73]
	global_load_dwordx4 v[162:165], v54, s[72:73] offset:1024
	v_readlane_b32 s74, v174, 7
	s_lshl_b32 s74, s74, 11
	s_add_u32 s72, s66, s74
	s_addc_u32 s73, s67, 0
	global_load_dwordx4 v[166:169], v54, s[72:73]
	global_load_dwordx4 v[170:173], v54, s[72:73] offset:1024

; DEV float gelu_exact(float x) { return 0.5f * x * (1.f + erff(x * 0.70710678118654752f)); }
; __device__ __forceinline__ void phase_peer_gather(PREF P, int slab, int tbeg, int tend) {
;     ...
;         for (int k = 0; k < 4; ++k) {
;           const float d = (float)id[k] * csu[k] * sh;
;           const float c = cg[k] * gelu_exact(d) * csv[k];
;           csum += c;
;           axpy_ub(acc + 0, c, va[k][0].x);  axpy_ub(acc + 4, c, va[k][0].y);
;           axpy_ub(acc + 8, c, va[k][0].z);  axpy_ub(acc + 12, c, va[k][0].w);
;           axpy_ub(acc + 16, c, va[k][1].x); axpy_ub(acc + 20, c, va[k][1].y);
;           axpy_ub(acc + 24, c, va[k][1].z); axpy_ub(acc + 28, c, va[k][1].w);
;         }
.Lpga_drain:
	s_waitcnt vmcnt(14)
	v_cvt_f32_ubyte0_e32 v230, v8
	v_cvt_f32_ubyte1_e32 v231, v8
	v_cvt_f32_ubyte2_e32 v232, v8
	v_cvt_f32_ubyte3_e32 v233, v8
	v_pk_fma_f32 v[134:135], s[80:81], v[230:231], v[134:135] op_sel_hi:[0,1,1]
	v_pk_fma_f32 v[132:133], s[80:81], v[232:233], v[132:133] op_sel_hi:[0,1,1]
	v_cvt_f32_ubyte0_e32 v234, v9
	v_cvt_f32_ubyte1_e32 v235, v9
	v_cvt_f32_ubyte2_e32 v236, v9
	v_cvt_f32_ubyte3_e32 v237, v9
	v_pk_fma_f32 v[130:131], s[80:81], v[234:235], v[130:131] op_sel_hi:[0,1,1]
	v_pk_fma_f32 v[128:129], s[80:81], v[236:237], v[128:129] op_sel_hi:[0,1,1]
	v_cvt_f32_ubyte0_e32 v238, v10
	v_cvt_f32_ubyte1_e32 v239, v10
	v_cvt_f32_ubyte2_e32 v240, v10
	v_cvt_f32_ubyte3_e32 v241, v10
	v_pk_fma_f32 v[126:127], s[80:81], v[238:239], v[126:127] op_sel_hi:[0,1,1]
	v_pk_fma_f32 v[124:125], s[80:81], v[240:241], v[124:125] op_sel_hi:[0,1,1]
	v_cvt_f32_ubyte0_e32 v242, v11
	v_cvt_f32_ubyte1_e32 v243, v11
	v_cvt_f32_ubyte2_e32 v244, v11
	v_cvt_f32_ubyte3_e32 v245, v11
	v_pk_fma_f32 v[122:123], s[80:81], v[242:243], v[122:123] op_sel_hi:[0,1,1]
	v_pk_fma_f32 v[120:121], s[80:81], v[244:245], v[120:121] op_sel_hi:[0,1,1]
	v_cvt_f32_ubyte0_e32 v230, v12
	v_cvt_f32_ubyte1_e32 v231, v12
	v_cvt_f32_ubyte2_e32 v232, v12
	v_cvt_f32_ubyte3_e32 v233, v12
	v_pk_fma_f32 v[118:119], s[80:81], v[230:231], v[118:119] op_sel_hi:[0,1,1]
	v_pk_fma_f32 v[116:117], s[80:81], v[232:233], v[116:117] op_sel_hi:[0,1,1]
	v_cvt_f32_ubyte0_e32 v234, v13
	v_cvt_f32_ubyte1_e32 v235, v13
	v_cvt_f32_ubyte2_e32 v236, v13
	v_cvt_f32_ubyte3_e32 v237, v13
	v_pk_fma_f32 v[114:115], s[80:81], v[234:235], v[114:115] op_sel_hi:[0,1,1]
	v_pk_fma_f32 v[112:113], s[80:81], v[236:237], v[112:113] op_sel_hi:[0,1,1]
	v_cvt_f32_ubyte0_e32 v238, v14
	v_cvt_f32_ubyte1_e32 v239, v14
	v_cvt_f32_ubyte2_e32 v240, v14
	v_cvt_f32_ubyte3_e32 v241, v14
	v_pk_fma_f32 v[110:111], s[80:81], v[238:239], v[110:111] op_sel_hi:[0,1,1]
	v_pk_fma_f32 v[108:109], s[80:81], v[240:241], v[108:109] op_sel_hi:[0,1,1]
	v_cvt_f32_ubyte0_e32 v242, v15
	v_cvt_f32_ubyte1_e32 v243, v15
	v_cvt_f32_ubyte2_e32 v244, v15
	v_cvt_f32_ubyte3_e32 v245, v15
	v_pk_fma_f32 v[106:107], s[80:81], v[242:243], v[106:107] op_sel_hi:[0,1,1]
	v_pk_fma_f32 v[136:137], s[80:81], v[244:245], v[136:137] op_sel_hi:[0,1,1]
	s_waitcnt vmcnt(12)
	v_cvt_f32_ubyte0_e32 v230, v16
	v_cvt_f32_ubyte1_e32 v231, v16
	v_cvt_f32_ubyte2_e32 v232, v16
	v_cvt_f32_ubyte3_e32 v233, v16
	v_pk_fma_f32 v[134:135], s[82:83], v[230:231], v[134:135] op_sel_hi:[0,1,1]
	v_pk_fma_f32 v[132:133], s[82:83], v[232:233], v[132:133] op_sel_hi:[0,1,1]
	v_cvt_f32_ubyte0_e32 v234, v17
	v_cvt_f32_ubyte1_e32 v235, v17
	v_cvt_f32_ubyte2_e32 v236, v17
	v_cvt_f32_ubyte3_e32 v237, v17
	v_pk_fma_f32 v[130:131], s[82:83], v[234:235], v[130:131] op_sel_hi:[0,1,1]
	v_pk_fma_f32 v[128:129], s[82:83], v[236:237], v[128:129] op_sel_hi:[0,1,1]
	v_cvt_f32_ubyte0_e32 v238, v18
	v_cvt_f32_ubyte1_e32 v239, v18
	v_cvt_f32_ubyte2_e32 v240, v18
	v_cvt_f32_ubyte3_e32 v241, v18
	v_pk_fma_f32 v[126:127], s[82:83], v[238:239], v[126:127] op_sel_hi:[0,1,1]
	v_pk_fma_f32 v[124:125], s[82:83], v[240:241], v[124:125] op_sel_hi:[0,1,1]
	v_cvt_f32_ubyte0_e32 v242, v19
	v_cvt_f32_ubyte1_e32 v243, v19
	v_cvt_f32_ubyte2_e32 v244, v19
	v_cvt_f32_ubyte3_e32 v245, v19
	v_pk_fma_f32 v[122:123], s[82:83], v[242:243], v[122:123] op_sel_hi:[0,1,1]
	v_pk_fma_f32 v[120:121], s[82:83], v[244:245], v[120:121] op_sel_hi:[0,1,1]
	v_cvt_f32_ubyte0_e32 v230, v20
	v_cvt_f32_ubyte1_e32 v231, v20
	v_cvt_f32_ubyte2_e32 v232, v20
	v_cvt_f32_ubyte3_e32 v233, v20
	v_pk_fma_f32 v[118:119], s[82:83], v[230:231], v[118:119] op_sel_hi:[0,1,1]
	v_pk_fma_f32 v[116:117], s[82:83], v[232:233], v[116:117] op_sel_hi:[0,1,1]
	v_cvt_f32_ubyte0_e32 v234, v21
	v_cvt_f32_ubyte1_e32 v235, v21
	v_cvt_f32_ubyte2_e32 v236, v21
	v_cvt_f32_ubyte3_e32 v237, v21
	v_pk_fma_f32 v[114:115], s[82:83], v[234:235], v[114:115] op_sel_hi:[0,1,1]
	v_pk_fma_f32 v[112:113], s[82:83], v[236:237], v[112:113] op_sel_hi:[0,1,1]
	v_cvt_f32_ubyte0_e32 v238, v22
	v_cvt_f32_ubyte1_e32 v239, v22
	v_cvt_f32_ubyte2_e32 v240, v22
	v_cvt_f32_ubyte3_e32 v241, v22
	v_pk_fma_f32 v[110:111], s[82:83], v[238:239], v[110:111] op_sel_hi:[0,1,1]
	v_pk_fma_f32 v[108:109], s[82:83], v[240:241], v[108:109] op_sel_hi:[0,1,1]
	v_cvt_f32_ubyte0_e32 v242, v23
	v_cvt_f32_ubyte1_e32 v243, v23
	v_cvt_f32_ubyte2_e32 v244, v23
	v_cvt_f32_ubyte3_e32 v245, v23
	v_pk_fma_f32 v[106:107], s[82:83], v[242:243], v[106:107] op_sel_hi:[0,1,1]
	v_pk_fma_f32 v[136:137], s[82:83], v[244:245], v[136:137] op_sel_hi:[0,1,1]
	s_waitcnt vmcnt(10)
; DEV float gelu_exact(float x) { return 0.5f * x * (1.f + erff(x * 0.70710678118654752f)); }
; __device__ __forceinline__ void phase_peer_gather(PREF P, int slab, int tbeg, int tend) {
;     ...
;         for (int k = 0; k < 4; ++k) {
;           const float d = (float)id[k] * csu[k] * sh;
;           const float c = cg[k] * gelu_exact(d) * csv[k];
;           csum += c;
;           axpy_ub(acc + 0, c, va[k][0].x);  axpy_ub(acc + 4, c, va[k][0].y);
;           axpy_ub(acc + 8, c, va[k][0].z);  axpy_ub(acc + 12, c, va[k][0].w);
;           axpy_ub(acc + 16, c, va[k][1].x); axpy_ub(acc + 20, c, va[k][1].y);
;           axpy_ub(acc + 24, c, va[k][1].z); axpy_ub(acc + 28, c, va[k][1].w);
;         }
	v_cvt_f32_ubyte0_e32 v230, v24
	v_cvt_f32_ubyte1_e32 v231, v24
	v_cvt_f32_ubyte2_e32 v232, v24
	v_cvt_f32_ubyte3_e32 v233, v24
	v_pk_fma_f32 v[134:135], s[84:85], v[230:231], v[134:135] op_sel_hi:[0,1,1]
	v_pk_fma_f32 v[132:133], s[84:85], v[232:233], v[132:133] op_sel_hi:[0,1,1]
	v_cvt_f32_ubyte0_e32 v234, v25
	v_cvt_f32_ubyte1_e32 v235, v25
	v_cvt_f32_ubyte2_e32 v236, v25
	v_cvt_f32_ubyte3_e32 v237, v25
	v_pk_fma_f32 v[130:131], s[84:85], v[234:235], v[130:131] op_sel_hi:[0,1,1]
	v_pk_fma_f32 v[128:129], s[84:85], v[236:237], v[128:129] op_sel_hi:[0,1,1]
	v_cvt_f32_ubyte0_e32 v238, v26
	v_cvt_f32_ubyte1_e32 v239, v26
	v_cvt_f32_ubyte2_e32 v240, v26
	v_cvt_f32_ubyte3_e32 v241, v26
	v_pk_fma_f32 v[126:127], s[84:85], v[238:239], v[126:127] op_sel_hi:[0,1,1]
	v_pk_fma_f32 v[124:125], s[84:85], v[240:241], v[124:125] op_sel_hi:[0,1,1]
	v_cvt_f32_ubyte0_e32 v242, v27
	v_cvt_f32_ubyte1_e32 v243, v27
	v_cvt_f32_ubyte2_e32 v244, v27
	v_cvt_f32_ubyte3_e32 v245, v27
	v_pk_fma_f32 v[122:123], s[84:85], v[242:243], v[122:123] op_sel_hi:[0,1,1]
	v_pk_fma_f32 v[120:121], s[84:85], v[244:245], v[120:121] op_sel_hi:[0,1,1]
	v_cvt_f32_ubyte0_e32 v230, v28
	v_cvt_f32_ubyte1_e32 v231, v28
	v_cvt_f32_ubyte2_e32 v232, v28
	v_cvt_f32_ubyte3_e32 v233, v28
	v_pk_fma_f32 v[118:119], s[84:85], v[230:231], v[118:119] op_sel_hi:[0,1,1]
	v_pk_fma_f32 v[116:117], s[84:85], v[232:233], v[116:117] op_sel_hi:[0,1,1]
	v_cvt_f32_ubyte0_e32 v234, v29
	v_cvt_f32_ubyte1_e32 v235, v29
	v_cvt_f32_ubyte2_e32 v236, v29
	v_cvt_f32_ubyte3_e32 v237, v29
	v_pk_fma_f32 v[114:115], s[84:85], v[234:235], v[114:115] op_sel_hi:[0,1,1]
	v_pk_fma_f32 v[112:113], s[84:85], v[236:237], v[112:113] op_sel_hi:[0,1,1]
	v_cvt_f32_ubyte0_e32 v238, v30
	v_cvt_f32_ubyte1_e32 v239, v30
	v_cvt_f32_ubyte2_e32 v240, v30
	v_cvt_f32_ubyte3_e32 v241, v30
	v_pk_fma_f32 v[110:111], s[84:85], v[238:239], v[110:111] op_sel_hi:[0,1,1]
	v_pk_fma_f32 v[108:109], s[84:85], v[240:241], v[108:109] op_sel_hi:[0,1,1]
	v_cvt_f32_ubyte0_e32 v242, v31
	v_cvt_f32_ubyte1_e32 v243, v31
	v_cvt_f32_ubyte2_e32 v244, v31
	v_cvt_f32_ubyte3_e32 v245, v31
	v_pk_fma_f32 v[106:107], s[84:85], v[242:243], v[106:107] op_sel_hi:[0,1,1]
	v_pk_fma_f32 v[136:137], s[84:85], v[244:245], v[136:137] op_sel_hi:[0,1,1]
	s_waitcnt vmcnt(8)
	v_cvt_f32_ubyte0_e32 v230, v32
	v_cvt_f32_ubyte1_e32 v231, v32
	v_cvt_f32_ubyte2_e32 v232, v32
	v_cvt_f32_ubyte3_e32 v233, v32
	v_pk_fma_f32 v[134:135], s[86:87], v[230:231], v[134:135] op_sel_hi:[0,1,1]
	v_pk_fma_f32 v[132:133], s[86:87], v[232:233], v[132:133] op_sel_hi:[0,1,1]
	v_cvt_f32_ubyte0_e32 v234, v33
	v_cvt_f32_ubyte1_e32 v235, v33
	v_cvt_f32_ubyte2_e32 v236, v33
	v_cvt_f32_ubyte3_e32 v237, v33
	v_pk_fma_f32 v[130:131], s[86:87], v[234:235], v[130:131] op_sel_hi:[0,1,1]
	v_pk_fma_f32 v[128:129], s[86:87], v[236:237], v[128:129] op_sel_hi:[0,1,1]
	v_cvt_f32_ubyte0_e32 v238, v34
	v_cvt_f32_ubyte1_e32 v239, v34
	v_cvt_f32_ubyte2_e32 v240, v34
	v_cvt_f32_ubyte3_e32 v241, v34
	v_pk_fma_f32 v[126:127], s[86:87], v[238:239], v[126:127] op_sel_hi:[0,1,1]
	v_pk_fma_f32 v[124:125], s[86:87], v[240:241], v[124:125] op_sel_hi:[0,1,1]
	v_cvt_f32_ubyte0_e32 v242, v35
	v_cvt_f32_ubyte1_e32 v243, v35
	v_cvt_f32_ubyte2_e32 v244, v35
	v_cvt_f32_ubyte3_e32 v245, v35
	v_pk_fma_f32 v[122:123], s[86:87], v[242:243], v[122:123] op_sel_hi:[0,1,1]
	v_pk_fma_f32 v[120:121], s[86:87], v[244:245], v[120:121] op_sel_hi:[0,1,1]
	v_cvt_f32_ubyte0_e32 v230, v36
	v_cvt_f32_ubyte1_e32 v231, v36
	v_cvt_f32_ubyte2_e32 v232, v36
	v_cvt_f32_ubyte3_e32 v233, v36
	v_pk_fma_f32 v[118:119], s[86:87], v[230:231], v[118:119] op_sel_hi:[0,1,1]
	v_pk_fma_f32 v[116:117], s[86:87], v[232:233], v[116:117] op_sel_hi:[0,1,1]
	v_cvt_f32_ubyte0_e32 v234, v37
	v_cvt_f32_ubyte1_e32 v235, v37
	v_cvt_f32_ubyte2_e32 v236, v37
	v_cvt_f32_ubyte3_e32 v237, v37
	v_pk_fma_f32 v[114:115], s[86:87], v[234:235], v[114:115] op_sel_hi:[0,1,1]
	v_pk_fma_f32 v[112:113], s[86:87], v[236:237], v[112:113] op_sel_hi:[0,1,1]
	v_cvt_f32_ubyte0_e32 v238, v38
	v_cvt_f32_ubyte1_e32 v239, v38
	v_cvt_f32_ubyte2_e32 v240, v38
	v_cvt_f32_ubyte3_e32 v241, v38
	v_pk_fma_f32 v[110:111], s[86:87], v[238:239], v[110:111] op_sel_hi:[0,1,1]
	v_pk_fma_f32 v[108:109], s[86:87], v[240:241], v[108:109] op_sel_hi:[0,1,1]
	v_cvt_f32_ubyte0_e32 v242, v39
	v_cvt_f32_ubyte1_e32 v243, v39
	v_cvt_f32_ubyte2_e32 v244, v39
	v_cvt_f32_ubyte3_e32 v245, v39
	v_pk_fma_f32 v[106:107], s[86:87], v[242:243], v[106:107] op_sel_hi:[0,1,1]
	v_pk_fma_f32 v[136:137], s[86:87], v[244:245], v[136:137] op_sel_hi:[0,1,1]
	s_waitcnt vmcnt(6)
; DEV float gelu_exact(float x) { return 0.5f * x * (1.f + erff(x * 0.70710678118654752f)); }
; __device__ __forceinline__ void phase_peer_gather(PREF P, int slab, int tbeg, int tend) {
;     ...
;         for (int k = 0; k < 4; ++k) {
;           const float d = (float)id[k] * csu[k] * sh;
;           const float c = cg[k] * gelu_exact(d) * csv[k];
;           csum += c;
;           axpy_ub(acc + 0, c, va[k][0].x);  axpy_ub(acc + 4, c, va[k][0].y);
;           axpy_ub(acc + 8, c, va[k][0].z);  axpy_ub(acc + 12, c, va[k][0].w);
;           axpy_ub(acc + 16, c, va[k][1].x); axpy_ub(acc + 20, c, va[k][1].y);
;           axpy_ub(acc + 24, c, va[k][1].z); axpy_ub(acc + 28, c, va[k][1].w);
;         }
	v_cvt_f32_ubyte0_e32 v230, v40
	v_cvt_f32_ubyte1_e32 v231, v40
	v_cvt_f32_ubyte2_e32 v232, v40
	v_cvt_f32_ubyte3_e32 v233, v40
	v_pk_fma_f32 v[134:135], s[88:89], v[230:231], v[134:135] op_sel_hi:[0,1,1]
	v_pk_fma_f32 v[132:133], s[88:89], v[232:233], v[132:133] op_sel_hi:[0,1,1]
	v_cvt_f32_ubyte0_e32 v234, v41
	v_cvt_f32_ubyte1_e32 v235, v41
	v_cvt_f32_ubyte2_e32 v236, v41
	v_cvt_f32_ubyte3_e32 v237, v41
	v_pk_fma_f32 v[130:131], s[88:89], v[234:235], v[130:131] op_sel_hi:[0,1,1]
	v_pk_fma_f32 v[128:129], s[88:89], v[236:237], v[128:129] op_sel_hi:[0,1,1]
	v_cvt_f32_ubyte0_e32 v238, v42
	v_cvt_f32_ubyte1_e32 v239, v42
	v_cvt_f32_ubyte2_e32 v240, v42
	v_cvt_f32_ubyte3_e32 v241, v42
	v_pk_fma_f32 v[126:127], s[88:89], v[238:239], v[126:127] op_sel_hi:[0,1,1]
	v_pk_fma_f32 v[124:125], s[88:89], v[240:241], v[124:125] op_sel_hi:[0,1,1]
	v_cvt_f32_ubyte0_e32 v242, v43
	v_cvt_f32_ubyte1_e32 v243, v43
	v_cvt_f32_ubyte2_e32 v244, v43
	v_cvt_f32_ubyte3_e32 v245, v43
	v_pk_fma_f32 v[122:123], s[88:89], v[242:243], v[122:123] op_sel_hi:[0,1,1]
	v_pk_fma_f32 v[120:121], s[88:89], v[244:245], v[120:121] op_sel_hi:[0,1,1]
	v_cvt_f32_ubyte0_e32 v230, v44
	v_cvt_f32_ubyte1_e32 v231, v44
	v_cvt_f32_ubyte2_e32 v232, v44
	v_cvt_f32_ubyte3_e32 v233, v44
	v_pk_fma_f32 v[118:119], s[88:89], v[230:231], v[118:119] op_sel_hi:[0,1,1]
	v_pk_fma_f32 v[116:117], s[88:89], v[232:233], v[116:117] op_sel_hi:[0,1,1]
	v_cvt_f32_ubyte0_e32 v234, v45
	v_cvt_f32_ubyte1_e32 v235, v45
	v_cvt_f32_ubyte2_e32 v236, v45
	v_cvt_f32_ubyte3_e32 v237, v45
	v_pk_fma_f32 v[114:115], s[88:89], v[234:235], v[114:115] op_sel_hi:[0,1,1]
	v_pk_fma_f32 v[112:113], s[88:89], v[236:237], v[112:113] op_sel_hi:[0,1,1]
	v_cvt_f32_ubyte0_e32 v238, v46
	v_cvt_f32_ubyte1_e32 v239, v46
	v_cvt_f32_ubyte2_e32 v240, v46
	v_cvt_f32_ubyte3_e32 v241, v46
	v_pk_fma_f32 v[110:111], s[88:89], v[238:239], v[110:111] op_sel_hi:[0,1,1]
	v_pk_fma_f32 v[108:109], s[88:89], v[240:241], v[108:109] op_sel_hi:[0,1,1]
	v_cvt_f32_ubyte0_e32 v242, v47
	v_cvt_f32_ubyte1_e32 v243, v47
	v_cvt_f32_ubyte2_e32 v244, v47
	v_cvt_f32_ubyte3_e32 v245, v47
	v_pk_fma_f32 v[106:107], s[88:89], v[242:243], v[106:107] op_sel_hi:[0,1,1]
	v_pk_fma_f32 v[136:137], s[88:89], v[244:245], v[136:137] op_sel_hi:[0,1,1]
	s_waitcnt vmcnt(4)
	v_cvt_f32_ubyte0_e32 v230, v150
	v_cvt_f32_ubyte1_e32 v231, v150
	v_cvt_f32_ubyte2_e32 v232, v150
	v_cvt_f32_ubyte3_e32 v233, v150
	v_pk_fma_f32 v[134:135], s[90:91], v[230:231], v[134:135] op_sel_hi:[0,1,1]
	v_pk_fma_f32 v[132:133], s[90:91], v[232:233], v[132:133] op_sel_hi:[0,1,1]
	v_cvt_f32_ubyte0_e32 v234, v151
	v_cvt_f32_ubyte1_e32 v235, v151
	v_cvt_f32_ubyte2_e32 v236, v151
	v_cvt_f32_ubyte3_e32 v237, v151
	v_pk_fma_f32 v[130:131], s[90:91], v[234:235], v[130:131] op_sel_hi:[0,1,1]
	v_pk_fma_f32 v[128:129], s[90:91], v[236:237], v[128:129] op_sel_hi:[0,1,1]
	v_cvt_f32_ubyte0_e32 v238, v152
	v_cvt_f32_ubyte1_e32 v239, v152
	v_cvt_f32_ubyte2_e32 v240, v152
	v_cvt_f32_ubyte3_e32 v241, v152
	v_pk_fma_f32 v[126:127], s[90:91], v[238:239], v[126:127] op_sel_hi:[0,1,1]
	v_pk_fma_f32 v[124:125], s[90:91], v[240:241], v[124:125] op_sel_hi:[0,1,1]
	v_cvt_f32_ubyte0_e32 v242, v153
	v_cvt_f32_ubyte1_e32 v243, v153
	v_cvt_f32_ubyte2_e32 v244, v153
	v_cvt_f32_ubyte3_e32 v245, v153
	v_pk_fma_f32 v[122:123], s[90:91], v[242:243], v[122:123] op_sel_hi:[0,1,1]
	v_pk_fma_f32 v[120:121], s[90:91], v[244:245], v[120:121] op_sel_hi:[0,1,1]
	v_cvt_f32_ubyte0_e32 v230, v154
	v_cvt_f32_ubyte1_e32 v231, v154
	v_cvt_f32_ubyte2_e32 v232, v154
	v_cvt_f32_ubyte3_e32 v233, v154
	v_pk_fma_f32 v[118:119], s[90:91], v[230:231], v[118:119] op_sel_hi:[0,1,1]
	v_pk_fma_f32 v[116:117], s[90:91], v[232:233], v[116:117] op_sel_hi:[0,1,1]
	v_cvt_f32_ubyte0_e32 v234, v155
	v_cvt_f32_ubyte1_e32 v235, v155
	v_cvt_f32_ubyte2_e32 v236, v155
	v_cvt_f32_ubyte3_e32 v237, v155
	v_pk_fma_f32 v[114:115], s[90:91], v[234:235], v[114:115] op_sel_hi:[0,1,1]
	v_pk_fma_f32 v[112:113], s[90:91], v[236:237], v[112:113] op_sel_hi:[0,1,1]
	v_cvt_f32_ubyte0_e32 v238, v156
	v_cvt_f32_ubyte1_e32 v239, v156
	v_cvt_f32_ubyte2_e32 v240, v156
	v_cvt_f32_ubyte3_e32 v241, v156
	v_pk_fma_f32 v[110:111], s[90:91], v[238:239], v[110:111] op_sel_hi:[0,1,1]
	v_pk_fma_f32 v[108:109], s[90:91], v[240:241], v[108:109] op_sel_hi:[0,1,1]
	v_cvt_f32_ubyte0_e32 v242, v157
	v_cvt_f32_ubyte1_e32 v243, v157
	v_cvt_f32_ubyte2_e32 v244, v157
	v_cvt_f32_ubyte3_e32 v245, v157
	v_pk_fma_f32 v[106:107], s[90:91], v[242:243], v[106:107] op_sel_hi:[0,1,1]
	v_pk_fma_f32 v[136:137], s[90:91], v[244:245], v[136:137] op_sel_hi:[0,1,1]
	s_waitcnt vmcnt(2)
; DEV float gelu_exact(float x) { return 0.5f * x * (1.f + erff(x * 0.70710678118654752f)); }
; __device__ __forceinline__ void phase_peer_gather(PREF P, int slab, int tbeg, int tend) {
;     ...
;     float csum = 0.f;
;     ...
;         for (int k = 0; k < 4; ++k) {
;           const float d = (float)id[k] * csu[k] * sh;
;           const float c = cg[k] * gelu_exact(d) * csv[k];
;           csum += c;
;           axpy_ub(acc + 0, c, va[k][0].x);  axpy_ub(acc + 4, c, va[k][0].y);
;           axpy_ub(acc + 8, c, va[k][0].z);  axpy_ub(acc + 12, c, va[k][0].w);
;           axpy_ub(acc + 16, c, va[k][1].x); axpy_ub(acc + 20, c, va[k][1].y);
;           axpy_ub(acc + 24, c, va[k][1].z); axpy_ub(acc + 28, c, va[k][1].w);
;         }
	v_cvt_f32_ubyte0_e32 v230, v158
	v_cvt_f32_ubyte1_e32 v231, v158
	v_cvt_f32_ubyte2_e32 v232, v158
	v_cvt_f32_ubyte3_e32 v233, v158
	v_pk_fma_f32 v[134:135], s[92:93], v[230:231], v[134:135] op_sel_hi:[0,1,1]
	v_pk_fma_f32 v[132:133], s[92:93], v[232:233], v[132:133] op_sel_hi:[0,1,1]
	v_cvt_f32_ubyte0_e32 v234, v159
	v_cvt_f32_ubyte1_e32 v235, v159
	v_cvt_f32_ubyte2_e32 v236, v159
	v_cvt_f32_ubyte3_e32 v237, v159
	v_pk_fma_f32 v[130:131], s[92:93], v[234:235], v[130:131] op_sel_hi:[0,1,1]
	v_pk_fma_f32 v[128:129], s[92:93], v[236:237], v[128:129] op_sel_hi:[0,1,1]
	v_cvt_f32_ubyte0_e32 v238, v160
	v_cvt_f32_ubyte1_e32 v239, v160
	v_cvt_f32_ubyte2_e32 v240, v160
	v_cvt_f32_ubyte3_e32 v241, v160
	v_pk_fma_f32 v[126:127], s[92:93], v[238:239], v[126:127] op_sel_hi:[0,1,1]
	v_pk_fma_f32 v[124:125], s[92:93], v[240:241], v[124:125] op_sel_hi:[0,1,1]
	v_cvt_f32_ubyte0_e32 v242, v161
	v_cvt_f32_ubyte1_e32 v243, v161
	v_cvt_f32_ubyte2_e32 v244, v161
	v_cvt_f32_ubyte3_e32 v245, v161
	v_pk_fma_f32 v[122:123], s[92:93], v[242:243], v[122:123] op_sel_hi:[0,1,1]
	v_pk_fma_f32 v[120:121], s[92:93], v[244:245], v[120:121] op_sel_hi:[0,1,1]
	v_cvt_f32_ubyte0_e32 v230, v162
	v_cvt_f32_ubyte1_e32 v231, v162
	v_cvt_f32_ubyte2_e32 v232, v162
	v_cvt_f32_ubyte3_e32 v233, v162
	v_pk_fma_f32 v[118:119], s[92:93], v[230:231], v[118:119] op_sel_hi:[0,1,1]
	v_pk_fma_f32 v[116:117], s[92:93], v[232:233], v[116:117] op_sel_hi:[0,1,1]
	v_cvt_f32_ubyte0_e32 v234, v163
	v_cvt_f32_ubyte1_e32 v235, v163
	v_cvt_f32_ubyte2_e32 v236, v163
	v_cvt_f32_ubyte3_e32 v237, v163
	v_pk_fma_f32 v[114:115], s[92:93], v[234:235], v[114:115] op_sel_hi:[0,1,1]
	v_pk_fma_f32 v[112:113], s[92:93], v[236:237], v[112:113] op_sel_hi:[0,1,1]
	v_cvt_f32_ubyte0_e32 v238, v164
	v_cvt_f32_ubyte1_e32 v239, v164
	v_cvt_f32_ubyte2_e32 v240, v164
	v_cvt_f32_ubyte3_e32 v241, v164
	v_pk_fma_f32 v[110:111], s[92:93], v[238:239], v[110:111] op_sel_hi:[0,1,1]
	v_pk_fma_f32 v[108:109], s[92:93], v[240:241], v[108:109] op_sel_hi:[0,1,1]
	v_cvt_f32_ubyte0_e32 v242, v165
	v_cvt_f32_ubyte1_e32 v243, v165
	v_cvt_f32_ubyte2_e32 v244, v165
	v_cvt_f32_ubyte3_e32 v245, v165
	v_pk_fma_f32 v[106:107], s[92:93], v[242:243], v[106:107] op_sel_hi:[0,1,1]
	v_pk_fma_f32 v[136:137], s[92:93], v[244:245], v[136:137] op_sel_hi:[0,1,1]
	s_waitcnt vmcnt(0)
	v_cvt_f32_ubyte0_e32 v230, v166
	v_cvt_f32_ubyte1_e32 v231, v166
	v_cvt_f32_ubyte2_e32 v232, v166
	v_cvt_f32_ubyte3_e32 v233, v166
	v_pk_fma_f32 v[134:135], s[94:95], v[230:231], v[134:135] op_sel_hi:[0,1,1]
	v_pk_fma_f32 v[132:133], s[94:95], v[232:233], v[132:133] op_sel_hi:[0,1,1]
	v_cvt_f32_ubyte0_e32 v234, v167
	v_cvt_f32_ubyte1_e32 v235, v167
	v_cvt_f32_ubyte2_e32 v236, v167
	v_cvt_f32_ubyte3_e32 v237, v167
	v_pk_fma_f32 v[130:131], s[94:95], v[234:235], v[130:131] op_sel_hi:[0,1,1]
	v_pk_fma_f32 v[128:129], s[94:95], v[236:237], v[128:129] op_sel_hi:[0,1,1]
	v_cvt_f32_ubyte0_e32 v238, v168
	v_cvt_f32_ubyte1_e32 v239, v168
	v_cvt_f32_ubyte2_e32 v240, v168
	v_cvt_f32_ubyte3_e32 v241, v168
	v_pk_fma_f32 v[126:127], s[94:95], v[238:239], v[126:127] op_sel_hi:[0,1,1]
	v_pk_fma_f32 v[124:125], s[94:95], v[240:241], v[124:125] op_sel_hi:[0,1,1]
	v_cvt_f32_ubyte0_e32 v242, v169
	v_cvt_f32_ubyte1_e32 v243, v169
	v_cvt_f32_ubyte2_e32 v244, v169
	v_cvt_f32_ubyte3_e32 v245, v169
	v_pk_fma_f32 v[122:123], s[94:95], v[242:243], v[122:123] op_sel_hi:[0,1,1]
	v_pk_fma_f32 v[120:121], s[94:95], v[244:245], v[120:121] op_sel_hi:[0,1,1]
	v_cvt_f32_ubyte0_e32 v230, v170
	v_cvt_f32_ubyte1_e32 v231, v170
	v_cvt_f32_ubyte2_e32 v232, v170
	v_cvt_f32_ubyte3_e32 v233, v170
	v_pk_fma_f32 v[118:119], s[94:95], v[230:231], v[118:119] op_sel_hi:[0,1,1]
	v_pk_fma_f32 v[116:117], s[94:95], v[232:233], v[116:117] op_sel_hi:[0,1,1]
	v_cvt_f32_ubyte0_e32 v234, v171
	v_cvt_f32_ubyte1_e32 v235, v171
	v_cvt_f32_ubyte2_e32 v236, v171
	v_cvt_f32_ubyte3_e32 v237, v171
	v_pk_fma_f32 v[114:115], s[94:95], v[234:235], v[114:115] op_sel_hi:[0,1,1]
	v_pk_fma_f32 v[112:113], s[94:95], v[236:237], v[112:113] op_sel_hi:[0,1,1]
	v_cvt_f32_ubyte0_e32 v238, v172
	v_cvt_f32_ubyte1_e32 v239, v172
	v_cvt_f32_ubyte2_e32 v240, v172
	v_cvt_f32_ubyte3_e32 v241, v172
	v_pk_fma_f32 v[110:111], s[94:95], v[238:239], v[110:111] op_sel_hi:[0,1,1]
	v_pk_fma_f32 v[108:109], s[94:95], v[240:241], v[108:109] op_sel_hi:[0,1,1]
	v_cvt_f32_ubyte0_e32 v242, v173
	v_cvt_f32_ubyte1_e32 v243, v173
	v_cvt_f32_ubyte2_e32 v244, v173
	v_cvt_f32_ubyte3_e32 v245, v173
	v_pk_fma_f32 v[106:107], s[94:95], v[242:243], v[106:107] op_sel_hi:[0,1,1]
	v_pk_fma_f32 v[136:137], s[94:95], v[244:245], v[136:137] op_sel_hi:[0,1,1]
	s_nop 1
	v_add_f32_dpp v186, v186, v186 quad_perm:[1,0,3,2] row_mask:0xf bank_mask:0xf
	s_nop 1
	v_add_f32_dpp v186, v186, v186 quad_perm:[2,3,0,1] row_mask:0xf bank_mask:0xf
	s_nop 1
	v_add_f32_dpp v186, v186, v186 row_half_mirror row_mask:0xf bank_mask:0xf
	s_nop 1
	v_add_f32_dpp v186, v186, v186 row_mirror row_mask:0xf bank_mask:0xf
	s_nop 1
	v_add_f32_dpp v186, v186, v186 row_bcast:15 row_mask:0xa bank_mask:0xf
	s_nop 1
	v_add_f32_dpp v186, v186, v186 row_bcast:31 row_mask:0xc bank_mask:0xf
	s_nop 1
	v_readlane_b32 s80, v186, 63
	s_mov_b64 s[42:43], 64
	s_mov_b64 s[40:41], 0
	s_nop 1
	v_mov_b32_e32 v55, s80
	s_branch .LBB0_153
.LBB0_175:
	s_or_b64 exec, exec, s[0:1]

; DEV int tid_() { int t = threadIdx.x; asm volatile("" : "+v"(t)); return t; }
; DEV int bid_() { int t = blockIdx.x; asm volatile("" : "+s"(t)); return t; }
; DEV int gdim_() { int t = gridDim.x; asm volatile("" : "+s"(t)); return t; }
; #define P (*launderP(lp))
; template <class FragT, class AccT>
; DEV void gemm_core_t(const char* __restrict__ A, size_t lda_bytes, const char* __restrict__ Bt, size_t ldb_bytes, int kbytes,
;                      int m0, int n0, int Sshift, int dl, char* smem, AccT (&acc)[4][4]) {
;   const int tid = tid_(), lane = tid & 63, wid = tid >> 6, wm = wid >> 1, wn = wid & 1;
;   const int l15 = lane & 15, q = lane >> 4;
;   const int srow = lane >> 3, schunk = (lane & 7) ^ (lane >> 3);
;   const char* ap[4];
;   const char* bp[4];
; #pragma unroll
;   for (int u = 0; u < 4; ++u) {
;     int r = (wid * 4 + u) * 8 + srow;
;     int ar = rowmap(m0 + r, Sshift, dl);
;     ap[u] = A + (size_t)ar * lda_bytes + schunk * 16;
;     bp[u] = Bt + (size_t)(n0 + r) * ldb_bytes + schunk * 16;
;   }
; #pragma unroll
;   for (int i = 0; i < 4; ++i)
; #pragma unroll
;     for (int j = 0; j < 4; ++j) acc[i][j] = AccT{0, 0, 0, 0};
;   const int nk = kbytes >> 7;
;   __syncthreads();
; #pragma unroll
;   for (int u = 0; u < 4; ++u) {
;     __builtin_amdgcn_global_load_lds((const unsigned*)ap[u], (unsigned*)(smem + (wid * 4 + u) * 1024 + lane * 16), 16, 0, 0);
;     __builtin_amdgcn_global_load_lds((const unsigned*)bp[u], (unsigned*)(smem + 16384 + (wid * 4 + u) * 1024 + lane * 16), 16, 0, 0);
;   }
; __device__ __forceinline__ void phase_gemm2(PREF P, char* smem) {
;     ...
;   for (int t = bid_(); t < 64 * 16; t += gdim_()) {
;     int mt, nt;
;     tile_map(t, 2, mt, nt);
;     const int m0 = mt * 128, n0 = nt * 128;
;     f32x4 acc[4][4];
;     gemm_core(P.ret, 2048, P.WretT, 2048, 2048, m0, n0, 13, 0, smem, acc);
.LBB0_399:
	s_ashr_i32 s0, s14, 3
	s_lshr_b32 s1, s0, 28
	s_add_i32 s1, s0, s1
	s_and_b32 s4, s1, -16
	v_mov_b32_e32 v22, v188
	s_sub_i32 s0, s0, s4
	s_lshl_b32 s4, s14, 1
	ds_read2_b64 v[0:3], v92 offset0:21 offset1:40
	s_and_b32 s4, s4, 14
	v_ashrrev_i32_e32 v24, 6, v22
	s_ashr_i32 s5, s0, 3
	s_lshl_b32 s1, s1, 6
	s_lshl_b32 s0, s0, 7
	v_bfe_u32 v25, v22, 3, 3
	v_lshlrev_b32_e32 v26, 5, v24
	s_add_i32 s4, s5, s4
	s_and_b32 s17, s1, 0xfffffc00
	s_and_b32 s18, s0, 0x380
	v_or_b32_e32 v20, v26, v25
	s_or_b32 s15, s18, s17
	s_lshl_b32 s0, s4, 7
	v_or_b32_e32 v14, 8, v20
	v_or_b32_e32 v18, 16, v20
	v_or_b32_e32 v27, 24, v20
	v_bitop3_b32 v4, v25, v22, 7 bitop3:0x78
	v_add_u32_e32 v8, s15, v20
	v_add_u32_e32 v10, s0, v20
	v_add_u32_e32 v12, s15, v14
	v_add_u32_e32 v16, s15, v18
	v_add_u32_e32 v20, s15, v27
	v_lshlrev_b32_e32 v180, 4, v4
	v_ashrrev_i32_e32 v9, 31, v8
	v_ashrrev_i32_e32 v13, 31, v12
	v_ashrrev_i32_e32 v17, 31, v16
	v_ashrrev_i32_e32 v21, 31, v20
	s_waitcnt lgkmcnt(0)
	v_lshl_add_u64 v[4:5], v[2:3], 0, v[180:181]
	v_lshlrev_b64 v[8:9], 12, v[8:9]
	v_lshlrev_b64 v[12:13], 12, v[12:13]
	v_lshlrev_b64 v[16:17], 12, v[16:17]
	v_lshlrev_b64 v[20:21], 12, v[20:21]
	v_lshl_add_u64 v[8:9], v[4:5], 0, v[8:9]
	v_lshl_add_u64 v[12:13], v[4:5], 0, v[12:13]
	v_add_u32_e32 v14, s0, v14
	v_lshl_add_u64 v[16:17], v[4:5], 0, v[16:17]
	v_add_u32_e32 v18, s0, v18
	v_lshl_add_u64 v[4:5], v[4:5], 0, v[20:21]
	v_add_u32_e32 v20, s0, v27
	v_ashrrev_i32_e32 v11, 31, v10
	v_ashrrev_i32_e32 v15, 31, v14
	v_ashrrev_i32_e32 v19, 31, v18
	v_ashrrev_i32_e32 v21, 31, v20
	v_lshl_add_u64 v[6:7], v[0:1], 0, v[180:181]
	v_lshlrev_b64 v[10:11], 12, v[10:11]
	v_lshlrev_b64 v[14:15], 12, v[14:15]
	v_lshlrev_b64 v[18:19], 12, v[18:19]
	v_lshlrev_b64 v[20:21], 12, v[20:21]
	v_and_b32_e32 v23, 63, v22
	v_lshl_add_u64 v[10:11], v[6:7], 0, v[10:11]
	v_lshl_add_u64 v[14:15], v[6:7], 0, v[14:15]
	v_lshl_add_u64 v[18:19], v[6:7], 0, v[18:19]
	v_lshl_add_u64 v[6:7], v[6:7], 0, v[20:21]
	v_lshlrev_b32_e32 v21, 12, v24
	v_lshl_or_b32 v80, v23, 4, v21
	s_nop 0
	v_readfirstlane_b32 s1, v80
	s_mov_b32 m0, s1
	s_barrier
	global_load_lds_dwordx4 v[8:9], off
	v_add_u32_e32 v8, 0x4000, v80
	v_and_b32_e32 v20, 15, v22
	v_readfirstlane_b32 s1, v8
	v_or_b32_e32 v8, 0x400, v80
	s_mov_b32 m0, s1
	v_readfirstlane_b32 s1, v8
	v_add_u32_e32 v8, 0x4400, v80
	global_load_lds_dwordx4 v[10:11], off
	s_mov_b32 m0, s1
	v_readfirstlane_b32 s1, v8
	v_or_b32_e32 v8, 0x800, v80
	global_load_lds_dwordx4 v[12:13], off
	s_mov_b32 m0, s1
	v_readfirstlane_b32 s1, v8
	v_add_u32_e32 v8, 0x4800, v80
	global_load_lds_dwordx4 v[14:15], off
	s_mov_b32 m0, s1
	v_readfirstlane_b32 s1, v8
	v_or_b32_e32 v8, 0xc00, v80
	global_load_lds_dwordx4 v[16:17], off
	s_mov_b32 m0, s1
	v_readfirstlane_b32 s1, v8
	global_load_lds_dwordx4 v[18:19], off
	s_mov_b32 m0, s1
	s_lshl_b32 s4, s5, 7
	global_load_lds_dwordx4 v[4:5], off
	v_add_u32_e32 v4, 0x4c00, v80
	v_lshrrev_b32_e32 v5, 1, v22
	v_readfirstlane_b32 s1, v4
	s_mov_b32 m0, s1
	v_lshlrev_b32_e32 v4, 4, v22
	global_load_lds_dwordx4 v[6:7], off
	s_mov_b32 s1, 0x1ffffc0
	v_bitop3_b32 v4, v23, s31, v4 bitop3:0x48
	v_and_or_b32 v5, v5, s1, v20
	v_and_or_b32 v6, v26, 32, v20
	s_lshl_b32 s1, s14, 8
	v_lshl_or_b32 v6, v6, 7, v4
	s_and_b32 s1, s1, 0x700
	v_lshlrev_b32_e32 v5, 7, v5
	v_or_b32_e32 v82, 0x4000, v6
	v_bitop3_b32 v83, v6, 64, v219 bitop3:0x36
	v_or_b32_e32 v6, 24, v25
	s_add_i32 s1, s4, s1
	v_or_b32_e32 v81, v4, v5
	v_bitop3_b32 v84, v4, 64, v5 bitop3:0x36
	v_or_b32_e32 v4, s1, v6
	v_add_u32_e32 v4, v4, v26
	v_ashrrev_i32_e32 v5, 31, v4
	s_mov_b64 s[36:37], 0x80
	v_lshlrev_b64 v[4:5], 12, v[4:5]
	v_lshl_add_u64 v[0:1], v[0:1], 0, s[36:37]
	v_or_b32_e32 v4, v4, v180
	v_lshl_add_u64 v[64:65], v[0:1], 0, v[4:5]
	v_or_b32_e32 v4, s17, v6
	v_or_b32_e32 v4, s18, v4
	v_add_u32_e32 v4, v4, v26
	v_ashrrev_i32_e32 v5, 31, v4
	v_lshlrev_b64 v[4:5], 12, v[4:5]
	v_lshl_add_u64 v[2:3], v[2:3], 0, s[36:37]
	v_or_b32_e32 v4, v4, v180
	v_or_b32_e32 v6, 16, v25
	v_lshl_add_u64 v[66:67], v[2:3], 0, v[4:5]
	v_or_b32_e32 v4, s1, v6
	v_add_u32_e32 v4, v4, v26
	v_ashrrev_i32_e32 v5, 31, v4
	v_lshlrev_b64 v[4:5], 12, v[4:5]
	v_or_b32_e32 v4, v4, v180
	v_lshl_add_u64 v[68:69], v[0:1], 0, v[4:5]
	v_or_b32_e32 v4, s17, v6
	v_or_b32_e32 v4, s18, v4
	v_add_u32_e32 v4, v4, v26
	v_ashrrev_i32_e32 v5, 31, v4
	v_lshlrev_b64 v[4:5], 12, v[4:5]
	v_or_b32_e32 v4, v4, v180
	v_or_b32_e32 v6, 8, v25
	v_lshl_add_u64 v[70:71], v[2:3], 0, v[4:5]
	v_or_b32_e32 v4, s1, v6
	v_add_u32_e32 v4, v4, v26
	v_ashrrev_i32_e32 v5, 31, v4
	v_lshlrev_b64 v[4:5], 12, v[4:5]
	v_or_b32_e32 v4, v4, v180
	v_lshl_add_u64 v[72:73], v[0:1], 0, v[4:5]
	v_or_b32_e32 v4, s17, v6
	v_or_b32_e32 v4, s18, v4
	v_add_u32_e32 v4, v4, v26
	v_ashrrev_i32_e32 v5, 31, v4
	v_lshlrev_b64 v[4:5], 12, v[4:5]
	v_or_b32_e32 v4, v4, v180
	v_lshl_add_u64 v[74:75], v[2:3], 0, v[4:5]
	v_or_b32_e32 v4, s1, v25
	v_add_u32_e32 v4, v4, v26
	v_ashrrev_i32_e32 v5, 31, v4
	v_lshlrev_b64 v[4:5], 12, v[4:5]
	v_or_b32_e32 v4, v4, v180
	v_lshl_add_u64 v[76:77], v[0:1], 0, v[4:5]
	v_or_b32_e32 v0, s17, v25
	v_or_b32_e32 v0, s18, v0
	v_add_u32_e32 v0, v0, v26
	v_ashrrev_i32_e32 v1, 31, v0
	v_lshlrev_b64 v[0:1], 12, v[0:1]
	s_waitcnt vmcnt(0)
; DEV int tid_() { int t = threadIdx.x; asm volatile("" : "+v"(t)); return t; }
; template <class FragT, class AccT>
; DEV void gemm_core_t(const char* __restrict__ A, size_t lda_bytes, const char* __restrict__ Bt, size_t ldb_bytes, int kbytes,
;                      int m0, int n0, int Sshift, int dl, char* smem, AccT (&acc)[4][4]) {
;   const int tid = tid_(), lane = tid & 63, wid = tid >> 6, wm = wid >> 1, wn = wid & 1;
;   const int l15 = lane & 15, q = lane >> 4;
;   const int srow = lane >> 3, schunk = (lane & 7) ^ (lane >> 3);
;   const char* ap[4];
;   const char* bp[4];
; #pragma unroll
;   for (int u = 0; u < 4; ++u) {
;     int r = (wid * 4 + u) * 8 + srow;
;     int ar = rowmap(m0 + r, Sshift, dl);
;     ap[u] = A + (size_t)ar * lda_bytes + schunk * 16;
;     bp[u] = Bt + (size_t)(n0 + r) * ldb_bytes + schunk * 16;
;   }
; #pragma unroll
;   for (int i = 0; i < 4; ++i)
; #pragma unroll
;     for (int j = 0; j < 4; ++j) acc[i][j] = AccT{0, 0, 0, 0};
;   const int nk = kbytes >> 7;
;   __syncthreads();
; #pragma unroll
;   for (int u = 0; u < 4; ++u) {
;     __builtin_amdgcn_global_load_lds((const unsigned*)ap[u], (unsigned*)(smem + (wid * 4 + u) * 1024 + lane * 16), 16, 0, 0);
;     __builtin_amdgcn_global_load_lds((const unsigned*)bp[u], (unsigned*)(smem + 16384 + (wid * 4 + u) * 1024 + lane * 16), 16, 0, 0);
;   }
;   const unsigned sbase = (unsigned)(unsigned long)((__attribute__((address_space(3))) char*)smem);
;   const unsigned sq0 = (unsigned)((q ^ (l15 & 7)) << 4);
;   const unsigned a0 = sbase + (unsigned)((wm * 64 + l15) * 128) + sq0;
;   const unsigned b0 = sbase + 16384u + (unsigned)((wn * 32 + l15) * 128) + sq0;
;   asm volatile("s_waitcnt vmcnt(0)" ::: "memory");
;   __syncthreads();
;   for (int kt = 0; kt < nk; ++kt) {
;     const unsigned so = (unsigned)(kt & 1) * 32768u;
;     char* nxt = smem + ((kt + 1) & 1) * 32768;
;     if (kt + 1 < nk) {
; #pragma unroll
;       for (int u = 0; u < 4; ++u) {
;         __builtin_amdgcn_global_load_lds((const unsigned*)(ap[u] + (size_t)(kt + 1) * 128), (unsigned*)(nxt + (wid * 4 + u) * 1024 + lane * 16), 16, 0, 0);
;         __builtin_amdgcn_global_load_lds((const unsigned*)(bp[u] + (size_t)(kt + 1) * 128), (unsigned*)(nxt + 16384 + (wid * 4 + u) * 1024 + lane * 16), 16, 0, 0);
;       }
;     }
	v_or_b32_e32 v0, v0, v180
	v_lshl_add_u64 v[78:79], v[2:3], 0, v[0:1]
	v_mov_b32_e32 v0, 0
	s_mov_b64 s[4:5], 0
	s_mov_b32 s6, 0x8000
	v_mov_b32_e32 v1, v0
	v_mov_b32_e32 v2, v0
	v_mov_b32_e32 v3, v0
	v_mov_b32_e32 v4, v0
	v_mov_b32_e32 v5, v0
	v_mov_b32_e32 v6, v0
	v_mov_b32_e32 v7, v0
	v_mov_b32_e32 v8, v0
	v_mov_b32_e32 v9, v0
	v_mov_b32_e32 v10, v0
	v_mov_b32_e32 v11, v0
	v_mov_b32_e32 v12, v0
	v_mov_b32_e32 v13, v0
	v_mov_b32_e32 v14, v0
	v_mov_b32_e32 v15, v0
	v_mov_b32_e32 v16, v0
	v_mov_b32_e32 v17, v0
	v_mov_b32_e32 v18, v0
	v_mov_b32_e32 v19, v0
	v_mov_b32_e32 v20, v0
	v_mov_b32_e32 v21, v0
	v_mov_b32_e32 v22, v0
	v_mov_b32_e32 v23, v0
	v_mov_b32_e32 v24, v0
	v_mov_b32_e32 v25, v0
	v_mov_b32_e32 v26, v0
	v_mov_b32_e32 v27, v0
	v_mov_b32_e32 v28, v0
	v_mov_b32_e32 v29, v0
	v_mov_b32_e32 v30, v0
	v_mov_b32_e32 v31, v0
	v_mov_b32_e32 v32, v0
	v_mov_b32_e32 v33, v0
	v_mov_b32_e32 v34, v0
	v_mov_b32_e32 v35, v0
	v_mov_b32_e32 v36, v0
	v_mov_b32_e32 v37, v0
	v_mov_b32_e32 v38, v0
	v_mov_b32_e32 v39, v0
	v_mov_b32_e32 v40, v0
	v_mov_b32_e32 v41, v0
	v_mov_b32_e32 v42, v0
	v_mov_b32_e32 v43, v0
	v_mov_b32_e32 v44, v0
	v_mov_b32_e32 v45, v0
	v_mov_b32_e32 v46, v0
	v_mov_b32_e32 v47, v0
	v_mov_b32_e32 v48, v0
	v_mov_b32_e32 v49, v0
	v_mov_b32_e32 v50, v0
	v_mov_b32_e32 v51, v0
	v_mov_b32_e32 v52, v0
	v_mov_b32_e32 v53, v0
	v_mov_b32_e32 v54, v0
	v_mov_b32_e32 v55, v0
	v_mov_b32_e32 v56, v0
	v_mov_b32_e32 v57, v0
	v_mov_b32_e32 v58, v0
	v_mov_b32_e32 v59, v0
	v_mov_b32_e32 v60, v0
	v_mov_b32_e32 v61, v0
	v_mov_b32_e32 v62, v0
	v_mov_b32_e32 v63, v0
	v_readfirstlane_b32 s64, v78
	v_readfirstlane_b32 s65, v79
	v_readfirstlane_b32 s66, v76
	v_readfirstlane_b32 s67, v77
	v_readfirstlane_b32 s62, v80
	s_sub_u32 s64, s64, 0x80000000
	s_subb_u32 s65, s65, 0
	s_sub_u32 s66, s66, 0x80000000
	s_subb_u32 s67, s67, 0
	v_subrev_u32_e32 v78, s64, v78
	v_subrev_u32_e32 v76, s66, v76
	v_subrev_u32_e32 v74, s64, v74
	v_subrev_u32_e32 v72, s66, v72
	v_subrev_u32_e32 v70, s64, v70
	v_subrev_u32_e32 v68, s66, v68
	v_subrev_u32_e32 v66, s64, v66
	v_subrev_u32_e32 v64, s66, v64
	s_waitcnt vmcnt(0) lgkmcnt(0)
	s_barrier
.LBB0_400:
	s_add_i32 s16, s6, 0xffff8000
	s_and_b32 s16, s16, 0x8000
	v_add_u32_e32 v85, s16, v81
	v_add_u32_e32 v90, s16, v84
	v_or_b32_e32 v91, s16, v82
	v_or_b32_e32 v95, s16, v83
	s_and_b32 s16, s6, 0x8000
	s_add_i32 s16, s16, s62
	s_mov_b32 m0, s16
	ds_read_b128 v[86:89], v85
	global_load_lds_dwordx4 v78, s[64:65]
	ds_read_b128 v[96:99], v85 offset:2048
	s_add_i32 m0, s16, 0x4000
	ds_read_b128 v[100:103], v85 offset:4096
	global_load_lds_dwordx4 v76, s[66:67]
	ds_read_b128 v[104:107], v85 offset:6144
	s_add_i32 m0, s16, 0x400
	ds_read_b128 v[108:111], v91
	global_load_lds_dwordx4 v74, s[64:65]
	ds_read_b128 v[112:115], v91 offset:2048
	s_add_i32 m0, s16, 0x4400
	ds_read_b128 v[116:119], v91 offset:8192
	global_load_lds_dwordx4 v72, s[66:67]
	ds_read_b128 v[120:123], v91 offset:10240
	s_add_i32 m0, s16, 0x800
	ds_read_b128 v[124:127], v90
	global_load_lds_dwordx4 v70, s[64:65]
	ds_read_b128 v[128:131], v90 offset:2048
	s_add_i32 m0, s16, 0x4800
	ds_read_b128 v[132:135], v90 offset:4096
	global_load_lds_dwordx4 v68, s[66:67]
	ds_read_b128 v[136:139], v90 offset:6144
	s_add_i32 m0, s16, 0xc00
	ds_read_b128 v[140:143], v95
	global_load_lds_dwordx4 v66, s[64:65]
	ds_read_b128 v[144:147], v95 offset:2048
	s_add_i32 m0, s16, 0x4c00
	ds_read_b128 v[148:151], v95 offset:8192
	global_load_lds_dwordx4 v64, s[66:67]
	ds_read_b128 v[152:155], v95 offset:10240
	s_waitcnt lgkmcnt(8)
	s_setprio 1
	v_mfma_f32_16x16x32_bf16 v[60:63], v[108:111], v[86:89], v[60:63]
	v_mfma_f32_16x16x32_bf16 v[56:59], v[112:115], v[86:89], v[56:59]
	v_mfma_f32_16x16x32_bf16 v[52:55], v[116:119], v[86:89], v[52:55]
	v_mfma_f32_16x16x32_bf16 v[48:51], v[120:123], v[86:89], v[48:51]
	v_mfma_f32_16x16x32_bf16 v[44:47], v[108:111], v[96:99], v[44:47]
	v_mfma_f32_16x16x32_bf16 v[40:43], v[112:115], v[96:99], v[40:43]
	v_mfma_f32_16x16x32_bf16 v[36:39], v[116:119], v[96:99], v[36:39]
	v_mfma_f32_16x16x32_bf16 v[32:35], v[120:123], v[96:99], v[32:35]
	v_mfma_f32_16x16x32_bf16 v[28:31], v[108:111], v[100:103], v[28:31]
	v_mfma_f32_16x16x32_bf16 v[24:27], v[112:115], v[100:103], v[24:27]
	v_mfma_f32_16x16x32_bf16 v[20:23], v[116:119], v[100:103], v[20:23]
	v_mfma_f32_16x16x32_bf16 v[16:19], v[120:123], v[100:103], v[16:19]
	v_mfma_f32_16x16x32_bf16 v[12:15], v[108:111], v[104:107], v[12:15]
	v_mfma_f32_16x16x32_bf16 v[8:11], v[112:115], v[104:107], v[8:11]
	v_mfma_f32_16x16x32_bf16 v[4:7], v[116:119], v[104:107], v[4:7]
	v_mfma_f32_16x16x32_bf16 v[0:3], v[120:123], v[104:107], v[0:3]
	s_waitcnt lgkmcnt(0)
	s_nop 0
	v_mfma_f32_16x16x32_bf16 v[60:63], v[140:143], v[124:127], v[60:63]
	v_mfma_f32_16x16x32_bf16 v[56:59], v[144:147], v[124:127], v[56:59]
	v_mfma_f32_16x16x32_bf16 v[52:55], v[148:151], v[124:127], v[52:55]
	v_mfma_f32_16x16x32_bf16 v[48:51], v[152:155], v[124:127], v[48:51]
	v_mfma_f32_16x16x32_bf16 v[44:47], v[140:143], v[128:131], v[44:47]
	v_mfma_f32_16x16x32_bf16 v[40:43], v[144:147], v[128:131], v[40:43]
	v_mfma_f32_16x16x32_bf16 v[36:39], v[148:151], v[128:131], v[36:39]
	v_mfma_f32_16x16x32_bf16 v[32:35], v[152:155], v[128:131], v[32:35]
	v_mfma_f32_16x16x32_bf16 v[28:31], v[140:143], v[132:135], v[28:31]
	v_mfma_f32_16x16x32_bf16 v[24:27], v[144:147], v[132:135], v[24:27]
	v_mfma_f32_16x16x32_bf16 v[20:23], v[148:151], v[132:135], v[20:23]
	v_mfma_f32_16x16x32_bf16 v[16:19], v[152:155], v[132:135], v[16:19]
	v_mfma_f32_16x16x32_bf16 v[12:15], v[140:143], v[136:139], v[12:15]
	v_mfma_f32_16x16x32_bf16 v[8:11], v[144:147], v[136:139], v[8:11]
	v_mfma_f32_16x16x32_bf16 v[4:7], v[148:151], v[136:139], v[4:7]
	v_mfma_f32_16x16x32_bf16 v[0:3], v[152:155], v[136:139], v[0:3]
	s_setprio 0
	s_waitcnt vmcnt(0)
	s_add_u32 s4, s4, 0x80
	s_addc_u32 s5, s5, 0
	s_add_u32 s64, s64, 0x80
	s_addc_u32 s65, s65, 0
	s_add_u32 s66, s66, 0x80
	s_addc_u32 s67, s67, 0
	s_add_i32 s6, s6, 0x8000
	s_cmpk_lg_i32 s4, 0xf80
	s_waitcnt vmcnt(0) lgkmcnt(0)
	s_barrier
; DEV f32x4 mma_step(bf16x8 a, bf16x8 b, f32x4 c) { return MFMA(a, b, c); }
; DEV i32x4 mma_step(i32x4 a, i32x4 b, i32x4 c) { return __builtin_amdgcn_mfma_i32_16x16x64_i8(a, b, c, 0, 0, 0); }
; #define P (*launderP(lp))
; template <class FragT, class AccT>
; DEV void gemm_core_t(const char* __restrict__ A, size_t lda_bytes, const char* __restrict__ Bt, size_t ldb_bytes, int kbytes,
;                      int m0, int n0, int Sshift, int dl, char* smem, AccT (&acc)[4][4]) {
;     ...
; #pragma unroll
;     for (int i = 0; i < 4; ++i)
; #pragma unroll
;       for (int j = 0; j < 4; ++j) acc[i][j] = mma_step(wb[0][j], xa[0][i], acc[i][j]);
;     asm volatile("s_waitcnt lgkmcnt(0)"
;                  : "+v"(xa[1][0]), "+v"(xa[1][1]), "+v"(xa[1][2]), "+v"(xa[1][3]), "+v"(wb[1][0]), "+v"(wb[1][1]), "+v"(wb[1][2]),
;                    "+v"(wb[1][3]), "+v"(acc[0][0]), "+v"(acc[0][1]), "+v"(acc[0][2]), "+v"(acc[0][3]), "+v"(acc[1][0]),
;                    "+v"(acc[1][1]), "+v"(acc[1][2]), "+v"(acc[1][3]), "+v"(acc[2][0]), "+v"(acc[2][1]), "+v"(acc[2][2]),
;                    "+v"(acc[2][3]), "+v"(acc[3][0]), "+v"(acc[3][1]), "+v"(acc[3][2]), "+v"(acc[3][3])
;                  :
;                  : "memory");
; #pragma unroll
;     for (int i = 0; i < 4; ++i)
; #pragma unroll
;       for (int j = 0; j < 4; ++j) acc[i][j] = mma_step(wb[1][j], xa[1][i], acc[i][j]);
;     __builtin_amdgcn_s_setprio(0);
; __device__ __forceinline__ void phase_gemm2(PREF P, char* smem) {
;     ...
; #pragma unroll
;     for (int i = 0; i < 4; ++i)
; #pragma unroll
;       for (int j = 0; j < 4; ++j) {
;         const int row = m0 + wm * 64 + i * 16 + l15, col = n0 + (j & 1) * 16 + wn * 32 + (j >> 1) * 64 + q * 4;
;         const unsigned g = *(const unsigned*)((const u8*)P.GA + (size_t)row * 2048 + col);
;         f32x4 v;
;         v[0] = (float)(g & 255u) * (1.f / 255.f) * acc[i][j][0]; v[1] = (float)((g >> 8) & 255u) * (1.f / 255.f) * acc[i][j][1];
;         v[2] = (float)((g >> 16) & 255u) * (1.f / 255.f) * acc[i][j][2]; v[3] = (float)(g >> 24) * (1.f / 255.f) * acc[i][j][3];
;         store_nat(P.merged, 2048, row, col, v);
;       }
	s_cbranch_scc1 .LBB0_400
	v_add_u32_e32 v95, 0x8000, v81
	v_add_u32_e32 v132, 0x8000, v84
	v_or_b32_e32 v133, 0x8000, v82
	v_or_b32_e32 v134, 0x8000, v83
	ds_read_b128 v[64:67], v95
	ds_read_b128 v[68:71], v95 offset:2048
	ds_read_b128 v[72:75], v95 offset:4096
	ds_read_b128 v[76:79], v95 offset:6144
	ds_read_b128 v[80:83], v133
	ds_read_b128 v[84:87], v133 offset:2048
	ds_read_b128 v[88:91], v133 offset:8192
	ds_read_b128 v[96:99], v133 offset:10240
	ds_read_b128 v[100:103], v132
	ds_read_b128 v[104:107], v132 offset:2048
	ds_read_b128 v[108:111], v132 offset:4096
	ds_read_b128 v[112:115], v132 offset:6144
	ds_read_b128 v[116:119], v134
	ds_read_b128 v[120:123], v134 offset:2048
	ds_read_b128 v[124:127], v134 offset:8192
	ds_read_b128 v[128:131], v134 offset:10240
	s_waitcnt lgkmcnt(8)
	s_mov_b32 s16, 0x8000
	s_setprio 1
	v_mfma_f32_16x16x32_bf16 v[60:63], v[80:83], v[64:67], v[60:63]
	v_mfma_f32_16x16x32_bf16 v[56:59], v[84:87], v[64:67], v[56:59]
	v_mfma_f32_16x16x32_bf16 v[52:55], v[88:91], v[64:67], v[52:55]
	v_mfma_f32_16x16x32_bf16 v[48:51], v[96:99], v[64:67], v[48:51]
	v_mfma_f32_16x16x32_bf16 v[44:47], v[80:83], v[68:71], v[44:47]
	v_mfma_f32_16x16x32_bf16 v[40:43], v[84:87], v[68:71], v[40:43]
	v_mfma_f32_16x16x32_bf16 v[36:39], v[88:91], v[68:71], v[36:39]
	v_mfma_f32_16x16x32_bf16 v[32:35], v[96:99], v[68:71], v[32:35]
	v_mfma_f32_16x16x32_bf16 v[28:31], v[80:83], v[72:75], v[28:31]
	v_mfma_f32_16x16x32_bf16 v[24:27], v[84:87], v[72:75], v[24:27]
	v_mfma_f32_16x16x32_bf16 v[20:23], v[88:91], v[72:75], v[20:23]
	v_mfma_f32_16x16x32_bf16 v[16:19], v[96:99], v[72:75], v[16:19]
	v_mfma_f32_16x16x32_bf16 v[12:15], v[80:83], v[76:79], v[12:15]
	v_mfma_f32_16x16x32_bf16 v[8:11], v[84:87], v[76:79], v[8:11]
	v_mfma_f32_16x16x32_bf16 v[4:7], v[88:91], v[76:79], v[4:7]
	v_mfma_f32_16x16x32_bf16 v[0:3], v[96:99], v[76:79], v[0:3]
	s_waitcnt lgkmcnt(0)
	s_nop 0
	v_mfma_f32_16x16x32_bf16 v[60:63], v[116:119], v[100:103], v[60:63]
	v_mfma_f32_16x16x32_bf16 v[70:73], v[120:123], v[100:103], v[56:59]
	v_mfma_f32_16x16x32_bf16 v[52:55], v[124:127], v[100:103], v[52:55]
	v_mfma_f32_16x16x32_bf16 v[48:51], v[128:131], v[100:103], v[48:51]
	v_mfma_f32_16x16x32_bf16 v[44:47], v[116:119], v[104:107], v[44:47]
	v_mfma_f32_16x16x32_bf16 v[40:43], v[120:123], v[104:107], v[40:43]
	v_mfma_f32_16x16x32_bf16 v[36:39], v[124:127], v[104:107], v[36:39]
	v_mfma_f32_16x16x32_bf16 v[32:35], v[128:131], v[104:107], v[32:35]
	v_mfma_f32_16x16x32_bf16 v[28:31], v[116:119], v[108:111], v[28:31]
	v_mfma_f32_16x16x32_bf16 v[24:27], v[120:123], v[108:111], v[24:27]
	v_mfma_f32_16x16x32_bf16 v[20:23], v[124:127], v[108:111], v[20:23]
	v_mfma_f32_16x16x32_bf16 v[16:19], v[128:131], v[108:111], v[16:19]
	v_mfma_f32_16x16x32_bf16 v[12:15], v[116:119], v[112:115], v[12:15]
	v_mfma_f32_16x16x32_bf16 v[8:11], v[120:123], v[112:115], v[8:11]
	v_mfma_f32_16x16x32_bf16 v[4:7], v[124:127], v[112:115], v[4:7]
	v_mfma_f32_16x16x32_bf16 v[0:3], v[128:131], v[112:115], v[0:3]
	s_setprio 0
	s_waitcnt vmcnt(0)
	s_barrier
	ds_read_b64 v[66:67], v92 offset:296
	ds_read_b64 v[74:75], v92 offset:336
	v_add_u32_e32 v56, s15, v93
	v_ashrrev_i32_e32 v57, 31, v56
	v_or_b32_e32 v64, s0, v94
	v_lshlrev_b64 v[68:69], 11, v[56:57]
	s_waitcnt lgkmcnt(1)
	v_lshl_add_u64 v[66:67], v[66:67], 0, v[68:69]
	v_ashrrev_i32_e32 v65, 31, v64
	v_lshl_add_u64 v[66:67], v[66:67], 0, v[64:65]
	v_lshlrev_b64 v[58:59], 12, v[56:57]
	flat_load_dword v57, v[66:67]
	s_mov_b32 s4, 0x3b808081
	s_add_i32 s18, s18, s17
	s_waitcnt vmcnt(0) lgkmcnt(0)
	v_cvt_f32_ubyte1_e32 v67, v57
	v_cvt_f32_ubyte0_e32 v66, v57
	v_pk_mul_f32 v[66:67], v[66:67], s[4:5] op_sel_hi:[1,0]
	s_nop 0
	v_pk_mul_f32 v[60:61], v[60:61], v[66:67]
	v_cvt_f32_ubyte3_e32 v67, v57
	v_cvt_f32_ubyte2_e32 v66, v57
	v_pk_mul_f32 v[66:67], v[66:67], s[4:5] op_sel_hi:[1,0]
	v_cvt_pk_bf16_f32 v60, v60, v61
	v_pk_mul_f32 v[62:63], v[62:63], v[66:67]
	v_lshlrev_b64 v[66:67], 1, v[64:65]
	v_cvt_pk_bf16_f32 v61, v62, v63
	v_lshl_add_u64 v[62:63], v[74:75], 0, v[58:59]
	v_lshl_add_u64 v[62:63], v[62:63], 0, v[66:67]
	flat_store_dwordx2 v[62:63], v[60:61]
	ds_read_b64 v[60:61], v92 offset:296
	ds_read_b64 v[62:63], v92 offset:336
	s_waitcnt lgkmcnt(0)
	v_lshl_add_u64 v[60:61], v[60:61], 0, v[68:69]
	v_lshl_add_u64 v[60:61], v[60:61], 0, v[64:65]
	flat_load_dword v57, v[60:61] offset:16
	v_lshl_add_u64 v[62:63], v[62:63], 0, v[58:59]
	v_lshl_add_u64 v[62:63], v[62:63], 0, v[66:67]
	s_waitcnt vmcnt(0) lgkmcnt(0)
	v_cvt_f32_ubyte1_e32 v61, v57
	v_cvt_f32_ubyte0_e32 v60, v57
	v_pk_mul_f32 v[60:61], v[60:61], s[4:5] op_sel_hi:[1,0]
	s_nop 0
	v_pk_mul_f32 v[60:61], v[70:71], v[60:61]
	v_cvt_f32_ubyte3_e32 v71, v57
	v_cvt_f32_ubyte2_e32 v70, v57
	v_pk_mul_f32 v[70:71], v[70:71], s[4:5] op_sel_hi:[1,0]
	v_cvt_pk_bf16_f32 v60, v60, v61
	v_pk_mul_f32 v[70:71], v[72:73], v[70:71]
	s_nop 0
	v_cvt_pk_bf16_f32 v61, v70, v71
	flat_store_dwordx2 v[62:63], v[60:61] offset:32
	ds_read_b64 v[60:61], v92 offset:296
	ds_read_b64 v[62:63], v92 offset:336
	s_waitcnt lgkmcnt(0)
	v_lshl_add_u64 v[60:61], v[60:61], 0, v[68:69]
	v_lshl_add_u64 v[60:61], v[60:61], 0, v[64:65]
	flat_load_dword v57, v[60:61] offset:64
	s_waitcnt vmcnt(0) lgkmcnt(0)
	v_cvt_f32_ubyte1_e32 v61, v57
	v_cvt_f32_ubyte0_e32 v60, v57
	v_pk_mul_f32 v[60:61], v[60:61], s[4:5] op_sel_hi:[1,0]
	s_nop 0
	v_pk_mul_f32 v[52:53], v[52:53], v[60:61]
	v_cvt_f32_ubyte3_e32 v61, v57
	v_cvt_f32_ubyte2_e32 v60, v57
	v_pk_mul_f32 v[60:61], v[60:61], s[4:5] op_sel_hi:[1,0]
	v_cvt_pk_bf16_f32 v52, v52, v53
	v_pk_mul_f32 v[54:55], v[54:55], v[60:61]
	s_nop 0
	v_cvt_pk_bf16_f32 v53, v54, v55
	v_lshl_add_u64 v[54:55], v[62:63], 0, v[58:59]
	v_lshl_add_u64 v[54:55], v[54:55], 0, v[66:67]
	flat_store_dwordx2 v[54:55], v[52:53] offset:128
	ds_read_b64 v[52:53], v92 offset:296
	ds_read_b64 v[54:55], v92 offset:336
	s_waitcnt lgkmcnt(0)
; #define P (*launderP(lp))
; __device__ __forceinline__ void phase_gemm2(PREF P, char* smem) {
;     ...
; #pragma unroll
;     for (int i = 0; i < 4; ++i)
; #pragma unroll
;       for (int j = 0; j < 4; ++j) {
;         const int row = m0 + wm * 64 + i * 16 + l15, col = n0 + (j & 1) * 16 + wn * 32 + (j >> 1) * 64 + q * 4;
;         const unsigned g = *(const unsigned*)((const u8*)P.GA + (size_t)row * 2048 + col);
;         f32x4 v;
;         v[0] = (float)(g & 255u) * (1.f / 255.f) * acc[i][j][0]; v[1] = (float)((g >> 8) & 255u) * (1.f / 255.f) * acc[i][j][1];
;         v[2] = (float)((g >> 16) & 255u) * (1.f / 255.f) * acc[i][j][2]; v[3] = (float)(g >> 24) * (1.f / 255.f) * acc[i][j][3];
;         store_nat(P.merged, 2048, row, col, v);
;       }
	v_lshl_add_u64 v[52:53], v[52:53], 0, v[68:69]
	v_lshl_add_u64 v[52:53], v[52:53], 0, v[64:65]
	flat_load_dword v57, v[52:53] offset:80
	s_waitcnt vmcnt(0) lgkmcnt(0)
	v_cvt_f32_ubyte1_e32 v53, v57
	v_cvt_f32_ubyte0_e32 v52, v57
	v_pk_mul_f32 v[52:53], v[52:53], s[4:5] op_sel_hi:[1,0]
	s_nop 0
	v_pk_mul_f32 v[48:49], v[48:49], v[52:53]
	v_cvt_f32_ubyte3_e32 v53, v57
	v_cvt_f32_ubyte2_e32 v52, v57
	v_pk_mul_f32 v[52:53], v[52:53], s[4:5] op_sel_hi:[1,0]
	v_cvt_pk_bf16_f32 v48, v48, v49
	v_pk_mul_f32 v[50:51], v[50:51], v[52:53]
	s_nop 0
	v_cvt_pk_bf16_f32 v49, v50, v51
	v_lshl_add_u64 v[50:51], v[54:55], 0, v[58:59]
	v_lshl_add_u64 v[50:51], v[50:51], 0, v[66:67]
	flat_store_dwordx2 v[50:51], v[48:49] offset:160
	ds_read_b64 v[50:51], v92 offset:296
	ds_read_b64 v[52:53], v92 offset:336
	v_or_b32_e32 v48, 16, v56
	v_ashrrev_i32_e32 v49, 31, v48
	v_lshlrev_b64 v[72:73], 11, v[48:49]
	s_waitcnt lgkmcnt(0)
	v_lshl_add_u64 v[50:51], v[50:51], 0, v[72:73]
	v_lshl_add_u64 v[50:51], v[50:51], 0, v[64:65]
	flat_load_dword v54, v[50:51]
	v_lshlrev_b64 v[48:49], 12, v[48:49]
	s_waitcnt vmcnt(0) lgkmcnt(0)
	v_cvt_f32_ubyte1_e32 v51, v54
	v_cvt_f32_ubyte0_e32 v50, v54
	v_pk_mul_f32 v[50:51], v[50:51], s[4:5] op_sel_hi:[1,0]
	s_nop 0
	v_pk_mul_f32 v[44:45], v[44:45], v[50:51]
	v_cvt_f32_ubyte3_e32 v51, v54
	v_cvt_f32_ubyte2_e32 v50, v54
	v_pk_mul_f32 v[50:51], v[50:51], s[4:5] op_sel_hi:[1,0]
	v_cvt_pk_bf16_f32 v44, v44, v45
	v_pk_mul_f32 v[46:47], v[46:47], v[50:51]
	s_nop 0
	v_cvt_pk_bf16_f32 v45, v46, v47
	v_lshl_add_u64 v[46:47], v[52:53], 0, v[48:49]
	v_lshl_add_u64 v[46:47], v[46:47], 0, v[66:67]
	flat_store_dwordx2 v[46:47], v[44:45]
	ds_read_b64 v[44:45], v92 offset:296
	ds_read_b64 v[46:47], v92 offset:336
	s_waitcnt lgkmcnt(0)
	v_lshl_add_u64 v[44:45], v[44:45], 0, v[72:73]
	v_lshl_add_u64 v[44:45], v[44:45], 0, v[64:65]
	flat_load_dword v50, v[44:45] offset:16
	s_waitcnt vmcnt(0) lgkmcnt(0)
	v_cvt_f32_ubyte1_e32 v45, v50
	v_cvt_f32_ubyte0_e32 v44, v50
	v_pk_mul_f32 v[44:45], v[44:45], s[4:5] op_sel_hi:[1,0]
	s_nop 0
	v_pk_mul_f32 v[40:41], v[40:41], v[44:45]
	v_cvt_f32_ubyte3_e32 v45, v50
	v_cvt_f32_ubyte2_e32 v44, v50
	v_pk_mul_f32 v[44:45], v[44:45], s[4:5] op_sel_hi:[1,0]
	v_cvt_pk_bf16_f32 v40, v40, v41
	v_pk_mul_f32 v[42:43], v[42:43], v[44:45]
	s_nop 0
	v_cvt_pk_bf16_f32 v41, v42, v43
	v_lshl_add_u64 v[42:43], v[46:47], 0, v[48:49]
	v_lshl_add_u64 v[42:43], v[42:43], 0, v[66:67]
	flat_store_dwordx2 v[42:43], v[40:41] offset:32
	ds_read_b64 v[40:41], v92 offset:296
	ds_read_b64 v[42:43], v92 offset:336
	s_waitcnt lgkmcnt(0)
	v_lshl_add_u64 v[40:41], v[40:41], 0, v[72:73]
	v_lshl_add_u64 v[40:41], v[40:41], 0, v[64:65]
	flat_load_dword v44, v[40:41] offset:64
	s_waitcnt vmcnt(0) lgkmcnt(0)
	v_cvt_f32_ubyte1_e32 v41, v44
	v_cvt_f32_ubyte0_e32 v40, v44
	v_pk_mul_f32 v[40:41], v[40:41], s[4:5] op_sel_hi:[1,0]
	s_nop 0
	v_pk_mul_f32 v[36:37], v[36:37], v[40:41]
	v_cvt_f32_ubyte3_e32 v41, v44
	v_cvt_f32_ubyte2_e32 v40, v44
	v_pk_mul_f32 v[40:41], v[40:41], s[4:5] op_sel_hi:[1,0]
	v_cvt_pk_bf16_f32 v36, v36, v37
	v_pk_mul_f32 v[38:39], v[38:39], v[40:41]
	s_nop 0
	v_cvt_pk_bf16_f32 v37, v38, v39
	v_lshl_add_u64 v[38:39], v[42:43], 0, v[48:49]
	v_lshl_add_u64 v[38:39], v[38:39], 0, v[66:67]
	flat_store_dwordx2 v[38:39], v[36:37] offset:128
	ds_read_b64 v[36:37], v92 offset:296
	ds_read_b64 v[38:39], v92 offset:336
	s_waitcnt lgkmcnt(0)
	v_lshl_add_u64 v[36:37], v[36:37], 0, v[72:73]
	v_lshl_add_u64 v[36:37], v[36:37], 0, v[64:65]
	flat_load_dword v40, v[36:37] offset:80
	s_waitcnt vmcnt(0) lgkmcnt(0)
	v_cvt_f32_ubyte1_e32 v37, v40
	v_cvt_f32_ubyte0_e32 v36, v40
	v_pk_mul_f32 v[36:37], v[36:37], s[4:5] op_sel_hi:[1,0]
	s_nop 0
	v_pk_mul_f32 v[32:33], v[32:33], v[36:37]
	v_cvt_f32_ubyte3_e32 v37, v40
	v_cvt_f32_ubyte2_e32 v36, v40
	v_pk_mul_f32 v[36:37], v[36:37], s[4:5] op_sel_hi:[1,0]
	v_cvt_pk_bf16_f32 v32, v32, v33
	v_pk_mul_f32 v[34:35], v[34:35], v[36:37]
	s_nop 0
	v_cvt_pk_bf16_f32 v33, v34, v35
	v_lshl_add_u64 v[34:35], v[38:39], 0, v[48:49]
	v_lshl_add_u64 v[34:35], v[34:35], 0, v[66:67]
	flat_store_dwordx2 v[34:35], v[32:33] offset:160
	ds_read_b64 v[34:35], v92 offset:296
	ds_read_b64 v[36:37], v92 offset:336
	v_or_b32_e32 v32, 32, v56
	v_ashrrev_i32_e32 v33, 31, v32
	v_lshlrev_b64 v[74:75], 11, v[32:33]
	s_waitcnt lgkmcnt(0)
	v_lshl_add_u64 v[34:35], v[34:35], 0, v[74:75]
	v_lshl_add_u64 v[34:35], v[34:35], 0, v[64:65]
	flat_load_dword v38, v[34:35]
	v_lshlrev_b64 v[32:33], 12, v[32:33]
	s_waitcnt vmcnt(0) lgkmcnt(0)
	v_cvt_f32_ubyte1_e32 v35, v38
	v_cvt_f32_ubyte0_e32 v34, v38
	v_pk_mul_f32 v[34:35], v[34:35], s[4:5] op_sel_hi:[1,0]
	s_nop 0
	v_pk_mul_f32 v[28:29], v[28:29], v[34:35]
	v_cvt_f32_ubyte3_e32 v35, v38
	v_cvt_f32_ubyte2_e32 v34, v38
	v_pk_mul_f32 v[34:35], v[34:35], s[4:5] op_sel_hi:[1,0]
	v_cvt_pk_bf16_f32 v28, v28, v29
	v_pk_mul_f32 v[30:31], v[30:31], v[34:35]
	s_nop 0
	v_cvt_pk_bf16_f32 v29, v30, v31
	v_lshl_add_u64 v[30:31], v[36:37], 0, v[32:33]
	v_lshl_add_u64 v[30:31], v[30:31], 0, v[66:67]
	flat_store_dwordx2 v[30:31], v[28:29]
	ds_read_b64 v[28:29], v92 offset:296
	ds_read_b64 v[30:31], v92 offset:336
	s_waitcnt lgkmcnt(0)
	v_lshl_add_u64 v[28:29], v[28:29], 0, v[74:75]
	v_lshl_add_u64 v[28:29], v[28:29], 0, v[64:65]
	flat_load_dword v34, v[28:29] offset:16
	s_waitcnt vmcnt(0) lgkmcnt(0)
; #define P (*launderP(lp))
; __device__ __forceinline__ void phase_gemm2(PREF P, char* smem) {
;     ...
; #pragma unroll
;     for (int i = 0; i < 4; ++i)
; #pragma unroll
;       for (int j = 0; j < 4; ++j) {
;         const int row = m0 + wm * 64 + i * 16 + l15, col = n0 + (j & 1) * 16 + wn * 32 + (j >> 1) * 64 + q * 4;
;         const unsigned g = *(const unsigned*)((const u8*)P.GA + (size_t)row * 2048 + col);
;         f32x4 v;
;         v[0] = (float)(g & 255u) * (1.f / 255.f) * acc[i][j][0]; v[1] = (float)((g >> 8) & 255u) * (1.f / 255.f) * acc[i][j][1];
;         v[2] = (float)((g >> 16) & 255u) * (1.f / 255.f) * acc[i][j][2]; v[3] = (float)(g >> 24) * (1.f / 255.f) * acc[i][j][3];
;         store_nat(P.merged, 2048, row, col, v);
;       }
;     gemm_core(P.att, 1024, P.WattT, 1024, 1024, m0, n0, 13, 0, smem, acc);
	v_cvt_f32_ubyte1_e32 v29, v34
	v_cvt_f32_ubyte0_e32 v28, v34
	v_pk_mul_f32 v[28:29], v[28:29], s[4:5] op_sel_hi:[1,0]
	s_nop 0
	v_pk_mul_f32 v[24:25], v[24:25], v[28:29]
	v_cvt_f32_ubyte3_e32 v29, v34
	v_cvt_f32_ubyte2_e32 v28, v34
	v_pk_mul_f32 v[28:29], v[28:29], s[4:5] op_sel_hi:[1,0]
	v_cvt_pk_bf16_f32 v24, v24, v25
	v_pk_mul_f32 v[26:27], v[26:27], v[28:29]
	s_nop 0
	v_cvt_pk_bf16_f32 v25, v26, v27
	v_lshl_add_u64 v[26:27], v[30:31], 0, v[32:33]
	v_lshl_add_u64 v[26:27], v[26:27], 0, v[66:67]
	flat_store_dwordx2 v[26:27], v[24:25] offset:32
	ds_read_b64 v[24:25], v92 offset:296
	ds_read_b64 v[26:27], v92 offset:336
	s_waitcnt lgkmcnt(0)
	v_lshl_add_u64 v[24:25], v[24:25], 0, v[74:75]
	v_lshl_add_u64 v[24:25], v[24:25], 0, v[64:65]
	flat_load_dword v28, v[24:25] offset:64
	s_waitcnt vmcnt(0) lgkmcnt(0)
	v_cvt_f32_ubyte1_e32 v25, v28
	v_cvt_f32_ubyte0_e32 v24, v28
	v_pk_mul_f32 v[24:25], v[24:25], s[4:5] op_sel_hi:[1,0]
	s_nop 0
	v_pk_mul_f32 v[20:21], v[20:21], v[24:25]
	v_cvt_f32_ubyte3_e32 v25, v28
	v_cvt_f32_ubyte2_e32 v24, v28
	v_pk_mul_f32 v[24:25], v[24:25], s[4:5] op_sel_hi:[1,0]
	v_cvt_pk_bf16_f32 v20, v20, v21
	v_pk_mul_f32 v[22:23], v[22:23], v[24:25]
	s_nop 0
	v_cvt_pk_bf16_f32 v21, v22, v23
	v_lshl_add_u64 v[22:23], v[26:27], 0, v[32:33]
	v_lshl_add_u64 v[22:23], v[22:23], 0, v[66:67]
	flat_store_dwordx2 v[22:23], v[20:21] offset:128
	ds_read_b64 v[20:21], v92 offset:296
	ds_read_b64 v[22:23], v92 offset:336
	s_waitcnt lgkmcnt(0)
	v_lshl_add_u64 v[20:21], v[20:21], 0, v[74:75]
	v_lshl_add_u64 v[20:21], v[20:21], 0, v[64:65]
	flat_load_dword v24, v[20:21] offset:80
	s_waitcnt vmcnt(0) lgkmcnt(0)
	v_cvt_f32_ubyte1_e32 v21, v24
	v_cvt_f32_ubyte0_e32 v20, v24
	v_pk_mul_f32 v[20:21], v[20:21], s[4:5] op_sel_hi:[1,0]
	s_nop 0
	v_pk_mul_f32 v[16:17], v[16:17], v[20:21]
	v_cvt_f32_ubyte3_e32 v21, v24
	v_cvt_f32_ubyte2_e32 v20, v24
	v_pk_mul_f32 v[20:21], v[20:21], s[4:5] op_sel_hi:[1,0]
	v_cvt_pk_bf16_f32 v16, v16, v17
	v_pk_mul_f32 v[18:19], v[18:19], v[20:21]
	v_mov_b32_e32 v24, v188
	v_cvt_pk_bf16_f32 v17, v18, v19
	v_lshl_add_u64 v[18:19], v[22:23], 0, v[32:33]
	v_lshl_add_u64 v[18:19], v[18:19], 0, v[66:67]
	flat_store_dwordx2 v[18:19], v[16:17] offset:160
	ds_read_b64 v[18:19], v92 offset:296
	ds_read_b64 v[20:21], v92 offset:336
	v_or_b32_e32 v16, 48, v56
	v_ashrrev_i32_e32 v17, 31, v16
	v_lshlrev_b64 v[70:71], 11, v[16:17]
	s_waitcnt lgkmcnt(0)
	v_lshl_add_u64 v[18:19], v[18:19], 0, v[70:71]
	v_lshl_add_u64 v[18:19], v[18:19], 0, v[64:65]
	flat_load_dword v22, v[18:19]
	v_lshlrev_b64 v[16:17], 12, v[16:17]
	s_waitcnt vmcnt(0) lgkmcnt(0)
	v_cvt_f32_ubyte1_e32 v19, v22
	v_cvt_f32_ubyte0_e32 v18, v22
	v_pk_mul_f32 v[18:19], v[18:19], s[4:5] op_sel_hi:[1,0]
	s_nop 0
	v_pk_mul_f32 v[12:13], v[12:13], v[18:19]
	v_cvt_f32_ubyte3_e32 v19, v22
	v_cvt_f32_ubyte2_e32 v18, v22
	v_pk_mul_f32 v[18:19], v[18:19], s[4:5] op_sel_hi:[1,0]
	v_cvt_pk_bf16_f32 v12, v12, v13
	v_pk_mul_f32 v[14:15], v[14:15], v[18:19]
	s_nop 0
	v_cvt_pk_bf16_f32 v13, v14, v15
	v_lshl_add_u64 v[14:15], v[20:21], 0, v[16:17]
	v_lshl_add_u64 v[14:15], v[14:15], 0, v[66:67]
	flat_store_dwordx2 v[14:15], v[12:13]
	ds_read_b64 v[12:13], v92 offset:296
	ds_read_b64 v[14:15], v92 offset:336
	s_waitcnt lgkmcnt(0)
	v_lshl_add_u64 v[12:13], v[12:13], 0, v[70:71]
	v_lshl_add_u64 v[12:13], v[12:13], 0, v[64:65]
	flat_load_dword v18, v[12:13] offset:16
	s_waitcnt vmcnt(0) lgkmcnt(0)
	v_cvt_f32_ubyte1_e32 v13, v18
	v_cvt_f32_ubyte0_e32 v12, v18
	v_pk_mul_f32 v[12:13], v[12:13], s[4:5] op_sel_hi:[1,0]
	s_nop 0
	v_pk_mul_f32 v[8:9], v[8:9], v[12:13]
	v_cvt_f32_ubyte3_e32 v13, v18
	v_cvt_f32_ubyte2_e32 v12, v18
	v_pk_mul_f32 v[12:13], v[12:13], s[4:5] op_sel_hi:[1,0]
	v_cvt_pk_bf16_f32 v8, v8, v9
	v_pk_mul_f32 v[10:11], v[10:11], v[12:13]
	s_nop 0
	v_cvt_pk_bf16_f32 v9, v10, v11
	v_lshl_add_u64 v[10:11], v[14:15], 0, v[16:17]
	v_lshl_add_u64 v[10:11], v[10:11], 0, v[66:67]
	flat_store_dwordx2 v[10:11], v[8:9] offset:32
	ds_read_b64 v[8:9], v92 offset:296
	ds_read_b64 v[10:11], v92 offset:336
	s_waitcnt lgkmcnt(0)
	v_lshl_add_u64 v[8:9], v[8:9], 0, v[70:71]
	v_lshl_add_u64 v[8:9], v[8:9], 0, v[64:65]
	flat_load_dword v12, v[8:9] offset:64
	s_waitcnt vmcnt(0) lgkmcnt(0)
	v_cvt_f32_ubyte1_e32 v9, v12
	v_cvt_f32_ubyte0_e32 v8, v12
	v_pk_mul_f32 v[8:9], v[8:9], s[4:5] op_sel_hi:[1,0]
	s_nop 0
	v_pk_mul_f32 v[4:5], v[4:5], v[8:9]
	v_cvt_f32_ubyte3_e32 v9, v12
	v_cvt_f32_ubyte2_e32 v8, v12
	v_pk_mul_f32 v[8:9], v[8:9], s[4:5] op_sel_hi:[1,0]
	v_cvt_pk_bf16_f32 v4, v4, v5
	v_pk_mul_f32 v[6:7], v[6:7], v[8:9]
	s_nop 0
	v_cvt_pk_bf16_f32 v5, v6, v7
	v_lshl_add_u64 v[6:7], v[10:11], 0, v[16:17]
	v_lshl_add_u64 v[6:7], v[6:7], 0, v[66:67]
	flat_store_dwordx2 v[6:7], v[4:5] offset:128
	ds_read_b64 v[4:5], v92 offset:296
	ds_read_b64 v[6:7], v92 offset:336
	s_waitcnt lgkmcnt(0)
	v_lshl_add_u64 v[4:5], v[4:5], 0, v[70:71]
	v_lshl_add_u64 v[4:5], v[4:5], 0, v[64:65]
	flat_load_dword v8, v[4:5] offset:80
	s_waitcnt vmcnt(0) lgkmcnt(0)
	v_cvt_f32_ubyte1_e32 v5, v8
	v_cvt_f32_ubyte0_e32 v4, v8
	v_pk_mul_f32 v[4:5], v[4:5], s[4:5] op_sel_hi:[1,0]
	s_nop 0
	v_pk_mul_f32 v[0:1], v[0:1], v[4:5]
	v_cvt_f32_ubyte3_e32 v5, v8
	v_cvt_f32_ubyte2_e32 v4, v8
	v_pk_mul_f32 v[4:5], v[4:5], s[4:5] op_sel_hi:[1,0]
	v_cvt_pk_bf16_f32 v0, v0, v1
	v_pk_mul_f32 v[2:3], v[2:3], v[4:5]
	s_nop 0
	v_cvt_pk_bf16_f32 v1, v2, v3
	v_lshl_add_u64 v[2:3], v[6:7], 0, v[16:17]
	v_lshl_add_u64 v[2:3], v[2:3], 0, v[66:67]
	flat_store_dwordx2 v[2:3], v[0:1] offset:160
	ds_read_b64 v[0:1], v92 offset:328
	ds_read_b64 v[2:3], v92 offset:176
	s_waitcnt lgkmcnt(0)
; DEV int tid_() { int t = threadIdx.x; asm volatile("" : "+v"(t)); return t; }
; template <class FragT, class AccT>
; DEV void gemm_core_t(const char* __restrict__ A, size_t lda_bytes, const char* __restrict__ Bt, size_t ldb_bytes, int kbytes,
;                      int m0, int n0, int Sshift, int dl, char* smem, AccT (&acc)[4][4]) {
;   const int tid = tid_(), lane = tid & 63, wid = tid >> 6, wm = wid >> 1, wn = wid & 1;
;   const int l15 = lane & 15, q = lane >> 4;
;   const int srow = lane >> 3, schunk = (lane & 7) ^ (lane >> 3);
;   const char* ap[4];
;   const char* bp[4];
; #pragma unroll
;   for (int u = 0; u < 4; ++u) {
;     int r = (wid * 4 + u) * 8 + srow;
;     int ar = rowmap(m0 + r, Sshift, dl);
;     ap[u] = A + (size_t)ar * lda_bytes + schunk * 16;
;     bp[u] = Bt + (size_t)(n0 + r) * ldb_bytes + schunk * 16;
;   }
; #pragma unroll
;   for (int i = 0; i < 4; ++i)
; #pragma unroll
;     for (int j = 0; j < 4; ++j) acc[i][j] = AccT{0, 0, 0, 0};
;   const int nk = kbytes >> 7;
;   __syncthreads();
; #pragma unroll
;   for (int u = 0; u < 4; ++u) {
;     __builtin_amdgcn_global_load_lds((const unsigned*)ap[u], (unsigned*)(smem + (wid * 4 + u) * 1024 + lane * 16), 16, 0, 0);
;     __builtin_amdgcn_global_load_lds((const unsigned*)bp[u], (unsigned*)(smem + 16384 + (wid * 4 + u) * 1024 + lane * 16), 16, 0, 0);
;   }
;   const unsigned sbase = (unsigned)(unsigned long)((__attribute__((address_space(3))) char*)smem);
;   const unsigned sq0 = (unsigned)((q ^ (l15 & 7)) << 4);
;   const unsigned a0 = sbase + (unsigned)((wm * 64 + l15) * 128) + sq0;
;   const unsigned b0 = sbase + 16384u + (unsigned)((wn * 32 + l15) * 128) + sq0;
;   asm volatile("s_waitcnt vmcnt(0)" ::: "memory");
;   __syncthreads();
	v_ashrrev_i32_e32 v26, 6, v24
	v_bfe_u32 v6, v24, 3, 3
	v_lshlrev_b32_e32 v7, 5, v26
	v_or_b32_e32 v22, v7, v6
	v_or_b32_e32 v16, 8, v22
	v_or_b32_e32 v20, 16, v22
	v_or_b32_e32 v27, 24, v22
	v_bitop3_b32 v4, v6, v24, 7 bitop3:0x78
	v_add_u32_e32 v10, s15, v22
	v_add_u32_e32 v12, s0, v22
	v_add_u32_e32 v14, s15, v16
	v_add_u32_e32 v18, s15, v20
	v_add_u32_e32 v22, s15, v27
	v_lshlrev_b32_e32 v180, 4, v4
	v_ashrrev_i32_e32 v11, 31, v10
	v_ashrrev_i32_e32 v15, 31, v14
	v_ashrrev_i32_e32 v19, 31, v18
	v_ashrrev_i32_e32 v23, 31, v22
	v_lshl_add_u64 v[4:5], v[0:1], 0, v[180:181]
	v_lshlrev_b64 v[10:11], 11, v[10:11]
	v_lshlrev_b64 v[14:15], 11, v[14:15]
	v_lshlrev_b64 v[18:19], 11, v[18:19]
	v_lshlrev_b64 v[22:23], 11, v[22:23]
	v_lshl_add_u64 v[10:11], v[4:5], 0, v[10:11]
	v_lshl_add_u64 v[14:15], v[4:5], 0, v[14:15]
	v_add_u32_e32 v16, s0, v16
	v_lshl_add_u64 v[18:19], v[4:5], 0, v[18:19]
	v_add_u32_e32 v20, s0, v20
	v_lshl_add_u64 v[4:5], v[4:5], 0, v[22:23]
	v_add_u32_e32 v22, s0, v27
	v_ashrrev_i32_e32 v13, 31, v12
	v_ashrrev_i32_e32 v17, 31, v16
	v_ashrrev_i32_e32 v21, 31, v20
	v_ashrrev_i32_e32 v23, 31, v22
	v_lshl_add_u64 v[8:9], v[2:3], 0, v[180:181]
	v_lshlrev_b64 v[12:13], 11, v[12:13]
	v_lshlrev_b64 v[16:17], 11, v[16:17]
	v_lshlrev_b64 v[20:21], 11, v[20:21]
	v_lshlrev_b64 v[22:23], 11, v[22:23]
	v_and_b32_e32 v25, 63, v24
	v_lshl_add_u64 v[12:13], v[8:9], 0, v[12:13]
	v_lshl_add_u64 v[16:17], v[8:9], 0, v[16:17]
	v_lshl_add_u64 v[20:21], v[8:9], 0, v[20:21]
	v_lshl_add_u64 v[8:9], v[8:9], 0, v[22:23]
	v_lshlrev_b32_e32 v23, 12, v26
	v_lshl_or_b32 v95, v25, 4, v23
	s_barrier
	v_readfirstlane_b32 s4, v95
	s_mov_b32 m0, s4
	s_nop 0
	global_load_lds_dwordx4 v[10:11], off
	v_add_u32_e32 v10, 0x4000, v95
	v_and_b32_e32 v22, 15, v24
	v_readfirstlane_b32 s4, v10
	v_or_b32_e32 v10, 0x400, v95
	s_mov_b32 m0, s4
	v_readfirstlane_b32 s4, v10
	v_add_u32_e32 v10, 0x4400, v95
	global_load_lds_dwordx4 v[12:13], off
	s_mov_b32 m0, s4
	v_readfirstlane_b32 s4, v10
	v_or_b32_e32 v10, 0x800, v95
	global_load_lds_dwordx4 v[14:15], off
	s_mov_b32 m0, s4
	v_readfirstlane_b32 s4, v10
	v_add_u32_e32 v10, 0x4800, v95
	global_load_lds_dwordx4 v[16:17], off
	s_mov_b32 m0, s4
	v_readfirstlane_b32 s4, v10
	v_or_b32_e32 v10, 0xc00, v95
	global_load_lds_dwordx4 v[18:19], off
	s_mov_b32 m0, s4
	v_readfirstlane_b32 s4, v10
	global_load_lds_dwordx4 v[20:21], off
	s_mov_b32 m0, s4
	s_nop 0
	global_load_lds_dwordx4 v[4:5], off
	v_add_u32_e32 v4, 0x4c00, v95
	v_lshrrev_b32_e32 v5, 1, v24
	v_readfirstlane_b32 s4, v4
	s_mov_b32 m0, s4
	v_lshlrev_b32_e32 v4, 4, v24
	global_load_lds_dwordx4 v[8:9], off
	v_bitop3_b32 v4, v25, s31, v4 bitop3:0x48
	s_mov_b32 s4, 0x1ffffc0
	v_and_or_b32 v8, v7, 32, v22
	v_and_or_b32 v5, v5, s4, v22
	v_lshl_or_b32 v8, v8, 7, v4
	v_lshlrev_b32_e32 v5, 7, v5
	v_or_b32_e32 v97, 0x4000, v8
	v_bitop3_b32 v98, v8, 64, v219 bitop3:0x36
	v_or_b32_e32 v8, 24, v6
	v_or_b32_e32 v96, v4, v5
	v_bitop3_b32 v99, v4, 64, v5 bitop3:0x36
	v_add3_u32 v4, s1, v8, v7
	v_ashrrev_i32_e32 v5, 31, v4
	s_mov_b64 s[4:5], 0x80
	v_lshlrev_b64 v[4:5], 11, v[4:5]
	v_lshl_add_u64 v[2:3], v[2:3], 0, s[4:5]
	v_or_b32_e32 v4, v4, v180
	v_lshl_add_u64 v[76:77], v[2:3], 0, v[4:5]
	v_add3_u32 v4, s18, v8, v7
	v_ashrrev_i32_e32 v5, 31, v4
	v_lshlrev_b64 v[4:5], 11, v[4:5]
	v_lshl_add_u64 v[0:1], v[0:1], 0, s[4:5]
	v_or_b32_e32 v4, v4, v180
	v_or_b32_e32 v8, 16, v6
	v_lshl_add_u64 v[78:79], v[0:1], 0, v[4:5]
	v_add3_u32 v4, s1, v8, v7
	v_ashrrev_i32_e32 v5, 31, v4
	v_lshlrev_b64 v[4:5], 11, v[4:5]
	v_or_b32_e32 v4, v4, v180
	v_lshl_add_u64 v[80:81], v[2:3], 0, v[4:5]
	v_add3_u32 v4, s18, v8, v7
	v_ashrrev_i32_e32 v5, 31, v4
	v_lshlrev_b64 v[4:5], 11, v[4:5]
	v_or_b32_e32 v4, v4, v180
	v_or_b32_e32 v8, 8, v6
	v_lshl_add_u64 v[82:83], v[0:1], 0, v[4:5]
	v_add3_u32 v4, s1, v8, v7
	v_ashrrev_i32_e32 v5, 31, v4
	v_lshlrev_b64 v[4:5], 11, v[4:5]
	v_or_b32_e32 v4, v4, v180
	v_lshl_add_u64 v[84:85], v[2:3], 0, v[4:5]
	v_add3_u32 v4, s18, v8, v7
	v_ashrrev_i32_e32 v5, 31, v4
	v_lshlrev_b64 v[4:5], 11, v[4:5]
	v_or_b32_e32 v4, v4, v180
	v_lshl_add_u64 v[86:87], v[0:1], 0, v[4:5]
	v_add3_u32 v4, s1, v6, v7
	v_ashrrev_i32_e32 v5, 31, v4
	v_lshlrev_b64 v[4:5], 11, v[4:5]
	v_or_b32_e32 v4, v4, v180
	v_lshl_add_u64 v[88:89], v[2:3], 0, v[4:5]
	v_add3_u32 v2, s18, v6, v7
	v_ashrrev_i32_e32 v3, 31, v2
	v_lshlrev_b64 v[2:3], 11, v[2:3]
	s_waitcnt vmcnt(0)
	v_or_b32_e32 v2, v2, v180
	v_lshl_add_u64 v[90:91], v[0:1], 0, v[2:3]
	v_mov_b32_e32 v0, 0
	s_mov_b64 s[4:5], 0
	v_mov_b32_e32 v1, v0
	v_mov_b32_e32 v2, v0
	v_mov_b32_e32 v3, v0
	v_mov_b32_e32 v4, v0
	v_mov_b32_e32 v5, v0
	v_mov_b32_e32 v6, v0
	v_mov_b32_e32 v7, v0
	v_mov_b32_e32 v8, v0
	v_mov_b32_e32 v9, v0
	v_mov_b32_e32 v10, v0
	v_mov_b32_e32 v11, v0
	v_mov_b32_e32 v12, v0
	v_mov_b32_e32 v13, v0
	v_mov_b32_e32 v14, v0
	v_mov_b32_e32 v15, v0
	v_mov_b32_e32 v16, v0
	v_mov_b32_e32 v17, v0
	v_mov_b32_e32 v18, v0
	v_mov_b32_e32 v19, v0
	v_mov_b32_e32 v20, v0
	v_mov_b32_e32 v21, v0
	v_mov_b32_e32 v22, v0
	v_mov_b32_e32 v23, v0
	v_mov_b32_e32 v24, v0
	v_mov_b32_e32 v25, v0
	v_mov_b32_e32 v26, v0
	v_mov_b32_e32 v27, v0
	v_mov_b32_e32 v28, v0
	v_mov_b32_e32 v29, v0
	v_mov_b32_e32 v30, v0
	v_mov_b32_e32 v31, v0
	v_mov_b32_e32 v32, v0
	v_mov_b32_e32 v33, v0
	v_mov_b32_e32 v34, v0
	v_mov_b32_e32 v35, v0
	v_mov_b32_e32 v36, v0
	v_mov_b32_e32 v37, v0
	v_mov_b32_e32 v38, v0
	v_mov_b32_e32 v39, v0
	v_mov_b32_e32 v40, v0
	v_mov_b32_e32 v41, v0
	v_mov_b32_e32 v42, v0
	v_mov_b32_e32 v43, v0
	v_mov_b32_e32 v44, v0
	v_mov_b32_e32 v45, v0
	v_mov_b32_e32 v46, v0
	v_mov_b32_e32 v47, v0
	v_mov_b32_e32 v48, v0
	v_mov_b32_e32 v49, v0
	v_mov_b32_e32 v50, v0
	v_mov_b32_e32 v51, v0
	v_mov_b32_e32 v52, v0
	v_mov_b32_e32 v53, v0
	v_mov_b32_e32 v54, v0
	v_mov_b32_e32 v55, v0
	v_mov_b32_e32 v56, v0
	v_mov_b32_e32 v57, v0
	v_mov_b32_e32 v58, v0
	v_mov_b32_e32 v59, v0
	v_mov_b32_e32 v60, v0
	v_mov_b32_e32 v61, v0
	v_mov_b32_e32 v62, v0
	v_mov_b32_e32 v63, v0
	v_readfirstlane_b32 s64, v90
	v_readfirstlane_b32 s65, v91
	v_readfirstlane_b32 s66, v88
	v_readfirstlane_b32 s67, v89
	v_readfirstlane_b32 s62, v95
	s_sub_u32 s64, s64, 0x80000000
	s_subb_u32 s65, s65, 0
	s_sub_u32 s66, s66, 0x80000000
	s_subb_u32 s67, s67, 0
	v_subrev_u32_e32 v90, s64, v90
	v_subrev_u32_e32 v88, s66, v88
	v_subrev_u32_e32 v86, s64, v86
	v_subrev_u32_e32 v84, s66, v84
	v_subrev_u32_e32 v82, s64, v82
	v_subrev_u32_e32 v80, s66, v80
	v_subrev_u32_e32 v78, s64, v78
	v_subrev_u32_e32 v76, s66, v76
	s_waitcnt vmcnt(0) lgkmcnt(0)
	s_barrier
; DEV f32x4 mma_step(bf16x8 a, bf16x8 b, f32x4 c) { return MFMA(a, b, c); }
; template <class FragT, class AccT>
; DEV void gemm_core_t(const char* __restrict__ A, size_t lda_bytes, const char* __restrict__ Bt, size_t ldb_bytes, int kbytes,
;                      int m0, int n0, int Sshift, int dl, char* smem, AccT (&acc)[4][4]) {
;     ...
;   for (int kt = 0; kt < nk; ++kt) {
;     const unsigned so = (unsigned)(kt & 1) * 32768u;
;     char* nxt = smem + ((kt + 1) & 1) * 32768;
;     if (kt + 1 < nk) {
; #pragma unroll
;       for (int u = 0; u < 4; ++u) {
;         __builtin_amdgcn_global_load_lds((const unsigned*)(ap[u] + (size_t)(kt + 1) * 128), (unsigned*)(nxt + (wid * 4 + u) * 1024 + lane * 16), 16, 0, 0);
;         __builtin_amdgcn_global_load_lds((const unsigned*)(bp[u] + (size_t)(kt + 1) * 128), (unsigned*)(nxt + 16384 + (wid * 4 + u) * 1024 + lane * 16), 16, 0, 0);
;       }
;     }
;     FragT xa[2][4], wb[2][4];
;     asm volatile(
;         "ds_read_b128 %0, %16\n\t"
;         "ds_read_b128 %1, %16 offset:2048\n\t"
;         "ds_read_b128 %2, %16 offset:4096\n\t"
;         "ds_read_b128 %3, %16 offset:6144\n\t"
;         "ds_read_b128 %4, %18\n\t"
;         "ds_read_b128 %5, %18 offset:2048\n\t"
;         "ds_read_b128 %6, %18 offset:8192\n\t"
;         "ds_read_b128 %7, %18 offset:10240\n\t"
;         "ds_read_b128 %8, %17\n\t"
;         "ds_read_b128 %9, %17 offset:2048\n\t"
;         "ds_read_b128 %10, %17 offset:4096\n\t"
;         "ds_read_b128 %11, %17 offset:6144\n\t"
;         "ds_read_b128 %12, %19\n\t"
;         "ds_read_b128 %13, %19 offset:2048\n\t"
;         "ds_read_b128 %14, %19 offset:8192\n\t"
;         "ds_read_b128 %15, %19 offset:10240\n\t"
;         "s_waitcnt lgkmcnt(8)"
;         : "=&v"(xa[0][0]), "=&v"(xa[0][1]), "=&v"(xa[0][2]), "=&v"(xa[0][3]), "=&v"(wb[0][0]), "=&v"(wb[0][1]), "=&v"(wb[0][2]),
;           "=&v"(wb[0][3]), "=&v"(xa[1][0]), "=&v"(xa[1][1]), "=&v"(xa[1][2]), "=&v"(xa[1][3]), "=&v"(wb[1][0]), "=&v"(wb[1][1]),
;           "=&v"(wb[1][2]), "=&v"(wb[1][3])
;         : "v"(a0 + so), "v"((a0 ^ 64u) + so), "v"(b0 + so), "v"((b0 ^ 64u) + so)
;         : "memory");
;     __builtin_amdgcn_s_setprio(1);
; #pragma unroll
;     for (int i = 0; i < 4; ++i)
; #pragma unroll
;       for (int j = 0; j < 4; ++j) acc[i][j] = mma_step(wb[0][j], xa[0][i], acc[i][j]);
;     asm volatile("s_waitcnt lgkmcnt(0)"
.LBB0_402:
	s_add_i32 s1, s16, 0xffff8000
	s_and_b32 s1, s1, 0x8000
	v_add_u32_e32 v164, s1, v96
	v_add_u32_e32 v165, s1, v99
	v_or_b32_e32 v166, s1, v97
	v_or_b32_e32 v167, s1, v98
	s_and_b32 s1, s16, 0x8000
	s_add_i32 s1, s1, s62
	s_mov_b32 m0, s1
	ds_read_b128 v[100:103], v164
	global_load_lds_dwordx4 v90, s[64:65]
	ds_read_b128 v[104:107], v164 offset:2048
	s_add_i32 m0, s1, 0x4000
	ds_read_b128 v[108:111], v164 offset:4096
	global_load_lds_dwordx4 v88, s[66:67]
	ds_read_b128 v[112:115], v164 offset:6144
	s_add_i32 m0, s1, 0x400
	ds_read_b128 v[116:119], v166
	global_load_lds_dwordx4 v86, s[64:65]
	ds_read_b128 v[120:123], v166 offset:2048
	s_add_i32 m0, s1, 0x4400
	ds_read_b128 v[124:127], v166 offset:8192
	global_load_lds_dwordx4 v84, s[66:67]
	ds_read_b128 v[128:131], v166 offset:10240
	s_add_i32 m0, s1, 0x800
	ds_read_b128 v[132:135], v165
	global_load_lds_dwordx4 v82, s[64:65]
	ds_read_b128 v[136:139], v165 offset:2048
	s_add_i32 m0, s1, 0x4800
	ds_read_b128 v[140:143], v165 offset:4096
	global_load_lds_dwordx4 v80, s[66:67]
	ds_read_b128 v[144:147], v165 offset:6144
	s_add_i32 m0, s1, 0xc00
	ds_read_b128 v[148:151], v167
	global_load_lds_dwordx4 v78, s[64:65]
	ds_read_b128 v[152:155], v167 offset:2048
	s_add_i32 m0, s1, 0x4c00
	ds_read_b128 v[156:159], v167 offset:8192
	global_load_lds_dwordx4 v76, s[66:67]
	ds_read_b128 v[160:163], v167 offset:10240
	s_waitcnt lgkmcnt(8)
	s_setprio 1
	v_mfma_f32_16x16x32_bf16 v[60:63], v[116:119], v[100:103], v[60:63]
	v_mfma_f32_16x16x32_bf16 v[56:59], v[120:123], v[100:103], v[56:59]
	v_mfma_f32_16x16x32_bf16 v[52:55], v[124:127], v[100:103], v[52:55]
	v_mfma_f32_16x16x32_bf16 v[48:51], v[128:131], v[100:103], v[48:51]
	v_mfma_f32_16x16x32_bf16 v[44:47], v[116:119], v[104:107], v[44:47]
	v_mfma_f32_16x16x32_bf16 v[40:43], v[120:123], v[104:107], v[40:43]
	v_mfma_f32_16x16x32_bf16 v[36:39], v[124:127], v[104:107], v[36:39]
	v_mfma_f32_16x16x32_bf16 v[32:35], v[128:131], v[104:107], v[32:35]
	v_mfma_f32_16x16x32_bf16 v[28:31], v[116:119], v[108:111], v[28:31]
	v_mfma_f32_16x16x32_bf16 v[24:27], v[120:123], v[108:111], v[24:27]
	v_mfma_f32_16x16x32_bf16 v[20:23], v[124:127], v[108:111], v[20:23]
	v_mfma_f32_16x16x32_bf16 v[16:19], v[128:131], v[108:111], v[16:19]
	v_mfma_f32_16x16x32_bf16 v[12:15], v[116:119], v[112:115], v[12:15]
	v_mfma_f32_16x16x32_bf16 v[8:11], v[120:123], v[112:115], v[8:11]
	v_mfma_f32_16x16x32_bf16 v[4:7], v[124:127], v[112:115], v[4:7]
	v_mfma_f32_16x16x32_bf16 v[0:3], v[128:131], v[112:115], v[0:3]
	s_waitcnt lgkmcnt(0)
	s_nop 0
	v_mfma_f32_16x16x32_bf16 v[60:63], v[148:151], v[132:135], v[60:63]
	v_mfma_f32_16x16x32_bf16 v[56:59], v[152:155], v[132:135], v[56:59]
	v_mfma_f32_16x16x32_bf16 v[52:55], v[156:159], v[132:135], v[52:55]
	v_mfma_f32_16x16x32_bf16 v[48:51], v[160:163], v[132:135], v[48:51]
	v_mfma_f32_16x16x32_bf16 v[44:47], v[148:151], v[136:139], v[44:47]
	v_mfma_f32_16x16x32_bf16 v[40:43], v[152:155], v[136:139], v[40:43]
	v_mfma_f32_16x16x32_bf16 v[36:39], v[156:159], v[136:139], v[36:39]
	v_mfma_f32_16x16x32_bf16 v[32:35], v[160:163], v[136:139], v[32:35]
	v_mfma_f32_16x16x32_bf16 v[28:31], v[148:151], v[140:143], v[28:31]
	v_mfma_f32_16x16x32_bf16 v[24:27], v[152:155], v[140:143], v[24:27]
	v_mfma_f32_16x16x32_bf16 v[20:23], v[156:159], v[140:143], v[20:23]
	v_mfma_f32_16x16x32_bf16 v[16:19], v[160:163], v[140:143], v[16:19]
	v_mfma_f32_16x16x32_bf16 v[12:15], v[148:151], v[144:147], v[12:15]
	v_mfma_f32_16x16x32_bf16 v[8:11], v[152:155], v[144:147], v[8:11]
	v_mfma_f32_16x16x32_bf16 v[4:7], v[156:159], v[144:147], v[4:7]
	v_mfma_f32_16x16x32_bf16 v[0:3], v[160:163], v[144:147], v[0:3]
	s_setprio 0
	s_waitcnt vmcnt(0)
	s_add_u32 s4, s4, 0x80
	s_addc_u32 s5, s5, 0
	s_add_u32 s64, s64, 0x80
	s_addc_u32 s65, s65, 0
	s_add_u32 s66, s66, 0x80
	s_addc_u32 s67, s67, 0
	s_add_i32 s16, s16, 0x8000
	s_cmpk_lg_i32 s4, 0x780
	s_waitcnt vmcnt(0) lgkmcnt(0)
	s_barrier
	s_cbranch_scc1 .LBB0_402
	v_add_u32_e32 v95, 0x8000, v96
	v_add_u32_e32 v144, 0x8000, v99
	v_or_b32_e32 v145, 0x8000, v97
	v_or_b32_e32 v146, 0x8000, v98
	ds_read_b128 v[76:79], v95
	ds_read_b128 v[80:83], v95 offset:2048
	ds_read_b128 v[84:87], v95 offset:4096
	ds_read_b128 v[88:91], v95 offset:6144
	ds_read_b128 v[96:99], v145
	ds_read_b128 v[100:103], v145 offset:2048
	ds_read_b128 v[104:107], v145 offset:8192
	ds_read_b128 v[108:111], v145 offset:10240
	ds_read_b128 v[112:115], v144
	ds_read_b128 v[116:119], v144 offset:2048
	ds_read_b128 v[120:123], v144 offset:4096
	ds_read_b128 v[124:127], v144 offset:6144
	ds_read_b128 v[128:131], v146
	ds_read_b128 v[132:135], v146 offset:2048
	ds_read_b128 v[136:139], v146 offset:8192
	ds_read_b128 v[140:143], v146 offset:10240
	s_waitcnt lgkmcnt(8)
	s_setprio 1
	v_mfma_f32_16x16x32_bf16 v[60:63], v[96:99], v[76:79], v[60:63]
	v_mfma_f32_16x16x32_bf16 v[56:59], v[100:103], v[76:79], v[56:59]
	v_mfma_f32_16x16x32_bf16 v[52:55], v[104:107], v[76:79], v[52:55]
	v_mfma_f32_16x16x32_bf16 v[48:51], v[108:111], v[76:79], v[48:51]
	v_mfma_f32_16x16x32_bf16 v[44:47], v[96:99], v[80:83], v[44:47]
	v_mfma_f32_16x16x32_bf16 v[40:43], v[100:103], v[80:83], v[40:43]
	v_mfma_f32_16x16x32_bf16 v[36:39], v[104:107], v[80:83], v[36:39]
	v_mfma_f32_16x16x32_bf16 v[32:35], v[108:111], v[80:83], v[32:35]
	v_mfma_f32_16x16x32_bf16 v[28:31], v[96:99], v[84:87], v[28:31]
	v_mfma_f32_16x16x32_bf16 v[24:27], v[100:103], v[84:87], v[24:27]
	v_mfma_f32_16x16x32_bf16 v[20:23], v[104:107], v[84:87], v[20:23]
	v_mfma_f32_16x16x32_bf16 v[16:19], v[108:111], v[84:87], v[16:19]
	v_mfma_f32_16x16x32_bf16 v[12:15], v[96:99], v[88:91], v[12:15]
	v_mfma_f32_16x16x32_bf16 v[8:11], v[100:103], v[88:91], v[8:11]
	v_mfma_f32_16x16x32_bf16 v[4:7], v[104:107], v[88:91], v[4:7]
	v_mfma_f32_16x16x32_bf16 v[0:3], v[108:111], v[88:91], v[0:3]
	s_waitcnt lgkmcnt(0)
	s_nop 0
	v_mfma_f32_16x16x32_bf16 v[60:63], v[128:131], v[112:115], v[60:63]
	v_mfma_f32_16x16x32_bf16 v[76:79], v[132:135], v[112:115], v[56:59]
	v_mfma_f32_16x16x32_bf16 v[80:83], v[136:139], v[112:115], v[52:55]
	v_mfma_f32_16x16x32_bf16 v[52:55], v[140:143], v[112:115], v[48:51]
	v_mfma_f32_16x16x32_bf16 v[48:51], v[128:131], v[116:119], v[44:47]
	v_mfma_f32_16x16x32_bf16 v[44:47], v[132:135], v[116:119], v[40:43]
	v_mfma_f32_16x16x32_bf16 v[40:43], v[136:139], v[116:119], v[36:39]
	v_mfma_f32_16x16x32_bf16 v[36:39], v[140:143], v[116:119], v[32:35]
	v_mfma_f32_16x16x32_bf16 v[32:35], v[128:131], v[120:123], v[28:31]
	v_mfma_f32_16x16x32_bf16 v[28:31], v[132:135], v[120:123], v[24:27]
	v_mfma_f32_16x16x32_bf16 v[24:27], v[136:139], v[120:123], v[20:23]
	v_mfma_f32_16x16x32_bf16 v[20:23], v[140:143], v[120:123], v[16:19]
	v_mfma_f32_16x16x32_bf16 v[16:19], v[128:131], v[124:127], v[12:15]
	v_mfma_f32_16x16x32_bf16 v[12:15], v[132:135], v[124:127], v[8:11]
	v_mfma_f32_16x16x32_bf16 v[8:11], v[136:139], v[124:127], v[4:7]
	v_mfma_f32_16x16x32_bf16 v[4:7], v[140:143], v[124:127], v[0:3]
	s_setprio 0
	s_waitcnt vmcnt(0)
	s_barrier
; DEV float bflo(unsigned u) { return __uint_as_float(u << 16); }
; DEV float bfhi(unsigned u) { return __uint_as_float(u & 0xffff0000u); }
; #define P (*launderP(lp))
; __device__ __forceinline__ void phase_gemm2(PREF P, char* smem) {
;     ...
; #pragma unroll
;     for (int i = 0; i < 4; ++i)
; #pragma unroll
;       for (int j = 0; j < 4; ++j) {
;         const int row = m0 + wm * 64 + i * 16 + l15, col = n0 + (j & 1) * 16 + wn * 32 + (j >> 1) * 64 + q * 4;
;         const unsigned g = *(const unsigned*)((const u8*)P.GB + (size_t)row * 2048 + col);
;         uint2 pr = *(const uint2*)(P.merged + (size_t)row * 2048 + col);
;         f32x4 v;
;         v[0] = bflo(pr.x) + (float)(g & 255u) * (1.f / 255.f) * acc[i][j][0];
;         v[1] = bfhi(pr.x) + (float)((g >> 8) & 255u) * (1.f / 255.f) * acc[i][j][1];
;         v[2] = bflo(pr.y) + (float)((g >> 16) & 255u) * (1.f / 255.f) * acc[i][j][2];
;         v[3] = bfhi(pr.y) + (float)(g >> 24) * (1.f / 255.f) * acc[i][j][3];
;         acc[i][j] = v;
;       }
	s_nop 0
	ds_read2_b64 v[0:3], v92 offset0:38 offset1:42
	s_mov_b32 s4, 0x3b808081
	s_mov_b32 s1, 0xfffffc0
	s_waitcnt lgkmcnt(0)
	v_lshl_add_u64 v[56:57], v[0:1], 0, v[68:69]
	v_lshl_add_u64 v[58:59], v[68:69], 1, v[2:3]
	v_lshl_add_u64 v[84:85], v[56:57], 0, v[64:65]
	flat_load_dword v88, v[84:85]
	v_lshl_add_u64 v[86:87], v[58:59], 0, v[66:67]
	flat_load_dwordx2 v[58:59], v[86:87]
	s_waitcnt vmcnt(0) lgkmcnt(0)
	v_cvt_f32_ubyte1_e32 v69, v88
	v_cvt_f32_ubyte0_e32 v68, v88
	v_lshlrev_b32_e32 v56, 16, v58
	v_and_b32_e32 v57, 0xffff0000, v58
	v_pk_mul_f32 v[68:69], v[68:69], s[4:5] op_sel_hi:[1,0]
	v_lshlrev_b32_e32 v58, 16, v59
	v_pk_fma_f32 v[56:57], v[60:61], v[68:69], v[56:57]
	v_cvt_f32_ubyte3_e32 v61, v88
	v_cvt_f32_ubyte2_e32 v60, v88
	v_and_b32_e32 v59, 0xffff0000, v59
	v_pk_mul_f32 v[60:61], v[60:61], s[4:5] op_sel_hi:[1,0]
	s_nop 0
	v_pk_fma_f32 v[58:59], v[62:63], v[60:61], v[58:59]
	flat_load_dword v88, v[84:85] offset:16
	flat_load_dwordx2 v[62:63], v[86:87] offset:32
	s_waitcnt vmcnt(0) lgkmcnt(0)
	v_cvt_f32_ubyte1_e32 v69, v88
	v_cvt_f32_ubyte0_e32 v68, v88
	v_lshlrev_b32_e32 v60, 16, v62
	v_and_b32_e32 v61, 0xffff0000, v62
	v_pk_mul_f32 v[68:69], v[68:69], s[4:5] op_sel_hi:[1,0]
	v_lshlrev_b32_e32 v62, 16, v63
	v_pk_fma_f32 v[60:61], v[76:77], v[68:69], v[60:61]
	v_cvt_f32_ubyte3_e32 v69, v88
	v_cvt_f32_ubyte2_e32 v68, v88
	flat_load_dword v88, v[84:85] offset:64
	flat_load_dwordx2 v[76:77], v[86:87] offset:128
	v_and_b32_e32 v63, 0xffff0000, v63
	v_pk_mul_f32 v[68:69], v[68:69], s[4:5] op_sel_hi:[1,0]
	s_nop 0
	v_pk_fma_f32 v[62:63], v[78:79], v[68:69], v[62:63]
	s_waitcnt vmcnt(0) lgkmcnt(0)
	v_cvt_f32_ubyte1_e32 v79, v88
	v_cvt_f32_ubyte0_e32 v78, v88
	v_lshlrev_b32_e32 v68, 16, v76
	v_and_b32_e32 v69, 0xffff0000, v76
	v_pk_mul_f32 v[78:79], v[78:79], s[4:5] op_sel_hi:[1,0]
	v_lshlrev_b32_e32 v76, 16, v77
	v_pk_fma_f32 v[68:69], v[80:81], v[78:79], v[68:69]
	v_cvt_f32_ubyte3_e32 v79, v88
	v_cvt_f32_ubyte2_e32 v78, v88
	v_and_b32_e32 v77, 0xffff0000, v77
	v_pk_mul_f32 v[78:79], v[78:79], s[4:5] op_sel_hi:[1,0]
	s_nop 0
	v_pk_fma_f32 v[76:77], v[82:83], v[78:79], v[76:77]
	flat_load_dword v84, v[84:85] offset:80
	s_nop 0
	flat_load_dwordx2 v[78:79], v[86:87] offset:160
	s_waitcnt vmcnt(0) lgkmcnt(0)
	v_cvt_f32_ubyte1_e32 v83, v84
	v_cvt_f32_ubyte0_e32 v82, v84
	v_lshlrev_b32_e32 v80, 16, v78
	v_and_b32_e32 v81, 0xffff0000, v78
	v_pk_mul_f32 v[82:83], v[82:83], s[4:5] op_sel_hi:[1,0]
	v_lshlrev_b32_e32 v78, 16, v79
	v_pk_fma_f32 v[52:53], v[52:53], v[82:83], v[80:81]
	v_cvt_f32_ubyte3_e32 v81, v84
	v_cvt_f32_ubyte2_e32 v80, v84
	v_and_b32_e32 v79, 0xffff0000, v79
	v_pk_mul_f32 v[80:81], v[80:81], s[4:5] op_sel_hi:[1,0]
	v_cvt_pk_bf16_f32 v52, v52, v53
	v_pk_fma_f32 v[54:55], v[54:55], v[80:81], v[78:79]
	v_lshl_add_u64 v[78:79], v[0:1], 0, v[72:73]
	v_lshl_add_u64 v[72:73], v[72:73], 1, v[2:3]
	v_lshl_add_u64 v[78:79], v[78:79], 0, v[64:65]
	flat_load_dword v86, v[78:79]
	v_lshl_add_u64 v[72:73], v[72:73], 0, v[66:67]
	flat_load_dwordx2 v[80:81], v[72:73]
	v_cvt_pk_bf16_f32 v53, v54, v55
	s_waitcnt vmcnt(0) lgkmcnt(0)
	v_cvt_f32_ubyte1_e32 v85, v86
	v_cvt_f32_ubyte0_e32 v84, v86
	v_lshlrev_b32_e32 v82, 16, v80
	v_and_b32_e32 v83, 0xffff0000, v80
	v_pk_mul_f32 v[84:85], v[84:85], s[4:5] op_sel_hi:[1,0]
	v_lshlrev_b32_e32 v80, 16, v81
	v_pk_fma_f32 v[48:49], v[48:49], v[84:85], v[82:83]
	v_cvt_f32_ubyte3_e32 v83, v86
	v_cvt_f32_ubyte2_e32 v82, v86
	v_and_b32_e32 v81, 0xffff0000, v81
	v_pk_mul_f32 v[82:83], v[82:83], s[4:5] op_sel_hi:[1,0]
	s_nop 0
	v_pk_fma_f32 v[50:51], v[50:51], v[82:83], v[80:81]
	flat_load_dword v86, v[78:79] offset:16
	flat_load_dwordx2 v[80:81], v[72:73] offset:32
	s_waitcnt vmcnt(0) lgkmcnt(0)
	v_cvt_f32_ubyte1_e32 v85, v86
	v_cvt_f32_ubyte0_e32 v84, v86
	v_lshlrev_b32_e32 v82, 16, v80
	v_and_b32_e32 v83, 0xffff0000, v80
	v_pk_mul_f32 v[84:85], v[84:85], s[4:5] op_sel_hi:[1,0]
	v_lshlrev_b32_e32 v80, 16, v81
	v_pk_fma_f32 v[44:45], v[44:45], v[84:85], v[82:83]
	v_cvt_f32_ubyte3_e32 v83, v86
	v_cvt_f32_ubyte2_e32 v82, v86
	v_and_b32_e32 v81, 0xffff0000, v81
	v_pk_mul_f32 v[82:83], v[82:83], s[4:5] op_sel_hi:[1,0]
	v_cvt_pk_bf16_f32 v44, v44, v45
	v_pk_fma_f32 v[46:47], v[46:47], v[82:83], v[80:81]
	flat_load_dword v86, v[78:79] offset:64
	flat_load_dwordx2 v[80:81], v[72:73] offset:128
	v_cvt_pk_bf16_f32 v45, v46, v47
	s_waitcnt vmcnt(0) lgkmcnt(0)
	v_cvt_f32_ubyte1_e32 v85, v86
	v_cvt_f32_ubyte0_e32 v84, v86
	v_lshlrev_b32_e32 v82, 16, v80
	v_and_b32_e32 v83, 0xffff0000, v80
	v_pk_mul_f32 v[84:85], v[84:85], s[4:5] op_sel_hi:[1,0]
	v_lshlrev_b32_e32 v80, 16, v81
	v_pk_fma_f32 v[40:41], v[40:41], v[84:85], v[82:83]
	v_cvt_f32_ubyte3_e32 v83, v86
	v_cvt_f32_ubyte2_e32 v82, v86
	v_and_b32_e32 v81, 0xffff0000, v81
	v_pk_mul_f32 v[82:83], v[82:83], s[4:5] op_sel_hi:[1,0]
	s_nop 0
	v_pk_fma_f32 v[42:43], v[42:43], v[82:83], v[80:81]
	flat_load_dword v82, v[78:79] offset:80
	s_nop 0
	flat_load_dwordx2 v[72:73], v[72:73] offset:160
	s_waitcnt vmcnt(0) lgkmcnt(0)
	v_cvt_f32_ubyte1_e32 v81, v82
	v_cvt_f32_ubyte0_e32 v80, v82
	v_lshlrev_b32_e32 v78, 16, v72
	v_and_b32_e32 v79, 0xffff0000, v72
	v_pk_mul_f32 v[80:81], v[80:81], s[4:5] op_sel_hi:[1,0]
	v_lshlrev_b32_e32 v72, 16, v73
	v_pk_fma_f32 v[36:37], v[36:37], v[80:81], v[78:79]
	v_cvt_f32_ubyte3_e32 v79, v82
	v_cvt_f32_ubyte2_e32 v78, v82
	v_and_b32_e32 v73, 0xffff0000, v73
	v_pk_mul_f32 v[78:79], v[78:79], s[4:5] op_sel_hi:[1,0]
	v_cvt_pk_bf16_f32 v36, v36, v37
	v_pk_fma_f32 v[38:39], v[38:39], v[78:79], v[72:73]
	v_lshl_add_u64 v[72:73], v[0:1], 0, v[74:75]
	v_lshl_add_u64 v[78:79], v[74:75], 1, v[2:3]
	v_lshl_add_u64 v[74:75], v[72:73], 0, v[64:65]
	flat_load_dword v84, v[74:75]
	v_lshl_add_u64 v[72:73], v[78:79], 0, v[66:67]
	flat_load_dwordx2 v[78:79], v[72:73]
	v_lshl_add_u64 v[0:1], v[0:1], 0, v[70:71]
	v_lshl_add_u64 v[70:71], v[70:71], 1, v[2:3]
	v_cvt_pk_bf16_f32 v37, v38, v39
	s_waitcnt vmcnt(0) lgkmcnt(0)
; DEV int tid_() { int t = threadIdx.x; asm volatile("" : "+v"(t)); return t; }
; DEV float bflo(unsigned u) { return __uint_as_float(u << 16); }
; DEV float bfhi(unsigned u) { return __uint_as_float(u & 0xffff0000u); }
; #define P (*launderP(lp))
; DEV void stage_tile_bf16(char* smem, const f32x4 (&v)[4][4], u16* buf, int ld, int m0, int col0) {
;   const int tid = tid_(), lane = tid & 63, wid = tid >> 6, wm = wid >> 1, wn = wid & 1, l15 = lane & 15, q = lane >> 4;
; #pragma unroll
;   for (int i = 0; i < 4; ++i)
; #pragma unroll
;     for (int j = 0; j < 4; ++j) {
;       const int rl = wm * 64 + i * 16 + l15, cl = (j & 1) * 16 + wn * 32 + (j >> 1) * 64 + q * 4;
;       u32x2 o; o.x = pack2(v[i][j][0], v[i][j][1]); o.y = pack2(v[i][j][2], v[i][j][3]);
;       *(u32x2*)(smem + rl * 272 + cl * 2) = o;
;     }
;   __syncthreads();
; __device__ __forceinline__ void phase_gemm2(PREF P, char* smem) {
;     ...
; #pragma unroll
;     for (int i = 0; i < 4; ++i)
; #pragma unroll
;       for (int j = 0; j < 4; ++j) {
;         const int row = m0 + wm * 64 + i * 16 + l15, col = n0 + (j & 1) * 16 + wn * 32 + (j >> 1) * 64 + q * 4;
;         const unsigned g = *(const unsigned*)((const u8*)P.GB + (size_t)row * 2048 + col);
;         uint2 pr = *(const uint2*)(P.merged + (size_t)row * 2048 + col);
;         f32x4 v;
;         v[0] = bflo(pr.x) + (float)(g & 255u) * (1.f / 255.f) * acc[i][j][0];
;         v[1] = bfhi(pr.x) + (float)((g >> 8) & 255u) * (1.f / 255.f) * acc[i][j][1];
;         v[2] = bflo(pr.y) + (float)((g >> 16) & 255u) * (1.f / 255.f) * acc[i][j][2];
;         v[3] = bfhi(pr.y) + (float)(g >> 24) * (1.f / 255.f) * acc[i][j][3];
;         acc[i][j] = v;
;       }
;     stage_tile_bf16(smem, acc, P.merged, 2048, m0, n0);
	v_cvt_f32_ubyte1_e32 v83, v84
	v_cvt_f32_ubyte0_e32 v82, v84
	v_lshlrev_b32_e32 v80, 16, v78
	v_and_b32_e32 v81, 0xffff0000, v78
	v_pk_mul_f32 v[82:83], v[82:83], s[4:5] op_sel_hi:[1,0]
	v_lshlrev_b32_e32 v78, 16, v79
	v_pk_fma_f32 v[32:33], v[32:33], v[82:83], v[80:81]
	v_cvt_f32_ubyte3_e32 v81, v84
	v_cvt_f32_ubyte2_e32 v80, v84
	v_and_b32_e32 v79, 0xffff0000, v79
	v_pk_mul_f32 v[80:81], v[80:81], s[4:5] op_sel_hi:[1,0]
	s_nop 0
	v_pk_fma_f32 v[34:35], v[34:35], v[80:81], v[78:79]
	flat_load_dword v84, v[74:75] offset:16
	flat_load_dwordx2 v[78:79], v[72:73] offset:32
	s_waitcnt vmcnt(0) lgkmcnt(0)
	v_cvt_f32_ubyte1_e32 v83, v84
	v_cvt_f32_ubyte0_e32 v82, v84
	v_lshlrev_b32_e32 v80, 16, v78
	v_and_b32_e32 v81, 0xffff0000, v78
	v_pk_mul_f32 v[82:83], v[82:83], s[4:5] op_sel_hi:[1,0]
	v_lshlrev_b32_e32 v78, 16, v79
	v_pk_fma_f32 v[28:29], v[28:29], v[82:83], v[80:81]
	v_cvt_f32_ubyte3_e32 v81, v84
	v_cvt_f32_ubyte2_e32 v80, v84
	v_and_b32_e32 v79, 0xffff0000, v79
	v_pk_mul_f32 v[80:81], v[80:81], s[4:5] op_sel_hi:[1,0]
	v_cvt_pk_bf16_f32 v28, v28, v29
	v_pk_fma_f32 v[30:31], v[30:31], v[80:81], v[78:79]
	flat_load_dword v84, v[74:75] offset:64
	flat_load_dwordx2 v[78:79], v[72:73] offset:128
	v_cvt_pk_bf16_f32 v29, v30, v31
	s_waitcnt vmcnt(0) lgkmcnt(0)
	v_cvt_f32_ubyte1_e32 v83, v84
	v_cvt_f32_ubyte0_e32 v82, v84
	v_lshlrev_b32_e32 v80, 16, v78
	v_and_b32_e32 v81, 0xffff0000, v78
	v_pk_mul_f32 v[82:83], v[82:83], s[4:5] op_sel_hi:[1,0]
	v_lshlrev_b32_e32 v78, 16, v79
	v_pk_fma_f32 v[24:25], v[24:25], v[82:83], v[80:81]
	v_cvt_f32_ubyte3_e32 v81, v84
	v_cvt_f32_ubyte2_e32 v80, v84
	v_and_b32_e32 v79, 0xffff0000, v79
	v_pk_mul_f32 v[80:81], v[80:81], s[4:5] op_sel_hi:[1,0]
	s_nop 0
	v_pk_fma_f32 v[26:27], v[26:27], v[80:81], v[78:79]
	flat_load_dword v80, v[74:75] offset:80
	s_nop 0
	flat_load_dwordx2 v[72:73], v[72:73] offset:160
	s_waitcnt vmcnt(0) lgkmcnt(0)
	v_cvt_f32_ubyte1_e32 v79, v80
	v_cvt_f32_ubyte0_e32 v78, v80
	v_lshlrev_b32_e32 v74, 16, v72
	v_and_b32_e32 v75, 0xffff0000, v72
	v_pk_mul_f32 v[78:79], v[78:79], s[4:5] op_sel_hi:[1,0]
	v_lshlrev_b32_e32 v72, 16, v73
	v_pk_fma_f32 v[20:21], v[20:21], v[78:79], v[74:75]
	v_cvt_f32_ubyte3_e32 v75, v80
	v_cvt_f32_ubyte2_e32 v74, v80
	v_and_b32_e32 v73, 0xffff0000, v73
	v_pk_mul_f32 v[74:75], v[74:75], s[4:5] op_sel_hi:[1,0]
	v_cvt_pk_bf16_f32 v20, v20, v21
	v_pk_fma_f32 v[22:23], v[22:23], v[74:75], v[72:73]
	v_lshl_add_u64 v[72:73], v[0:1], 0, v[64:65]
	flat_load_dword v74, v[72:73]
	v_lshl_add_u64 v[64:65], v[70:71], 0, v[66:67]
	flat_load_dwordx2 v[66:67], v[64:65]
	v_cvt_pk_bf16_f32 v21, v22, v23
	s_waitcnt vmcnt(0) lgkmcnt(0)
	v_cvt_f32_ubyte1_e32 v71, v74
	v_cvt_f32_ubyte0_e32 v70, v74
	v_lshlrev_b32_e32 v0, 16, v66
	v_and_b32_e32 v1, 0xffff0000, v66
	v_pk_mul_f32 v[70:71], v[70:71], s[4:5] op_sel_hi:[1,0]
	v_cvt_f32_ubyte2_e32 v66, v74
	v_pk_fma_f32 v[0:1], v[16:17], v[70:71], v[0:1]
	v_lshlrev_b32_e32 v16, 16, v67
	v_and_b32_e32 v17, 0xffff0000, v67
	v_cvt_f32_ubyte3_e32 v67, v74
	v_pk_mul_f32 v[66:67], v[66:67], s[4:5] op_sel_hi:[1,0]
	v_cvt_pk_bf16_f32 v0, v0, v1
	v_pk_fma_f32 v[16:17], v[18:19], v[66:67], v[16:17]
	flat_load_dword v74, v[72:73] offset:16
	flat_load_dwordx2 v[18:19], v[64:65] offset:32
	v_cvt_pk_bf16_f32 v1, v16, v17
	s_waitcnt vmcnt(0) lgkmcnt(0)
	v_cvt_f32_ubyte1_e32 v71, v74
	v_cvt_f32_ubyte0_e32 v70, v74
	v_lshlrev_b32_e32 v66, 16, v18
	v_and_b32_e32 v67, 0xffff0000, v18
	v_pk_mul_f32 v[70:71], v[70:71], s[4:5] op_sel_hi:[1,0]
	v_lshlrev_b32_e32 v18, 16, v19
	v_pk_fma_f32 v[12:13], v[12:13], v[70:71], v[66:67]
	v_cvt_f32_ubyte3_e32 v67, v74
	v_cvt_f32_ubyte2_e32 v66, v74
	v_and_b32_e32 v19, 0xffff0000, v19
	v_pk_mul_f32 v[66:67], v[66:67], s[4:5] op_sel_hi:[1,0]
	v_cvt_pk_bf16_f32 v12, v12, v13
	v_pk_fma_f32 v[14:15], v[14:15], v[66:67], v[18:19]
	flat_load_dword v74, v[72:73] offset:64
	flat_load_dwordx2 v[18:19], v[64:65] offset:128
	v_cvt_pk_bf16_f32 v13, v14, v15
	s_waitcnt vmcnt(0) lgkmcnt(0)
	v_cvt_f32_ubyte1_e32 v71, v74
	v_cvt_f32_ubyte0_e32 v70, v74
	v_lshlrev_b32_e32 v66, 16, v18
	v_and_b32_e32 v67, 0xffff0000, v18
	v_pk_mul_f32 v[70:71], v[70:71], s[4:5] op_sel_hi:[1,0]
	v_lshlrev_b32_e32 v18, 16, v19
	v_pk_fma_f32 v[8:9], v[8:9], v[70:71], v[66:67]
	v_cvt_f32_ubyte3_e32 v67, v74
	v_cvt_f32_ubyte2_e32 v66, v74
	v_and_b32_e32 v19, 0xffff0000, v19
	v_pk_mul_f32 v[66:67], v[66:67], s[4:5] op_sel_hi:[1,0]
	s_nop 0
	v_pk_fma_f32 v[10:11], v[10:11], v[66:67], v[18:19]
	flat_load_dword v70, v[72:73] offset:80
	flat_load_dwordx2 v[18:19], v[64:65] offset:160
	s_waitcnt vmcnt(0) lgkmcnt(0)
	v_cvt_f32_ubyte1_e32 v67, v70
	v_cvt_f32_ubyte0_e32 v66, v70
	v_lshlrev_b32_e32 v64, 16, v18
	v_and_b32_e32 v65, 0xffff0000, v18
	v_pk_mul_f32 v[66:67], v[66:67], s[4:5] op_sel_hi:[1,0]
	v_lshlrev_b32_e32 v18, 16, v19
	v_pk_fma_f32 v[4:5], v[4:5], v[66:67], v[64:65]
	v_cvt_f32_ubyte3_e32 v65, v70
	v_cvt_f32_ubyte2_e32 v64, v70
	v_and_b32_e32 v19, 0xffff0000, v19
	v_pk_mul_f32 v[64:65], v[64:65], s[4:5] op_sel_hi:[1,0]
	v_cvt_pk_bf16_f32 v4, v4, v5
	v_pk_fma_f32 v[6:7], v[6:7], v[64:65], v[18:19]
	v_mov_b32_e32 v64, v188
	v_cvt_pk_bf16_f32 v18, v56, v57
	v_and_b32_e32 v65, 15, v64
	v_lshrrev_b32_e32 v66, 1, v64
	v_and_b32_e32 v56, 64, v64
	v_and_or_b32 v67, v66, s1, v65
	v_and_or_b32 v56, v66, 24, v56
	v_cvt_pk_bf16_f32 v19, v58, v59
	v_mad_u64_u32 v[56:57], s[4:5], v67, s11, v[56:57]
	v_cvt_pk_bf16_f32 v58, v60, v61
	v_cvt_pk_bf16_f32 v59, v62, v63
	ds_write2_b64 v56, v[18:19], v[58:59] offset1:4
	v_cvt_pk_bf16_f32 v18, v68, v69
	v_cvt_pk_bf16_f32 v19, v76, v77
	ds_write2_b64 v56, v[18:19], v[52:53] offset0:16 offset1:20
	v_cvt_pk_bf16_f32 v18, v48, v49
	v_cvt_pk_bf16_f32 v19, v50, v51
	v_add_u32_e32 v46, 0x1000, v56
	v_add_u32_e32 v14, 0x3000, v56
	ds_write2_b64 v46, v[18:19], v[44:45] offset0:32 offset1:36
	v_cvt_pk_bf16_f32 v18, v40, v41
	v_cvt_pk_bf16_f32 v19, v42, v43
	ds_write2_b64 v14, v[0:1], v[12:13] offset0:96 offset1:100
	v_cvt_pk_bf16_f32 v0, v8, v9
	v_cvt_pk_bf16_f32 v1, v10, v11
	v_cvt_pk_bf16_f32 v5, v6, v7
	s_ashr_i32 s1, s0, 31
	ds_write2_b64 v46, v[18:19], v[36:37] offset0:48 offset1:52
	v_cvt_pk_bf16_f32 v18, v32, v33
	v_cvt_pk_bf16_f32 v19, v34, v35
	v_add_u32_e32 v30, 0x2000, v56
	ds_write2_b64 v14, v[0:1], v[4:5] offset0:112 offset1:116
	v_lshlrev_b32_e32 v180, 4, v65
	v_lshl_add_u64 v[0:1], s[0:1], 1, v[2:3]
	v_ashrrev_i32_e32 v6, 4, v64
	ds_write2_b64 v30, v[18:19], v[28:29] offset0:64 offset1:68
	v_cvt_pk_bf16_f32 v18, v24, v25
	v_cvt_pk_bf16_f32 v19, v26, v27
	v_lshl_add_u64 v[4:5], v[0:1], 0, v[180:181]
	v_mad_u64_u32 v[0:1], s[0:1], v6, s11, v[180:181]
	ds_write2_b64 v30, v[18:19], v[20:21] offset0:80 offset1:84
	s_waitcnt lgkmcnt(0)
	s_barrier
; DEV int bid_() { int t = blockIdx.x; asm volatile("" : "+s"(t)); return t; }
; DEV int gdim_() { int t = gridDim.x; asm volatile("" : "+s"(t)); return t; }
; DEV void stage_tile_bf16(char* smem, const f32x4 (&v)[4][4], u16* buf, int ld, int m0, int col0) {
;     ...
; #pragma unroll
;   for (int k = 0; k < 8; ++k) {
;     const int chunk = tid + 256 * k, rl = chunk >> 4, c16 = chunk & 15;
;     u32x4 d = *(const u32x4*)(smem + rl * 272 + c16 * 16);
;     *(u32x4*)(buf + (size_t)(m0 + rl) * ld + col0 + c16 * 8) = d;
;   }
; __device__ __forceinline__ void phase_gemm2(PREF P, char* smem) {
;     ...
;   for (int t = bid_(); t < 64 * 16; t += gdim_()) {
	ds_read_b128 v[0:3], v0
	v_add_u32_e32 v6, s15, v6
	v_ashrrev_i32_e32 v7, 31, v6
	v_lshlrev_b64 v[6:7], 12, v[6:7]
	v_lshl_add_u64 v[6:7], v[4:5], 0, v[6:7]
	s_waitcnt lgkmcnt(0)
	flat_store_dwordx4 v[6:7], v[0:3]
	s_nop 1
	v_add_u32_e32 v0, 0x100, v64
	v_ashrrev_i32_e32 v6, 4, v0
	v_mad_u64_u32 v[0:1], s[0:1], v6, s11, v[180:181]
	ds_read_b128 v[0:3], v0
	v_add_u32_e32 v6, s15, v6
	v_ashrrev_i32_e32 v7, 31, v6
	v_lshlrev_b64 v[6:7], 12, v[6:7]
	v_lshl_add_u64 v[6:7], v[4:5], 0, v[6:7]
	s_waitcnt lgkmcnt(0)
	flat_store_dwordx4 v[6:7], v[0:3]
	s_nop 1
	v_add_u32_e32 v0, 0x200, v64
	v_ashrrev_i32_e32 v6, 4, v0
	v_mad_u64_u32 v[0:1], s[0:1], v6, s11, v[180:181]
	ds_read_b128 v[0:3], v0
	v_add_u32_e32 v6, s15, v6
	v_ashrrev_i32_e32 v7, 31, v6
	v_lshlrev_b64 v[6:7], 12, v[6:7]
	v_lshl_add_u64 v[6:7], v[4:5], 0, v[6:7]
	s_waitcnt lgkmcnt(0)
	flat_store_dwordx4 v[6:7], v[0:3]
	s_nop 1
	v_add_u32_e32 v0, 0x300, v64
	v_ashrrev_i32_e32 v6, 4, v0
	v_mad_u64_u32 v[0:1], s[0:1], v6, s11, v[180:181]
	ds_read_b128 v[0:3], v0
	v_add_u32_e32 v6, s15, v6
	v_ashrrev_i32_e32 v7, 31, v6
	v_lshlrev_b64 v[6:7], 12, v[6:7]
	v_lshl_add_u64 v[6:7], v[4:5], 0, v[6:7]
	s_waitcnt lgkmcnt(0)
	flat_store_dwordx4 v[6:7], v[0:3]
	s_nop 1
	v_add_u32_e32 v0, 0x400, v64
	v_ashrrev_i32_e32 v6, 4, v0
	v_mad_u64_u32 v[0:1], s[0:1], v6, s11, v[180:181]
	ds_read_b128 v[0:3], v0
	v_add_u32_e32 v6, s15, v6
	v_ashrrev_i32_e32 v7, 31, v6
	v_lshlrev_b64 v[6:7], 12, v[6:7]
	v_lshl_add_u64 v[6:7], v[4:5], 0, v[6:7]
	s_waitcnt lgkmcnt(0)
	flat_store_dwordx4 v[6:7], v[0:3]
	s_nop 1
	v_add_u32_e32 v0, 0x500, v64
	v_ashrrev_i32_e32 v6, 4, v0
	v_mad_u64_u32 v[0:1], s[0:1], v6, s11, v[180:181]
	ds_read_b128 v[0:3], v0
	v_add_u32_e32 v6, s15, v6
	v_ashrrev_i32_e32 v7, 31, v6
	v_lshlrev_b64 v[6:7], 12, v[6:7]
	v_lshl_add_u64 v[6:7], v[4:5], 0, v[6:7]
	s_waitcnt lgkmcnt(0)
	flat_store_dwordx4 v[6:7], v[0:3]
	s_nop 1
	v_add_u32_e32 v0, 0x600, v64
	v_ashrrev_i32_e32 v6, 4, v0
	v_mad_u64_u32 v[0:1], s[0:1], v6, s11, v[180:181]
	ds_read_b128 v[0:3], v0
	v_add_u32_e32 v6, s15, v6
	v_ashrrev_i32_e32 v7, 31, v6
	v_lshlrev_b64 v[6:7], 12, v[6:7]
	v_lshl_add_u64 v[6:7], v[4:5], 0, v[6:7]
	s_waitcnt lgkmcnt(0)
	flat_store_dwordx4 v[6:7], v[0:3]
	s_nop 1
	v_add_u32_e32 v0, 0x700, v64
	v_ashrrev_i32_e32 v6, 4, v0
	v_mad_u64_u32 v[0:1], s[0:1], v6, s11, v[180:181]
	ds_read_b128 v[0:3], v0
	v_add_u32_e32 v6, s15, v6
	v_ashrrev_i32_e32 v7, 31, v6
	v_lshlrev_b64 v[6:7], 12, v[6:7]
	v_lshl_add_u64 v[4:5], v[4:5], 0, v[6:7]
	v_readlane_b32 s0, v251, 6
	s_waitcnt lgkmcnt(0)
	flat_store_dwordx4 v[4:5], v[0:3]
	s_add_i32 s14, s0, s14
	s_cmpk_lt_i32 s14, 0x400
	v_readlane_b32 s1, v251, 7
	s_cbranch_scc1 .LBB0_399

; DEV int tid_() { int t = threadIdx.x; asm volatile("" : "+v"(t)); return t; }
; DEV int bid_() { int t = blockIdx.x; asm volatile("" : "+s"(t)); return t; }
; DEV int gdim_() { int t = gridDim.x; asm volatile("" : "+s"(t)); return t; }
; #define P (*launderP(lp))
; template <class FragT, class AccT>
; DEV void gemm_core_t(const char* __restrict__ A, size_t lda_bytes, const char* __restrict__ Bt, size_t ldb_bytes, int kbytes,
;                      int m0, int n0, int Sshift, int dl, char* smem, AccT (&acc)[4][4]) {
;   const int tid = tid_(), lane = tid & 63, wid = tid >> 6, wm = wid >> 1, wn = wid & 1;
;   const int l15 = lane & 15, q = lane >> 4;
;   const int srow = lane >> 3, schunk = (lane & 7) ^ (lane >> 3);
;   const char* ap[4];
;   const char* bp[4];
; #pragma unroll
;   for (int u = 0; u < 4; ++u) {
;     int r = (wid * 4 + u) * 8 + srow;
;     int ar = rowmap(m0 + r, Sshift, dl);
;     ap[u] = A + (size_t)ar * lda_bytes + schunk * 16;
;     bp[u] = Bt + (size_t)(n0 + r) * ldb_bytes + schunk * 16;
;   }
; #pragma unroll
;   for (int i = 0; i < 4; ++i)
; #pragma unroll
;     for (int j = 0; j < 4; ++j) acc[i][j] = AccT{0, 0, 0, 0};
;   const int nk = kbytes >> 7;
;   __syncthreads();
; #pragma unroll
;   for (int u = 0; u < 4; ++u) {
;     __builtin_amdgcn_global_load_lds((const unsigned*)ap[u], (unsigned*)(smem + (wid * 4 + u) * 1024 + lane * 16), 16, 0, 0);
;     __builtin_amdgcn_global_load_lds((const unsigned*)bp[u], (unsigned*)(smem + 16384 + (wid * 4 + u) * 1024 + lane * 16), 16, 0, 0);
;   }
; __device__ __forceinline__ void phase_gemm3(PREF P, int slab, char* smem) {
;     ...
;   for (int t = bid_(); t < 64 * 16; t += gdim_()) {
;     int mt, nt;
;     tile_map(t, 2, mt, nt);
;     const int m0 = mt * 128, n0 = nt * 128;
;     f32x4 acc[4][4];
;     gemm_core(P.merged, 2048, P.WoutT, 2048, 2048, m0, n0, 13, 0, smem, acc);
.LBB0_458:
	s_ashr_i32 s0, s6, 3
	s_lshr_b32 s1, s0, 28
	s_add_i32 s1, s0, s1
	s_and_b32 s4, s1, -16
	v_mov_b32_e32 v22, v188
	s_sub_i32 s0, s0, s4
	s_lshl_b32 s4, s6, 1
	ds_read2_b64 v[0:3], v82 offset0:23 offset1:42
	s_and_b32 s4, s4, 14
	v_ashrrev_i32_e32 v24, 6, v22
	s_ashr_i32 s5, s0, 3
	s_lshl_b32 s1, s1, 6
	s_lshl_b32 s0, s0, 7
	v_bfe_u32 v25, v22, 3, 3
	v_lshlrev_b32_e32 v26, 5, v24
	s_add_i32 s15, s5, s4
	s_and_b32 s1, s1, 0xfffffc00
	s_and_b32 s4, s0, 0x380
	v_or_b32_e32 v20, v26, v25
	s_or_b32 s14, s4, s1
	s_lshl_b32 s0, s15, 7
	v_or_b32_e32 v14, 8, v20
	v_or_b32_e32 v18, 16, v20
	v_or_b32_e32 v27, 24, v20
	v_bitop3_b32 v4, v25, v22, 7 bitop3:0x78
	v_add_u32_e32 v8, s14, v20
	v_add_u32_e32 v10, s0, v20
	v_add_u32_e32 v12, s14, v14
	v_add_u32_e32 v16, s14, v18
	v_add_u32_e32 v20, s14, v27
	v_lshlrev_b32_e32 v180, 4, v4
	v_ashrrev_i32_e32 v9, 31, v8
	v_ashrrev_i32_e32 v13, 31, v12
	v_ashrrev_i32_e32 v17, 31, v16
	v_ashrrev_i32_e32 v21, 31, v20
	s_waitcnt lgkmcnt(0)
	v_lshl_add_u64 v[4:5], v[2:3], 0, v[180:181]
	v_lshlrev_b64 v[8:9], 12, v[8:9]
	v_lshlrev_b64 v[12:13], 12, v[12:13]
	v_lshlrev_b64 v[16:17], 12, v[16:17]
	v_lshlrev_b64 v[20:21], 12, v[20:21]
	v_lshl_add_u64 v[8:9], v[4:5], 0, v[8:9]
	v_lshl_add_u64 v[12:13], v[4:5], 0, v[12:13]
	v_add_u32_e32 v14, s0, v14
	v_lshl_add_u64 v[16:17], v[4:5], 0, v[16:17]
	v_add_u32_e32 v18, s0, v18
	v_lshl_add_u64 v[4:5], v[4:5], 0, v[20:21]
	v_add_u32_e32 v20, s0, v27
	v_ashrrev_i32_e32 v11, 31, v10
	v_ashrrev_i32_e32 v15, 31, v14
	v_ashrrev_i32_e32 v19, 31, v18
	v_ashrrev_i32_e32 v21, 31, v20
	v_lshl_add_u64 v[6:7], v[0:1], 0, v[180:181]
	v_lshlrev_b64 v[10:11], 12, v[10:11]
	v_lshlrev_b64 v[14:15], 12, v[14:15]
	v_lshlrev_b64 v[18:19], 12, v[18:19]
	v_lshlrev_b64 v[20:21], 12, v[20:21]
	v_and_b32_e32 v23, 63, v22
	v_lshl_add_u64 v[10:11], v[6:7], 0, v[10:11]
	v_lshl_add_u64 v[14:15], v[6:7], 0, v[14:15]
	v_lshl_add_u64 v[18:19], v[6:7], 0, v[18:19]
	v_lshl_add_u64 v[6:7], v[6:7], 0, v[20:21]
	v_lshlrev_b32_e32 v21, 12, v24
	v_lshl_or_b32 v85, v23, 4, v21
	s_nop 0
	v_readfirstlane_b32 s15, v85
	s_mov_b32 m0, s15
	s_barrier
	global_load_lds_dwordx4 v[8:9], off
	v_add_u32_e32 v8, 0x4000, v85
	v_and_b32_e32 v20, 15, v22
	v_readfirstlane_b32 s15, v8
	v_or_b32_e32 v8, 0x400, v85
	s_mov_b32 m0, s15
	v_readfirstlane_b32 s15, v8
	v_add_u32_e32 v8, 0x4400, v85
	global_load_lds_dwordx4 v[10:11], off
	s_mov_b32 m0, s15
	v_readfirstlane_b32 s15, v8
	v_or_b32_e32 v8, 0x800, v85
	global_load_lds_dwordx4 v[12:13], off
	s_mov_b32 m0, s15
	v_readfirstlane_b32 s15, v8
	v_add_u32_e32 v8, 0x4800, v85
	global_load_lds_dwordx4 v[14:15], off
	s_mov_b32 m0, s15
	v_readfirstlane_b32 s15, v8
	v_or_b32_e32 v8, 0xc00, v85
	global_load_lds_dwordx4 v[16:17], off
	s_mov_b32 m0, s15
	v_readfirstlane_b32 s15, v8
	global_load_lds_dwordx4 v[18:19], off
	s_mov_b32 m0, s15
	s_lshl_b32 s5, s5, 7
	global_load_lds_dwordx4 v[4:5], off
	v_add_u32_e32 v4, 0x4c00, v85
	v_lshrrev_b32_e32 v5, 1, v22
	v_readfirstlane_b32 s15, v4
	s_mov_b32 m0, s15
	v_lshlrev_b32_e32 v4, 4, v22
	global_load_lds_dwordx4 v[6:7], off
	s_mov_b32 s15, 0x1ffffc0
	v_bitop3_b32 v4, v23, s31, v4 bitop3:0x48
	v_and_or_b32 v5, v5, s15, v20
	v_and_or_b32 v6, v26, 32, v20
	s_and_b32 s15, s6, 7
	v_lshl_or_b32 v6, v6, 7, v4
	s_lshl_b32 s15, s15, 8
	v_lshlrev_b32_e32 v5, 7, v5
	v_or_b32_e32 v87, 0x4000, v6
	v_bitop3_b32 v88, v6, 64, v219 bitop3:0x36
	v_or_b32_e32 v6, 24, v25
	s_add_i32 s5, s5, s15
	v_or_b32_e32 v86, v4, v5
	v_bitop3_b32 v89, v4, 64, v5 bitop3:0x36
	v_or_b32_e32 v4, s5, v6
	v_add_u32_e32 v4, v4, v26
	v_ashrrev_i32_e32 v5, 31, v4
	s_mov_b64 s[16:17], 0x80
	v_lshlrev_b64 v[4:5], 12, v[4:5]
	v_lshl_add_u64 v[0:1], v[0:1], 0, s[16:17]
	v_or_b32_e32 v4, v4, v180
	v_lshl_add_u64 v[66:67], v[0:1], 0, v[4:5]
	v_or_b32_e32 v4, s1, v6
	v_or_b32_e32 v4, s4, v4
	v_add_u32_e32 v4, v4, v26
	v_ashrrev_i32_e32 v5, 31, v4
	v_lshlrev_b64 v[4:5], 12, v[4:5]
	v_lshl_add_u64 v[2:3], v[2:3], 0, s[16:17]
	v_or_b32_e32 v4, v4, v180
	v_or_b32_e32 v6, 16, v25
	v_lshl_add_u64 v[68:69], v[2:3], 0, v[4:5]
	v_or_b32_e32 v4, s5, v6
	v_add_u32_e32 v4, v4, v26
	v_ashrrev_i32_e32 v5, 31, v4
	v_lshlrev_b64 v[4:5], 12, v[4:5]
	v_or_b32_e32 v4, v4, v180
	v_lshl_add_u64 v[70:71], v[0:1], 0, v[4:5]
	v_or_b32_e32 v4, s1, v6
	v_or_b32_e32 v4, s4, v4
	v_add_u32_e32 v4, v4, v26
	v_ashrrev_i32_e32 v5, 31, v4
	v_lshlrev_b64 v[4:5], 12, v[4:5]
	v_or_b32_e32 v4, v4, v180
	v_or_b32_e32 v6, 8, v25
	v_lshl_add_u64 v[72:73], v[2:3], 0, v[4:5]
	v_or_b32_e32 v4, s5, v6
	v_add_u32_e32 v4, v4, v26
	v_ashrrev_i32_e32 v5, 31, v4
	v_lshlrev_b64 v[4:5], 12, v[4:5]
	v_or_b32_e32 v4, v4, v180
	v_lshl_add_u64 v[74:75], v[0:1], 0, v[4:5]
	v_or_b32_e32 v4, s1, v6
	v_or_b32_e32 v4, s4, v4
	v_add_u32_e32 v4, v4, v26
	v_ashrrev_i32_e32 v5, 31, v4
	v_lshlrev_b64 v[4:5], 12, v[4:5]
	v_or_b32_e32 v4, v4, v180
	v_lshl_add_u64 v[76:77], v[2:3], 0, v[4:5]
	v_or_b32_e32 v4, s5, v25
	v_add_u32_e32 v4, v4, v26
	v_ashrrev_i32_e32 v5, 31, v4
	v_lshlrev_b64 v[4:5], 12, v[4:5]
	v_or_b32_e32 v4, v4, v180
	v_lshl_add_u64 v[78:79], v[0:1], 0, v[4:5]
	v_or_b32_e32 v0, s1, v25
	v_or_b32_e32 v0, s4, v0
	v_add_u32_e32 v0, v0, v26
	v_ashrrev_i32_e32 v1, 31, v0
	v_lshlrev_b64 v[0:1], 12, v[0:1]
	s_waitcnt vmcnt(0)
; DEV f32x4 mma_step(bf16x8 a, bf16x8 b, f32x4 c) { return MFMA(a, b, c); }
; template <class FragT, class AccT>
; DEV void gemm_core_t(const char* __restrict__ A, size_t lda_bytes, const char* __restrict__ Bt, size_t ldb_bytes, int kbytes,
;                      int m0, int n0, int Sshift, int dl, char* smem, AccT (&acc)[4][4]) {
;     ...
;   for (int kt = 0; kt < nk; ++kt) {
;     const unsigned so = (unsigned)(kt & 1) * 32768u;
;     char* nxt = smem + ((kt + 1) & 1) * 32768;
;     if (kt + 1 < nk) {
; #pragma unroll
;       for (int u = 0; u < 4; ++u) {
;         __builtin_amdgcn_global_load_lds((const unsigned*)(ap[u] + (size_t)(kt + 1) * 128), (unsigned*)(nxt + (wid * 4 + u) * 1024 + lane * 16), 16, 0, 0);
;         __builtin_amdgcn_global_load_lds((const unsigned*)(bp[u] + (size_t)(kt + 1) * 128), (unsigned*)(nxt + 16384 + (wid * 4 + u) * 1024 + lane * 16), 16, 0, 0);
;       }
;     }
;     FragT xa[2][4], wb[2][4];
;     asm volatile(
;         "ds_read_b128 %0, %16\n\t"
;         "ds_read_b128 %1, %16 offset:2048\n\t"
;         "ds_read_b128 %2, %16 offset:4096\n\t"
;         "ds_read_b128 %3, %16 offset:6144\n\t"
;         "ds_read_b128 %4, %18\n\t"
;         "ds_read_b128 %5, %18 offset:2048\n\t"
;         "ds_read_b128 %6, %18 offset:8192\n\t"
;         "ds_read_b128 %7, %18 offset:10240\n\t"
;         "ds_read_b128 %8, %17\n\t"
;         "ds_read_b128 %9, %17 offset:2048\n\t"
;         "ds_read_b128 %10, %17 offset:4096\n\t"
;         "ds_read_b128 %11, %17 offset:6144\n\t"
;         "ds_read_b128 %12, %19\n\t"
;         "ds_read_b128 %13, %19 offset:2048\n\t"
;         "ds_read_b128 %14, %19 offset:8192\n\t"
;         "ds_read_b128 %15, %19 offset:10240\n\t"
;         "s_waitcnt lgkmcnt(8)"
;         : "=&v"(xa[0][0]), "=&v"(xa[0][1]), "=&v"(xa[0][2]), "=&v"(xa[0][3]), "=&v"(wb[0][0]), "=&v"(wb[0][1]), "=&v"(wb[0][2]),
;           "=&v"(wb[0][3]), "=&v"(xa[1][0]), "=&v"(xa[1][1]), "=&v"(xa[1][2]), "=&v"(xa[1][3]), "=&v"(wb[1][0]), "=&v"(wb[1][1]),
;           "=&v"(wb[1][2]), "=&v"(wb[1][3])
;         : "v"(a0 + so), "v"((a0 ^ 64u) + so), "v"(b0 + so), "v"((b0 ^ 64u) + so)
;         : "memory");
;     __builtin_amdgcn_s_setprio(1);
; #pragma unroll
;     for (int i = 0; i < 4; ++i)
; #pragma unroll
;       for (int j = 0; j < 4; ++j) acc[i][j] = mma_step(wb[0][j], xa[0][i], acc[i][j]);
;     asm volatile("s_waitcnt lgkmcnt(0)"
	v_or_b32_e32 v0, v0, v180
	v_lshl_add_u64 v[80:81], v[2:3], 0, v[0:1]
	v_mov_b32_e32 v0, 0
	s_mov_b64 s[4:5], 0
	s_mov_b32 s1, 0x8000
	v_mov_b32_e32 v1, v0
	v_mov_b32_e32 v2, v0
	v_mov_b32_e32 v3, v0
	v_mov_b32_e32 v4, v0
	v_mov_b32_e32 v5, v0
	v_mov_b32_e32 v6, v0
	v_mov_b32_e32 v7, v0
	v_mov_b32_e32 v8, v0
	v_mov_b32_e32 v9, v0
	v_mov_b32_e32 v10, v0
	v_mov_b32_e32 v11, v0
	v_mov_b32_e32 v12, v0
	v_mov_b32_e32 v13, v0
	v_mov_b32_e32 v14, v0
	v_mov_b32_e32 v15, v0
	v_mov_b32_e32 v16, v0
	v_mov_b32_e32 v17, v0
	v_mov_b32_e32 v18, v0
	v_mov_b32_e32 v19, v0
	v_mov_b32_e32 v20, v0
	v_mov_b32_e32 v21, v0
	v_mov_b32_e32 v22, v0
	v_mov_b32_e32 v23, v0
	v_mov_b32_e32 v24, v0
	v_mov_b32_e32 v25, v0
	v_mov_b32_e32 v26, v0
	v_mov_b32_e32 v27, v0
	v_mov_b32_e32 v28, v0
	v_mov_b32_e32 v29, v0
	v_mov_b32_e32 v30, v0
	v_mov_b32_e32 v31, v0
	v_mov_b32_e32 v32, v0
	v_mov_b32_e32 v33, v0
	v_mov_b32_e32 v34, v0
	v_mov_b32_e32 v35, v0
	v_mov_b32_e32 v36, v0
	v_mov_b32_e32 v37, v0
	v_mov_b32_e32 v38, v0
	v_mov_b32_e32 v39, v0
	v_mov_b32_e32 v40, v0
	v_mov_b32_e32 v41, v0
	v_mov_b32_e32 v42, v0
	v_mov_b32_e32 v43, v0
	v_mov_b32_e32 v44, v0
	v_mov_b32_e32 v45, v0
	v_mov_b32_e32 v46, v0
	v_mov_b32_e32 v47, v0
	v_mov_b32_e32 v48, v0
	v_mov_b32_e32 v49, v0
	v_mov_b32_e32 v50, v0
	v_mov_b32_e32 v51, v0
	v_mov_b32_e32 v52, v0
	v_mov_b32_e32 v53, v0
	v_mov_b32_e32 v54, v0
	v_mov_b32_e32 v55, v0
	v_mov_b32_e32 v56, v0
	v_mov_b32_e32 v57, v0
	v_mov_b32_e32 v58, v0
	v_mov_b32_e32 v59, v0
	v_mov_b32_e32 v60, v0
	v_mov_b32_e32 v61, v0
	v_mov_b32_e32 v62, v0
	v_mov_b32_e32 v63, v0
	v_readfirstlane_b32 s64, v80
	v_readfirstlane_b32 s65, v81
	v_readfirstlane_b32 s66, v78
	v_readfirstlane_b32 s67, v79
	v_readfirstlane_b32 s62, v85
	s_sub_u32 s64, s64, 0x80000000
	s_subb_u32 s65, s65, 0
	s_sub_u32 s66, s66, 0x80000000
	s_subb_u32 s67, s67, 0
	v_subrev_u32_e32 v80, s64, v80
	v_subrev_u32_e32 v78, s66, v78
	v_subrev_u32_e32 v76, s64, v76
	v_subrev_u32_e32 v74, s66, v74
	v_subrev_u32_e32 v72, s64, v72
	v_subrev_u32_e32 v70, s66, v70
	v_subrev_u32_e32 v68, s64, v68
	v_subrev_u32_e32 v66, s66, v66
	s_waitcnt vmcnt(0) lgkmcnt(0)
	s_barrier
.LBB0_459:
	s_add_i32 s15, s1, 0xffff8000
	s_and_b32 s15, s15, 0x8000
	v_add_u32_e32 v154, s15, v86
	v_add_u32_e32 v155, s15, v89
	v_or_b32_e32 v156, s15, v87
	v_or_b32_e32 v157, s15, v88
	s_and_b32 s15, s1, 0x8000
	s_add_i32 s15, s15, s62
	s_mov_b32 m0, s15
	ds_read_b128 v[90:93], v154
	global_load_lds_dwordx4 v80, s[64:65]
	ds_read_b128 v[94:97], v154 offset:2048
	s_add_i32 m0, s15, 0x4000
	ds_read_b128 v[98:101], v154 offset:4096
	global_load_lds_dwordx4 v78, s[66:67]
	ds_read_b128 v[102:105], v154 offset:6144
	s_add_i32 m0, s15, 0x400
	ds_read_b128 v[106:109], v156
	global_load_lds_dwordx4 v76, s[64:65]
	ds_read_b128 v[110:113], v156 offset:2048
	s_add_i32 m0, s15, 0x4400
	ds_read_b128 v[114:117], v156 offset:8192
	global_load_lds_dwordx4 v74, s[66:67]
	ds_read_b128 v[118:121], v156 offset:10240
	s_add_i32 m0, s15, 0x800
	ds_read_b128 v[122:125], v155
	global_load_lds_dwordx4 v72, s[64:65]
	ds_read_b128 v[126:129], v155 offset:2048
	s_add_i32 m0, s15, 0x4800
	ds_read_b128 v[130:133], v155 offset:4096
	global_load_lds_dwordx4 v70, s[66:67]
	ds_read_b128 v[134:137], v155 offset:6144
	s_add_i32 m0, s15, 0xc00
	ds_read_b128 v[138:141], v157
	global_load_lds_dwordx4 v68, s[64:65]
	ds_read_b128 v[142:145], v157 offset:2048
	s_add_i32 m0, s15, 0x4c00
	ds_read_b128 v[146:149], v157 offset:8192
	global_load_lds_dwordx4 v66, s[66:67]
	ds_read_b128 v[150:153], v157 offset:10240
	s_waitcnt lgkmcnt(8)
	s_setprio 1
	v_mfma_f32_16x16x32_bf16 v[60:63], v[106:109], v[90:93], v[60:63]
	v_mfma_f32_16x16x32_bf16 v[56:59], v[110:113], v[90:93], v[56:59]
	v_mfma_f32_16x16x32_bf16 v[52:55], v[114:117], v[90:93], v[52:55]
	v_mfma_f32_16x16x32_bf16 v[48:51], v[118:121], v[90:93], v[48:51]
	v_mfma_f32_16x16x32_bf16 v[44:47], v[106:109], v[94:97], v[44:47]
	v_mfma_f32_16x16x32_bf16 v[40:43], v[110:113], v[94:97], v[40:43]
	v_mfma_f32_16x16x32_bf16 v[36:39], v[114:117], v[94:97], v[36:39]
	v_mfma_f32_16x16x32_bf16 v[32:35], v[118:121], v[94:97], v[32:35]
	v_mfma_f32_16x16x32_bf16 v[28:31], v[106:109], v[98:101], v[28:31]
	v_mfma_f32_16x16x32_bf16 v[24:27], v[110:113], v[98:101], v[24:27]
	v_mfma_f32_16x16x32_bf16 v[20:23], v[114:117], v[98:101], v[20:23]
	v_mfma_f32_16x16x32_bf16 v[16:19], v[118:121], v[98:101], v[16:19]
	v_mfma_f32_16x16x32_bf16 v[12:15], v[106:109], v[102:105], v[12:15]
	v_mfma_f32_16x16x32_bf16 v[8:11], v[110:113], v[102:105], v[8:11]
	v_mfma_f32_16x16x32_bf16 v[4:7], v[114:117], v[102:105], v[4:7]
	v_mfma_f32_16x16x32_bf16 v[0:3], v[118:121], v[102:105], v[0:3]
	s_waitcnt lgkmcnt(0)
	s_nop 0
	v_mfma_f32_16x16x32_bf16 v[60:63], v[138:141], v[122:125], v[60:63]
	v_mfma_f32_16x16x32_bf16 v[56:59], v[142:145], v[122:125], v[56:59]
	v_mfma_f32_16x16x32_bf16 v[52:55], v[146:149], v[122:125], v[52:55]
	v_mfma_f32_16x16x32_bf16 v[48:51], v[150:153], v[122:125], v[48:51]
	v_mfma_f32_16x16x32_bf16 v[44:47], v[138:141], v[126:129], v[44:47]
	v_mfma_f32_16x16x32_bf16 v[40:43], v[142:145], v[126:129], v[40:43]
	v_mfma_f32_16x16x32_bf16 v[36:39], v[146:149], v[126:129], v[36:39]
	v_mfma_f32_16x16x32_bf16 v[32:35], v[150:153], v[126:129], v[32:35]
	v_mfma_f32_16x16x32_bf16 v[28:31], v[138:141], v[130:133], v[28:31]
	v_mfma_f32_16x16x32_bf16 v[24:27], v[142:145], v[130:133], v[24:27]
	v_mfma_f32_16x16x32_bf16 v[20:23], v[146:149], v[130:133], v[20:23]
	v_mfma_f32_16x16x32_bf16 v[16:19], v[150:153], v[130:133], v[16:19]
	v_mfma_f32_16x16x32_bf16 v[12:15], v[138:141], v[134:137], v[12:15]
	v_mfma_f32_16x16x32_bf16 v[8:11], v[142:145], v[134:137], v[8:11]
	v_mfma_f32_16x16x32_bf16 v[4:7], v[146:149], v[134:137], v[4:7]
	v_mfma_f32_16x16x32_bf16 v[0:3], v[150:153], v[134:137], v[0:3]
	s_setprio 0
	s_waitcnt vmcnt(0)
	s_add_u32 s4, s4, 0x80
	s_addc_u32 s5, s5, 0
	s_add_u32 s64, s64, 0x80
	s_addc_u32 s65, s65, 0
	s_add_u32 s66, s66, 0x80
	s_addc_u32 s67, s67, 0
	s_add_i32 s1, s1, 0x8000
	s_cmpk_lg_i32 s4, 0xf80
	s_waitcnt vmcnt(0) lgkmcnt(0)
	s_barrier
; DEV f32x4 mma_step(bf16x8 a, bf16x8 b, f32x4 c) { return MFMA(a, b, c); }
; DEV i32x4 mma_step(i32x4 a, i32x4 b, i32x4 c) { return __builtin_amdgcn_mfma_i32_16x16x64_i8(a, b, c, 0, 0, 0); }
; template <class FragT, class AccT>
; DEV void gemm_core_t(const char* __restrict__ A, size_t lda_bytes, const char* __restrict__ Bt, size_t ldb_bytes, int kbytes,
;                      int m0, int n0, int Sshift, int dl, char* smem, AccT (&acc)[4][4]) {
;     ...
; #pragma unroll
;     for (int i = 0; i < 4; ++i)
; #pragma unroll
;       for (int j = 0; j < 4; ++j) acc[i][j] = mma_step(wb[0][j], xa[0][i], acc[i][j]);
;     asm volatile("s_waitcnt lgkmcnt(0)"
;                  : "+v"(xa[1][0]), "+v"(xa[1][1]), "+v"(xa[1][2]), "+v"(xa[1][3]), "+v"(wb[1][0]), "+v"(wb[1][1]), "+v"(wb[1][2]),
;                    "+v"(wb[1][3]), "+v"(acc[0][0]), "+v"(acc[0][1]), "+v"(acc[0][2]), "+v"(acc[0][3]), "+v"(acc[1][0]),
;                    "+v"(acc[1][1]), "+v"(acc[1][2]), "+v"(acc[1][3]), "+v"(acc[2][0]), "+v"(acc[2][1]), "+v"(acc[2][2]),
;                    "+v"(acc[2][3]), "+v"(acc[3][0]), "+v"(acc[3][1]), "+v"(acc[3][2]), "+v"(acc[3][3])
;                  :
;                  : "memory");
; #pragma unroll
;     for (int i = 0; i < 4; ++i)
; #pragma unroll
;       for (int j = 0; j < 4; ++j) acc[i][j] = mma_step(wb[1][j], xa[1][i], acc[i][j]);
;     __builtin_amdgcn_s_setprio(0);
; __device__ __forceinline__ void phase_gemm3(PREF P, int slab, char* smem) {
;     ...
; #pragma unroll
;     for (int i = 0; i < 4; ++i)
; #pragma unroll
;       for (int j = 0; j < 4; ++j) {
;         const int row = m0 + wm * 64 + i * 16 + l15, col = n0 + (j & 1) * 16 + wn * 32 + (j >> 1) * 64 + q * 4;
;         float4 xv = *(const float4*)(xs + (size_t)row * 2048 + col);
;         f32x4 o;
;         o[0] = DN_ALPHA * xv.x + acc[i][j][0]; o[1] = DN_ALPHA * xv.y + acc[i][j][1];
;         o[2] = DN_ALPHA * xv.z + acc[i][j][2]; o[3] = DN_ALPHA * xv.w + acc[i][j][3];
;         acc[i][j] = o;
;       }
	s_cbranch_scc1 .LBB0_459
	v_add_u32_e32 v85, 0x8000, v86
	v_add_u32_e32 v134, 0x8000, v89
	v_or_b32_e32 v135, 0x8000, v87
	v_or_b32_e32 v136, 0x8000, v88
	ds_read_b128 v[66:69], v85
	ds_read_b128 v[70:73], v85 offset:2048
	ds_read_b128 v[74:77], v85 offset:4096
	ds_read_b128 v[78:81], v85 offset:6144
	ds_read_b128 v[86:89], v135
	ds_read_b128 v[90:93], v135 offset:2048
	ds_read_b128 v[94:97], v135 offset:8192
	ds_read_b128 v[98:101], v135 offset:10240
	ds_read_b128 v[102:105], v134
	ds_read_b128 v[106:109], v134 offset:2048
	ds_read_b128 v[110:113], v134 offset:4096
	ds_read_b128 v[114:117], v134 offset:6144
	ds_read_b128 v[118:121], v136
	ds_read_b128 v[122:125], v136 offset:2048
	ds_read_b128 v[126:129], v136 offset:8192
	ds_read_b128 v[130:133], v136 offset:10240
	s_waitcnt lgkmcnt(8)
	s_setprio 1
	v_mfma_f32_16x16x32_bf16 v[60:63], v[86:89], v[66:69], v[60:63]
	v_mfma_f32_16x16x32_bf16 v[56:59], v[90:93], v[66:69], v[56:59]
	v_mfma_f32_16x16x32_bf16 v[52:55], v[94:97], v[66:69], v[52:55]
	v_mfma_f32_16x16x32_bf16 v[48:51], v[98:101], v[66:69], v[48:51]
	v_mfma_f32_16x16x32_bf16 v[44:47], v[86:89], v[70:73], v[44:47]
	v_mfma_f32_16x16x32_bf16 v[40:43], v[90:93], v[70:73], v[40:43]
	v_mfma_f32_16x16x32_bf16 v[36:39], v[94:97], v[70:73], v[36:39]
	v_mfma_f32_16x16x32_bf16 v[32:35], v[98:101], v[70:73], v[32:35]
	v_mfma_f32_16x16x32_bf16 v[28:31], v[86:89], v[74:77], v[28:31]
	v_mfma_f32_16x16x32_bf16 v[24:27], v[90:93], v[74:77], v[24:27]
	v_mfma_f32_16x16x32_bf16 v[20:23], v[94:97], v[74:77], v[20:23]
	v_mfma_f32_16x16x32_bf16 v[16:19], v[98:101], v[74:77], v[16:19]
	v_mfma_f32_16x16x32_bf16 v[12:15], v[86:89], v[78:81], v[12:15]
	v_mfma_f32_16x16x32_bf16 v[8:11], v[90:93], v[78:81], v[8:11]
	v_mfma_f32_16x16x32_bf16 v[4:7], v[94:97], v[78:81], v[4:7]
	v_mfma_f32_16x16x32_bf16 v[0:3], v[98:101], v[78:81], v[0:3]
	s_waitcnt lgkmcnt(0)
	s_nop 0
	v_mfma_f32_16x16x32_bf16 v[60:63], v[118:121], v[102:105], v[60:63]
	v_mfma_f32_16x16x32_bf16 v[56:59], v[122:125], v[102:105], v[56:59]
	v_mfma_f32_16x16x32_bf16 v[52:55], v[126:129], v[102:105], v[52:55]
	v_mfma_f32_16x16x32_bf16 v[48:51], v[130:133], v[102:105], v[48:51]
	v_mfma_f32_16x16x32_bf16 v[44:47], v[118:121], v[106:109], v[44:47]
	v_mfma_f32_16x16x32_bf16 v[40:43], v[122:125], v[106:109], v[40:43]
	v_mfma_f32_16x16x32_bf16 v[36:39], v[126:129], v[106:109], v[36:39]
	v_mfma_f32_16x16x32_bf16 v[32:35], v[130:133], v[106:109], v[32:35]
	v_mfma_f32_16x16x32_bf16 v[66:69], v[118:121], v[110:113], v[28:31]
	v_mfma_f32_16x16x32_bf16 v[70:73], v[122:125], v[110:113], v[24:27]
	v_mfma_f32_16x16x32_bf16 v[74:77], v[126:129], v[110:113], v[20:23]
	v_mfma_f32_16x16x32_bf16 v[78:81], v[130:133], v[110:113], v[16:19]
	v_mfma_f32_16x16x32_bf16 v[86:89], v[118:121], v[114:117], v[12:15]
	v_mfma_f32_16x16x32_bf16 v[90:93], v[122:125], v[114:117], v[8:11]
	v_mfma_f32_16x16x32_bf16 v[94:97], v[126:129], v[114:117], v[4:7]
	v_mfma_f32_16x16x32_bf16 v[0:3], v[130:133], v[114:117], v[0:3]
	s_setprio 0
	v_add_u32_e32 v98, s14, v83
	v_or_b32_e32 v4, s0, v84
	v_ashrrev_i32_e32 v99, 31, v98
	v_ashrrev_i32_e32 v5, 31, v4
	v_lshlrev_b64 v[6:7], 13, v[98:99]
	v_lshl_add_u64 v[6:7], v[64:65], 0, v[6:7]
	v_lshlrev_b64 v[100:101], 2, v[4:5]
	v_lshl_add_u64 v[12:13], v[6:7], 0, v[100:101]
	s_waitcnt vmcnt(0)
	s_barrier
	flat_load_dwordx4 v[4:7], v[12:13]
	flat_load_dwordx4 v[8:11], v[12:13] offset:256
	v_or_b32_e32 v16, 16, v98
	v_ashrrev_i32_e32 v17, 31, v16
	v_lshlrev_b64 v[16:17], 13, v[16:17]
	v_lshl_add_u64 v[16:17], v[64:65], 0, v[16:17]
	v_lshl_add_u64 v[28:29], v[16:17], 0, v[100:101]
	flat_load_dwordx4 v[24:27], v[28:29] offset:256
	s_mov_b32 s1, 0xfffffc0
	flat_load_dwordx4 v[16:19], v[28:29]
	flat_load_dwordx4 v[20:23], v[28:29] offset:64
	s_waitcnt vmcnt(0) lgkmcnt(0)
	v_pk_fma_f32 v[60:61], v[4:5], s[28:29], v[60:61] op_sel_hi:[1,0,1]
	v_pk_fma_f32 v[62:63], v[6:7], s[28:29], v[62:63] op_sel_hi:[1,0,1]
	flat_load_dwordx4 v[4:7], v[12:13] offset:64
	v_pk_fma_f32 v[8:9], v[8:9], s[28:29], v[52:53] op_sel_hi:[1,0,1]
	flat_load_dwordx4 v[12:15], v[12:13] offset:320
	v_pk_fma_f32 v[10:11], v[10:11], s[28:29], v[54:55] op_sel_hi:[1,0,1]
	flat_load_dwordx4 v[28:31], v[28:29] offset:320
	v_pk_fma_f32 v[24:25], v[24:25], s[28:29], v[36:37] op_sel_hi:[1,0,1]
	v_pk_fma_f32 v[26:27], v[26:27], s[28:29], v[38:39] op_sel_hi:[1,0,1]
	v_pk_fma_f32 v[16:17], v[16:17], s[28:29], v[44:45] op_sel_hi:[1,0,1]
	v_pk_fma_f32 v[18:19], v[18:19], s[28:29], v[46:47] op_sel_hi:[1,0,1]
	v_pk_fma_f32 v[20:21], v[20:21], s[28:29], v[40:41] op_sel_hi:[1,0,1]
	v_pk_fma_f32 v[22:23], v[22:23], s[28:29], v[42:43] op_sel_hi:[1,0,1]
	s_waitcnt vmcnt(0) lgkmcnt(0)
	v_pk_fma_f32 v[4:5], v[4:5], s[28:29], v[56:57] op_sel_hi:[1,0,1]
	v_pk_fma_f32 v[6:7], v[6:7], s[28:29], v[58:59] op_sel_hi:[1,0,1]
	v_pk_fma_f32 v[12:13], v[12:13], s[28:29], v[48:49] op_sel_hi:[1,0,1]
	v_pk_fma_f32 v[14:15], v[14:15], s[28:29], v[50:51] op_sel_hi:[1,0,1]
	v_pk_fma_f32 v[28:29], v[28:29], s[28:29], v[32:33] op_sel_hi:[1,0,1]
	v_or_b32_e32 v32, 32, v98
	v_ashrrev_i32_e32 v33, 31, v32
	v_lshlrev_b64 v[32:33], 13, v[32:33]
	v_lshl_add_u64 v[32:33], v[64:65], 0, v[32:33]
	v_lshl_add_u64 v[44:45], v[32:33], 0, v[100:101]
	v_pk_fma_f32 v[30:31], v[30:31], s[28:29], v[34:35] op_sel_hi:[1,0,1]
	flat_load_dwordx4 v[32:35], v[44:45]
	flat_load_dwordx4 v[36:39], v[44:45] offset:64
	flat_load_dwordx4 v[40:43], v[44:45] offset:256
	v_cvt_pk_bf16_f32 v4, v4, v5
	flat_load_dwordx4 v[44:47], v[44:45] offset:320
	v_cvt_pk_bf16_f32 v5, v6, v7
	v_cvt_pk_bf16_f32 v6, v12, v13
	v_cvt_pk_bf16_f32 v7, v14, v15
	s_waitcnt vmcnt(0) lgkmcnt(0)
; DEV int tid_() { int t = threadIdx.x; asm volatile("" : "+v"(t)); return t; }
; #define P (*launderP(lp))
; DEV void stage_tile_bf16(char* smem, const f32x4 (&v)[4][4], u16* buf, int ld, int m0, int col0) {
;   const int tid = tid_(), lane = tid & 63, wid = tid >> 6, wm = wid >> 1, wn = wid & 1, l15 = lane & 15, q = lane >> 4;
; #pragma unroll
;   for (int i = 0; i < 4; ++i)
; #pragma unroll
;     for (int j = 0; j < 4; ++j) {
;       const int rl = wm * 64 + i * 16 + l15, cl = (j & 1) * 16 + wn * 32 + (j >> 1) * 64 + q * 4;
;       u32x2 o; o.x = pack2(v[i][j][0], v[i][j][1]); o.y = pack2(v[i][j][2], v[i][j][3]);
;       *(u32x2*)(smem + rl * 272 + cl * 2) = o;
;     }
;   __syncthreads();
; #pragma unroll
;   for (int k = 0; k < 8; ++k) {
;     const int chunk = tid + 256 * k, rl = chunk >> 4, c16 = chunk & 15;
;     u32x4 d = *(const u32x4*)(smem + rl * 272 + c16 * 16);
;     *(u32x4*)(buf + (size_t)(m0 + rl) * ld + col0 + c16 * 8) = d;
;   }
; __device__ __forceinline__ void phase_gemm3(PREF P, int slab, char* smem) {
;     ...
; #pragma unroll
;     for (int i = 0; i < 4; ++i)
; #pragma unroll
;       for (int j = 0; j < 4; ++j) {
;         const int row = m0 + wm * 64 + i * 16 + l15, col = n0 + (j & 1) * 16 + wn * 32 + (j >> 1) * 64 + q * 4;
;         float4 xv = *(const float4*)(xs + (size_t)row * 2048 + col);
;         f32x4 o;
;         o[0] = DN_ALPHA * xv.x + acc[i][j][0]; o[1] = DN_ALPHA * xv.y + acc[i][j][1];
;         o[2] = DN_ALPHA * xv.z + acc[i][j][2]; o[3] = DN_ALPHA * xv.w + acc[i][j][3];
;         acc[i][j] = o;
;       }
;     stage_tile_bf16(smem, acc, (u16*)P.y, 2048, m0, n0);
	v_pk_fma_f32 v[32:33], v[32:33], s[28:29], v[66:67] op_sel_hi:[1,0,1]
	v_pk_fma_f32 v[34:35], v[34:35], s[28:29], v[68:69] op_sel_hi:[1,0,1]
	v_pk_fma_f32 v[36:37], v[36:37], s[28:29], v[70:71] op_sel_hi:[1,0,1]
	v_pk_fma_f32 v[38:39], v[38:39], s[28:29], v[72:73] op_sel_hi:[1,0,1]
	v_pk_fma_f32 v[48:49], v[44:45], s[28:29], v[78:79] op_sel_hi:[1,0,1]
	v_or_b32_e32 v44, 48, v98
	v_ashrrev_i32_e32 v45, 31, v44
	v_lshlrev_b64 v[44:45], 13, v[44:45]
	v_lshl_add_u64 v[44:45], v[64:65], 0, v[44:45]
	v_lshl_add_u64 v[52:53], v[44:45], 0, v[100:101]
	v_pk_fma_f32 v[50:51], v[46:47], s[28:29], v[80:81] op_sel_hi:[1,0,1]
	flat_load_dwordx4 v[44:47], v[52:53]
	v_mov_b32_e32 v72, v188
	v_pk_fma_f32 v[40:41], v[40:41], s[28:29], v[74:75] op_sel_hi:[1,0,1]
	v_pk_fma_f32 v[42:43], v[42:43], s[28:29], v[76:77] op_sel_hi:[1,0,1]
	s_waitcnt vmcnt(0) lgkmcnt(0)
	v_pk_fma_f32 v[54:55], v[44:45], s[28:29], v[86:87] op_sel_hi:[1,0,1]
	v_pk_fma_f32 v[56:57], v[46:47], s[28:29], v[88:89] op_sel_hi:[1,0,1]
	flat_load_dwordx4 v[44:47], v[52:53] offset:64
	s_waitcnt vmcnt(0) lgkmcnt(0)
	v_pk_fma_f32 v[58:59], v[44:45], s[28:29], v[90:91] op_sel_hi:[1,0,1]
	v_pk_fma_f32 v[66:67], v[46:47], s[28:29], v[92:93] op_sel_hi:[1,0,1]
	flat_load_dwordx4 v[44:47], v[52:53] offset:256
	s_waitcnt vmcnt(0) lgkmcnt(0)
	v_pk_fma_f32 v[68:69], v[44:45], s[28:29], v[94:95] op_sel_hi:[1,0,1]
	v_pk_fma_f32 v[70:71], v[46:47], s[28:29], v[96:97] op_sel_hi:[1,0,1]
	flat_load_dwordx4 v[44:47], v[52:53] offset:320
	s_waitcnt vmcnt(0) lgkmcnt(0)
	v_pk_fma_f32 v[0:1], v[44:45], s[28:29], v[0:1] op_sel_hi:[1,0,1]
	v_pk_fma_f32 v[2:3], v[46:47], s[28:29], v[2:3] op_sel_hi:[1,0,1]
	ds_read_b64 v[44:45], v82 offset:376
	v_cvt_pk_bf16_f32 v46, v60, v61
	v_and_b32_e32 v73, 15, v72
	v_lshrrev_b32_e32 v52, 1, v72
	v_and_b32_e32 v60, 64, v72
	v_and_or_b32 v53, v52, s1, v73
	v_and_or_b32 v52, v52, 24, v60
	v_cvt_pk_bf16_f32 v47, v62, v63
	v_mad_u64_u32 v[52:53], s[4:5], v53, s11, v[52:53]
	ds_write2_b64 v52, v[46:47], v[4:5] offset1:4
	v_cvt_pk_bf16_f32 v4, v8, v9
	v_cvt_pk_bf16_f32 v5, v10, v11
	ds_write2_b64 v52, v[4:5], v[6:7] offset0:16 offset1:20
	v_cvt_pk_bf16_f32 v4, v16, v17
	v_cvt_pk_bf16_f32 v5, v18, v19
	v_cvt_pk_bf16_f32 v6, v20, v21
	v_cvt_pk_bf16_f32 v7, v22, v23
	v_add_u32_e32 v8, 0x1000, v52
	ds_write2_b64 v8, v[4:5], v[6:7] offset0:32 offset1:36
	v_cvt_pk_bf16_f32 v4, v24, v25
	v_cvt_pk_bf16_f32 v5, v26, v27
	v_cvt_pk_bf16_f32 v6, v28, v29
	v_cvt_pk_bf16_f32 v7, v30, v31
	ds_write2_b64 v8, v[4:5], v[6:7] offset0:48 offset1:52
	v_cvt_pk_bf16_f32 v4, v32, v33
	v_cvt_pk_bf16_f32 v5, v34, v35
	v_cvt_pk_bf16_f32 v6, v36, v37
	v_cvt_pk_bf16_f32 v7, v38, v39
	v_add_u32_e32 v8, 0x2000, v52
	ds_write2_b64 v8, v[4:5], v[6:7] offset0:64 offset1:68
	v_cvt_pk_bf16_f32 v4, v40, v41
	v_cvt_pk_bf16_f32 v5, v42, v43
	v_cvt_pk_bf16_f32 v6, v48, v49
	v_cvt_pk_bf16_f32 v7, v50, v51
	ds_write2_b64 v8, v[4:5], v[6:7] offset0:80 offset1:84
	v_cvt_pk_bf16_f32 v4, v54, v55
	v_cvt_pk_bf16_f32 v5, v56, v57
	v_cvt_pk_bf16_f32 v6, v58, v59
	v_cvt_pk_bf16_f32 v7, v66, v67
	v_add_u32_e32 v8, 0x3000, v52
	ds_write2_b64 v8, v[4:5], v[6:7] offset0:96 offset1:100
	v_cvt_pk_bf16_f32 v4, v68, v69
	v_cvt_pk_bf16_f32 v5, v70, v71
	v_cvt_pk_bf16_f32 v0, v0, v1
	v_cvt_pk_bf16_f32 v1, v2, v3
	s_ashr_i32 s1, s0, 31
	ds_write2_b64 v8, v[4:5], v[0:1] offset0:112 offset1:116
	v_lshlrev_b32_e32 v180, 4, v73
	s_waitcnt lgkmcnt(8)
	v_lshl_add_u64 v[0:1], s[0:1], 1, v[44:45]
	v_ashrrev_i32_e32 v6, 4, v72
	v_lshl_add_u64 v[4:5], v[0:1], 0, v[180:181]
	v_mad_u64_u32 v[0:1], s[0:1], v6, s11, v[180:181]
	s_waitcnt lgkmcnt(0)
	s_barrier
	ds_read_b128 v[0:3], v0
	v_add_u32_e32 v6, s14, v6
	v_ashrrev_i32_e32 v7, 31, v6
	v_lshlrev_b64 v[6:7], 12, v[6:7]
	v_lshl_add_u64 v[6:7], v[4:5], 0, v[6:7]
	s_waitcnt lgkmcnt(0)
	flat_store_dwordx4 v[6:7], v[0:3]
	s_nop 1
	v_add_u32_e32 v0, 0x100, v72
	v_ashrrev_i32_e32 v6, 4, v0
	v_mad_u64_u32 v[0:1], s[0:1], v6, s11, v[180:181]
	ds_read_b128 v[0:3], v0
	v_add_u32_e32 v6, s14, v6
	v_ashrrev_i32_e32 v7, 31, v6
	v_lshlrev_b64 v[6:7], 12, v[6:7]
	v_lshl_add_u64 v[6:7], v[4:5], 0, v[6:7]
	s_waitcnt lgkmcnt(0)
	flat_store_dwordx4 v[6:7], v[0:3]
	s_nop 1
	v_add_u32_e32 v0, 0x200, v72
	v_ashrrev_i32_e32 v6, 4, v0
	v_mad_u64_u32 v[0:1], s[0:1], v6, s11, v[180:181]
	ds_read_b128 v[0:3], v0
	v_add_u32_e32 v6, s14, v6
	v_ashrrev_i32_e32 v7, 31, v6
	v_lshlrev_b64 v[6:7], 12, v[6:7]
	v_lshl_add_u64 v[6:7], v[4:5], 0, v[6:7]
	s_waitcnt lgkmcnt(0)
	flat_store_dwordx4 v[6:7], v[0:3]
	s_nop 1
	v_add_u32_e32 v0, 0x300, v72
	v_ashrrev_i32_e32 v6, 4, v0
	v_mad_u64_u32 v[0:1], s[0:1], v6, s11, v[180:181]
	ds_read_b128 v[0:3], v0
	v_add_u32_e32 v6, s14, v6
	v_ashrrev_i32_e32 v7, 31, v6
	v_lshlrev_b64 v[6:7], 12, v[6:7]
	v_lshl_add_u64 v[6:7], v[4:5], 0, v[6:7]
	s_waitcnt lgkmcnt(0)
	flat_store_dwordx4 v[6:7], v[0:3]
	s_nop 1
	v_add_u32_e32 v0, 0x400, v72
	v_ashrrev_i32_e32 v6, 4, v0
	v_mad_u64_u32 v[0:1], s[0:1], v6, s11, v[180:181]
	ds_read_b128 v[0:3], v0
	v_add_u32_e32 v6, s14, v6
	v_ashrrev_i32_e32 v7, 31, v6
	v_lshlrev_b64 v[6:7], 12, v[6:7]
	v_lshl_add_u64 v[6:7], v[4:5], 0, v[6:7]
	s_waitcnt lgkmcnt(0)
	flat_store_dwordx4 v[6:7], v[0:3]
	s_nop 1
	v_add_u32_e32 v0, 0x500, v72
	v_ashrrev_i32_e32 v6, 4, v0
	v_mad_u64_u32 v[0:1], s[0:1], v6, s11, v[180:181]
	ds_read_b128 v[0:3], v0
	v_add_u32_e32 v6, s14, v6
	v_ashrrev_i32_e32 v7, 31, v6
	v_lshlrev_b64 v[6:7], 12, v[6:7]
	v_lshl_add_u64 v[6:7], v[4:5], 0, v[6:7]
	s_waitcnt lgkmcnt(0)
	flat_store_dwordx4 v[6:7], v[0:3]
	s_nop 1
	v_add_u32_e32 v0, 0x600, v72
	v_ashrrev_i32_e32 v6, 4, v0
	v_mad_u64_u32 v[0:1], s[0:1], v6, s11, v[180:181]
	ds_read_b128 v[0:3], v0
	v_add_u32_e32 v6, s14, v6
	v_ashrrev_i32_e32 v7, 31, v6
	v_lshlrev_b64 v[6:7], 12, v[6:7]
	v_lshl_add_u64 v[6:7], v[4:5], 0, v[6:7]
	s_waitcnt lgkmcnt(0)
	flat_store_dwordx4 v[6:7], v[0:3]
	s_nop 1
	v_add_u32_e32 v0, 0x700, v72
	v_ashrrev_i32_e32 v6, 4, v0
	v_mad_u64_u32 v[0:1], s[0:1], v6, s11, v[180:181]
	ds_read_b128 v[0:3], v0
	v_add_u32_e32 v6, s14, v6
	v_ashrrev_i32_e32 v7, 31, v6
	v_lshlrev_b64 v[6:7], 12, v[6:7]
	v_lshl_add_u64 v[4:5], v[4:5], 0, v[6:7]
	v_readlane_b32 s0, v251, 6
	s_waitcnt lgkmcnt(0)
	flat_store_dwordx4 v[4:5], v[0:3]
	s_add_i32 s6, s0, s6
	s_cmpk_lt_i32 s6, 0x400
	v_readlane_b32 s1, v251, 7
	s_cbranch_scc1 .LBB0_458

; DEV int tid_() { int t = threadIdx.x; asm volatile("" : "+v"(t)); return t; }
; #define P (*launderP(lp))
; template <class FragT, class AccT>
; DEV void gemm_core_t(const char* __restrict__ A, size_t lda_bytes, const char* __restrict__ Bt, size_t ldb_bytes, int kbytes,
;                      int m0, int n0, int Sshift, int dl, char* smem, AccT (&acc)[4][4]) {
;   const int tid = tid_(), lane = tid & 63, wid = tid >> 6, wm = wid >> 1, wn = wid & 1;
;   const int l15 = lane & 15, q = lane >> 4;
;   const int srow = lane >> 3, schunk = (lane & 7) ^ (lane >> 3);
;   const char* ap[4];
;   const char* bp[4];
; #pragma unroll
;   for (int u = 0; u < 4; ++u) {
;     int r = (wid * 4 + u) * 8 + srow;
;     int ar = rowmap(m0 + r, Sshift, dl);
;     ap[u] = A + (size_t)ar * lda_bytes + schunk * 16;
;     bp[u] = Bt + (size_t)(n0 + r) * ldb_bytes + schunk * 16;
;   }
; #pragma unroll
;   for (int i = 0; i < 4; ++i)
; #pragma unroll
;     for (int j = 0; j < 4; ++j) acc[i][j] = AccT{0, 0, 0, 0};
;   const int nk = kbytes >> 7;
;   __syncthreads();
; #pragma unroll
;   for (int u = 0; u < 4; ++u) {
;     __builtin_amdgcn_global_load_lds((const unsigned*)ap[u], (unsigned*)(smem + (wid * 4 + u) * 1024 + lane * 16), 16, 0, 0);
;     __builtin_amdgcn_global_load_lds((const unsigned*)bp[u], (unsigned*)(smem + 16384 + (wid * 4 + u) * 1024 + lane * 16), 16, 0, 0);
;   }
; __device__ __forceinline__ void phase_gemm45(PREF P, char* smem, int which) {
;     ...
;     if (!which) {
;       i32x4 iacc[4][4];
;       gemm_core_i8(P.h8, 2048, P.Wq8, 2048, 2048, m0, n0, 13, 0, smem, iacc);
.LBB0_564:
	s_ashr_i32 s0, s6, 3
	s_lshr_b32 s1, s0, 28
	s_add_i32 s1, s0, s1
	s_and_b32 s4, s1, -16
	v_mov_b32_e32 v22, v188
	s_sub_i32 s0, s0, s4
	s_lshl_b32 s4, s6, 1
	ds_read2_b64 v[0:3], v80 offset0:60 offset1:61
	s_and_b32 s4, s4, 14
	v_ashrrev_i32_e32 v24, 6, v22
	s_ashr_i32 s5, s0, 3
	s_lshl_b32 s1, s1, 6
	s_lshl_b32 s0, s0, 7
	v_bfe_u32 v25, v22, 3, 3
	v_lshlrev_b32_e32 v26, 5, v24
	s_add_i32 s15, s5, s4
	s_and_b32 s1, s1, 0xfffffc00
	s_and_b32 s4, s0, 0x380
	v_or_b32_e32 v20, v26, v25
	s_or_b32 s14, s4, s1
	s_lshl_b32 s0, s15, 7
	v_or_b32_e32 v14, 8, v20
	v_or_b32_e32 v18, 16, v20
	v_or_b32_e32 v27, 24, v20
	v_bitop3_b32 v4, v25, v22, 7 bitop3:0x78
	v_add_u32_e32 v8, s14, v20
	v_add_u32_e32 v10, s0, v20
	v_add_u32_e32 v12, s14, v14
	v_add_u32_e32 v16, s14, v18
	v_add_u32_e32 v20, s14, v27
	v_lshlrev_b32_e32 v180, 4, v4
	v_ashrrev_i32_e32 v9, 31, v8
	v_ashrrev_i32_e32 v13, 31, v12
	v_ashrrev_i32_e32 v17, 31, v16
	v_ashrrev_i32_e32 v21, 31, v20
	s_waitcnt lgkmcnt(0)
	v_lshl_add_u64 v[4:5], v[2:3], 0, v[180:181]
	v_lshlrev_b64 v[8:9], 11, v[8:9]
	v_lshlrev_b64 v[12:13], 11, v[12:13]
	v_lshlrev_b64 v[16:17], 11, v[16:17]
	v_lshlrev_b64 v[20:21], 11, v[20:21]
	v_lshl_add_u64 v[8:9], v[4:5], 0, v[8:9]
	v_lshl_add_u64 v[12:13], v[4:5], 0, v[12:13]
	v_add_u32_e32 v14, s0, v14
	v_lshl_add_u64 v[16:17], v[4:5], 0, v[16:17]
	v_add_u32_e32 v18, s0, v18
	v_lshl_add_u64 v[4:5], v[4:5], 0, v[20:21]
	v_add_u32_e32 v20, s0, v27
	v_ashrrev_i32_e32 v11, 31, v10
	v_ashrrev_i32_e32 v15, 31, v14
	v_ashrrev_i32_e32 v19, 31, v18
	v_ashrrev_i32_e32 v21, 31, v20
	v_lshl_add_u64 v[6:7], v[0:1], 0, v[180:181]
	v_lshlrev_b64 v[10:11], 11, v[10:11]
	v_lshlrev_b64 v[14:15], 11, v[14:15]
	v_lshlrev_b64 v[18:19], 11, v[18:19]
	v_lshlrev_b64 v[20:21], 11, v[20:21]
	v_and_b32_e32 v23, 63, v22
	v_lshl_add_u64 v[10:11], v[6:7], 0, v[10:11]
	v_lshl_add_u64 v[14:15], v[6:7], 0, v[14:15]
	v_lshl_add_u64 v[18:19], v[6:7], 0, v[18:19]
	v_lshl_add_u64 v[6:7], v[6:7], 0, v[20:21]
	v_lshlrev_b32_e32 v20, 12, v24
	v_lshl_or_b32 v83, v23, 4, v20
	s_nop 0
	v_readfirstlane_b32 s15, v83
	s_mov_b32 m0, s15
	s_barrier
	global_load_lds_dwordx4 v[8:9], off
	v_add_u32_e32 v8, 0x4000, v83
	s_lshl_b32 s5, s5, 7
	v_readfirstlane_b32 s15, v8
	v_or_b32_e32 v8, 0x400, v83
	s_mov_b32 m0, s15
	v_readfirstlane_b32 s15, v8
	v_add_u32_e32 v8, 0x4400, v83
	global_load_lds_dwordx4 v[10:11], off
	s_mov_b32 m0, s15
	v_readfirstlane_b32 s15, v8
	v_or_b32_e32 v8, 0x800, v83
	global_load_lds_dwordx4 v[12:13], off
	s_mov_b32 m0, s15
	v_readfirstlane_b32 s15, v8
	v_add_u32_e32 v8, 0x4800, v83
	global_load_lds_dwordx4 v[14:15], off
	s_mov_b32 m0, s15
	v_readfirstlane_b32 s15, v8
	v_or_b32_e32 v8, 0xc00, v83
	global_load_lds_dwordx4 v[16:17], off
	s_mov_b32 m0, s15
	v_readfirstlane_b32 s15, v8
	global_load_lds_dwordx4 v[18:19], off
	s_mov_b32 m0, s15
	s_mov_b64 s[16:17], 0x80
	global_load_lds_dwordx4 v[4:5], off
	v_add_u32_e32 v4, 0x4c00, v83
	v_lshlrev_b32_e32 v5, 4, v22
	v_readfirstlane_b32 s15, v4
	s_mov_b32 m0, s15
	v_and_b32_e32 v4, 15, v22
	global_load_lds_dwordx4 v[6:7], off
	v_lshrrev_b32_e32 v6, 1, v22
	s_mov_b32 s15, 0x1ffffc0
	v_and_or_b32 v6, v6, s15, v4
	s_and_b32 s15, s6, 7
	v_bitop3_b32 v5, v23, s31, v5 bitop3:0x48
	v_lshlrev_b32_e32 v6, 7, v6
	v_and_or_b32 v4, v26, 32, v4
	s_lshl_b32 s15, s15, 8
	v_or_b32_e32 v84, v5, v6
	v_lshl_or_b32 v4, v4, 7, v5
	v_bitop3_b32 v87, v5, 64, v6 bitop3:0x36
	v_or_b32_e32 v6, 24, v25
	s_add_i32 s5, s5, s15
	v_or_b32_e32 v85, 0x4000, v4
	v_bitop3_b32 v86, v4, 64, v219 bitop3:0x36
	v_or_b32_e32 v4, s5, v6
	v_add_u32_e32 v4, v4, v26
	v_ashrrev_i32_e32 v5, 31, v4
	v_lshlrev_b64 v[4:5], 11, v[4:5]
	v_lshl_add_u64 v[0:1], v[0:1], 0, s[16:17]
	v_or_b32_e32 v4, v4, v180
	v_lshl_add_u64 v[64:65], v[0:1], 0, v[4:5]
	v_or_b32_e32 v4, s1, v6
	v_or_b32_e32 v4, s4, v4
	v_add_u32_e32 v4, v4, v26
	v_ashrrev_i32_e32 v5, 31, v4
	v_lshlrev_b64 v[4:5], 11, v[4:5]
	v_lshl_add_u64 v[2:3], v[2:3], 0, s[16:17]
	v_or_b32_e32 v4, v4, v180
	v_or_b32_e32 v6, 16, v25
	v_lshl_add_u64 v[66:67], v[2:3], 0, v[4:5]
	v_or_b32_e32 v4, s5, v6
	v_add_u32_e32 v4, v4, v26
	v_ashrrev_i32_e32 v5, 31, v4
	v_lshlrev_b64 v[4:5], 11, v[4:5]
	v_or_b32_e32 v4, v4, v180
	v_lshl_add_u64 v[68:69], v[0:1], 0, v[4:5]
	v_or_b32_e32 v4, s1, v6
	v_or_b32_e32 v4, s4, v4
	v_add_u32_e32 v4, v4, v26
	v_ashrrev_i32_e32 v5, 31, v4
	v_lshlrev_b64 v[4:5], 11, v[4:5]
	v_or_b32_e32 v4, v4, v180
	v_or_b32_e32 v6, 8, v25
	v_lshl_add_u64 v[70:71], v[2:3], 0, v[4:5]
	v_or_b32_e32 v4, s5, v6
	v_add_u32_e32 v4, v4, v26
	v_ashrrev_i32_e32 v5, 31, v4
	v_lshlrev_b64 v[4:5], 11, v[4:5]
	v_or_b32_e32 v4, v4, v180
	v_lshl_add_u64 v[72:73], v[0:1], 0, v[4:5]
	v_or_b32_e32 v4, s1, v6
	v_or_b32_e32 v4, s4, v4
	v_add_u32_e32 v4, v4, v26
	v_ashrrev_i32_e32 v5, 31, v4
	v_lshlrev_b64 v[4:5], 11, v[4:5]
	v_or_b32_e32 v4, v4, v180
	v_lshl_add_u64 v[74:75], v[2:3], 0, v[4:5]
	v_or_b32_e32 v4, s5, v25
	v_add_u32_e32 v4, v4, v26
	v_ashrrev_i32_e32 v5, 31, v4
	v_lshlrev_b64 v[4:5], 11, v[4:5]
	v_or_b32_e32 v4, v4, v180
	v_lshl_add_u64 v[76:77], v[0:1], 0, v[4:5]
	v_or_b32_e32 v0, s1, v25
	v_or_b32_e32 v0, s4, v0
	v_add_u32_e32 v0, v0, v26
	v_ashrrev_i32_e32 v1, 31, v0
	v_lshlrev_b64 v[0:1], 11, v[0:1]
	s_waitcnt vmcnt(0)
; DEV f32x4 mma_step(bf16x8 a, bf16x8 b, f32x4 c) { return MFMA(a, b, c); }
; template <class FragT, class AccT>
; DEV void gemm_core_t(const char* __restrict__ A, size_t lda_bytes, const char* __restrict__ Bt, size_t ldb_bytes, int kbytes,
;                      int m0, int n0, int Sshift, int dl, char* smem, AccT (&acc)[4][4]) {
;     ...
;   for (int kt = 0; kt < nk; ++kt) {
;     const unsigned so = (unsigned)(kt & 1) * 32768u;
;     char* nxt = smem + ((kt + 1) & 1) * 32768;
;     if (kt + 1 < nk) {
; #pragma unroll
;       for (int u = 0; u < 4; ++u) {
;         __builtin_amdgcn_global_load_lds((const unsigned*)(ap[u] + (size_t)(kt + 1) * 128), (unsigned*)(nxt + (wid * 4 + u) * 1024 + lane * 16), 16, 0, 0);
;         __builtin_amdgcn_global_load_lds((const unsigned*)(bp[u] + (size_t)(kt + 1) * 128), (unsigned*)(nxt + 16384 + (wid * 4 + u) * 1024 + lane * 16), 16, 0, 0);
;       }
;     }
;     FragT xa[2][4], wb[2][4];
;     asm volatile(
;         "ds_read_b128 %0, %16\n\t"
;         "ds_read_b128 %1, %16 offset:2048\n\t"
;         "ds_read_b128 %2, %16 offset:4096\n\t"
;         "ds_read_b128 %3, %16 offset:6144\n\t"
;         "ds_read_b128 %4, %18\n\t"
;         "ds_read_b128 %5, %18 offset:2048\n\t"
;         "ds_read_b128 %6, %18 offset:8192\n\t"
;         "ds_read_b128 %7, %18 offset:10240\n\t"
;         "ds_read_b128 %8, %17\n\t"
;         "ds_read_b128 %9, %17 offset:2048\n\t"
;         "ds_read_b128 %10, %17 offset:4096\n\t"
;         "ds_read_b128 %11, %17 offset:6144\n\t"
;         "ds_read_b128 %12, %19\n\t"
;         "ds_read_b128 %13, %19 offset:2048\n\t"
;         "ds_read_b128 %14, %19 offset:8192\n\t"
;         "ds_read_b128 %15, %19 offset:10240\n\t"
;         "s_waitcnt lgkmcnt(8)"
;         : "=&v"(xa[0][0]), "=&v"(xa[0][1]), "=&v"(xa[0][2]), "=&v"(xa[0][3]), "=&v"(wb[0][0]), "=&v"(wb[0][1]), "=&v"(wb[0][2]),
;           "=&v"(wb[0][3]), "=&v"(xa[1][0]), "=&v"(xa[1][1]), "=&v"(xa[1][2]), "=&v"(xa[1][3]), "=&v"(wb[1][0]), "=&v"(wb[1][1]),
;           "=&v"(wb[1][2]), "=&v"(wb[1][3])
;         : "v"(a0 + so), "v"((a0 ^ 64u) + so), "v"(b0 + so), "v"((b0 ^ 64u) + so)
;         : "memory");
;     __builtin_amdgcn_s_setprio(1);
; #pragma unroll
;     for (int i = 0; i < 4; ++i)
; #pragma unroll
;       for (int j = 0; j < 4; ++j) acc[i][j] = mma_step(wb[0][j], xa[0][i], acc[i][j]);
;     asm volatile("s_waitcnt lgkmcnt(0)"
	v_or_b32_e32 v0, v0, v180
	v_lshl_add_u64 v[78:79], v[2:3], 0, v[0:1]
	v_mov_b32_e32 v0, 0
	s_mov_b64 s[4:5], 0
	s_mov_b32 s1, 0x8000
	v_mov_b32_e32 v1, v0
	v_mov_b32_e32 v2, v0
	v_mov_b32_e32 v3, v0
	v_mov_b32_e32 v4, v0
	v_mov_b32_e32 v5, v0
	v_mov_b32_e32 v6, v0
	v_mov_b32_e32 v7, v0
	v_mov_b32_e32 v8, v0
	v_mov_b32_e32 v9, v0
	v_mov_b32_e32 v10, v0
	v_mov_b32_e32 v11, v0
	v_mov_b32_e32 v12, v0
	v_mov_b32_e32 v13, v0
	v_mov_b32_e32 v14, v0
	v_mov_b32_e32 v15, v0
	v_mov_b32_e32 v16, v0
	v_mov_b32_e32 v17, v0
	v_mov_b32_e32 v18, v0
	v_mov_b32_e32 v19, v0
	v_mov_b32_e32 v20, v0
	v_mov_b32_e32 v21, v0
	v_mov_b32_e32 v22, v0
	v_mov_b32_e32 v23, v0
	v_mov_b32_e32 v24, v0
	v_mov_b32_e32 v25, v0
	v_mov_b32_e32 v26, v0
	v_mov_b32_e32 v27, v0
	v_mov_b32_e32 v28, v0
	v_mov_b32_e32 v29, v0
	v_mov_b32_e32 v30, v0
	v_mov_b32_e32 v31, v0
	v_mov_b32_e32 v32, v0
	v_mov_b32_e32 v33, v0
	v_mov_b32_e32 v34, v0
	v_mov_b32_e32 v35, v0
	v_mov_b32_e32 v36, v0
	v_mov_b32_e32 v37, v0
	v_mov_b32_e32 v38, v0
	v_mov_b32_e32 v39, v0
	v_mov_b32_e32 v40, v0
	v_mov_b32_e32 v41, v0
	v_mov_b32_e32 v42, v0
	v_mov_b32_e32 v43, v0
	v_mov_b32_e32 v44, v0
	v_mov_b32_e32 v45, v0
	v_mov_b32_e32 v46, v0
	v_mov_b32_e32 v47, v0
	v_mov_b32_e32 v48, v0
	v_mov_b32_e32 v49, v0
	v_mov_b32_e32 v50, v0
	v_mov_b32_e32 v51, v0
	v_mov_b32_e32 v52, v0
	v_mov_b32_e32 v53, v0
	v_mov_b32_e32 v54, v0
	v_mov_b32_e32 v55, v0
	v_mov_b32_e32 v56, v0
	v_mov_b32_e32 v57, v0
	v_mov_b32_e32 v58, v0
	v_mov_b32_e32 v59, v0
	v_mov_b32_e32 v60, v0
	v_mov_b32_e32 v61, v0
	v_mov_b32_e32 v62, v0
	v_mov_b32_e32 v63, v0
	v_readfirstlane_b32 s64, v78
	v_readfirstlane_b32 s65, v79
	v_readfirstlane_b32 s66, v76
	v_readfirstlane_b32 s67, v77
	v_readfirstlane_b32 s62, v83
	s_sub_u32 s64, s64, 0x80000000
	s_subb_u32 s65, s65, 0
	s_sub_u32 s66, s66, 0x80000000
	s_subb_u32 s67, s67, 0
	v_subrev_u32_e32 v78, s64, v78
	v_subrev_u32_e32 v76, s66, v76
	v_subrev_u32_e32 v74, s64, v74
	v_subrev_u32_e32 v72, s66, v72
	v_subrev_u32_e32 v70, s64, v70
	v_subrev_u32_e32 v68, s66, v68
	v_subrev_u32_e32 v66, s64, v66
	v_subrev_u32_e32 v64, s66, v64
	s_waitcnt vmcnt(0) lgkmcnt(0)
	s_barrier
.LBB0_565:
	s_add_i32 s15, s1, 0xffff8000
	s_and_b32 s15, s15, 0x8000
	v_add_u32_e32 v152, s15, v84
	v_add_u32_e32 v153, s15, v87
	v_or_b32_e32 v154, s15, v85
	v_or_b32_e32 v155, s15, v86
	s_and_b32 s15, s1, 0x8000
	s_add_i32 s15, s15, s62
	s_mov_b32 m0, s15
	ds_read_b128 v[88:91], v152
	global_load_lds_dwordx4 v78, s[64:65]
	ds_read_b128 v[92:95], v152 offset:2048
	s_add_i32 m0, s15, 0x4000
	ds_read_b128 v[96:99], v152 offset:4096
	global_load_lds_dwordx4 v76, s[66:67]
	ds_read_b128 v[100:103], v152 offset:6144
	s_add_i32 m0, s15, 0x400
	ds_read_b128 v[104:107], v154
	global_load_lds_dwordx4 v74, s[64:65]
	ds_read_b128 v[108:111], v154 offset:2048
	s_add_i32 m0, s15, 0x4400
	ds_read_b128 v[112:115], v154 offset:8192
	global_load_lds_dwordx4 v72, s[66:67]
	ds_read_b128 v[116:119], v154 offset:10240
	s_add_i32 m0, s15, 0x800
	ds_read_b128 v[120:123], v153
	global_load_lds_dwordx4 v70, s[64:65]
	ds_read_b128 v[124:127], v153 offset:2048
	s_add_i32 m0, s15, 0x4800
	ds_read_b128 v[128:131], v153 offset:4096
	global_load_lds_dwordx4 v68, s[66:67]
	ds_read_b128 v[132:135], v153 offset:6144
	s_add_i32 m0, s15, 0xc00
	ds_read_b128 v[136:139], v155
	global_load_lds_dwordx4 v66, s[64:65]
	ds_read_b128 v[140:143], v155 offset:2048
	s_add_i32 m0, s15, 0x4c00
	ds_read_b128 v[144:147], v155 offset:8192
	global_load_lds_dwordx4 v64, s[66:67]
	ds_read_b128 v[148:151], v155 offset:10240
	s_waitcnt lgkmcnt(8)
	s_setprio 1
	v_mfma_i32_16x16x64_i8 v[60:63], v[104:107], v[88:91], v[60:63]
	v_mfma_i32_16x16x64_i8 v[56:59], v[108:111], v[88:91], v[56:59]
	v_mfma_i32_16x16x64_i8 v[52:55], v[112:115], v[88:91], v[52:55]
	v_mfma_i32_16x16x64_i8 v[48:51], v[116:119], v[88:91], v[48:51]
	v_mfma_i32_16x16x64_i8 v[44:47], v[104:107], v[92:95], v[44:47]
	v_mfma_i32_16x16x64_i8 v[40:43], v[108:111], v[92:95], v[40:43]
	v_mfma_i32_16x16x64_i8 v[36:39], v[112:115], v[92:95], v[36:39]
	v_mfma_i32_16x16x64_i8 v[32:35], v[116:119], v[92:95], v[32:35]
	v_mfma_i32_16x16x64_i8 v[28:31], v[104:107], v[96:99], v[28:31]
	v_mfma_i32_16x16x64_i8 v[24:27], v[108:111], v[96:99], v[24:27]
	v_mfma_i32_16x16x64_i8 v[20:23], v[112:115], v[96:99], v[20:23]
	v_mfma_i32_16x16x64_i8 v[16:19], v[116:119], v[96:99], v[16:19]
	v_mfma_i32_16x16x64_i8 v[12:15], v[104:107], v[100:103], v[12:15]
	v_mfma_i32_16x16x64_i8 v[8:11], v[108:111], v[100:103], v[8:11]
	v_mfma_i32_16x16x64_i8 v[4:7], v[112:115], v[100:103], v[4:7]
	v_mfma_i32_16x16x64_i8 v[0:3], v[116:119], v[100:103], v[0:3]
	s_waitcnt lgkmcnt(0)
	s_nop 0
	v_mfma_i32_16x16x64_i8 v[60:63], v[136:139], v[120:123], v[60:63]
	v_mfma_i32_16x16x64_i8 v[56:59], v[140:143], v[120:123], v[56:59]
	v_mfma_i32_16x16x64_i8 v[52:55], v[144:147], v[120:123], v[52:55]
	v_mfma_i32_16x16x64_i8 v[48:51], v[148:151], v[120:123], v[48:51]
	v_mfma_i32_16x16x64_i8 v[44:47], v[136:139], v[124:127], v[44:47]
	v_mfma_i32_16x16x64_i8 v[40:43], v[140:143], v[124:127], v[40:43]
	v_mfma_i32_16x16x64_i8 v[36:39], v[144:147], v[124:127], v[36:39]
	v_mfma_i32_16x16x64_i8 v[32:35], v[148:151], v[124:127], v[32:35]
	v_mfma_i32_16x16x64_i8 v[28:31], v[136:139], v[128:131], v[28:31]
	v_mfma_i32_16x16x64_i8 v[24:27], v[140:143], v[128:131], v[24:27]
	v_mfma_i32_16x16x64_i8 v[20:23], v[144:147], v[128:131], v[20:23]
	v_mfma_i32_16x16x64_i8 v[16:19], v[148:151], v[128:131], v[16:19]
	v_mfma_i32_16x16x64_i8 v[12:15], v[136:139], v[132:135], v[12:15]
	v_mfma_i32_16x16x64_i8 v[8:11], v[140:143], v[132:135], v[8:11]
	v_mfma_i32_16x16x64_i8 v[4:7], v[144:147], v[132:135], v[4:7]
	v_mfma_i32_16x16x64_i8 v[0:3], v[148:151], v[132:135], v[0:3]
	s_setprio 0
	s_waitcnt vmcnt(0)
	s_add_u32 s4, s4, 0x80
	s_addc_u32 s5, s5, 0
	s_add_u32 s64, s64, 0x80
	s_addc_u32 s65, s65, 0
	s_add_u32 s66, s66, 0x80
	s_addc_u32 s67, s67, 0
	s_add_i32 s1, s1, 0x8000
	s_cmpk_lg_i32 s4, 0x780
	s_waitcnt vmcnt(0) lgkmcnt(0)
	s_barrier
; template <class FragT, class AccT>
; DEV void gemm_core_t(const char* __restrict__ A, size_t lda_bytes, const char* __restrict__ Bt, size_t ldb_bytes, int kbytes,
;                      int m0, int n0, int Sshift, int dl, char* smem, AccT (&acc)[4][4]) {
;     ...
;     asm volatile(
;         "ds_read_b128 %0, %16\n\t"
;         "ds_read_b128 %1, %16 offset:2048\n\t"
;         "ds_read_b128 %2, %16 offset:4096\n\t"
;         "ds_read_b128 %3, %16 offset:6144\n\t"
;         "ds_read_b128 %4, %18\n\t"
;         "ds_read_b128 %5, %18 offset:2048\n\t"
;         "ds_read_b128 %6, %18 offset:8192\n\t"
;         "ds_read_b128 %7, %18 offset:10240\n\t"
;         "ds_read_b128 %8, %17\n\t"
;         "ds_read_b128 %9, %17 offset:2048\n\t"
;         "ds_read_b128 %10, %17 offset:4096\n\t"
;         "ds_read_b128 %11, %17 offset:6144\n\t"
;         "ds_read_b128 %12, %19\n\t"
;         "ds_read_b128 %13, %19 offset:2048\n\t"
;         "ds_read_b128 %14, %19 offset:8192\n\t"
;         "ds_read_b128 %15, %19 offset:10240\n\t"
;         "s_waitcnt lgkmcnt(8)"
;         : "=&v"(xa[0][0]), "=&v"(xa[0][1]), "=&v"(xa[0][2]), "=&v"(xa[0][3]), "=&v"(wb[0][0]), "=&v"(wb[0][1]), "=&v"(wb[0][2]),
;           "=&v"(wb[0][3]), "=&v"(xa[1][0]), "=&v"(xa[1][1]), "=&v"(xa[1][2]), "=&v"(xa[1][3]), "=&v"(wb[1][0]), "=&v"(wb[1][1]),
;           "=&v"(wb[1][2]), "=&v"(wb[1][3])
;         : "v"(a0 + so), "v"((a0 ^ 64u) + so), "v"(b0 + so), "v"((b0 ^ 64u) + so)
;         : "memory");
;     __builtin_amdgcn_s_setprio(1);
; #pragma unroll
;     for (int i = 0; i < 4; ++i)
; #pragma unroll
;       for (int j = 0; j < 4; ++j) acc[i][j] = mma_step(wb[0][j], xa[0][i], acc[i][j]);
;     asm volatile("s_waitcnt lgkmcnt(0)"
;                  : "+v"(xa[1][0]), "+v"(xa[1][1]), "+v"(xa[1][2]), "+v"(xa[1][3]), "+v"(wb[1][0]), "+v"(wb[1][1]), "+v"(wb[1][2]),
;                    "+v"(wb[1][3]), "+v"(acc[0][0]), "+v"(acc[0][1]), "+v"(acc[0][2]), "+v"(acc[0][3]), "+v"(acc[1][0]),
;                    "+v"(acc[1][1]), "+v"(acc[1][2]), "+v"(acc[1][3]), "+v"(acc[2][0]), "+v"(acc[2][1]), "+v"(acc[2][2]),
;                    "+v"(acc[2][3]), "+v"(acc[3][0]), "+v"(acc[3][1]), "+v"(acc[3][2]), "+v"(acc[3][3])
;                  :
;                  : "memory");
; #pragma unroll
;     for (int i = 0; i < 4; ++i)
; #pragma unroll
;       for (int j = 0; j < 4; ++j) acc[i][j] = mma_step(wb[1][j], xa[1][i], acc[i][j]);
	s_cbranch_scc1 .LBB0_565
	v_add_u32_e32 v83, 0x8000, v84
	v_add_u32_e32 v132, 0x8000, v87
	v_or_b32_e32 v133, 0x8000, v85
	v_or_b32_e32 v134, 0x8000, v86
	ds_read_b128 v[64:67], v83
	ds_read_b128 v[68:71], v83 offset:2048
	ds_read_b128 v[72:75], v83 offset:4096
	ds_read_b128 v[76:79], v83 offset:6144
	ds_read_b128 v[84:87], v133
	ds_read_b128 v[88:91], v133 offset:2048
	ds_read_b128 v[92:95], v133 offset:8192
	ds_read_b128 v[96:99], v133 offset:10240
	ds_read_b128 v[100:103], v132
	ds_read_b128 v[104:107], v132 offset:2048
	ds_read_b128 v[108:111], v132 offset:4096
	ds_read_b128 v[112:115], v132 offset:6144
	ds_read_b128 v[116:119], v134
	ds_read_b128 v[120:123], v134 offset:2048
	ds_read_b128 v[124:127], v134 offset:8192
	ds_read_b128 v[128:131], v134 offset:10240
	s_waitcnt lgkmcnt(8)
	s_setprio 1
	v_mfma_i32_16x16x64_i8 v[60:63], v[84:87], v[64:67], v[60:63]
	v_mfma_i32_16x16x64_i8 v[56:59], v[88:91], v[64:67], v[56:59]
	v_mfma_i32_16x16x64_i8 v[52:55], v[92:95], v[64:67], v[52:55]
	v_mfma_i32_16x16x64_i8 v[48:51], v[96:99], v[64:67], v[48:51]
	v_mfma_i32_16x16x64_i8 v[44:47], v[84:87], v[68:71], v[44:47]
	v_mfma_i32_16x16x64_i8 v[40:43], v[88:91], v[68:71], v[40:43]
	v_mfma_i32_16x16x64_i8 v[36:39], v[92:95], v[68:71], v[36:39]
	v_mfma_i32_16x16x64_i8 v[32:35], v[96:99], v[68:71], v[32:35]
	v_mfma_i32_16x16x64_i8 v[28:31], v[84:87], v[72:75], v[28:31]
	v_mfma_i32_16x16x64_i8 v[24:27], v[88:91], v[72:75], v[24:27]
	v_mfma_i32_16x16x64_i8 v[20:23], v[92:95], v[72:75], v[20:23]
	v_mfma_i32_16x16x64_i8 v[16:19], v[96:99], v[72:75], v[16:19]
	v_mfma_i32_16x16x64_i8 v[12:15], v[84:87], v[76:79], v[12:15]
	v_mfma_i32_16x16x64_i8 v[8:11], v[88:91], v[76:79], v[8:11]
	v_mfma_i32_16x16x64_i8 v[4:7], v[92:95], v[76:79], v[4:7]
	v_mfma_i32_16x16x64_i8 v[0:3], v[96:99], v[76:79], v[0:3]
	s_waitcnt lgkmcnt(0)
	s_nop 0
	v_mfma_i32_16x16x64_i8 v[60:63], v[116:119], v[100:103], v[60:63]
	v_mfma_i32_16x16x64_i8 v[56:59], v[120:123], v[100:103], v[56:59]
	v_mfma_i32_16x16x64_i8 v[52:55], v[124:127], v[100:103], v[52:55]
	v_mfma_i32_16x16x64_i8 v[64:67], v[128:131], v[100:103], v[48:51]
	v_mfma_i32_16x16x64_i8 v[44:47], v[116:119], v[104:107], v[44:47]
	v_mfma_i32_16x16x64_i8 v[48:51], v[120:123], v[104:107], v[40:43]
	v_mfma_i32_16x16x64_i8 v[38:41], v[124:127], v[104:107], v[36:39]
	v_mfma_i32_16x16x64_i8 v[68:71], v[128:131], v[104:107], v[32:35]
	v_mfma_i32_16x16x64_i8 v[28:31], v[116:119], v[108:111], v[28:31]
	v_mfma_i32_16x16x64_i8 v[34:37], v[120:123], v[108:111], v[24:27]
	v_mfma_i32_16x16x64_i8 v[72:75], v[124:127], v[108:111], v[20:23]
	v_mfma_i32_16x16x64_i8 v[76:79], v[128:131], v[108:111], v[16:19]
	v_mfma_i32_16x16x64_i8 v[12:15], v[116:119], v[112:115], v[12:15]
	v_mfma_i32_16x16x64_i8 v[84:87], v[120:123], v[112:115], v[8:11]
	v_mfma_i32_16x16x64_i8 v[88:91], v[124:127], v[112:115], v[4:7]
	v_mfma_i32_16x16x64_i8 v[92:95], v[128:131], v[112:115], v[0:3]
	s_setprio 0
	s_waitcnt vmcnt(0)
	s_barrier
	s_nop 0
	ds_read2_b64 v[0:3], v80 offset0:55 offset1:56
	v_add_u32_e32 v4, s14, v81
	v_or_b32_e32 v6, s0, v82
	v_ashrrev_i32_e32 v7, 31, v6
	v_ashrrev_i32_e32 v5, 31, v4
	s_waitcnt lgkmcnt(0)
	v_lshl_add_u64 v[96:97], v[6:7], 2, v[0:1]
	v_lshl_add_u64 v[0:1], v[4:5], 2, v[2:3]
	flat_load_dword v98, v[0:1]
	flat_load_dword v100, v[0:1] offset:64
	flat_load_dword v102, v[0:1] offset:128
	flat_load_dword v104, v[0:1] offset:192
	flat_load_dwordx4 v[4:7], v[96:97]
	v_cvt_f32_i32_e32 v1, v61
	v_cvt_f32_i32_e32 v0, v60
	v_cvt_f32_i32_e32 v21, v53
	v_cvt_f32_i32_e32 v20, v52
	s_mov_b32 s1, 0xfffffc0
	s_waitcnt vmcnt(0) lgkmcnt(0)
	v_pk_mul_f32 v[0:1], v[98:99], v[0:1] op_sel_hi:[0,1]
	v_pk_mul_f32 v[20:21], v[98:99], v[20:21] op_sel_hi:[0,1]
	v_pk_mul_f32 v[18:19], v[4:5], v[0:1]
	v_cvt_f32_i32_e32 v1, v45
	v_cvt_f32_i32_e32 v0, v44
	v_cvt_pk_bf16_f32 v18, v18, v19
	v_pk_mul_f32 v[0:1], v[100:101], v[0:1] op_sel_hi:[0,1]
	v_pk_mul_f32 v[8:9], v[4:5], v[0:1]
	v_cvt_f32_i32_e32 v1, v29
	v_cvt_f32_i32_e32 v0, v28
	v_cvt_pk_bf16_f32 v8, v8, v9
	v_pk_mul_f32 v[0:1], v[102:103], v[0:1] op_sel_hi:[0,1]
	v_pk_mul_f32 v[2:3], v[4:5], v[0:1]
	v_cvt_f32_i32_e32 v1, v13
	v_cvt_f32_i32_e32 v0, v12
	v_cvt_pk_bf16_f32 v2, v2, v3
	v_pk_mul_f32 v[0:1], v[104:105], v[0:1] op_sel_hi:[0,1]
	v_pk_mul_f32 v[0:1], v[4:5], v[0:1]
	v_cvt_f32_i32_e32 v5, v63
	v_cvt_f32_i32_e32 v4, v62
	v_cvt_pk_bf16_f32 v0, v0, v1
	v_pk_mul_f32 v[4:5], v[98:99], v[4:5] op_sel_hi:[0,1]
	v_pk_mul_f32 v[26:27], v[4:5], v[6:7]
	v_cvt_f32_i32_e32 v5, v47
	v_cvt_f32_i32_e32 v4, v46
	flat_load_dwordx4 v[44:47], v[96:97] offset:256
	v_cvt_pk_bf16_f32 v19, v26, v27
	v_pk_mul_f32 v[4:5], v[100:101], v[4:5] op_sel_hi:[0,1]
	v_pk_mul_f32 v[16:17], v[6:7], v[4:5]
	v_cvt_f32_i32_e32 v5, v31
	v_cvt_f32_i32_e32 v4, v30
	flat_load_dwordx4 v[28:31], v[96:97] offset:64
	v_cvt_pk_bf16_f32 v9, v16, v17
	v_pk_mul_f32 v[4:5], v[102:103], v[4:5] op_sel_hi:[0,1]
	v_pk_mul_f32 v[10:11], v[6:7], v[4:5]
	v_cvt_f32_i32_e32 v5, v15
	v_cvt_f32_i32_e32 v4, v14
	v_cvt_f32_i32_e32 v15, v59
	v_cvt_f32_i32_e32 v14, v58
	v_cvt_pk_bf16_f32 v3, v10, v11
	v_pk_mul_f32 v[4:5], v[104:105], v[4:5] op_sel_hi:[0,1]
	v_pk_mul_f32 v[4:5], v[6:7], v[4:5]
	v_cvt_f32_i32_e32 v7, v57
	v_cvt_f32_i32_e32 v6, v56
	v_pk_mul_f32 v[14:15], v[98:99], v[14:15] op_sel_hi:[0,1]
	v_cvt_pk_bf16_f32 v1, v4, v5
	v_pk_mul_f32 v[6:7], v[98:99], v[6:7] op_sel_hi:[0,1]
	s_waitcnt vmcnt(0) lgkmcnt(0)
; DEV int tid_() { int t = threadIdx.x; asm volatile("" : "+v"(t)); return t; }
; #define P (*launderP(lp))
; DEV void stage_tile_bf16(char* smem, const f32x4 (&v)[4][4], u16* buf, int ld, int m0, int col0) {
;   const int tid = tid_(), lane = tid & 63, wid = tid >> 6, wm = wid >> 1, wn = wid & 1, l15 = lane & 15, q = lane >> 4;
; #pragma unroll
;   for (int i = 0; i < 4; ++i)
; #pragma unroll
;     for (int j = 0; j < 4; ++j) {
;       const int rl = wm * 64 + i * 16 + l15, cl = (j & 1) * 16 + wn * 32 + (j >> 1) * 64 + q * 4;
;       u32x2 o; o.x = pack2(v[i][j][0], v[i][j][1]); o.y = pack2(v[i][j][2], v[i][j][3]);
;       *(u32x2*)(smem + rl * 272 + cl * 2) = o;
;     }
;   __syncthreads();
; __device__ __forceinline__ void phase_gemm45(PREF P, char* smem, int which) {
;     ...
;         for (int j = 0; j < 4; ++j) {
;           const int col = n0 + (j & 1) * 16 + wn * 32 + (j >> 1) * 64 + q * 4;
;           const float4 swc = *(const float4*)(P.swq + col);
;           f32x4 v;
;           v[0] = (float)iacc[i][j][0] * shr * swc.x; v[1] = (float)iacc[i][j][1] * shr * swc.y;
;           v[2] = (float)iacc[i][j][2] * shr * swc.z; v[3] = (float)iacc[i][j][3] * shr * swc.w;
;           acc[i][j] = v;
;         }
;       }
;       stage_tile_bf16(smem, acc, P.qb, 2048, m0, n0);
	v_pk_mul_f32 v[32:33], v[6:7], v[28:29]
	v_cvt_f32_i32_e32 v7, v49
	v_cvt_f32_i32_e32 v6, v48
	v_pk_mul_f32 v[42:43], v[14:15], v[30:31]
	v_cvt_f32_i32_e32 v15, v51
	v_cvt_f32_i32_e32 v14, v50
	v_pk_mul_f32 v[6:7], v[100:101], v[6:7] op_sel_hi:[0,1]
	v_pk_mul_f32 v[22:23], v[28:29], v[6:7]
	v_cvt_f32_i32_e32 v7, v35
	v_pk_mul_f32 v[14:15], v[100:101], v[14:15] op_sel_hi:[0,1]
	v_cvt_f32_i32_e32 v6, v34
	v_pk_mul_f32 v[34:35], v[30:31], v[14:15]
	v_cvt_f32_i32_e32 v15, v37
	v_cvt_f32_i32_e32 v14, v36
	v_pk_mul_f32 v[48:49], v[20:21], v[44:45]
	v_cvt_f32_i32_e32 v21, v39
	v_cvt_f32_i32_e32 v20, v38
	v_pk_mul_f32 v[14:15], v[102:103], v[14:15] op_sel_hi:[0,1]
	v_pk_mul_f32 v[24:25], v[30:31], v[14:15]
	v_cvt_f32_i32_e32 v15, v87
	v_cvt_f32_i32_e32 v14, v86
	v_pk_mul_f32 v[20:21], v[100:101], v[20:21] op_sel_hi:[0,1]
	v_pk_mul_f32 v[38:39], v[44:45], v[20:21]
	v_cvt_f32_i32_e32 v21, v73
	v_pk_mul_f32 v[14:15], v[104:105], v[14:15] op_sel_hi:[0,1]
	v_pk_mul_f32 v[14:15], v[30:31], v[14:15]
	v_cvt_f32_i32_e32 v31, v55
	v_cvt_f32_i32_e32 v30, v54
	v_cvt_f32_i32_e32 v20, v72
	v_cvt_f32_i32_e32 v37, v65
	v_cvt_f32_i32_e32 v36, v64
	v_pk_mul_f32 v[30:31], v[98:99], v[30:31] op_sel_hi:[0,1]
	v_pk_mul_f32 v[56:57], v[30:31], v[46:47]
	v_cvt_f32_i32_e32 v31, v41
	v_cvt_f32_i32_e32 v30, v40
	v_pk_mul_f32 v[6:7], v[102:103], v[6:7] op_sel_hi:[0,1]
	v_pk_mul_f32 v[36:37], v[98:99], v[36:37] op_sel_hi:[0,1]
	v_pk_mul_f32 v[12:13], v[28:29], v[6:7]
	v_pk_mul_f32 v[30:31], v[100:101], v[30:31] op_sel_hi:[0,1]
	v_pk_mul_f32 v[50:51], v[46:47], v[30:31]
	v_cvt_f32_i32_e32 v31, v75
	v_cvt_f32_i32_e32 v30, v74
	flat_load_dwordx4 v[72:75], v[96:97] offset:320
	v_cvt_f32_i32_e32 v7, v85
	v_cvt_f32_i32_e32 v6, v84
	v_pk_mul_f32 v[30:31], v[102:103], v[30:31] op_sel_hi:[0,1]
	v_pk_mul_f32 v[40:41], v[46:47], v[30:31]
	v_cvt_f32_i32_e32 v31, v91
	v_cvt_f32_i32_e32 v30, v90
	v_pk_mul_f32 v[6:7], v[104:105], v[6:7] op_sel_hi:[0,1]
	v_pk_mul_f32 v[20:21], v[102:103], v[20:21] op_sel_hi:[0,1]
	v_pk_mul_f32 v[6:7], v[28:29], v[6:7]
	v_pk_mul_f32 v[30:31], v[104:105], v[30:31] op_sel_hi:[0,1]
	v_pk_mul_f32 v[30:31], v[46:47], v[30:31]
	v_cvt_f32_i32_e32 v47, v67
	v_cvt_f32_i32_e32 v46, v66
	v_pk_mul_f32 v[28:29], v[44:45], v[20:21]
	v_cvt_f32_i32_e32 v21, v89
	v_cvt_f32_i32_e32 v20, v88
	v_pk_mul_f32 v[46:47], v[98:99], v[46:47] op_sel_hi:[0,1]
	v_mov_b32_e32 v66, v188
	ds_read_b64 v[64:65], v80 offset:352
	v_pk_mul_f32 v[20:21], v[104:105], v[20:21] op_sel_hi:[0,1]
	v_and_b32_e32 v67, 15, v66
	v_and_b32_e32 v26, 64, v66
	v_cvt_pk_bf16_f32 v32, v32, v33
	v_cvt_pk_bf16_f32 v33, v42, v43
	v_pk_mul_f32 v[20:21], v[44:45], v[20:21]
	v_cvt_pk_bf16_f32 v16, v22, v23
	v_cvt_pk_bf16_f32 v17, v34, v35
	v_lshlrev_b32_e32 v180, 4, v67
	s_waitcnt vmcnt(0) lgkmcnt(0)
	v_pk_mul_f32 v[58:59], v[36:37], v[72:73]
	v_cvt_f32_i32_e32 v37, v69
	v_cvt_f32_i32_e32 v36, v68
	v_pk_mul_f32 v[62:63], v[46:47], v[74:75]
	v_cvt_f32_i32_e32 v47, v71
	v_cvt_f32_i32_e32 v46, v70
	v_pk_mul_f32 v[36:37], v[100:101], v[36:37] op_sel_hi:[0,1]
	v_pk_mul_f32 v[52:53], v[72:73], v[36:37]
	v_cvt_f32_i32_e32 v37, v77
	v_pk_mul_f32 v[46:47], v[100:101], v[46:47] op_sel_hi:[0,1]
	v_cvt_f32_i32_e32 v36, v76
	v_pk_mul_f32 v[60:61], v[74:75], v[46:47]
	v_cvt_f32_i32_e32 v47, v79
	v_cvt_f32_i32_e32 v46, v78
	v_lshrrev_b32_e32 v68, 1, v66
	v_and_or_b32 v69, v68, s1, v67
	v_and_or_b32 v26, v68, 24, v26
	v_pk_mul_f32 v[36:37], v[102:103], v[36:37] op_sel_hi:[0,1]
	v_pk_mul_f32 v[46:47], v[102:103], v[46:47] op_sel_hi:[0,1]
	v_mad_u64_u32 v[26:27], s[4:5], v69, s11, v[26:27]
	v_pk_mul_f32 v[44:45], v[72:73], v[36:37]
	v_cvt_f32_i32_e32 v37, v93
	v_cvt_f32_i32_e32 v36, v92
	v_pk_mul_f32 v[54:55], v[74:75], v[46:47]
	v_cvt_f32_i32_e32 v47, v95
	v_cvt_f32_i32_e32 v46, v94
	ds_write2_b64 v26, v[18:19], v[32:33] offset1:4
	v_cvt_pk_bf16_f32 v18, v48, v49
	v_cvt_pk_bf16_f32 v19, v56, v57
	v_cvt_pk_bf16_f32 v32, v58, v59
	v_cvt_pk_bf16_f32 v33, v62, v63
	ds_write2_b64 v26, v[18:19], v[32:33] offset0:16 offset1:20
	v_add_u32_e32 v18, 0x1000, v26
	ds_write2_b64 v18, v[8:9], v[16:17] offset0:32 offset1:36
	v_cvt_pk_bf16_f32 v8, v38, v39
	v_cvt_pk_bf16_f32 v9, v50, v51
	v_cvt_pk_bf16_f32 v16, v52, v53
	v_cvt_pk_bf16_f32 v17, v60, v61
	ds_write2_b64 v18, v[8:9], v[16:17] offset0:48 offset1:52
	v_cvt_pk_bf16_f32 v8, v12, v13
	v_cvt_pk_bf16_f32 v9, v24, v25
	v_add_u32_e32 v10, 0x2000, v26
	v_pk_mul_f32 v[36:37], v[104:105], v[36:37] op_sel_hi:[0,1]
	v_pk_mul_f32 v[46:47], v[104:105], v[46:47] op_sel_hi:[0,1]
	ds_write2_b64 v10, v[2:3], v[8:9] offset0:64 offset1:68
	v_cvt_pk_bf16_f32 v2, v28, v29
	v_cvt_pk_bf16_f32 v3, v40, v41
	v_cvt_pk_bf16_f32 v8, v44, v45
	v_cvt_pk_bf16_f32 v9, v54, v55
	v_pk_mul_f32 v[36:37], v[72:73], v[36:37]
	v_pk_mul_f32 v[46:47], v[74:75], v[46:47]
	ds_write2_b64 v10, v[2:3], v[8:9] offset0:80 offset1:84
	v_cvt_pk_bf16_f32 v2, v6, v7
	v_cvt_pk_bf16_f32 v3, v14, v15
	v_add_u32_e32 v4, 0x3000, v26
	ds_write2_b64 v4, v[0:1], v[2:3] offset0:96 offset1:100
	v_cvt_pk_bf16_f32 v0, v20, v21
	v_cvt_pk_bf16_f32 v1, v30, v31
	v_cvt_pk_bf16_f32 v2, v36, v37
	v_cvt_pk_bf16_f32 v3, v46, v47
	s_ashr_i32 s1, s0, 31
	ds_write2_b64 v4, v[0:1], v[2:3] offset0:112 offset1:116
	v_lshl_add_u64 v[0:1], s[0:1], 1, v[64:65]
	v_ashrrev_i32_e32 v6, 4, v66
	v_lshl_add_u64 v[4:5], v[0:1], 0, v[180:181]
	v_mad_u64_u32 v[0:1], s[0:1], v6, s11, v[180:181]
	s_waitcnt lgkmcnt(0)
	s_barrier
; DEV void stage_tile_bf16(char* smem, const f32x4 (&v)[4][4], u16* buf, int ld, int m0, int col0) {
;     ...
; #pragma unroll
;   for (int k = 0; k < 8; ++k) {
;     const int chunk = tid + 256 * k, rl = chunk >> 4, c16 = chunk & 15;
;     u32x4 d = *(const u32x4*)(smem + rl * 272 + c16 * 16);
;     *(u32x4*)(buf + (size_t)(m0 + rl) * ld + col0 + c16 * 8) = d;
;   }
	ds_read_b128 v[0:3], v0
	v_add_u32_e32 v6, s14, v6
	v_ashrrev_i32_e32 v7, 31, v6
	v_lshlrev_b64 v[6:7], 12, v[6:7]
	v_lshl_add_u64 v[6:7], v[4:5], 0, v[6:7]
	s_waitcnt lgkmcnt(0)
	flat_store_dwordx4 v[6:7], v[0:3]
	s_nop 1
	v_add_u32_e32 v0, 0x100, v66
	v_ashrrev_i32_e32 v6, 4, v0
	v_mad_u64_u32 v[0:1], s[0:1], v6, s11, v[180:181]
	ds_read_b128 v[0:3], v0
	v_add_u32_e32 v6, s14, v6
	v_ashrrev_i32_e32 v7, 31, v6
	v_lshlrev_b64 v[6:7], 12, v[6:7]
	v_lshl_add_u64 v[6:7], v[4:5], 0, v[6:7]
	s_waitcnt lgkmcnt(0)
	flat_store_dwordx4 v[6:7], v[0:3]
	s_nop 1
	v_add_u32_e32 v0, 0x200, v66
	v_ashrrev_i32_e32 v6, 4, v0
	v_mad_u64_u32 v[0:1], s[0:1], v6, s11, v[180:181]
	ds_read_b128 v[0:3], v0
	v_add_u32_e32 v6, s14, v6
	v_ashrrev_i32_e32 v7, 31, v6
	v_lshlrev_b64 v[6:7], 12, v[6:7]
	v_lshl_add_u64 v[6:7], v[4:5], 0, v[6:7]
	s_waitcnt lgkmcnt(0)
	flat_store_dwordx4 v[6:7], v[0:3]
	s_nop 1
	v_add_u32_e32 v0, 0x300, v66
	v_ashrrev_i32_e32 v6, 4, v0
	v_mad_u64_u32 v[0:1], s[0:1], v6, s11, v[180:181]
	ds_read_b128 v[0:3], v0
	v_add_u32_e32 v6, s14, v6
	v_ashrrev_i32_e32 v7, 31, v6
	v_lshlrev_b64 v[6:7], 12, v[6:7]
	v_lshl_add_u64 v[6:7], v[4:5], 0, v[6:7]
	s_waitcnt lgkmcnt(0)
	flat_store_dwordx4 v[6:7], v[0:3]
	s_nop 1
	v_add_u32_e32 v0, 0x400, v66
	v_ashrrev_i32_e32 v6, 4, v0
	v_mad_u64_u32 v[0:1], s[0:1], v6, s11, v[180:181]
	ds_read_b128 v[0:3], v0
	v_add_u32_e32 v6, s14, v6
	v_ashrrev_i32_e32 v7, 31, v6
	v_lshlrev_b64 v[6:7], 12, v[6:7]
	v_lshl_add_u64 v[6:7], v[4:5], 0, v[6:7]
	s_waitcnt lgkmcnt(0)
	flat_store_dwordx4 v[6:7], v[0:3]
	s_nop 1
	v_add_u32_e32 v0, 0x500, v66
	v_ashrrev_i32_e32 v6, 4, v0
	v_mad_u64_u32 v[0:1], s[0:1], v6, s11, v[180:181]
	ds_read_b128 v[0:3], v0
	v_add_u32_e32 v6, s14, v6
	v_ashrrev_i32_e32 v7, 31, v6
	v_lshlrev_b64 v[6:7], 12, v[6:7]
	v_lshl_add_u64 v[6:7], v[4:5], 0, v[6:7]
	s_waitcnt lgkmcnt(0)
	flat_store_dwordx4 v[6:7], v[0:3]
	s_nop 1
	v_add_u32_e32 v0, 0x600, v66
	v_ashrrev_i32_e32 v6, 4, v0
	v_mad_u64_u32 v[0:1], s[0:1], v6, s11, v[180:181]
	ds_read_b128 v[0:3], v0
	v_add_u32_e32 v6, s14, v6
	v_ashrrev_i32_e32 v7, 31, v6
	v_lshlrev_b64 v[6:7], 12, v[6:7]
	v_lshl_add_u64 v[6:7], v[4:5], 0, v[6:7]
	s_waitcnt lgkmcnt(0)
	flat_store_dwordx4 v[6:7], v[0:3]
	s_nop 1
	v_add_u32_e32 v0, 0x700, v66
	v_ashrrev_i32_e32 v6, 4, v0
	v_mad_u64_u32 v[0:1], s[0:1], v6, s11, v[180:181]
	ds_read_b128 v[0:3], v0
	v_add_u32_e32 v6, s14, v6
	v_ashrrev_i32_e32 v7, 31, v6
	v_lshlrev_b64 v[6:7], 12, v[6:7]
	v_lshl_add_u64 v[4:5], v[4:5], 0, v[6:7]
	v_readlane_b32 s0, v251, 6
	s_waitcnt lgkmcnt(0)
	flat_store_dwordx4 v[4:5], v[0:3]
	s_add_i32 s6, s0, s6
	s_cmpk_lt_i32 s6, 0x400
	v_readlane_b32 s1, v251, 7
	s_cbranch_scc1 .LBB0_564

; DEV int tid_() { int t = threadIdx.x; asm volatile("" : "+v"(t)); return t; }
; template <class FragT, class AccT>
; DEV void gemm_core_t(const char* __restrict__ A, size_t lda_bytes, const char* __restrict__ Bt, size_t ldb_bytes, int kbytes,
;                      int m0, int n0, int Sshift, int dl, char* smem, AccT (&acc)[4][4]) {
;   const int tid = tid_(), lane = tid & 63, wid = tid >> 6, wm = wid >> 1, wn = wid & 1;
;   const int l15 = lane & 15, q = lane >> 4;
;   const int srow = lane >> 3, schunk = (lane & 7) ^ (lane >> 3);
;   const char* ap[4];
;   const char* bp[4];
; #pragma unroll
;   for (int u = 0; u < 4; ++u) {
;     int r = (wid * 4 + u) * 8 + srow;
;     int ar = rowmap(m0 + r, Sshift, dl);
;     ap[u] = A + (size_t)ar * lda_bytes + schunk * 16;
;     bp[u] = Bt + (size_t)(n0 + r) * ldb_bytes + schunk * 16;
;   }
; #pragma unroll
;   for (int i = 0; i < 4; ++i)
; #pragma unroll
;     for (int j = 0; j < 4; ++j) acc[i][j] = AccT{0, 0, 0, 0};
;   const int nk = kbytes >> 7;
;   __syncthreads();
; #pragma unroll
;   for (int u = 0; u < 4; ++u) {
;     __builtin_amdgcn_global_load_lds((const unsigned*)ap[u], (unsigned*)(smem + (wid * 4 + u) * 1024 + lane * 16), 16, 0, 0);
;     __builtin_amdgcn_global_load_lds((const unsigned*)bp[u], (unsigned*)(smem + 16384 + (wid * 4 + u) * 1024 + lane * 16), 16, 0, 0);
;   }
;   const unsigned sbase = (unsigned)(unsigned long)((__attribute__((address_space(3))) char*)smem);
;   const unsigned sq0 = (unsigned)((q ^ (l15 & 7)) << 4);
;   const unsigned a0 = sbase + (unsigned)((wm * 64 + l15) * 128) + sq0;
;   const unsigned b0 = sbase + 16384u + (unsigned)((wn * 32 + l15) * 128) + sq0;
;   asm volatile("s_waitcnt vmcnt(0)" ::: "memory");
;   __syncthreads();
.LBB0_623:
	s_ashr_i32 s4, s16, 3
	s_lshr_b32 s5, s4, 28
	s_add_i32 s5, s4, s5
	s_and_b32 s6, s5, -16
	v_mov_b32_e32 v22, v188
	s_sub_i32 s4, s4, s6
	s_lshl_b32 s6, s16, 1
	ds_read2_b64 v[0:3], v80 offset0:59 offset1:61
	s_and_b32 s6, s6, 14
	v_ashrrev_i32_e32 v24, 6, v22
	s_ashr_i32 s14, s4, 3
	s_lshl_b32 s5, s5, 6
	s_lshl_b32 s4, s4, 7
	v_bfe_u32 v25, v22, 3, 3
	v_lshlrev_b32_e32 v26, 5, v24
	s_add_i32 s15, s14, s6
	s_and_b32 s5, s5, 0xfffffc00
	s_and_b32 s6, s4, 0x380
	v_or_b32_e32 v20, v26, v25
	s_or_b32 s17, s6, s5
	s_lshl_b32 s4, s15, 7
	v_or_b32_e32 v14, 8, v20
	v_or_b32_e32 v18, 16, v20
	v_or_b32_e32 v27, 24, v20
	v_bitop3_b32 v4, v25, v22, 7 bitop3:0x78
	v_add_u32_e32 v8, s17, v20
	v_add_u32_e32 v10, s4, v20
	v_add_u32_e32 v12, s17, v14
	v_add_u32_e32 v16, s17, v18
	v_add_u32_e32 v20, s17, v27
	v_lshlrev_b32_e32 v180, 4, v4
	v_ashrrev_i32_e32 v9, 31, v8
	v_ashrrev_i32_e32 v13, 31, v12
	v_ashrrev_i32_e32 v17, 31, v16
	v_ashrrev_i32_e32 v21, 31, v20
	s_waitcnt lgkmcnt(0)
	v_lshl_add_u64 v[4:5], v[2:3], 0, v[180:181]
	v_lshlrev_b64 v[8:9], 11, v[8:9]
	v_lshlrev_b64 v[12:13], 11, v[12:13]
	v_lshlrev_b64 v[16:17], 11, v[16:17]
	v_lshlrev_b64 v[20:21], 11, v[20:21]
	v_lshl_add_u64 v[8:9], v[4:5], 0, v[8:9]
	v_lshl_add_u64 v[12:13], v[4:5], 0, v[12:13]
	v_add_u32_e32 v14, s4, v14
	v_lshl_add_u64 v[16:17], v[4:5], 0, v[16:17]
	v_add_u32_e32 v18, s4, v18
	v_lshl_add_u64 v[4:5], v[4:5], 0, v[20:21]
	v_add_u32_e32 v20, s4, v27
	v_ashrrev_i32_e32 v11, 31, v10
	v_ashrrev_i32_e32 v15, 31, v14
	v_ashrrev_i32_e32 v19, 31, v18
	v_ashrrev_i32_e32 v21, 31, v20
	v_lshl_add_u64 v[6:7], v[0:1], 0, v[180:181]
	v_lshlrev_b64 v[10:11], 11, v[10:11]
	v_lshlrev_b64 v[14:15], 11, v[14:15]
	v_lshlrev_b64 v[18:19], 11, v[18:19]
	v_lshlrev_b64 v[20:21], 11, v[20:21]
	v_and_b32_e32 v23, 63, v22
	v_lshl_add_u64 v[10:11], v[6:7], 0, v[10:11]
	v_lshl_add_u64 v[14:15], v[6:7], 0, v[14:15]
	v_lshl_add_u64 v[18:19], v[6:7], 0, v[18:19]
	v_lshl_add_u64 v[6:7], v[6:7], 0, v[20:21]
	v_lshlrev_b32_e32 v20, 12, v24
	v_lshl_or_b32 v83, v23, 4, v20
	s_nop 0
	v_readfirstlane_b32 s15, v83
	s_mov_b32 m0, s15
	s_barrier
	global_load_lds_dwordx4 v[8:9], off
	v_add_u32_e32 v8, 0x4000, v83
	s_lshl_b32 s14, s14, 7
	v_readfirstlane_b32 s15, v8
	v_or_b32_e32 v8, 0x400, v83
	s_mov_b32 m0, s15
	v_readfirstlane_b32 s15, v8
	v_add_u32_e32 v8, 0x4400, v83
	global_load_lds_dwordx4 v[10:11], off
	s_mov_b32 m0, s15
	v_readfirstlane_b32 s15, v8
	v_or_b32_e32 v8, 0x800, v83
	global_load_lds_dwordx4 v[12:13], off
	s_mov_b32 m0, s15
	v_readfirstlane_b32 s15, v8
	v_add_u32_e32 v8, 0x4800, v83
	global_load_lds_dwordx4 v[14:15], off
	s_mov_b32 m0, s15
	v_readfirstlane_b32 s15, v8
	v_or_b32_e32 v8, 0xc00, v83
	global_load_lds_dwordx4 v[16:17], off
	s_mov_b32 m0, s15
	v_readfirstlane_b32 s15, v8
	global_load_lds_dwordx4 v[18:19], off
	s_mov_b32 m0, s15
	v_lshl_add_u64 v[0:1], v[0:1], 0, s[46:47]
	global_load_lds_dwordx4 v[4:5], off
	v_add_u32_e32 v4, 0x4c00, v83
	v_lshlrev_b32_e32 v5, 4, v22
	v_readfirstlane_b32 s15, v4
	s_mov_b32 m0, s15
	v_and_b32_e32 v4, 15, v22
	global_load_lds_dwordx4 v[6:7], off
	v_lshrrev_b32_e32 v6, 1, v22
	v_and_or_b32 v6, v6, s44, v4
	s_and_b32 s15, s16, 7
	v_bitop3_b32 v5, v23, s31, v5 bitop3:0x48
	v_lshlrev_b32_e32 v6, 7, v6
	v_and_or_b32 v4, v26, 32, v4
	s_lshl_b32 s15, s15, 8
	v_or_b32_e32 v84, v5, v6
	v_lshl_or_b32 v4, v4, 7, v5
	v_bitop3_b32 v87, v5, 64, v6 bitop3:0x36
	v_or_b32_e32 v6, 24, v25
	s_add_i32 s14, s14, s15
	v_or_b32_e32 v85, 0x4000, v4
	v_bitop3_b32 v86, v4, 64, v219 bitop3:0x36
	v_or_b32_e32 v4, s14, v6
	v_add_u32_e32 v4, v4, v26
	v_ashrrev_i32_e32 v5, 31, v4
	v_lshlrev_b64 v[4:5], 11, v[4:5]
	v_or_b32_e32 v4, v4, v180
	v_lshl_add_u64 v[64:65], v[0:1], 0, v[4:5]
	v_or_b32_e32 v4, s5, v6
	v_or_b32_e32 v4, s6, v4
	v_add_u32_e32 v4, v4, v26
	v_ashrrev_i32_e32 v5, 31, v4
	v_lshlrev_b64 v[4:5], 11, v[4:5]
	v_lshl_add_u64 v[2:3], v[2:3], 0, s[46:47]
	v_or_b32_e32 v4, v4, v180
	v_or_b32_e32 v6, 16, v25
	v_lshl_add_u64 v[66:67], v[2:3], 0, v[4:5]
	v_or_b32_e32 v4, s14, v6
	v_add_u32_e32 v4, v4, v26
	v_ashrrev_i32_e32 v5, 31, v4
	v_lshlrev_b64 v[4:5], 11, v[4:5]
	v_or_b32_e32 v4, v4, v180
	v_lshl_add_u64 v[68:69], v[0:1], 0, v[4:5]
	v_or_b32_e32 v4, s5, v6
	v_or_b32_e32 v4, s6, v4
	v_add_u32_e32 v4, v4, v26
	v_ashrrev_i32_e32 v5, 31, v4
	v_lshlrev_b64 v[4:5], 11, v[4:5]
	v_or_b32_e32 v4, v4, v180
	v_or_b32_e32 v6, 8, v25
	v_lshl_add_u64 v[70:71], v[2:3], 0, v[4:5]
	v_or_b32_e32 v4, s14, v6
	v_add_u32_e32 v4, v4, v26
	v_ashrrev_i32_e32 v5, 31, v4
	v_lshlrev_b64 v[4:5], 11, v[4:5]
	v_or_b32_e32 v4, v4, v180
	v_lshl_add_u64 v[72:73], v[0:1], 0, v[4:5]
	v_or_b32_e32 v4, s5, v6
	v_or_b32_e32 v4, s6, v4
	v_add_u32_e32 v4, v4, v26
	v_ashrrev_i32_e32 v5, 31, v4
	v_lshlrev_b64 v[4:5], 11, v[4:5]
	v_or_b32_e32 v4, v4, v180
	v_lshl_add_u64 v[74:75], v[2:3], 0, v[4:5]
	v_or_b32_e32 v4, s14, v25
	v_add_u32_e32 v4, v4, v26
	v_ashrrev_i32_e32 v5, 31, v4
	v_lshlrev_b64 v[4:5], 11, v[4:5]
	v_or_b32_e32 v4, v4, v180
	v_lshl_add_u64 v[76:77], v[0:1], 0, v[4:5]
	v_or_b32_e32 v0, s5, v25
	v_or_b32_e32 v0, s6, v0
	v_add_u32_e32 v0, v0, v26
	v_ashrrev_i32_e32 v1, 31, v0
	v_lshlrev_b64 v[0:1], 11, v[0:1]
	s_waitcnt vmcnt(0)
; DEV f32x4 mma_step(bf16x8 a, bf16x8 b, f32x4 c) { return MFMA(a, b, c); }
; template <class FragT, class AccT>
; DEV void gemm_core_t(const char* __restrict__ A, size_t lda_bytes, const char* __restrict__ Bt, size_t ldb_bytes, int kbytes,
;                      int m0, int n0, int Sshift, int dl, char* smem, AccT (&acc)[4][4]) {
;     ...
;   for (int kt = 0; kt < nk; ++kt) {
;     const unsigned so = (unsigned)(kt & 1) * 32768u;
;     char* nxt = smem + ((kt + 1) & 1) * 32768;
;     if (kt + 1 < nk) {
; #pragma unroll
;       for (int u = 0; u < 4; ++u) {
;         __builtin_amdgcn_global_load_lds((const unsigned*)(ap[u] + (size_t)(kt + 1) * 128), (unsigned*)(nxt + (wid * 4 + u) * 1024 + lane * 16), 16, 0, 0);
;         __builtin_amdgcn_global_load_lds((const unsigned*)(bp[u] + (size_t)(kt + 1) * 128), (unsigned*)(nxt + 16384 + (wid * 4 + u) * 1024 + lane * 16), 16, 0, 0);
;       }
;     }
;     FragT xa[2][4], wb[2][4];
;     asm volatile(
;         "ds_read_b128 %0, %16\n\t"
;         "ds_read_b128 %1, %16 offset:2048\n\t"
;         "ds_read_b128 %2, %16 offset:4096\n\t"
;         "ds_read_b128 %3, %16 offset:6144\n\t"
;         "ds_read_b128 %4, %18\n\t"
;         "ds_read_b128 %5, %18 offset:2048\n\t"
;         "ds_read_b128 %6, %18 offset:8192\n\t"
;         "ds_read_b128 %7, %18 offset:10240\n\t"
;         "ds_read_b128 %8, %17\n\t"
;         "ds_read_b128 %9, %17 offset:2048\n\t"
;         "ds_read_b128 %10, %17 offset:4096\n\t"
;         "ds_read_b128 %11, %17 offset:6144\n\t"
;         "ds_read_b128 %12, %19\n\t"
;         "ds_read_b128 %13, %19 offset:2048\n\t"
;         "ds_read_b128 %14, %19 offset:8192\n\t"
;         "ds_read_b128 %15, %19 offset:10240\n\t"
;         "s_waitcnt lgkmcnt(8)"
;         : "=&v"(xa[0][0]), "=&v"(xa[0][1]), "=&v"(xa[0][2]), "=&v"(xa[0][3]), "=&v"(wb[0][0]), "=&v"(wb[0][1]), "=&v"(wb[0][2]),
;           "=&v"(wb[0][3]), "=&v"(xa[1][0]), "=&v"(xa[1][1]), "=&v"(xa[1][2]), "=&v"(xa[1][3]), "=&v"(wb[1][0]), "=&v"(wb[1][1]),
;           "=&v"(wb[1][2]), "=&v"(wb[1][3])
;         : "v"(a0 + so), "v"((a0 ^ 64u) + so), "v"(b0 + so), "v"((b0 ^ 64u) + so)
;         : "memory");
;     __builtin_amdgcn_s_setprio(1);
; #pragma unroll
;     for (int i = 0; i < 4; ++i)
; #pragma unroll
;       for (int j = 0; j < 4; ++j) acc[i][j] = mma_step(wb[0][j], xa[0][i], acc[i][j]);
;     asm volatile("s_waitcnt lgkmcnt(0)"
	v_or_b32_e32 v0, v0, v180
	v_lshl_add_u64 v[78:79], v[2:3], 0, v[0:1]
	v_mov_b32_e32 v0, 0
	s_mov_b64 s[14:15], 0
	s_mov_b32 s5, 0x8000
	v_mov_b32_e32 v1, v0
	v_mov_b32_e32 v2, v0
	v_mov_b32_e32 v3, v0
	v_mov_b32_e32 v4, v0
	v_mov_b32_e32 v5, v0
	v_mov_b32_e32 v6, v0
	v_mov_b32_e32 v7, v0
	v_mov_b32_e32 v8, v0
	v_mov_b32_e32 v9, v0
	v_mov_b32_e32 v10, v0
	v_mov_b32_e32 v11, v0
	v_mov_b32_e32 v12, v0
	v_mov_b32_e32 v13, v0
	v_mov_b32_e32 v14, v0
	v_mov_b32_e32 v15, v0
	v_mov_b32_e32 v16, v0
	v_mov_b32_e32 v17, v0
	v_mov_b32_e32 v18, v0
	v_mov_b32_e32 v19, v0
	v_mov_b32_e32 v20, v0
	v_mov_b32_e32 v21, v0
	v_mov_b32_e32 v22, v0
	v_mov_b32_e32 v23, v0
	v_mov_b32_e32 v24, v0
	v_mov_b32_e32 v25, v0
	v_mov_b32_e32 v26, v0
	v_mov_b32_e32 v27, v0
	v_mov_b32_e32 v28, v0
	v_mov_b32_e32 v29, v0
	v_mov_b32_e32 v30, v0
	v_mov_b32_e32 v31, v0
	v_mov_b32_e32 v32, v0
	v_mov_b32_e32 v33, v0
	v_mov_b32_e32 v34, v0
	v_mov_b32_e32 v35, v0
	v_mov_b32_e32 v36, v0
	v_mov_b32_e32 v37, v0
	v_mov_b32_e32 v38, v0
	v_mov_b32_e32 v39, v0
	v_mov_b32_e32 v40, v0
	v_mov_b32_e32 v41, v0
	v_mov_b32_e32 v42, v0
	v_mov_b32_e32 v43, v0
	v_mov_b32_e32 v44, v0
	v_mov_b32_e32 v45, v0
	v_mov_b32_e32 v46, v0
	v_mov_b32_e32 v47, v0
	v_mov_b32_e32 v48, v0
	v_mov_b32_e32 v49, v0
	v_mov_b32_e32 v50, v0
	v_mov_b32_e32 v51, v0
	v_mov_b32_e32 v52, v0
	v_mov_b32_e32 v53, v0
	v_mov_b32_e32 v54, v0
	v_mov_b32_e32 v55, v0
	v_mov_b32_e32 v56, v0
	v_mov_b32_e32 v57, v0
	v_mov_b32_e32 v58, v0
	v_mov_b32_e32 v59, v0
	v_mov_b32_e32 v60, v0
	v_mov_b32_e32 v61, v0
	v_mov_b32_e32 v62, v0
	v_mov_b32_e32 v63, v0
	v_readfirstlane_b32 s64, v78
	v_readfirstlane_b32 s65, v79
	v_readfirstlane_b32 s66, v76
	v_readfirstlane_b32 s67, v77
	v_readfirstlane_b32 s62, v83
	s_sub_u32 s64, s64, 0x80000000
	s_subb_u32 s65, s65, 0
	s_sub_u32 s66, s66, 0x80000000
	s_subb_u32 s67, s67, 0
	v_subrev_u32_e32 v78, s64, v78
	v_subrev_u32_e32 v76, s66, v76
	v_subrev_u32_e32 v74, s64, v74
	v_subrev_u32_e32 v72, s66, v72
	v_subrev_u32_e32 v70, s64, v70
	v_subrev_u32_e32 v68, s66, v68
	v_subrev_u32_e32 v66, s64, v66
	v_subrev_u32_e32 v64, s66, v64
	s_waitcnt vmcnt(0) lgkmcnt(0)
	s_barrier
.LBB0_624:
	s_add_i32 s6, s5, 0xffff8000
	s_and_b32 s6, s6, 0x8000
	v_add_u32_e32 v152, s6, v84
	v_add_u32_e32 v153, s6, v87
	v_or_b32_e32 v154, s6, v85
	v_or_b32_e32 v155, s6, v86
	s_and_b32 s6, s5, 0x8000
	s_add_i32 s6, s6, s62
	s_mov_b32 m0, s6
	ds_read_b128 v[88:91], v152
	global_load_lds_dwordx4 v78, s[64:65]
	ds_read_b128 v[92:95], v152 offset:2048
	s_add_i32 m0, s6, 0x4000
	ds_read_b128 v[96:99], v152 offset:4096
	global_load_lds_dwordx4 v76, s[66:67]
	ds_read_b128 v[100:103], v152 offset:6144
	s_add_i32 m0, s6, 0x400
	ds_read_b128 v[104:107], v154
	global_load_lds_dwordx4 v74, s[64:65]
	ds_read_b128 v[108:111], v154 offset:2048
	s_add_i32 m0, s6, 0x4400
	ds_read_b128 v[112:115], v154 offset:8192
	global_load_lds_dwordx4 v72, s[66:67]
	ds_read_b128 v[116:119], v154 offset:10240
	s_add_i32 m0, s6, 0x800
	ds_read_b128 v[120:123], v153
	global_load_lds_dwordx4 v70, s[64:65]
	ds_read_b128 v[124:127], v153 offset:2048
	s_add_i32 m0, s6, 0x4800
	ds_read_b128 v[128:131], v153 offset:4096
	global_load_lds_dwordx4 v68, s[66:67]
	ds_read_b128 v[132:135], v153 offset:6144
	s_add_i32 m0, s6, 0xc00
	ds_read_b128 v[136:139], v155
	global_load_lds_dwordx4 v66, s[64:65]
	ds_read_b128 v[140:143], v155 offset:2048
	s_add_i32 m0, s6, 0x4c00
	ds_read_b128 v[144:147], v155 offset:8192
	global_load_lds_dwordx4 v64, s[66:67]
	ds_read_b128 v[148:151], v155 offset:10240
	s_waitcnt lgkmcnt(8)
	s_setprio 1
	v_mfma_i32_16x16x64_i8 v[60:63], v[104:107], v[88:91], v[60:63]
	v_mfma_i32_16x16x64_i8 v[56:59], v[108:111], v[88:91], v[56:59]
	v_mfma_i32_16x16x64_i8 v[52:55], v[112:115], v[88:91], v[52:55]
	v_mfma_i32_16x16x64_i8 v[48:51], v[116:119], v[88:91], v[48:51]
	v_mfma_i32_16x16x64_i8 v[44:47], v[104:107], v[92:95], v[44:47]
	v_mfma_i32_16x16x64_i8 v[40:43], v[108:111], v[92:95], v[40:43]
	v_mfma_i32_16x16x64_i8 v[36:39], v[112:115], v[92:95], v[36:39]
	v_mfma_i32_16x16x64_i8 v[32:35], v[116:119], v[92:95], v[32:35]
	v_mfma_i32_16x16x64_i8 v[28:31], v[104:107], v[96:99], v[28:31]
	v_mfma_i32_16x16x64_i8 v[24:27], v[108:111], v[96:99], v[24:27]
	v_mfma_i32_16x16x64_i8 v[20:23], v[112:115], v[96:99], v[20:23]
	v_mfma_i32_16x16x64_i8 v[16:19], v[116:119], v[96:99], v[16:19]
	v_mfma_i32_16x16x64_i8 v[12:15], v[104:107], v[100:103], v[12:15]
	v_mfma_i32_16x16x64_i8 v[8:11], v[108:111], v[100:103], v[8:11]
	v_mfma_i32_16x16x64_i8 v[4:7], v[112:115], v[100:103], v[4:7]
	v_mfma_i32_16x16x64_i8 v[0:3], v[116:119], v[100:103], v[0:3]
	s_waitcnt lgkmcnt(0)
	s_nop 0
	v_mfma_i32_16x16x64_i8 v[60:63], v[136:139], v[120:123], v[60:63]
	v_mfma_i32_16x16x64_i8 v[56:59], v[140:143], v[120:123], v[56:59]
	v_mfma_i32_16x16x64_i8 v[52:55], v[144:147], v[120:123], v[52:55]
	v_mfma_i32_16x16x64_i8 v[48:51], v[148:151], v[120:123], v[48:51]
	v_mfma_i32_16x16x64_i8 v[44:47], v[136:139], v[124:127], v[44:47]
	v_mfma_i32_16x16x64_i8 v[40:43], v[140:143], v[124:127], v[40:43]
	v_mfma_i32_16x16x64_i8 v[36:39], v[144:147], v[124:127], v[36:39]
	v_mfma_i32_16x16x64_i8 v[32:35], v[148:151], v[124:127], v[32:35]
	v_mfma_i32_16x16x64_i8 v[28:31], v[136:139], v[128:131], v[28:31]
	v_mfma_i32_16x16x64_i8 v[24:27], v[140:143], v[128:131], v[24:27]
	v_mfma_i32_16x16x64_i8 v[20:23], v[144:147], v[128:131], v[20:23]
	v_mfma_i32_16x16x64_i8 v[16:19], v[148:151], v[128:131], v[16:19]
	v_mfma_i32_16x16x64_i8 v[12:15], v[136:139], v[132:135], v[12:15]
	v_mfma_i32_16x16x64_i8 v[8:11], v[140:143], v[132:135], v[8:11]
	v_mfma_i32_16x16x64_i8 v[4:7], v[144:147], v[132:135], v[4:7]
	v_mfma_i32_16x16x64_i8 v[0:3], v[148:151], v[132:135], v[0:3]
	s_setprio 0
	s_waitcnt vmcnt(0)
	s_add_u32 s14, s14, 0x80
	s_addc_u32 s15, s15, 0
	s_add_u32 s64, s64, 0x80
	s_addc_u32 s65, s65, 0
	s_add_u32 s66, s66, 0x80
	s_addc_u32 s67, s67, 0
	s_add_i32 s5, s5, 0x8000
	s_cmpk_lg_i32 s14, 0x780
	s_waitcnt vmcnt(0) lgkmcnt(0)
	s_barrier
; template <class FragT, class AccT>
; DEV void gemm_core_t(const char* __restrict__ A, size_t lda_bytes, const char* __restrict__ Bt, size_t ldb_bytes, int kbytes,
;                      int m0, int n0, int Sshift, int dl, char* smem, AccT (&acc)[4][4]) {
;     ...
;     asm volatile(
;         "ds_read_b128 %0, %16\n\t"
;         "ds_read_b128 %1, %16 offset:2048\n\t"
;         "ds_read_b128 %2, %16 offset:4096\n\t"
;         "ds_read_b128 %3, %16 offset:6144\n\t"
;         "ds_read_b128 %4, %18\n\t"
;         "ds_read_b128 %5, %18 offset:2048\n\t"
;         "ds_read_b128 %6, %18 offset:8192\n\t"
;         "ds_read_b128 %7, %18 offset:10240\n\t"
;         "ds_read_b128 %8, %17\n\t"
;         "ds_read_b128 %9, %17 offset:2048\n\t"
;         "ds_read_b128 %10, %17 offset:4096\n\t"
;         "ds_read_b128 %11, %17 offset:6144\n\t"
;         "ds_read_b128 %12, %19\n\t"
;         "ds_read_b128 %13, %19 offset:2048\n\t"
;         "ds_read_b128 %14, %19 offset:8192\n\t"
;         "ds_read_b128 %15, %19 offset:10240\n\t"
;         "s_waitcnt lgkmcnt(8)"
;         : "=&v"(xa[0][0]), "=&v"(xa[0][1]), "=&v"(xa[0][2]), "=&v"(xa[0][3]), "=&v"(wb[0][0]), "=&v"(wb[0][1]), "=&v"(wb[0][2]),
;           "=&v"(wb[0][3]), "=&v"(xa[1][0]), "=&v"(xa[1][1]), "=&v"(xa[1][2]), "=&v"(xa[1][3]), "=&v"(wb[1][0]), "=&v"(wb[1][1]),
;           "=&v"(wb[1][2]), "=&v"(wb[1][3])
;         : "v"(a0 + so), "v"((a0 ^ 64u) + so), "v"(b0 + so), "v"((b0 ^ 64u) + so)
;         : "memory");
;     __builtin_amdgcn_s_setprio(1);
; #pragma unroll
;     for (int i = 0; i < 4; ++i)
; #pragma unroll
;       for (int j = 0; j < 4; ++j) acc[i][j] = mma_step(wb[0][j], xa[0][i], acc[i][j]);
;     asm volatile("s_waitcnt lgkmcnt(0)"
;                  : "+v"(xa[1][0]), "+v"(xa[1][1]), "+v"(xa[1][2]), "+v"(xa[1][3]), "+v"(wb[1][0]), "+v"(wb[1][1]), "+v"(wb[1][2]),
;                    "+v"(wb[1][3]), "+v"(acc[0][0]), "+v"(acc[0][1]), "+v"(acc[0][2]), "+v"(acc[0][3]), "+v"(acc[1][0]),
;                    "+v"(acc[1][1]), "+v"(acc[1][2]), "+v"(acc[1][3]), "+v"(acc[2][0]), "+v"(acc[2][1]), "+v"(acc[2][2]),
;                    "+v"(acc[2][3]), "+v"(acc[3][0]), "+v"(acc[3][1]), "+v"(acc[3][2]), "+v"(acc[3][3])
;                  :
;                  : "memory");
; #pragma unroll
;     for (int i = 0; i < 4; ++i)
; #pragma unroll
;       for (int j = 0; j < 4; ++j) acc[i][j] = mma_step(wb[1][j], xa[1][i], acc[i][j]);
	s_cbranch_scc1 .LBB0_624
	v_add_u32_e32 v83, 0x8000, v84
	v_add_u32_e32 v132, 0x8000, v87
	v_or_b32_e32 v133, 0x8000, v85
	v_or_b32_e32 v134, 0x8000, v86
	ds_read_b128 v[64:67], v83
	ds_read_b128 v[68:71], v83 offset:2048
	ds_read_b128 v[72:75], v83 offset:4096
	ds_read_b128 v[76:79], v83 offset:6144
	ds_read_b128 v[84:87], v133
	ds_read_b128 v[88:91], v133 offset:2048
	ds_read_b128 v[92:95], v133 offset:8192
	ds_read_b128 v[96:99], v133 offset:10240
	ds_read_b128 v[100:103], v132
	ds_read_b128 v[104:107], v132 offset:2048
	ds_read_b128 v[108:111], v132 offset:4096
	ds_read_b128 v[112:115], v132 offset:6144
	ds_read_b128 v[116:119], v134
	ds_read_b128 v[120:123], v134 offset:2048
	ds_read_b128 v[124:127], v134 offset:8192
	ds_read_b128 v[128:131], v134 offset:10240
	s_waitcnt lgkmcnt(8)
	s_setprio 1
	v_mfma_i32_16x16x64_i8 v[60:63], v[84:87], v[64:67], v[60:63]
	v_mfma_i32_16x16x64_i8 v[56:59], v[88:91], v[64:67], v[56:59]
	v_mfma_i32_16x16x64_i8 v[52:55], v[92:95], v[64:67], v[52:55]
	v_mfma_i32_16x16x64_i8 v[48:51], v[96:99], v[64:67], v[48:51]
	v_mfma_i32_16x16x64_i8 v[44:47], v[84:87], v[68:71], v[44:47]
	v_mfma_i32_16x16x64_i8 v[40:43], v[88:91], v[68:71], v[40:43]
	v_mfma_i32_16x16x64_i8 v[36:39], v[92:95], v[68:71], v[36:39]
	v_mfma_i32_16x16x64_i8 v[32:35], v[96:99], v[68:71], v[32:35]
	v_mfma_i32_16x16x64_i8 v[28:31], v[84:87], v[72:75], v[28:31]
	v_mfma_i32_16x16x64_i8 v[24:27], v[88:91], v[72:75], v[24:27]
	v_mfma_i32_16x16x64_i8 v[20:23], v[92:95], v[72:75], v[20:23]
	v_mfma_i32_16x16x64_i8 v[68:71], v[96:99], v[72:75], v[16:19]
	v_mfma_i32_16x16x64_i8 v[72:75], v[84:87], v[76:79], v[12:15]
	v_mfma_i32_16x16x64_i8 v[8:11], v[88:91], v[76:79], v[8:11]
	v_mfma_i32_16x16x64_i8 v[4:7], v[92:95], v[76:79], v[4:7]
	v_mfma_i32_16x16x64_i8 v[0:3], v[96:99], v[76:79], v[0:3]
	s_waitcnt lgkmcnt(0)
	s_nop 0
	v_mfma_i32_16x16x64_i8 v[84:87], v[116:119], v[100:103], v[60:63]
	v_mfma_i32_16x16x64_i8 v[16:19], v[120:123], v[100:103], v[56:59]
	v_mfma_i32_16x16x64_i8 v[12:15], v[124:127], v[100:103], v[52:55]
	v_mfma_i32_16x16x64_i8 v[64:67], v[128:131], v[100:103], v[48:51]
	v_mfma_i32_16x16x64_i8 v[60:63], v[116:119], v[104:107], v[44:47]
	v_mfma_i32_16x16x64_i8 v[56:59], v[120:123], v[104:107], v[40:43]
	v_mfma_i32_16x16x64_i8 v[52:55], v[124:127], v[104:107], v[36:39]
	v_mfma_i32_16x16x64_i8 v[48:51], v[128:131], v[104:107], v[32:35]
	v_mfma_i32_16x16x64_i8 v[44:47], v[116:119], v[108:111], v[28:31]
	v_mfma_i32_16x16x64_i8 v[40:43], v[120:123], v[108:111], v[24:27]
	v_mfma_i32_16x16x64_i8 v[36:39], v[124:127], v[108:111], v[20:23]
	v_mfma_i32_16x16x64_i8 v[32:35], v[128:131], v[108:111], v[68:71]
	v_mfma_i32_16x16x64_i8 v[20:23], v[116:119], v[112:115], v[72:75]
	v_mfma_i32_16x16x64_i8 v[8:11], v[120:123], v[112:115], v[8:11]
	v_mfma_i32_16x16x64_i8 v[4:7], v[124:127], v[112:115], v[4:7]
	v_mfma_i32_16x16x64_i8 v[0:3], v[128:131], v[112:115], v[0:3]
	s_setprio 0
	s_waitcnt vmcnt(0)
	s_barrier
	ds_read2_b64 v[24:27], v80 offset0:54 offset1:56
	v_add_u32_e32 v28, s17, v81
	v_or_b32_e32 v30, s4, v82
	v_ashrrev_i32_e32 v29, 31, v28
	v_ashrrev_i32_e32 v31, 31, v30
	s_waitcnt lgkmcnt(0)
	v_lshl_add_u64 v[68:69], v[28:29], 2, v[26:27]
	v_lshl_add_u64 v[70:71], v[30:31], 2, v[24:25]
	flat_load_dword v78, v[68:69]
	flat_load_dwordx4 v[24:27], v[70:71]
	v_cvt_f32_i32_e32 v28, v84
	v_cvt_f32_i32_e32 v29, v85
	v_cvt_f32_i32_e32 v16, v16
	v_cvt_f32_i32_e32 v17, v17
	v_cvt_f32_i32_e32 v12, v12
	v_cvt_f32_i32_e32 v13, v13
	v_cvt_f32_i32_e32 v64, v64
	v_cvt_f32_i32_e32 v65, v65
	v_cvt_f32_i32_e32 v60, v60
	v_cvt_f32_i32_e32 v61, v61
	v_cvt_f32_i32_e32 v56, v56
	v_cvt_f32_i32_e32 v57, v57
	v_cvt_f32_i32_e32 v52, v52
	v_cvt_f32_i32_e32 v53, v53
	v_cvt_f32_i32_e32 v48, v48
	v_cvt_f32_i32_e32 v49, v49
	v_cvt_f32_i32_e32 v44, v44
	v_cvt_f32_i32_e32 v45, v45
	v_cvt_f32_i32_e32 v40, v40
	v_cvt_f32_i32_e32 v41, v41
	v_cvt_f32_i32_e32 v36, v36
	v_cvt_f32_i32_e32 v37, v37
	v_cvt_f32_i32_e32 v32, v32
	v_cvt_f32_i32_e32 v33, v33
	v_cvt_f32_i32_e32 v20, v20
	v_cvt_f32_i32_e32 v21, v21
	v_cvt_f32_i32_e32 v8, v8
	v_cvt_f32_i32_e32 v9, v9
	v_cvt_f32_i32_e32 v4, v4
	v_cvt_f32_i32_e32 v5, v5
	v_cvt_f32_i32_e32 v0, v0
	v_cvt_f32_i32_e32 v1, v1
	s_mov_b32 s44, 0x1ffffc0
	s_mov_b64 s[46:47], 0x80
	s_waitcnt vmcnt(0) lgkmcnt(0)
	v_mul_f32_e32 v28, v78, v28
	v_mul_f32_e32 v29, v78, v29
	v_mul_f32_e32 v28, v24, v28
	v_mul_f32_e32 v29, v29, v25
	v_mul_f32_e32 v28, 0xbfb8aa3b, v28
	v_mul_f32_e32 v29, 0xbfb8aa3b, v29
	v_exp_f32_e32 v28, v28
	v_exp_f32_e32 v29, v29
	v_mul_f32_e32 v16, v78, v16
	v_mul_f32_e32 v17, v78, v17
	v_mul_f32_e32 v12, v78, v12
	v_pk_add_f32 v[28:29], v[28:29], 1.0 op_sel_hi:[1,0]
	v_mul_f32_e32 v13, v78, v13
	v_div_scale_f32 v30, s[14:15], v29, v29, 1.0
	v_rcp_f32_e32 v31, v30
	v_mul_f32_e32 v64, v78, v64
	v_mul_f32_e32 v65, v78, v65
	v_fma_f32 v72, -v30, v31, 1.0
	v_fmac_f32_e32 v31, v72, v31
	v_div_scale_f32 v72, vcc, 1.0, v29, 1.0
	v_mul_f32_e32 v73, v72, v31
	v_fma_f32 v74, -v30, v73, v72
	v_fmac_f32_e32 v73, v74, v31
	v_fma_f32 v30, -v30, v73, v72
	v_div_fmas_f32 v30, v30, v31, v73
	v_div_fixup_f32 v29, v30, v29, 1.0
	v_div_scale_f32 v30, s[14:15], v28, v28, 1.0
	v_rcp_f32_e32 v31, v30
	s_nop 0
	v_fma_f32 v72, -v30, v31, 1.0
	v_fmac_f32_e32 v31, v72, v31
	v_div_scale_f32 v72, vcc, 1.0, v28, 1.0
	v_mul_f32_e32 v73, v72, v31
	v_fma_f32 v74, -v30, v73, v72
	v_fmac_f32_e32 v73, v74, v31
	v_fma_f32 v30, -v30, v73, v72
	v_div_fmas_f32 v30, v30, v31, v73
	v_div_fixup_f32 v28, v30, v28, 1.0
	v_cvt_pk_bf16_f32 v72, v28, v29
	v_cvt_f32_i32_e32 v28, v86
	v_cvt_f32_i32_e32 v29, v87
	v_mul_f32_e32 v28, v78, v28
	v_mul_f32_e32 v29, v78, v29
	v_mul_f32_e32 v28, v28, v26
	v_mul_f32_e32 v29, v29, v27
	v_mul_f32_e32 v28, 0xbfb8aa3b, v28
	v_mul_f32_e32 v29, 0xbfb8aa3b, v29
	v_exp_f32_e32 v28, v28
	v_exp_f32_e32 v29, v29
	s_nop 0
	v_pk_add_f32 v[28:29], v[28:29], 1.0 op_sel_hi:[1,0]
	s_nop 0
	v_div_scale_f32 v30, s[14:15], v29, v29, 1.0
	v_rcp_f32_e32 v31, v30
	s_nop 0
	v_fma_f32 v73, -v30, v31, 1.0
	v_fmac_f32_e32 v31, v73, v31
	v_div_scale_f32 v73, vcc, 1.0, v29, 1.0
	v_mul_f32_e32 v74, v73, v31
	v_fma_f32 v75, -v30, v74, v73
	v_fmac_f32_e32 v74, v75, v31
	v_fma_f32 v30, -v30, v74, v73
	v_div_fmas_f32 v30, v30, v31, v74
	v_div_fixup_f32 v29, v30, v29, 1.0
	v_div_scale_f32 v30, s[14:15], v28, v28, 1.0
	v_rcp_f32_e32 v31, v30
	s_nop 0
	v_fma_f32 v73, -v30, v31, 1.0
	v_fmac_f32_e32 v31, v73, v31
	v_div_scale_f32 v73, vcc, 1.0, v28, 1.0
	v_mul_f32_e32 v74, v73, v31
	v_fma_f32 v75, -v30, v74, v73
	v_fmac_f32_e32 v74, v75, v31
	v_fma_f32 v30, -v30, v74, v73
	v_div_fmas_f32 v30, v30, v31, v74
	v_div_fixup_f32 v28, v30, v28, 1.0
	v_cvt_pk_bf16_f32 v73, v28, v29
	flat_load_dwordx4 v[28:31], v[70:71] offset:64
	s_waitcnt vmcnt(0) lgkmcnt(0)
; #define P (*launderP(lp))
; DEV float sigm(float x) { return 1.f / (1.f + __expf(-x)); }
; __device__ __forceinline__ void phase_gemm45(PREF P, char* smem, int which) {
;     ...
;         for (int i = 0; i < 4; ++i) {
;           const int row = m0 + wm * 64 + i * 16 + l15;
;     ...
; #pragma unroll
;           for (int j = 0; j < 4; ++j) {
;             const int col = n0 + (j & 1) * 16 + wn * 32 + (j >> 1) * 64 + q * 4;
;             const float4 swc = *(const float4*)(P.swpg + col);
;             part[i][j][0] = pack2(sigm((float)iacc[i][j][0] * shr * swc.x), sigm((float)iacc[i][j][1] * shr * swc.y));
;             part[i][j][1] = pack2(sigm((float)iacc[i][j][2] * shr * swc.z), sigm((float)iacc[i][j][3] * shr * swc.w));
;           }
	v_mul_f32_e32 v16, v16, v28
	v_mul_f32_e32 v17, v17, v29
	v_mul_f32_e32 v16, 0xbfb8aa3b, v16
	v_mul_f32_e32 v17, 0xbfb8aa3b, v17
	v_exp_f32_e32 v16, v16
	v_exp_f32_e32 v17, v17
	s_nop 0
	v_pk_add_f32 v[16:17], v[16:17], 1.0 op_sel_hi:[1,0]
	s_nop 0
	v_div_scale_f32 v74, s[14:15], v17, v17, 1.0
	v_rcp_f32_e32 v75, v74
	s_nop 0
	v_fma_f32 v76, -v74, v75, 1.0
	v_fmac_f32_e32 v75, v76, v75
	v_div_scale_f32 v76, vcc, 1.0, v17, 1.0
	v_mul_f32_e32 v77, v76, v75
	v_fma_f32 v79, -v74, v77, v76
	v_fmac_f32_e32 v77, v79, v75
	v_fma_f32 v74, -v74, v77, v76
	v_div_fmas_f32 v74, v74, v75, v77
	v_div_fixup_f32 v17, v74, v17, 1.0
	v_div_scale_f32 v74, s[14:15], v16, v16, 1.0
	v_rcp_f32_e32 v75, v74
	s_nop 0
	v_fma_f32 v76, -v74, v75, 1.0
	v_fmac_f32_e32 v75, v76, v75
	v_div_scale_f32 v76, vcc, 1.0, v16, 1.0
	v_mul_f32_e32 v77, v76, v75
	v_fma_f32 v79, -v74, v77, v76
	v_fmac_f32_e32 v77, v79, v75
	v_fma_f32 v74, -v74, v77, v76
	v_div_fmas_f32 v74, v74, v75, v77
	v_div_fixup_f32 v16, v74, v16, 1.0
	v_cvt_pk_bf16_f32 v74, v16, v17
	v_cvt_f32_i32_e32 v16, v18
	v_cvt_f32_i32_e32 v17, v19
	v_mul_f32_e32 v16, v78, v16
	v_mul_f32_e32 v17, v78, v17
	v_mul_f32_e32 v16, v16, v30
	v_mul_f32_e32 v17, v17, v31
	v_mul_f32_e32 v16, 0xbfb8aa3b, v16
	v_mul_f32_e32 v17, 0xbfb8aa3b, v17
	v_exp_f32_e32 v16, v16
	v_exp_f32_e32 v17, v17
	s_nop 0
	v_pk_add_f32 v[16:17], v[16:17], 1.0 op_sel_hi:[1,0]
	s_nop 0
	v_div_scale_f32 v18, s[14:15], v17, v17, 1.0
	v_rcp_f32_e32 v19, v18
	s_nop 0
	v_fma_f32 v75, -v18, v19, 1.0
	v_fmac_f32_e32 v19, v75, v19
	v_div_scale_f32 v75, vcc, 1.0, v17, 1.0
	v_mul_f32_e32 v76, v75, v19
	v_fma_f32 v77, -v18, v76, v75
	v_fmac_f32_e32 v76, v77, v19
	v_fma_f32 v18, -v18, v76, v75
	v_div_fmas_f32 v18, v18, v19, v76
	v_div_fixup_f32 v17, v18, v17, 1.0
	v_div_scale_f32 v18, s[14:15], v16, v16, 1.0
	v_rcp_f32_e32 v19, v18
	s_nop 0
	v_fma_f32 v75, -v18, v19, 1.0
	v_fmac_f32_e32 v19, v75, v19
	v_div_scale_f32 v75, vcc, 1.0, v16, 1.0
	v_mul_f32_e32 v76, v75, v19
	v_fma_f32 v77, -v18, v76, v75
	v_fmac_f32_e32 v76, v77, v19
	v_fma_f32 v18, -v18, v76, v75
	v_div_fmas_f32 v18, v18, v19, v76
	v_div_fixup_f32 v16, v18, v16, 1.0
	v_cvt_pk_bf16_f32 v75, v16, v17
	flat_load_dwordx4 v[16:19], v[70:71] offset:256
	s_waitcnt vmcnt(0) lgkmcnt(0)
	v_mul_f32_e32 v12, v12, v16
	v_mul_f32_e32 v13, v13, v17
	v_mul_f32_e32 v12, 0xbfb8aa3b, v12
	v_mul_f32_e32 v13, 0xbfb8aa3b, v13
	v_exp_f32_e32 v12, v12
	v_exp_f32_e32 v13, v13
	s_nop 0
	v_pk_add_f32 v[12:13], v[12:13], 1.0 op_sel_hi:[1,0]
	s_nop 0
	v_div_scale_f32 v76, s[14:15], v13, v13, 1.0
	v_rcp_f32_e32 v77, v76
	s_nop 0
	v_fma_f32 v79, -v76, v77, 1.0
	v_fmac_f32_e32 v77, v79, v77
	v_div_scale_f32 v79, vcc, 1.0, v13, 1.0
	v_mul_f32_e32 v83, v79, v77
	v_fma_f32 v84, -v76, v83, v79
	v_fmac_f32_e32 v83, v84, v77
	v_fma_f32 v76, -v76, v83, v79
	v_div_fmas_f32 v76, v76, v77, v83
	v_div_fixup_f32 v13, v76, v13, 1.0
	v_div_scale_f32 v76, s[14:15], v12, v12, 1.0
	v_rcp_f32_e32 v77, v76
	s_nop 0
	v_fma_f32 v79, -v76, v77, 1.0
	v_fmac_f32_e32 v77, v79, v77
	v_div_scale_f32 v79, vcc, 1.0, v12, 1.0
	v_mul_f32_e32 v83, v79, v77
	v_fma_f32 v84, -v76, v83, v79
	v_fmac_f32_e32 v83, v84, v77
	v_fma_f32 v76, -v76, v83, v79
	v_div_fmas_f32 v76, v76, v77, v83
	v_div_fixup_f32 v12, v76, v12, 1.0
	v_cvt_pk_bf16_f32 v76, v12, v13
	v_cvt_f32_i32_e32 v12, v14
	v_cvt_f32_i32_e32 v13, v15
	v_mul_f32_e32 v12, v78, v12
	v_mul_f32_e32 v13, v78, v13
	v_mul_f32_e32 v12, v12, v18
	v_mul_f32_e32 v13, v13, v19
	v_mul_f32_e32 v12, 0xbfb8aa3b, v12
	v_mul_f32_e32 v13, 0xbfb8aa3b, v13
	v_exp_f32_e32 v12, v12
	v_exp_f32_e32 v13, v13
	s_nop 0
	v_pk_add_f32 v[12:13], v[12:13], 1.0 op_sel_hi:[1,0]
	s_nop 0
	v_div_scale_f32 v14, s[14:15], v13, v13, 1.0
	v_rcp_f32_e32 v15, v14
	s_nop 0
	v_fma_f32 v77, -v14, v15, 1.0
	v_fmac_f32_e32 v15, v77, v15
	v_div_scale_f32 v77, vcc, 1.0, v13, 1.0
	v_mul_f32_e32 v79, v77, v15
	v_fma_f32 v83, -v14, v79, v77
	v_fmac_f32_e32 v79, v83, v15
	v_fma_f32 v14, -v14, v79, v77
	v_div_fmas_f32 v14, v14, v15, v79
	v_div_fixup_f32 v13, v14, v13, 1.0
	v_div_scale_f32 v14, s[14:15], v12, v12, 1.0
	v_rcp_f32_e32 v15, v14
	s_nop 0
	v_fma_f32 v77, -v14, v15, 1.0
	v_fmac_f32_e32 v15, v77, v15
	v_div_scale_f32 v77, vcc, 1.0, v12, 1.0
	v_mul_f32_e32 v79, v77, v15
	v_fma_f32 v83, -v14, v79, v77
	v_fmac_f32_e32 v79, v83, v15
	v_fma_f32 v14, -v14, v79, v77
	v_div_fmas_f32 v14, v14, v15, v79
	v_div_fixup_f32 v12, v14, v12, 1.0
	v_cvt_pk_bf16_f32 v77, v12, v13
	flat_load_dwordx4 v[12:15], v[70:71] offset:320
	s_waitcnt vmcnt(0) lgkmcnt(0)
	v_mul_f32_e32 v64, v64, v12
	v_mul_f32_e32 v65, v65, v13
	v_mul_f32_e32 v64, 0xbfb8aa3b, v64
	v_mul_f32_e32 v65, 0xbfb8aa3b, v65
	v_exp_f32_e32 v64, v64
	v_exp_f32_e32 v65, v65
	s_nop 0
	v_pk_add_f32 v[64:65], v[64:65], 1.0 op_sel_hi:[1,0]
	s_nop 0
	v_div_scale_f32 v70, s[14:15], v65, v65, 1.0
	v_rcp_f32_e32 v71, v70
	s_nop 0
	v_fma_f32 v79, -v70, v71, 1.0
	v_fmac_f32_e32 v71, v79, v71
	v_div_scale_f32 v79, vcc, 1.0, v65, 1.0
	v_mul_f32_e32 v83, v79, v71
	v_fma_f32 v84, -v70, v83, v79
	v_fmac_f32_e32 v83, v84, v71
	v_fma_f32 v70, -v70, v83, v79
	v_div_fmas_f32 v70, v70, v71, v83
	v_div_fixup_f32 v65, v70, v65, 1.0
	v_div_scale_f32 v70, s[14:15], v64, v64, 1.0
	v_rcp_f32_e32 v71, v70
	s_nop 0
	v_fma_f32 v79, -v70, v71, 1.0
	v_fmac_f32_e32 v71, v79, v71
	v_div_scale_f32 v79, vcc, 1.0, v64, 1.0
	v_mul_f32_e32 v83, v79, v71
	v_fma_f32 v84, -v70, v83, v79
	v_fmac_f32_e32 v83, v84, v71
	v_fma_f32 v70, -v70, v83, v79
	v_div_fmas_f32 v70, v70, v71, v83
	v_div_fixup_f32 v64, v70, v64, 1.0
	v_cvt_pk_bf16_f32 v64, v64, v65
	v_cvt_f32_i32_e32 v65, v66
	v_mul_f32_e32 v65, v78, v65
	v_mul_f32_e32 v65, v65, v14
	v_mul_f32_e32 v65, 0xbfb8aa3b, v65
	v_exp_f32_e32 v66, v65
	v_cvt_f32_i32_e32 v65, v67
	v_mul_f32_e32 v65, v78, v65
	v_mul_f32_e32 v65, v65, v15
	v_mul_f32_e32 v65, 0xbfb8aa3b, v65
	v_exp_f32_e32 v67, v65
	s_nop 0
	v_pk_add_f32 v[66:67], v[66:67], 1.0 op_sel_hi:[1,0]
	s_nop 0
	v_div_scale_f32 v65, s[14:15], v67, v67, 1.0
	v_rcp_f32_e32 v70, v65
	s_nop 0
	v_fma_f32 v71, -v65, v70, 1.0
	v_fmac_f32_e32 v70, v71, v70
	v_div_scale_f32 v71, vcc, 1.0, v67, 1.0
	v_mul_f32_e32 v78, v71, v70
	v_fma_f32 v79, -v65, v78, v71
	v_fmac_f32_e32 v78, v79, v70
	v_fma_f32 v65, -v65, v78, v71
	v_div_fmas_f32 v65, v65, v70, v78
	v_div_fixup_f32 v65, v65, v67, 1.0
	v_div_scale_f32 v67, s[14:15], v66, v66, 1.0
	v_rcp_f32_e32 v70, v67
	s_nop 0
	v_fma_f32 v71, -v67, v70, 1.0
	v_fmac_f32_e32 v70, v71, v70
	v_div_scale_f32 v71, vcc, 1.0, v66, 1.0
	v_mul_f32_e32 v78, v71, v70
	v_fma_f32 v79, -v67, v78, v71
	v_fmac_f32_e32 v78, v79, v70
	v_fma_f32 v67, -v67, v78, v71
	v_div_fmas_f32 v67, v67, v70, v78
	v_div_fixup_f32 v66, v67, v66, 1.0
	v_cvt_pk_bf16_f32 v65, v66, v65
	flat_load_dword v66, v[68:69] offset:64
	s_waitcnt vmcnt(0) lgkmcnt(0)
; #define P (*launderP(lp))
; DEV float sigm(float x) { return 1.f / (1.f + __expf(-x)); }
; __device__ __forceinline__ void phase_gemm45(PREF P, char* smem, int which) {
;     ...
;         for (int i = 0; i < 4; ++i) {
;           const int row = m0 + wm * 64 + i * 16 + l15;
;     ...
; #pragma unroll
;           for (int j = 0; j < 4; ++j) {
;             const int col = n0 + (j & 1) * 16 + wn * 32 + (j >> 1) * 64 + q * 4;
;             const float4 swc = *(const float4*)(P.swpg + col);
;             part[i][j][0] = pack2(sigm((float)iacc[i][j][0] * shr * swc.x), sigm((float)iacc[i][j][1] * shr * swc.y));
;             part[i][j][1] = pack2(sigm((float)iacc[i][j][2] * shr * swc.z), sigm((float)iacc[i][j][3] * shr * swc.w));
;           }
	v_mul_f32_e32 v60, v66, v60
	v_mul_f32_e32 v61, v66, v61
	v_mul_f32_e32 v60, v24, v60
	v_mul_f32_e32 v61, v25, v61
	v_mul_f32_e32 v60, 0xbfb8aa3b, v60
	v_mul_f32_e32 v61, 0xbfb8aa3b, v61
	v_exp_f32_e32 v60, v60
	v_exp_f32_e32 v61, v61
	v_mul_f32_e32 v56, v66, v56
	v_mul_f32_e32 v57, v66, v57
	v_mul_f32_e32 v56, v28, v56
	v_pk_add_f32 v[60:61], v[60:61], 1.0 op_sel_hi:[1,0]
	v_mul_f32_e32 v57, v29, v57
	v_div_scale_f32 v67, s[14:15], v61, v61, 1.0
	v_rcp_f32_e32 v70, v67
	v_mul_f32_e32 v56, 0xbfb8aa3b, v56
	v_mul_f32_e32 v57, 0xbfb8aa3b, v57
	v_exp_f32_e32 v56, v56
	v_fma_f32 v71, -v67, v70, 1.0
	v_fmac_f32_e32 v70, v71, v70
	v_div_scale_f32 v71, vcc, 1.0, v61, 1.0
	v_mul_f32_e32 v78, v71, v70
	v_fma_f32 v79, -v67, v78, v71
	v_fmac_f32_e32 v78, v79, v70
	v_fma_f32 v67, -v67, v78, v71
	v_div_fmas_f32 v67, v67, v70, v78
	v_div_fixup_f32 v61, v67, v61, 1.0
	v_div_scale_f32 v67, s[14:15], v60, v60, 1.0
	v_rcp_f32_e32 v70, v67
	v_exp_f32_e32 v57, v57
	v_mul_f32_e32 v52, v66, v52
	v_mul_f32_e32 v53, v66, v53
	v_fma_f32 v71, -v67, v70, 1.0
	v_fmac_f32_e32 v70, v71, v70
	v_div_scale_f32 v71, vcc, 1.0, v60, 1.0
	v_mul_f32_e32 v78, v71, v70
	v_fma_f32 v79, -v67, v78, v71
	v_fmac_f32_e32 v78, v79, v70
	v_fma_f32 v67, -v67, v78, v71
	v_div_fmas_f32 v67, v67, v70, v78
	v_div_fixup_f32 v60, v67, v60, 1.0
	v_cvt_pk_bf16_f32 v60, v60, v61
	v_cvt_f32_i32_e32 v61, v62
	v_pk_add_f32 v[56:57], v[56:57], 1.0 op_sel_hi:[1,0]
	v_mul_f32_e32 v52, v16, v52
	v_mul_f32_e32 v53, v17, v53
	v_mul_f32_e32 v61, v66, v61
	v_mul_f32_e32 v61, v26, v61
	v_mul_f32_e32 v61, 0xbfb8aa3b, v61
	v_exp_f32_e32 v62, v61
	v_cvt_f32_i32_e32 v61, v63
	v_mul_f32_e32 v52, 0xbfb8aa3b, v52
	v_mul_f32_e32 v53, 0xbfb8aa3b, v53
	v_exp_f32_e32 v52, v52
	v_mul_f32_e32 v61, v66, v61
	v_mul_f32_e32 v61, v27, v61
	v_mul_f32_e32 v61, 0xbfb8aa3b, v61
	v_exp_f32_e32 v63, v61
	v_exp_f32_e32 v53, v53
	v_mul_f32_e32 v48, v66, v48
	v_mul_f32_e32 v49, v66, v49
	v_pk_add_f32 v[62:63], v[62:63], 1.0 op_sel_hi:[1,0]
	v_pk_add_f32 v[52:53], v[52:53], 1.0 op_sel_hi:[1,0]
	v_div_scale_f32 v61, s[14:15], v63, v63, 1.0
	v_rcp_f32_e32 v67, v61
	v_mul_f32_e32 v48, v12, v48
	v_mul_f32_e32 v49, v13, v49
	v_mul_f32_e32 v48, 0xbfb8aa3b, v48
	v_fma_f32 v70, -v61, v67, 1.0
	v_fmac_f32_e32 v67, v70, v67
	v_div_scale_f32 v70, vcc, 1.0, v63, 1.0
	v_mul_f32_e32 v71, v70, v67
	v_fma_f32 v78, -v61, v71, v70
	v_fmac_f32_e32 v71, v78, v67
	v_fma_f32 v61, -v61, v71, v70
	v_div_fmas_f32 v61, v61, v67, v71
	v_div_fixup_f32 v61, v61, v63, 1.0
	v_div_scale_f32 v63, s[14:15], v62, v62, 1.0
	v_rcp_f32_e32 v67, v63
	v_mul_f32_e32 v49, 0xbfb8aa3b, v49
	v_exp_f32_e32 v48, v48
	v_exp_f32_e32 v49, v49
	v_fma_f32 v70, -v63, v67, 1.0
	v_fmac_f32_e32 v67, v70, v67
	v_div_scale_f32 v70, vcc, 1.0, v62, 1.0
	v_mul_f32_e32 v71, v70, v67
	v_fma_f32 v78, -v63, v71, v70
	v_fmac_f32_e32 v71, v78, v67
	v_fma_f32 v63, -v63, v71, v70
	v_div_fmas_f32 v63, v63, v67, v71
	v_div_fixup_f32 v62, v63, v62, 1.0
	v_cvt_pk_bf16_f32 v61, v62, v61
	v_div_scale_f32 v62, s[14:15], v57, v57, 1.0
	v_rcp_f32_e32 v63, v62
	v_pk_add_f32 v[48:49], v[48:49], 1.0 op_sel_hi:[1,0]
	v_fma_f32 v67, -v62, v63, 1.0
	v_fmac_f32_e32 v63, v67, v63
	v_div_scale_f32 v67, vcc, 1.0, v57, 1.0
	v_mul_f32_e32 v70, v67, v63
	v_fma_f32 v71, -v62, v70, v67
	v_fmac_f32_e32 v70, v71, v63
	v_fma_f32 v62, -v62, v70, v67
	v_div_fmas_f32 v62, v62, v63, v70
	v_div_fixup_f32 v57, v62, v57, 1.0
	v_div_scale_f32 v62, s[14:15], v56, v56, 1.0
	v_rcp_f32_e32 v63, v62
	s_nop 0
	v_fma_f32 v67, -v62, v63, 1.0
	v_fmac_f32_e32 v63, v67, v63
	v_div_scale_f32 v67, vcc, 1.0, v56, 1.0
	v_mul_f32_e32 v70, v67, v63
	v_fma_f32 v71, -v62, v70, v67
	v_fmac_f32_e32 v70, v71, v63
	v_fma_f32 v62, -v62, v70, v67
	v_div_fmas_f32 v62, v62, v63, v70
	v_div_fixup_f32 v56, v62, v56, 1.0
	v_cvt_pk_bf16_f32 v56, v56, v57
	v_cvt_f32_i32_e32 v57, v58
	v_mul_f32_e32 v57, v66, v57
	v_mul_f32_e32 v57, v30, v57
	v_mul_f32_e32 v57, 0xbfb8aa3b, v57
	v_exp_f32_e32 v58, v57
	v_cvt_f32_i32_e32 v57, v59
	v_mul_f32_e32 v57, v66, v57
	v_mul_f32_e32 v57, v31, v57
	v_mul_f32_e32 v57, 0xbfb8aa3b, v57
	v_exp_f32_e32 v59, v57
	s_nop 0
	v_pk_add_f32 v[58:59], v[58:59], 1.0 op_sel_hi:[1,0]
	s_nop 0
	v_div_scale_f32 v57, s[14:15], v59, v59, 1.0
	v_rcp_f32_e32 v62, v57
	s_nop 0
	v_fma_f32 v63, -v57, v62, 1.0
	v_fmac_f32_e32 v62, v63, v62
	v_div_scale_f32 v63, vcc, 1.0, v59, 1.0
	v_mul_f32_e32 v67, v63, v62
	v_fma_f32 v70, -v57, v67, v63
	v_fmac_f32_e32 v67, v70, v62
	v_fma_f32 v57, -v57, v67, v63
	v_div_fmas_f32 v57, v57, v62, v67
	v_div_fixup_f32 v57, v57, v59, 1.0
	v_div_scale_f32 v59, s[14:15], v58, v58, 1.0
	v_rcp_f32_e32 v62, v59
	s_nop 0
	v_fma_f32 v63, -v59, v62, 1.0
	v_fmac_f32_e32 v62, v63, v62
	v_div_scale_f32 v63, vcc, 1.0, v58, 1.0
	v_mul_f32_e32 v67, v63, v62
	v_fma_f32 v70, -v59, v67, v63
	v_fmac_f32_e32 v67, v70, v62
	v_fma_f32 v59, -v59, v67, v63
	v_div_fmas_f32 v59, v59, v62, v67
	v_div_fixup_f32 v58, v59, v58, 1.0
	v_cvt_pk_bf16_f32 v57, v58, v57
	v_div_scale_f32 v58, s[14:15], v53, v53, 1.0
	v_rcp_f32_e32 v59, v58
	s_nop 0
	v_fma_f32 v62, -v58, v59, 1.0
	v_fmac_f32_e32 v59, v62, v59
	v_div_scale_f32 v62, vcc, 1.0, v53, 1.0
	v_mul_f32_e32 v63, v62, v59
	v_fma_f32 v67, -v58, v63, v62
	v_fmac_f32_e32 v63, v67, v59
	v_fma_f32 v58, -v58, v63, v62
	v_div_fmas_f32 v58, v58, v59, v63
	v_div_fixup_f32 v53, v58, v53, 1.0
	v_div_scale_f32 v58, s[14:15], v52, v52, 1.0
	v_rcp_f32_e32 v59, v58
	s_nop 0
	v_fma_f32 v62, -v58, v59, 1.0
	v_fmac_f32_e32 v59, v62, v59
	v_div_scale_f32 v62, vcc, 1.0, v52, 1.0
	v_mul_f32_e32 v63, v62, v59
	v_fma_f32 v67, -v58, v63, v62
	v_fmac_f32_e32 v63, v67, v59
	v_fma_f32 v58, -v58, v63, v62
	v_div_fmas_f32 v58, v58, v59, v63
; #define P (*launderP(lp))
; DEV float sigm(float x) { return 1.f / (1.f + __expf(-x)); }
; __device__ __forceinline__ void phase_gemm45(PREF P, char* smem, int which) {
;     ...
;         for (int i = 0; i < 4; ++i) {
;           const int row = m0 + wm * 64 + i * 16 + l15;
;     ...
; #pragma unroll
;           for (int j = 0; j < 4; ++j) {
;             const int col = n0 + (j & 1) * 16 + wn * 32 + (j >> 1) * 64 + q * 4;
;             const float4 swc = *(const float4*)(P.swpg + col);
;             part[i][j][0] = pack2(sigm((float)iacc[i][j][0] * shr * swc.x), sigm((float)iacc[i][j][1] * shr * swc.y));
;             part[i][j][1] = pack2(sigm((float)iacc[i][j][2] * shr * swc.z), sigm((float)iacc[i][j][3] * shr * swc.w));
;           }
	v_div_fixup_f32 v52, v58, v52, 1.0
	v_cvt_pk_bf16_f32 v52, v52, v53
	v_cvt_f32_i32_e32 v53, v54
	v_mul_f32_e32 v53, v66, v53
	v_mul_f32_e32 v53, v18, v53
	v_mul_f32_e32 v53, 0xbfb8aa3b, v53
	v_exp_f32_e32 v54, v53
	v_cvt_f32_i32_e32 v53, v55
	v_mul_f32_e32 v53, v66, v53
	v_mul_f32_e32 v53, v19, v53
	v_mul_f32_e32 v53, 0xbfb8aa3b, v53
	v_exp_f32_e32 v55, v53
	s_nop 0
	v_pk_add_f32 v[54:55], v[54:55], 1.0 op_sel_hi:[1,0]
	s_nop 0
	v_div_scale_f32 v53, s[14:15], v55, v55, 1.0
	v_rcp_f32_e32 v58, v53
	s_nop 0
	v_fma_f32 v59, -v53, v58, 1.0
	v_fmac_f32_e32 v58, v59, v58
	v_div_scale_f32 v59, vcc, 1.0, v55, 1.0
	v_mul_f32_e32 v62, v59, v58
	v_fma_f32 v63, -v53, v62, v59
	v_fmac_f32_e32 v62, v63, v58
	v_fma_f32 v53, -v53, v62, v59
	v_div_fmas_f32 v53, v53, v58, v62
	v_div_fixup_f32 v53, v53, v55, 1.0
	v_div_scale_f32 v55, s[14:15], v54, v54, 1.0
	v_rcp_f32_e32 v58, v55
	s_nop 0
	v_fma_f32 v59, -v55, v58, 1.0
	v_fmac_f32_e32 v58, v59, v58
	v_div_scale_f32 v59, vcc, 1.0, v54, 1.0
	v_mul_f32_e32 v62, v59, v58
	v_fma_f32 v63, -v55, v62, v59
	v_fmac_f32_e32 v62, v63, v58
	v_fma_f32 v55, -v55, v62, v59
	v_div_fmas_f32 v55, v55, v58, v62
	v_div_fixup_f32 v54, v55, v54, 1.0
	v_cvt_pk_bf16_f32 v53, v54, v53
	v_div_scale_f32 v54, s[14:15], v49, v49, 1.0
	v_rcp_f32_e32 v55, v54
	s_nop 0
	v_fma_f32 v58, -v54, v55, 1.0
	v_fmac_f32_e32 v55, v58, v55
	v_div_scale_f32 v58, vcc, 1.0, v49, 1.0
	v_mul_f32_e32 v59, v58, v55
	v_fma_f32 v62, -v54, v59, v58
	v_fmac_f32_e32 v59, v62, v55
	v_fma_f32 v54, -v54, v59, v58
	v_div_fmas_f32 v54, v54, v55, v59
	v_div_fixup_f32 v49, v54, v49, 1.0
	v_div_scale_f32 v54, s[14:15], v48, v48, 1.0
	v_rcp_f32_e32 v55, v54
	s_nop 0
	v_fma_f32 v58, -v54, v55, 1.0
	v_fmac_f32_e32 v55, v58, v55
	v_div_scale_f32 v58, vcc, 1.0, v48, 1.0
	v_mul_f32_e32 v59, v58, v55
	v_fma_f32 v62, -v54, v59, v58
	v_fmac_f32_e32 v59, v62, v55
	v_fma_f32 v54, -v54, v59, v58
	v_div_fmas_f32 v54, v54, v55, v59
	v_div_fixup_f32 v48, v54, v48, 1.0
	v_cvt_pk_bf16_f32 v48, v48, v49
	v_cvt_f32_i32_e32 v49, v50
	v_mul_f32_e32 v49, v66, v49
	v_mul_f32_e32 v49, v14, v49
	v_mul_f32_e32 v49, 0xbfb8aa3b, v49
	v_exp_f32_e32 v50, v49
	v_cvt_f32_i32_e32 v49, v51
	v_mul_f32_e32 v49, v66, v49
	v_mul_f32_e32 v49, v15, v49
	v_mul_f32_e32 v49, 0xbfb8aa3b, v49
	v_exp_f32_e32 v51, v49
	s_nop 0
	v_pk_add_f32 v[50:51], v[50:51], 1.0 op_sel_hi:[1,0]
	s_nop 0
	v_div_scale_f32 v49, s[14:15], v51, v51, 1.0
	v_rcp_f32_e32 v54, v49
	s_nop 0
	v_fma_f32 v55, -v49, v54, 1.0
	v_fmac_f32_e32 v54, v55, v54
	v_div_scale_f32 v55, vcc, 1.0, v51, 1.0
	v_mul_f32_e32 v58, v55, v54
	v_fma_f32 v59, -v49, v58, v55
	v_fmac_f32_e32 v58, v59, v54
	v_fma_f32 v49, -v49, v58, v55
	v_div_fmas_f32 v49, v49, v54, v58
	v_div_fixup_f32 v49, v49, v51, 1.0
	v_div_scale_f32 v51, s[14:15], v50, v50, 1.0
	v_rcp_f32_e32 v54, v51
	s_nop 0
	v_fma_f32 v55, -v51, v54, 1.0
	v_fmac_f32_e32 v54, v55, v54
	v_div_scale_f32 v55, vcc, 1.0, v50, 1.0
	v_mul_f32_e32 v58, v55, v54
	v_fma_f32 v59, -v51, v58, v55
	v_fmac_f32_e32 v58, v59, v54
	v_fma_f32 v51, -v51, v58, v55
	v_div_fmas_f32 v51, v51, v54, v58
	v_div_fixup_f32 v50, v51, v50, 1.0
	v_cvt_pk_bf16_f32 v49, v50, v49
	flat_load_dword v50, v[68:69] offset:128
	s_waitcnt vmcnt(0) lgkmcnt(0)
	v_mul_f32_e32 v44, v50, v44
	v_mul_f32_e32 v45, v50, v45
	v_mul_f32_e32 v44, v24, v44
	v_mul_f32_e32 v45, v25, v45
	v_mul_f32_e32 v44, 0xbfb8aa3b, v44
	v_mul_f32_e32 v45, 0xbfb8aa3b, v45
	v_exp_f32_e32 v44, v44
	v_exp_f32_e32 v45, v45
	v_mul_f32_e32 v40, v50, v40
	v_mul_f32_e32 v41, v50, v41
	v_mul_f32_e32 v40, v28, v40
	v_pk_add_f32 v[44:45], v[44:45], 1.0 op_sel_hi:[1,0]
	v_mul_f32_e32 v41, v29, v41
	v_div_scale_f32 v51, s[14:15], v45, v45, 1.0
	v_rcp_f32_e32 v54, v51
	v_mul_f32_e32 v40, 0xbfb8aa3b, v40
	v_mul_f32_e32 v41, 0xbfb8aa3b, v41
	v_exp_f32_e32 v40, v40
	v_fma_f32 v55, -v51, v54, 1.0
	v_fmac_f32_e32 v54, v55, v54
	v_div_scale_f32 v55, vcc, 1.0, v45, 1.0
	v_mul_f32_e32 v58, v55, v54
	v_fma_f32 v59, -v51, v58, v55
	v_fmac_f32_e32 v58, v59, v54
	v_fma_f32 v51, -v51, v58, v55
	v_div_fmas_f32 v51, v51, v54, v58
	v_div_fixup_f32 v45, v51, v45, 1.0
	v_div_scale_f32 v51, s[14:15], v44, v44, 1.0
	v_rcp_f32_e32 v54, v51
	v_exp_f32_e32 v41, v41
	v_mul_f32_e32 v36, v50, v36
	v_mul_f32_e32 v37, v50, v37
	v_fma_f32 v55, -v51, v54, 1.0
	v_fmac_f32_e32 v54, v55, v54
	v_div_scale_f32 v55, vcc, 1.0, v44, 1.0
	v_mul_f32_e32 v58, v55, v54
	v_fma_f32 v59, -v51, v58, v55
	v_fmac_f32_e32 v58, v59, v54
	v_fma_f32 v51, -v51, v58, v55
	v_div_fmas_f32 v51, v51, v54, v58
	v_div_fixup_f32 v44, v51, v44, 1.0
	v_cvt_pk_bf16_f32 v44, v44, v45
	v_cvt_f32_i32_e32 v45, v46
	v_pk_add_f32 v[40:41], v[40:41], 1.0 op_sel_hi:[1,0]
	v_mul_f32_e32 v36, v16, v36
	v_mul_f32_e32 v37, v17, v37
	v_mul_f32_e32 v45, v50, v45
	v_mul_f32_e32 v45, v26, v45
	v_mul_f32_e32 v45, 0xbfb8aa3b, v45
	v_exp_f32_e32 v46, v45
	v_cvt_f32_i32_e32 v45, v47
	v_mul_f32_e32 v36, 0xbfb8aa3b, v36
	v_mul_f32_e32 v37, 0xbfb8aa3b, v37
	v_exp_f32_e32 v36, v36
	v_mul_f32_e32 v45, v50, v45
	v_mul_f32_e32 v45, v27, v45
	v_mul_f32_e32 v45, 0xbfb8aa3b, v45
	v_exp_f32_e32 v47, v45
	v_exp_f32_e32 v37, v37
	v_mul_f32_e32 v32, v50, v32
	v_mul_f32_e32 v33, v50, v33
	v_pk_add_f32 v[46:47], v[46:47], 1.0 op_sel_hi:[1,0]
	v_pk_add_f32 v[36:37], v[36:37], 1.0 op_sel_hi:[1,0]
	v_div_scale_f32 v45, s[14:15], v47, v47, 1.0
	v_rcp_f32_e32 v51, v45
	v_mul_f32_e32 v32, v12, v32
	v_mul_f32_e32 v33, v13, v33
	v_mul_f32_e32 v32, 0xbfb8aa3b, v32
	v_fma_f32 v54, -v45, v51, 1.0
	v_fmac_f32_e32 v51, v54, v51
	v_div_scale_f32 v54, vcc, 1.0, v47, 1.0
	v_mul_f32_e32 v55, v54, v51
	v_fma_f32 v58, -v45, v55, v54
	v_fmac_f32_e32 v55, v58, v51
	v_fma_f32 v45, -v45, v55, v54
; #define P (*launderP(lp))
; DEV float sigm(float x) { return 1.f / (1.f + __expf(-x)); }
; __device__ __forceinline__ void phase_gemm45(PREF P, char* smem, int which) {
;     ...
;         for (int i = 0; i < 4; ++i) {
;           const int row = m0 + wm * 64 + i * 16 + l15;
;     ...
; #pragma unroll
;           for (int j = 0; j < 4; ++j) {
;             const int col = n0 + (j & 1) * 16 + wn * 32 + (j >> 1) * 64 + q * 4;
;             const float4 swc = *(const float4*)(P.swpg + col);
;             part[i][j][0] = pack2(sigm((float)iacc[i][j][0] * shr * swc.x), sigm((float)iacc[i][j][1] * shr * swc.y));
;             part[i][j][1] = pack2(sigm((float)iacc[i][j][2] * shr * swc.z), sigm((float)iacc[i][j][3] * shr * swc.w));
;           }
	v_div_fmas_f32 v45, v45, v51, v55
	v_div_fixup_f32 v45, v45, v47, 1.0
	v_div_scale_f32 v47, s[14:15], v46, v46, 1.0
	v_rcp_f32_e32 v51, v47
	v_mul_f32_e32 v33, 0xbfb8aa3b, v33
	v_exp_f32_e32 v32, v32
	v_exp_f32_e32 v33, v33
	v_fma_f32 v54, -v47, v51, 1.0
	v_fmac_f32_e32 v51, v54, v51
	v_div_scale_f32 v54, vcc, 1.0, v46, 1.0
	v_mul_f32_e32 v55, v54, v51
	v_fma_f32 v58, -v47, v55, v54
	v_fmac_f32_e32 v55, v58, v51
	v_fma_f32 v47, -v47, v55, v54
	v_div_fmas_f32 v47, v47, v51, v55
	v_div_fixup_f32 v46, v47, v46, 1.0
	v_cvt_pk_bf16_f32 v45, v46, v45
	v_div_scale_f32 v46, s[14:15], v41, v41, 1.0
	v_rcp_f32_e32 v47, v46
	v_pk_add_f32 v[32:33], v[32:33], 1.0 op_sel_hi:[1,0]
	v_fma_f32 v51, -v46, v47, 1.0
	v_fmac_f32_e32 v47, v51, v47
	v_div_scale_f32 v51, vcc, 1.0, v41, 1.0
	v_mul_f32_e32 v54, v51, v47
	v_fma_f32 v55, -v46, v54, v51
	v_fmac_f32_e32 v54, v55, v47
	v_fma_f32 v46, -v46, v54, v51
	v_div_fmas_f32 v46, v46, v47, v54
	v_div_fixup_f32 v41, v46, v41, 1.0
	v_div_scale_f32 v46, s[14:15], v40, v40, 1.0
	v_rcp_f32_e32 v47, v46
	s_nop 0
	v_fma_f32 v51, -v46, v47, 1.0
	v_fmac_f32_e32 v47, v51, v47
	v_div_scale_f32 v51, vcc, 1.0, v40, 1.0
	v_mul_f32_e32 v54, v51, v47
	v_fma_f32 v55, -v46, v54, v51
	v_fmac_f32_e32 v54, v55, v47
	v_fma_f32 v46, -v46, v54, v51
	v_div_fmas_f32 v46, v46, v47, v54
	v_div_fixup_f32 v40, v46, v40, 1.0
	v_cvt_pk_bf16_f32 v40, v40, v41
	v_cvt_f32_i32_e32 v41, v42
	v_mul_f32_e32 v41, v50, v41
	v_mul_f32_e32 v41, v30, v41
	v_mul_f32_e32 v41, 0xbfb8aa3b, v41
	v_exp_f32_e32 v42, v41
	v_cvt_f32_i32_e32 v41, v43
	v_mul_f32_e32 v41, v50, v41
	v_mul_f32_e32 v41, v31, v41
	v_mul_f32_e32 v41, 0xbfb8aa3b, v41
	v_exp_f32_e32 v43, v41
	s_nop 0
	v_pk_add_f32 v[42:43], v[42:43], 1.0 op_sel_hi:[1,0]
	s_nop 0
	v_div_scale_f32 v41, s[14:15], v43, v43, 1.0
	v_rcp_f32_e32 v46, v41
	s_nop 0
	v_fma_f32 v47, -v41, v46, 1.0
	v_fmac_f32_e32 v46, v47, v46
	v_div_scale_f32 v47, vcc, 1.0, v43, 1.0
	v_mul_f32_e32 v51, v47, v46
	v_fma_f32 v54, -v41, v51, v47
	v_fmac_f32_e32 v51, v54, v46
	v_fma_f32 v41, -v41, v51, v47
	v_div_fmas_f32 v41, v41, v46, v51
	v_div_fixup_f32 v41, v41, v43, 1.0
	v_div_scale_f32 v43, s[14:15], v42, v42, 1.0
	v_rcp_f32_e32 v46, v43
	s_nop 0
	v_fma_f32 v47, -v43, v46, 1.0
	v_fmac_f32_e32 v46, v47, v46
	v_div_scale_f32 v47, vcc, 1.0, v42, 1.0
	v_mul_f32_e32 v51, v47, v46
	v_fma_f32 v54, -v43, v51, v47
	v_fmac_f32_e32 v51, v54, v46
	v_fma_f32 v43, -v43, v51, v47
	v_div_fmas_f32 v43, v43, v46, v51
	v_div_fixup_f32 v42, v43, v42, 1.0
	v_cvt_pk_bf16_f32 v41, v42, v41
	v_div_scale_f32 v42, s[14:15], v37, v37, 1.0
	v_rcp_f32_e32 v43, v42
	s_nop 0
	v_fma_f32 v46, -v42, v43, 1.0
	v_fmac_f32_e32 v43, v46, v43
	v_div_scale_f32 v46, vcc, 1.0, v37, 1.0
	v_mul_f32_e32 v47, v46, v43
	v_fma_f32 v51, -v42, v47, v46
	v_fmac_f32_e32 v47, v51, v43
	v_fma_f32 v42, -v42, v47, v46
	v_div_fmas_f32 v42, v42, v43, v47
	v_div_fixup_f32 v37, v42, v37, 1.0
	v_div_scale_f32 v42, s[14:15], v36, v36, 1.0
	v_rcp_f32_e32 v43, v42
	s_nop 0
	v_fma_f32 v46, -v42, v43, 1.0
	v_fmac_f32_e32 v43, v46, v43
	v_div_scale_f32 v46, vcc, 1.0, v36, 1.0
	v_mul_f32_e32 v47, v46, v43
	v_fma_f32 v51, -v42, v47, v46
	v_fmac_f32_e32 v47, v51, v43
	v_fma_f32 v42, -v42, v47, v46
	v_div_fmas_f32 v42, v42, v43, v47
	v_div_fixup_f32 v36, v42, v36, 1.0
	v_cvt_pk_bf16_f32 v36, v36, v37
	v_cvt_f32_i32_e32 v37, v38
	v_mul_f32_e32 v37, v50, v37
	v_mul_f32_e32 v37, v18, v37
	v_mul_f32_e32 v37, 0xbfb8aa3b, v37
	v_exp_f32_e32 v38, v37
	v_cvt_f32_i32_e32 v37, v39
	v_mul_f32_e32 v37, v50, v37
	v_mul_f32_e32 v37, v19, v37
	v_mul_f32_e32 v37, 0xbfb8aa3b, v37
	v_exp_f32_e32 v39, v37
	s_nop 0
	v_pk_add_f32 v[38:39], v[38:39], 1.0 op_sel_hi:[1,0]
	s_nop 0
	v_div_scale_f32 v37, s[14:15], v39, v39, 1.0
	v_rcp_f32_e32 v42, v37
	s_nop 0
	v_fma_f32 v43, -v37, v42, 1.0
	v_fmac_f32_e32 v42, v43, v42
	v_div_scale_f32 v43, vcc, 1.0, v39, 1.0
	v_mul_f32_e32 v46, v43, v42
	v_fma_f32 v47, -v37, v46, v43
	v_fmac_f32_e32 v46, v47, v42
	v_fma_f32 v37, -v37, v46, v43
	v_div_fmas_f32 v37, v37, v42, v46
	v_div_fixup_f32 v37, v37, v39, 1.0
	v_div_scale_f32 v39, s[14:15], v38, v38, 1.0
	v_rcp_f32_e32 v42, v39
	s_nop 0
	v_fma_f32 v43, -v39, v42, 1.0
	v_fmac_f32_e32 v42, v43, v42
	v_div_scale_f32 v43, vcc, 1.0, v38, 1.0
	v_mul_f32_e32 v46, v43, v42
	v_fma_f32 v47, -v39, v46, v43
	v_fmac_f32_e32 v46, v47, v42
	v_fma_f32 v39, -v39, v46, v43
	v_div_fmas_f32 v39, v39, v42, v46
	v_div_fixup_f32 v38, v39, v38, 1.0
	v_cvt_pk_bf16_f32 v37, v38, v37
	v_div_scale_f32 v38, s[14:15], v33, v33, 1.0
	v_rcp_f32_e32 v39, v38
	s_nop 0
	v_fma_f32 v42, -v38, v39, 1.0
	v_fmac_f32_e32 v39, v42, v39
	v_div_scale_f32 v42, vcc, 1.0, v33, 1.0
	v_mul_f32_e32 v43, v42, v39
	v_fma_f32 v46, -v38, v43, v42
	v_fmac_f32_e32 v43, v46, v39
	v_fma_f32 v38, -v38, v43, v42
	v_div_fmas_f32 v38, v38, v39, v43
	v_div_fixup_f32 v33, v38, v33, 1.0
	v_div_scale_f32 v38, s[14:15], v32, v32, 1.0
	v_rcp_f32_e32 v39, v38
	s_nop 0
	v_fma_f32 v42, -v38, v39, 1.0
	v_fmac_f32_e32 v39, v42, v39
	v_div_scale_f32 v42, vcc, 1.0, v32, 1.0
	v_mul_f32_e32 v43, v42, v39
	v_fma_f32 v46, -v38, v43, v42
	v_fmac_f32_e32 v43, v46, v39
	v_fma_f32 v38, -v38, v43, v42
	v_div_fmas_f32 v38, v38, v39, v43
	v_div_fixup_f32 v32, v38, v32, 1.0
	v_cvt_pk_bf16_f32 v32, v32, v33
	v_cvt_f32_i32_e32 v33, v34
	v_mul_f32_e32 v33, v50, v33
	v_mul_f32_e32 v33, v14, v33
	v_mul_f32_e32 v33, 0xbfb8aa3b, v33
	v_exp_f32_e32 v34, v33
	v_cvt_f32_i32_e32 v33, v35
	v_mul_f32_e32 v33, v50, v33
	v_mul_f32_e32 v33, v15, v33
	v_mul_f32_e32 v33, 0xbfb8aa3b, v33
	v_exp_f32_e32 v35, v33
	s_nop 0
	v_pk_add_f32 v[34:35], v[34:35], 1.0 op_sel_hi:[1,0]
	s_nop 0
	v_div_scale_f32 v33, s[14:15], v35, v35, 1.0
	v_rcp_f32_e32 v38, v33
	s_nop 0
	v_fma_f32 v39, -v33, v38, 1.0
	v_fmac_f32_e32 v38, v39, v38
	v_div_scale_f32 v39, vcc, 1.0, v35, 1.0
	v_mul_f32_e32 v42, v39, v38
	v_fma_f32 v43, -v33, v42, v39
	v_fmac_f32_e32 v42, v43, v38
	v_fma_f32 v33, -v33, v42, v39
	v_div_fmas_f32 v33, v33, v38, v42
	v_div_fixup_f32 v33, v33, v35, 1.0
	v_div_scale_f32 v35, s[14:15], v34, v34, 1.0
	v_rcp_f32_e32 v38, v35
	s_nop 0
	v_fma_f32 v39, -v35, v38, 1.0
	v_fmac_f32_e32 v38, v39, v38
	v_div_scale_f32 v39, vcc, 1.0, v34, 1.0
	v_mul_f32_e32 v42, v39, v38
	v_fma_f32 v43, -v35, v42, v39
	v_fmac_f32_e32 v42, v43, v38
	v_fma_f32 v35, -v35, v42, v39
	v_div_fmas_f32 v35, v35, v38, v42
	v_div_fixup_f32 v34, v35, v34, 1.0
	v_cvt_pk_bf16_f32 v33, v34, v33
	flat_load_dword v34, v[68:69] offset:192
	s_waitcnt vmcnt(0) lgkmcnt(0)
; #define P (*launderP(lp))
; DEV float sigm(float x) { return 1.f / (1.f + __expf(-x)); }
; __device__ __forceinline__ void phase_gemm45(PREF P, char* smem, int which) {
;     ...
;         for (int i = 0; i < 4; ++i) {
;           const int row = m0 + wm * 64 + i * 16 + l15;
;     ...
; #pragma unroll
;           for (int j = 0; j < 4; ++j) {
;             const int col = n0 + (j & 1) * 16 + wn * 32 + (j >> 1) * 64 + q * 4;
;             const float4 swc = *(const float4*)(P.swpg + col);
;             part[i][j][0] = pack2(sigm((float)iacc[i][j][0] * shr * swc.x), sigm((float)iacc[i][j][1] * shr * swc.y));
;             part[i][j][1] = pack2(sigm((float)iacc[i][j][2] * shr * swc.z), sigm((float)iacc[i][j][3] * shr * swc.w));
;           }
	v_mul_f32_e32 v20, v34, v20
	v_mul_f32_e32 v21, v34, v21
	v_mul_f32_e32 v20, v24, v20
	v_mul_f32_e32 v21, v25, v21
	v_mul_f32_e32 v20, 0xbfb8aa3b, v20
	v_mul_f32_e32 v21, 0xbfb8aa3b, v21
	v_exp_f32_e32 v20, v20
	v_exp_f32_e32 v21, v21
	v_mul_f32_e32 v8, v34, v8
	v_mul_f32_e32 v9, v34, v9
	v_mul_f32_e32 v8, v28, v8
	v_pk_add_f32 v[20:21], v[20:21], 1.0 op_sel_hi:[1,0]
	v_mul_f32_e32 v9, v29, v9
	v_div_scale_f32 v24, s[14:15], v21, v21, 1.0
	v_rcp_f32_e32 v25, v24
	v_mul_f32_e32 v8, 0xbfb8aa3b, v8
	v_mul_f32_e32 v9, 0xbfb8aa3b, v9
	v_exp_f32_e32 v8, v8
	v_fma_f32 v35, -v24, v25, 1.0
	v_fmac_f32_e32 v25, v35, v25
	v_div_scale_f32 v35, vcc, 1.0, v21, 1.0
	v_mul_f32_e32 v38, v35, v25
	v_fma_f32 v39, -v24, v38, v35
	v_fmac_f32_e32 v38, v39, v25
	v_fma_f32 v24, -v24, v38, v35
	v_div_fmas_f32 v24, v24, v25, v38
	v_div_fixup_f32 v21, v24, v21, 1.0
	v_div_scale_f32 v24, s[14:15], v20, v20, 1.0
	v_rcp_f32_e32 v25, v24
	v_exp_f32_e32 v9, v9
	v_mul_f32_e32 v4, v34, v4
	v_mul_f32_e32 v5, v34, v5
	v_fma_f32 v35, -v24, v25, 1.0
	v_fmac_f32_e32 v25, v35, v25
	v_div_scale_f32 v35, vcc, 1.0, v20, 1.0
	v_mul_f32_e32 v38, v35, v25
	v_fma_f32 v39, -v24, v38, v35
	v_fmac_f32_e32 v38, v39, v25
	v_fma_f32 v24, -v24, v38, v35
	v_div_fmas_f32 v24, v24, v25, v38
	v_div_fixup_f32 v20, v24, v20, 1.0
	v_cvt_pk_bf16_f32 v20, v20, v21
	v_cvt_f32_i32_e32 v21, v22
	v_pk_add_f32 v[8:9], v[8:9], 1.0 op_sel_hi:[1,0]
	v_mul_f32_e32 v4, v16, v4
	v_mul_f32_e32 v5, v17, v5
	v_mul_f32_e32 v21, v34, v21
	v_mul_f32_e32 v21, v26, v21
	v_mul_f32_e32 v21, 0xbfb8aa3b, v21
	v_exp_f32_e32 v22, v21
	v_cvt_f32_i32_e32 v21, v23
	v_mul_f32_e32 v4, 0xbfb8aa3b, v4
	v_mul_f32_e32 v5, 0xbfb8aa3b, v5
	v_exp_f32_e32 v4, v4
	v_mul_f32_e32 v21, v34, v21
	v_mul_f32_e32 v21, v27, v21
	v_mul_f32_e32 v21, 0xbfb8aa3b, v21
	v_exp_f32_e32 v23, v21
	v_exp_f32_e32 v5, v5
	v_mul_f32_e32 v0, v34, v0
	v_mul_f32_e32 v1, v34, v1
	v_pk_add_f32 v[22:23], v[22:23], 1.0 op_sel_hi:[1,0]
	v_pk_add_f32 v[4:5], v[4:5], 1.0 op_sel_hi:[1,0]
	v_div_scale_f32 v21, s[14:15], v23, v23, 1.0
	v_rcp_f32_e32 v24, v21
	v_mul_f32_e32 v0, v12, v0
	v_mul_f32_e32 v1, v13, v1
	v_mul_f32_e32 v0, 0xbfb8aa3b, v0
	v_fma_f32 v25, -v21, v24, 1.0
	v_fmac_f32_e32 v24, v25, v24
	v_div_scale_f32 v25, vcc, 1.0, v23, 1.0
	v_mul_f32_e32 v26, v25, v24
	v_fma_f32 v27, -v21, v26, v25
	v_fmac_f32_e32 v26, v27, v24
	v_fma_f32 v21, -v21, v26, v25
	v_div_fmas_f32 v21, v21, v24, v26
	v_div_fixup_f32 v21, v21, v23, 1.0
	v_div_scale_f32 v23, s[14:15], v22, v22, 1.0
	v_rcp_f32_e32 v24, v23
	v_mul_f32_e32 v1, 0xbfb8aa3b, v1
	v_exp_f32_e32 v0, v0
	v_exp_f32_e32 v1, v1
	v_fma_f32 v25, -v23, v24, 1.0
	v_fmac_f32_e32 v24, v25, v24
	v_div_scale_f32 v25, vcc, 1.0, v22, 1.0
	v_mul_f32_e32 v26, v25, v24
	v_fma_f32 v27, -v23, v26, v25
	v_fmac_f32_e32 v26, v27, v24
	v_fma_f32 v23, -v23, v26, v25
	v_div_fmas_f32 v23, v23, v24, v26
	v_div_fixup_f32 v22, v23, v22, 1.0
	v_cvt_pk_bf16_f32 v21, v22, v21
	v_div_scale_f32 v22, s[14:15], v9, v9, 1.0
	v_rcp_f32_e32 v23, v22
	v_pk_add_f32 v[0:1], v[0:1], 1.0 op_sel_hi:[1,0]
	v_fma_f32 v24, -v22, v23, 1.0
	v_fmac_f32_e32 v23, v24, v23
	v_div_scale_f32 v24, vcc, 1.0, v9, 1.0
	v_mul_f32_e32 v25, v24, v23
	v_fma_f32 v26, -v22, v25, v24
	v_fmac_f32_e32 v25, v26, v23
	v_fma_f32 v22, -v22, v25, v24
	v_div_fmas_f32 v22, v22, v23, v25
	v_div_fixup_f32 v9, v22, v9, 1.0
	v_div_scale_f32 v22, s[14:15], v8, v8, 1.0
	v_rcp_f32_e32 v23, v22
	s_nop 0
	v_fma_f32 v24, -v22, v23, 1.0
	v_fmac_f32_e32 v23, v24, v23
	v_div_scale_f32 v24, vcc, 1.0, v8, 1.0
	v_mul_f32_e32 v25, v24, v23
	v_fma_f32 v26, -v22, v25, v24
	v_fmac_f32_e32 v25, v26, v23
	v_fma_f32 v22, -v22, v25, v24
	v_div_fmas_f32 v22, v22, v23, v25
	v_div_fixup_f32 v8, v22, v8, 1.0
	v_cvt_pk_bf16_f32 v22, v8, v9
	v_cvt_f32_i32_e32 v8, v10
	v_cvt_f32_i32_e32 v9, v11
	v_mov_b32_e32 v26, v188
	v_mul_f32_e32 v8, v34, v8
	v_mul_f32_e32 v9, v34, v9
	v_mul_f32_e32 v8, v30, v8
	v_mul_f32_e32 v9, v31, v9
	v_mul_f32_e32 v8, 0xbfb8aa3b, v8
	v_mul_f32_e32 v9, 0xbfb8aa3b, v9
	v_exp_f32_e32 v8, v8
	v_exp_f32_e32 v9, v9
	s_nop 0
	v_pk_add_f32 v[8:9], v[8:9], 1.0 op_sel_hi:[1,0]
	s_nop 0
	v_div_scale_f32 v10, s[14:15], v9, v9, 1.0
	v_rcp_f32_e32 v11, v10
	s_nop 0
	v_fma_f32 v23, -v10, v11, 1.0
	v_fmac_f32_e32 v11, v23, v11
	v_div_scale_f32 v23, vcc, 1.0, v9, 1.0
	v_mul_f32_e32 v24, v23, v11
	v_fma_f32 v25, -v10, v24, v23
	v_fmac_f32_e32 v24, v25, v11
	v_fma_f32 v10, -v10, v24, v23
	v_div_fmas_f32 v10, v10, v11, v24
	v_div_fixup_f32 v9, v10, v9, 1.0
	v_div_scale_f32 v10, s[14:15], v8, v8, 1.0
	v_rcp_f32_e32 v11, v10
	s_nop 0
	v_fma_f32 v23, -v10, v11, 1.0
	v_fmac_f32_e32 v11, v23, v11
	v_div_scale_f32 v23, vcc, 1.0, v8, 1.0
	v_mul_f32_e32 v24, v23, v11
	v_fma_f32 v25, -v10, v24, v23
	v_fmac_f32_e32 v24, v25, v11
	v_fma_f32 v10, -v10, v24, v23
	v_div_fmas_f32 v10, v10, v11, v24
	v_div_fixup_f32 v8, v10, v8, 1.0
	v_cvt_pk_bf16_f32 v23, v8, v9
	v_div_scale_f32 v8, s[14:15], v5, v5, 1.0
	v_rcp_f32_e32 v9, v8
	s_nop 0
	v_fma_f32 v10, -v8, v9, 1.0
	v_fmac_f32_e32 v9, v10, v9
	v_div_scale_f32 v10, vcc, 1.0, v5, 1.0
	v_mul_f32_e32 v11, v10, v9
	v_fma_f32 v16, -v8, v11, v10
	v_fmac_f32_e32 v11, v16, v9
	v_fma_f32 v8, -v8, v11, v10
	v_div_fmas_f32 v8, v8, v9, v11
	v_div_fixup_f32 v5, v8, v5, 1.0
	v_div_scale_f32 v8, s[14:15], v4, v4, 1.0
	v_rcp_f32_e32 v9, v8
	s_nop 0
	v_fma_f32 v10, -v8, v9, 1.0
	v_fmac_f32_e32 v9, v10, v9
	v_div_scale_f32 v10, vcc, 1.0, v4, 1.0
	v_mul_f32_e32 v11, v10, v9
	v_fma_f32 v16, -v8, v11, v10
	v_fmac_f32_e32 v11, v16, v9
	v_fma_f32 v8, -v8, v11, v10
	v_div_fmas_f32 v8, v8, v9, v11
	v_div_fixup_f32 v4, v8, v4, 1.0
	v_cvt_pk_bf16_f32 v16, v4, v5
	v_cvt_f32_i32_e32 v4, v6
	v_cvt_f32_i32_e32 v5, v7
; DEV int tid_() { int t = threadIdx.x; asm volatile("" : "+v"(t)); return t; }
; template <class FragT, class AccT>
; DEV void gemm_core_t(const char* __restrict__ A, size_t lda_bytes, const char* __restrict__ Bt, size_t ldb_bytes, int kbytes,
;                      int m0, int n0, int Sshift, int dl, char* smem, AccT (&acc)[4][4]) {
;   const int tid = tid_(), lane = tid & 63, wid = tid >> 6, wm = wid >> 1, wn = wid & 1;
;   const int l15 = lane & 15, q = lane >> 4;
;   const int srow = lane >> 3, schunk = (lane & 7) ^ (lane >> 3);
;   const char* ap[4];
;   const char* bp[4];
; #pragma unroll
;   for (int u = 0; u < 4; ++u) {
;     int r = (wid * 4 + u) * 8 + srow;
;     int ar = rowmap(m0 + r, Sshift, dl);
;     ap[u] = A + (size_t)ar * lda_bytes + schunk * 16;
;     bp[u] = Bt + (size_t)(n0 + r) * ldb_bytes + schunk * 16;
;   }
; #pragma unroll
;   for (int i = 0; i < 4; ++i)
; #pragma unroll
;     for (int j = 0; j < 4; ++j) acc[i][j] = AccT{0, 0, 0, 0};
;   const int nk = kbytes >> 7;
;   __syncthreads();
; #pragma unroll
;   for (int u = 0; u < 4; ++u) {
;     __builtin_amdgcn_global_load_lds((const unsigned*)ap[u], (unsigned*)(smem + (wid * 4 + u) * 1024 + lane * 16), 16, 0, 0);
;     __builtin_amdgcn_global_load_lds((const unsigned*)bp[u], (unsigned*)(smem + 16384 + (wid * 4 + u) * 1024 + lane * 16), 16, 0, 0);
;   }
;   const unsigned sbase = (unsigned)(unsigned long)((__attribute__((address_space(3))) char*)smem);
;   const unsigned sq0 = (unsigned)((q ^ (l15 & 7)) << 4);
;   const unsigned a0 = sbase + (unsigned)((wm * 64 + l15) * 128) + sq0;
;   const unsigned b0 = sbase + 16384u + (unsigned)((wn * 32 + l15) * 128) + sq0;
;   asm volatile("s_waitcnt vmcnt(0)" ::: "memory");
;   __syncthreads();
; __device__ __forceinline__ void phase_gemm45(PREF P, char* smem, int which) {
;     ...
;         for (int i = 0; i < 4; ++i) {
;           const int row = m0 + wm * 64 + i * 16 + l15;
;     ...
; #pragma unroll
;           for (int j = 0; j < 4; ++j) {
;             const int col = n0 + (j & 1) * 16 + wn * 32 + (j >> 1) * 64 + q * 4;
;             const float4 swc = *(const float4*)(P.swpg + col);
;             part[i][j][0] = pack2(sigm((float)iacc[i][j][0] * shr * swc.x), sigm((float)iacc[i][j][1] * shr * swc.y));
;             part[i][j][1] = pack2(sigm((float)iacc[i][j][2] * shr * swc.z), sigm((float)iacc[i][j][3] * shr * swc.w));
;           }
	v_mul_f32_e32 v4, v34, v4
	v_mul_f32_e32 v5, v34, v5
	v_mul_f32_e32 v4, v18, v4
	v_mul_f32_e32 v5, v19, v5
	v_mul_f32_e32 v4, 0xbfb8aa3b, v4
	v_mul_f32_e32 v5, 0xbfb8aa3b, v5
	v_exp_f32_e32 v4, v4
	v_exp_f32_e32 v5, v5
	s_nop 0
	v_pk_add_f32 v[4:5], v[4:5], 1.0 op_sel_hi:[1,0]
	s_nop 0
	v_div_scale_f32 v6, s[14:15], v5, v5, 1.0
	v_rcp_f32_e32 v7, v6
	s_nop 0
	v_fma_f32 v8, -v6, v7, 1.0
	v_fmac_f32_e32 v7, v8, v7
	v_div_scale_f32 v8, vcc, 1.0, v5, 1.0
	v_mul_f32_e32 v9, v8, v7
	v_fma_f32 v10, -v6, v9, v8
	v_fmac_f32_e32 v9, v10, v7
	v_fma_f32 v6, -v6, v9, v8
	v_div_fmas_f32 v6, v6, v7, v9
	v_div_fixup_f32 v5, v6, v5, 1.0
	v_div_scale_f32 v6, s[14:15], v4, v4, 1.0
	v_rcp_f32_e32 v7, v6
	s_nop 0
	v_fma_f32 v8, -v6, v7, 1.0
	v_fmac_f32_e32 v7, v8, v7
	v_div_scale_f32 v8, vcc, 1.0, v4, 1.0
	v_mul_f32_e32 v9, v8, v7
	v_fma_f32 v10, -v6, v9, v8
	v_fmac_f32_e32 v9, v10, v7
	v_fma_f32 v6, -v6, v9, v8
	v_div_fmas_f32 v6, v6, v7, v9
	v_div_fixup_f32 v4, v6, v4, 1.0
	v_cvt_pk_bf16_f32 v17, v4, v5
	v_div_scale_f32 v4, s[14:15], v1, v1, 1.0
	v_rcp_f32_e32 v5, v4
	s_nop 0
	v_fma_f32 v6, -v4, v5, 1.0
	v_fmac_f32_e32 v5, v6, v5
	v_div_scale_f32 v6, vcc, 1.0, v1, 1.0
	v_mul_f32_e32 v7, v6, v5
	v_fma_f32 v8, -v4, v7, v6
	v_fmac_f32_e32 v7, v8, v5
	v_fma_f32 v4, -v4, v7, v6
	v_div_fmas_f32 v4, v4, v5, v7
	v_div_fixup_f32 v1, v4, v1, 1.0
	v_div_scale_f32 v4, s[14:15], v0, v0, 1.0
	v_rcp_f32_e32 v5, v4
	s_nop 0
	v_fma_f32 v6, -v4, v5, 1.0
	v_fmac_f32_e32 v5, v6, v5
	v_div_scale_f32 v6, vcc, 1.0, v0, 1.0
	v_mul_f32_e32 v7, v6, v5
	v_fma_f32 v8, -v4, v7, v6
	v_fmac_f32_e32 v7, v8, v5
	v_fma_f32 v4, -v4, v7, v6
	v_div_fmas_f32 v4, v4, v5, v7
	v_div_fixup_f32 v0, v4, v0, 1.0
	v_cvt_pk_bf16_f32 v18, v0, v1
	v_cvt_f32_i32_e32 v0, v2
	v_cvt_f32_i32_e32 v1, v3
	v_mul_f32_e32 v0, v34, v0
	v_mul_f32_e32 v1, v34, v1
	v_mul_f32_e32 v0, v14, v0
	v_mul_f32_e32 v1, v15, v1
	v_mul_f32_e32 v0, 0xbfb8aa3b, v0
	v_mul_f32_e32 v1, 0xbfb8aa3b, v1
	v_exp_f32_e32 v0, v0
	v_exp_f32_e32 v1, v1
	s_nop 0
	v_pk_add_f32 v[0:1], v[0:1], 1.0 op_sel_hi:[1,0]
	s_nop 0
	v_div_scale_f32 v2, s[14:15], v1, v1, 1.0
	v_rcp_f32_e32 v3, v2
	s_nop 0
	v_fma_f32 v4, -v2, v3, 1.0
	v_fmac_f32_e32 v3, v4, v3
	v_div_scale_f32 v4, vcc, 1.0, v1, 1.0
	v_mul_f32_e32 v5, v4, v3
	v_fma_f32 v6, -v2, v5, v4
	v_fmac_f32_e32 v5, v6, v3
	v_fma_f32 v2, -v2, v5, v4
	v_div_fmas_f32 v2, v2, v3, v5
	v_div_fixup_f32 v1, v2, v1, 1.0
	v_div_scale_f32 v2, s[14:15], v0, v0, 1.0
	v_rcp_f32_e32 v3, v2
	s_nop 0
	v_fma_f32 v4, -v2, v3, 1.0
	v_fmac_f32_e32 v3, v4, v3
	v_div_scale_f32 v4, vcc, 1.0, v0, 1.0
	v_mul_f32_e32 v5, v4, v3
	v_fma_f32 v6, -v2, v5, v4
	v_fmac_f32_e32 v5, v6, v3
	v_fma_f32 v2, -v2, v5, v4
	v_div_fmas_f32 v2, v2, v3, v5
	v_div_fixup_f32 v0, v2, v0, 1.0
	v_cvt_pk_bf16_f32 v19, v0, v1
	ds_read2_b64 v[0:3], v80 offset0:24 offset1:28
	s_waitcnt lgkmcnt(0)
	v_ashrrev_i32_e32 v28, 6, v26
	v_bfe_u32 v4, v26, 3, 3
	v_lshlrev_b32_e32 v29, 5, v28
	v_bitop3_b32 v5, v4, v26, 7 bitop3:0x78
	v_or_b32_e32 v24, v29, v4
	v_lshlrev_b32_e32 v180, 4, v5
	v_or_b32_e32 v6, 8, v24
	v_or_b32_e32 v10, 16, v24
	v_or_b32_e32 v30, 24, v24
	v_lshl_add_u64 v[12:13], v[2:3], 0, v[180:181]
	v_lshl_add_u64 v[14:15], v[0:1], 0, v[180:181]
	v_add_u32_e32 v0, s17, v24
	v_add_u32_e32 v2, s4, v24
	v_add_u32_e32 v4, s17, v6
	v_add_u32_e32 v8, s17, v10
	v_add_u32_e32 v24, s17, v30
	v_ashrrev_i32_e32 v1, 31, v0
	v_ashrrev_i32_e32 v5, 31, v4
	v_ashrrev_i32_e32 v9, 31, v8
	v_ashrrev_i32_e32 v25, 31, v24
	v_lshlrev_b64 v[0:1], 9, v[0:1]
	v_lshlrev_b64 v[4:5], 9, v[4:5]
	v_lshlrev_b64 v[8:9], 9, v[8:9]
	v_lshlrev_b64 v[24:25], 9, v[24:25]
	v_lshl_add_u64 v[0:1], v[12:13], 0, v[0:1]
	v_lshl_add_u64 v[4:5], v[12:13], 0, v[4:5]
	v_add_u32_e32 v6, s4, v6
	v_lshl_add_u64 v[8:9], v[12:13], 0, v[8:9]
	v_add_u32_e32 v10, s4, v10
	v_lshl_add_u64 v[12:13], v[12:13], 0, v[24:25]
	v_add_u32_e32 v24, s4, v30
	v_ashrrev_i32_e32 v3, 31, v2
	v_ashrrev_i32_e32 v7, 31, v6
	v_ashrrev_i32_e32 v11, 31, v10
	v_ashrrev_i32_e32 v25, 31, v24
	v_lshlrev_b64 v[2:3], 9, v[2:3]
	v_lshlrev_b64 v[6:7], 9, v[6:7]
	v_lshlrev_b64 v[10:11], 9, v[10:11]
	v_lshlrev_b64 v[24:25], 9, v[24:25]
	v_and_b32_e32 v27, 63, v26
	v_lshl_add_u64 v[2:3], v[14:15], 0, v[2:3]
	v_lshl_add_u64 v[6:7], v[14:15], 0, v[6:7]
	v_lshl_add_u64 v[10:11], v[14:15], 0, v[10:11]
	v_lshl_add_u64 v[14:15], v[14:15], 0, v[24:25]
	v_lshlrev_b32_e32 v24, 12, v28
	v_lshl_or_b32 v28, v27, 4, v24
	v_add_u32_e32 v24, 0x4000, v28
	v_readfirstlane_b32 s43, v28
	v_readfirstlane_b32 s36, v24
	v_or_b32_e32 v24, 0x400, v28
	s_mov_b32 m0, s43
	v_readfirstlane_b32 s37, v24
	v_add_u32_e32 v24, 0x4400, v28
	s_barrier
	v_readfirstlane_b32 s38, v24
	v_or_b32_e32 v24, 0x800, v28
	global_load_lds_dwordx4 v[0:1], off
	s_mov_b32 m0, s36
	v_readfirstlane_b32 s39, v24
	v_add_u32_e32 v24, 0x4800, v28
	global_load_lds_dwordx4 v[2:3], off
	s_mov_b32 m0, s37
	v_readfirstlane_b32 s40, v24
	v_or_b32_e32 v24, 0xc00, v28
	global_load_lds_dwordx4 v[4:5], off
	s_mov_b32 m0, s38
	v_readfirstlane_b32 s41, v24
	v_add_u32_e32 v24, 0x4c00, v28
	global_load_lds_dwordx4 v[6:7], off
	s_mov_b32 m0, s39
	v_readfirstlane_b32 s42, v24
	v_lshlrev_b32_e32 v24, 4, v26
	v_and_b32_e32 v25, 15, v26
	global_load_lds_dwordx4 v[8:9], off
	s_mov_b32 m0, s40
	v_bitop3_b32 v27, v27, s31, v24 bitop3:0x48
	v_lshrrev_b32_e32 v24, 1, v26
	global_load_lds_dwordx4 v[10:11], off
	s_mov_b32 m0, s41
	v_and_or_b32 v24, v24, s44, v25
	v_and_or_b32 v25, v29, 32, v25
	v_add_u32_e32 v29, 0x8000, v28
	global_load_lds_dwordx4 v[12:13], off
	s_mov_b32 m0, s42
	v_lshlrev_b32_e32 v26, 7, v24
	v_readfirstlane_b32 s31, v29
	v_add_u32_e32 v29, 0xc000, v28
	global_load_lds_dwordx4 v[14:15], off
	v_or_b32_e32 v24, v27, v26
	v_lshl_or_b32 v34, v25, 7, v27
	v_bitop3_b32 v35, v27, 64, v26 bitop3:0x36
	v_lshl_add_u64 v[26:27], v[0:1], 0, s[46:47]
	s_mov_b32 m0, s31
	v_readfirstlane_b32 s5, v29
	v_add_u32_e32 v29, 0x8400, v28
	s_waitcnt vmcnt(0)
	s_waitcnt vmcnt(0) lgkmcnt(0)
	s_barrier
; DEV f32x4 mma_step(bf16x8 a, bf16x8 b, f32x4 c) { return MFMA(a, b, c); }
; template <class FragT, class AccT>
; DEV void gemm_core_t(const char* __restrict__ A, size_t lda_bytes, const char* __restrict__ Bt, size_t ldb_bytes, int kbytes,
;                      int m0, int n0, int Sshift, int dl, char* smem, AccT (&acc)[4][4]) {
;     ...
;   for (int kt = 0; kt < nk; ++kt) {
;     const unsigned so = (unsigned)(kt & 1) * 32768u;
;     char* nxt = smem + ((kt + 1) & 1) * 32768;
;     if (kt + 1 < nk) {
; #pragma unroll
;       for (int u = 0; u < 4; ++u) {
;         __builtin_amdgcn_global_load_lds((const unsigned*)(ap[u] + (size_t)(kt + 1) * 128), (unsigned*)(nxt + (wid * 4 + u) * 1024 + lane * 16), 16, 0, 0);
;         __builtin_amdgcn_global_load_lds((const unsigned*)(bp[u] + (size_t)(kt + 1) * 128), (unsigned*)(nxt + 16384 + (wid * 4 + u) * 1024 + lane * 16), 16, 0, 0);
;       }
;     }
;     FragT xa[2][4], wb[2][4];
;     asm volatile(
;         "ds_read_b128 %0, %16\n\t"
;         "ds_read_b128 %1, %16 offset:2048\n\t"
;         "ds_read_b128 %2, %16 offset:4096\n\t"
;         "ds_read_b128 %3, %16 offset:6144\n\t"
;         "ds_read_b128 %4, %18\n\t"
;         "ds_read_b128 %5, %18 offset:2048\n\t"
;         "ds_read_b128 %6, %18 offset:8192\n\t"
;         "ds_read_b128 %7, %18 offset:10240\n\t"
;         "ds_read_b128 %8, %17\n\t"
;         "ds_read_b128 %9, %17 offset:2048\n\t"
;         "ds_read_b128 %10, %17 offset:4096\n\t"
;         "ds_read_b128 %11, %17 offset:6144\n\t"
;         "ds_read_b128 %12, %19\n\t"
;         "ds_read_b128 %13, %19 offset:2048\n\t"
;         "ds_read_b128 %14, %19 offset:8192\n\t"
;         "ds_read_b128 %15, %19 offset:10240\n\t"
;         "s_waitcnt lgkmcnt(8)"
;         : "=&v"(xa[0][0]), "=&v"(xa[0][1]), "=&v"(xa[0][2]), "=&v"(xa[0][3]), "=&v"(wb[0][0]), "=&v"(wb[0][1]), "=&v"(wb[0][2]),
;           "=&v"(wb[0][3]), "=&v"(xa[1][0]), "=&v"(xa[1][1]), "=&v"(xa[1][2]), "=&v"(xa[1][3]), "=&v"(wb[1][0]), "=&v"(wb[1][1]),
;           "=&v"(wb[1][2]), "=&v"(wb[1][3])
;         : "v"(a0 + so), "v"((a0 ^ 64u) + so), "v"(b0 + so), "v"((b0 ^ 64u) + so)
;         : "memory");
;     __builtin_amdgcn_s_setprio(1);
; #pragma unroll
;     for (int i = 0; i < 4; ++i)
; #pragma unroll
;       for (int j = 0; j < 4; ++j) acc[i][j] = mma_step(wb[0][j], xa[0][i], acc[i][j]);
;     asm volatile("s_waitcnt lgkmcnt(0)"
	global_load_lds_dwordx4 v[26:27], off
	v_lshl_add_u64 v[26:27], v[2:3], 0, s[46:47]
	s_mov_b32 m0, s5
	v_readfirstlane_b32 s6, v29
	v_add_u32_e32 v29, 0xc400, v28
	global_load_lds_dwordx4 v[26:27], off
	v_lshl_add_u64 v[26:27], v[4:5], 0, s[46:47]
	s_mov_b32 m0, s6
	v_readfirstlane_b32 s14, v29
	v_add_u32_e32 v29, 0x8800, v28
	global_load_lds_dwordx4 v[26:27], off
	v_lshl_add_u64 v[26:27], v[6:7], 0, s[46:47]
	s_mov_b32 m0, s14
	v_readfirstlane_b32 s15, v29
	v_add_u32_e32 v29, 0xc800, v28
	global_load_lds_dwordx4 v[26:27], off
	v_lshl_add_u64 v[26:27], v[8:9], 0, s[46:47]
	s_mov_b32 m0, s15
	v_readfirstlane_b32 s18, v29
	v_add_u32_e32 v29, 0x8c00, v28
	global_load_lds_dwordx4 v[26:27], off
	v_lshl_add_u64 v[26:27], v[10:11], 0, s[46:47]
	s_mov_b32 m0, s18
	v_readfirstlane_b32 s19, v29
	v_add_u32_e32 v28, 0xcc00, v28
	global_load_lds_dwordx4 v[26:27], off
	v_lshl_add_u64 v[26:27], v[12:13], 0, s[46:47]
	s_mov_b32 m0, s19
	v_readfirstlane_b32 s24, v28
	global_load_lds_dwordx4 v[26:27], off
	v_lshl_add_u64 v[26:27], v[14:15], 0, s[46:47]
	s_mov_b32 m0, s24
	v_or_b32_e32 v25, 0x4000, v34
	global_load_lds_dwordx4 v[26:27], off
	v_bitop3_b32 v38, v34, 64, v219 bitop3:0x36
	ds_read_b128 v[26:29], v24
	ds_read_b128 v[66:69], v24 offset:2048
	ds_read_b128 v[84:87], v24 offset:4096
	ds_read_b128 v[88:91], v24 offset:6144
	ds_read_b128 v[92:95], v25
	ds_read_b128 v[96:99], v25 offset:2048
	ds_read_b128 v[100:103], v25 offset:8192
	ds_read_b128 v[104:107], v25 offset:10240
	ds_read_b128 v[108:111], v35
	ds_read_b128 v[112:115], v35 offset:2048
	ds_read_b128 v[116:119], v35 offset:4096
	ds_read_b128 v[120:123], v35 offset:6144
	ds_read_b128 v[124:127], v38
	ds_read_b128 v[128:131], v38 offset:2048
	ds_read_b128 v[132:135], v38 offset:8192
	ds_read_b128 v[136:139], v38 offset:10240
	s_waitcnt lgkmcnt(8)
	s_setprio 1
	v_mfma_f32_16x16x32_bf16 v[140:143], v[92:95], v[26:29], 0
	v_mfma_f32_16x16x32_bf16 v[144:147], v[96:99], v[26:29], 0
	v_mfma_f32_16x16x32_bf16 v[148:151], v[100:103], v[26:29], 0
	v_mfma_f32_16x16x32_bf16 v[26:29], v[104:107], v[26:29], 0
	v_mfma_f32_16x16x32_bf16 v[152:155], v[92:95], v[66:69], 0
	v_mfma_f32_16x16x32_bf16 v[156:159], v[96:99], v[66:69], 0
	v_mfma_f32_16x16x32_bf16 v[160:163], v[100:103], v[66:69], 0
	v_mfma_f32_16x16x32_bf16 v[66:69], v[104:107], v[66:69], 0
	v_mfma_f32_16x16x32_bf16 v[164:167], v[92:95], v[84:87], 0
	v_mfma_f32_16x16x32_bf16 v[168:171], v[96:99], v[84:87], 0
	v_mfma_f32_16x16x32_bf16 v[172:175], v[100:103], v[84:87], 0
	v_mfma_f32_16x16x32_bf16 v[84:87], v[104:107], v[84:87], 0
	v_mfma_f32_16x16x32_bf16 v[92:95], v[92:95], v[88:91], 0
	v_mfma_f32_16x16x32_bf16 v[96:99], v[96:99], v[88:91], 0
	v_mfma_f32_16x16x32_bf16 v[100:103], v[100:103], v[88:91], 0
	v_mfma_f32_16x16x32_bf16 v[88:91], v[104:107], v[88:91], 0
	s_waitcnt lgkmcnt(0)
	s_nop 0
	v_mfma_f32_16x16x32_bf16 v[104:107], v[124:127], v[108:111], v[140:143]
	v_mfma_f32_16x16x32_bf16 v[140:143], v[128:131], v[108:111], v[144:147]
	v_mfma_f32_16x16x32_bf16 v[144:147], v[132:135], v[108:111], v[148:151]
	v_mfma_f32_16x16x32_bf16 v[26:29], v[136:139], v[108:111], v[26:29]
	v_mfma_f32_16x16x32_bf16 v[108:111], v[124:127], v[112:115], v[152:155]
	v_mfma_f32_16x16x32_bf16 v[148:151], v[128:131], v[112:115], v[156:159]
	v_mfma_f32_16x16x32_bf16 v[152:155], v[132:135], v[112:115], v[160:163]
	v_mfma_f32_16x16x32_bf16 v[66:69], v[136:139], v[112:115], v[66:69]
	v_mfma_f32_16x16x32_bf16 v[112:115], v[124:127], v[116:119], v[164:167]
	v_mfma_f32_16x16x32_bf16 v[156:159], v[128:131], v[116:119], v[168:171]
	v_mfma_f32_16x16x32_bf16 v[160:163], v[132:135], v[116:119], v[172:175]
	v_mfma_f32_16x16x32_bf16 v[84:87], v[136:139], v[116:119], v[84:87]
	v_mfma_f32_16x16x32_bf16 v[92:95], v[124:127], v[120:123], v[92:95]
	v_mfma_f32_16x16x32_bf16 v[96:99], v[128:131], v[120:123], v[96:99]
	v_mfma_f32_16x16x32_bf16 v[100:103], v[132:135], v[120:123], v[100:103]
	v_mfma_f32_16x16x32_bf16 v[88:91], v[136:139], v[120:123], v[88:91]
	s_setprio 0
	s_mov_b64 s[48:49], 0x100
	s_mov_b32 m0, s43
	v_lshl_add_u64 v[30:31], v[0:1], 0, s[48:49]
	s_waitcnt vmcnt(0)
	s_waitcnt vmcnt(0) lgkmcnt(0)
	s_barrier
	global_load_lds_dwordx4 v[30:31], off
	v_lshl_add_u64 v[30:31], v[2:3], 0, s[48:49]
	s_mov_b32 m0, s36
	v_add_u32_e32 v39, 0x8000, v24
	global_load_lds_dwordx4 v[30:31], off
	v_lshl_add_u64 v[30:31], v[4:5], 0, s[48:49]
	s_mov_b32 m0, s37
	v_readlane_b32 s36, v251, 55
	global_load_lds_dwordx4 v[30:31], off
	v_lshl_add_u64 v[30:31], v[6:7], 0, s[48:49]
	s_mov_b32 m0, s38
	v_add_u32_e32 v42, 0x8000, v35
	global_load_lds_dwordx4 v[30:31], off
	v_lshl_add_u64 v[30:31], v[8:9], 0, s[48:49]
	s_mov_b32 m0, s39
	v_or_b32_e32 v34, 0xc000, v34
	global_load_lds_dwordx4 v[30:31], off
	v_lshl_add_u64 v[30:31], v[10:11], 0, s[48:49]
	s_mov_b32 m0, s40
	v_bitop3_b32 v43, v25, s36, 64 bitop3:0xde
	global_load_lds_dwordx4 v[30:31], off
	v_lshl_add_u64 v[30:31], v[12:13], 0, s[48:49]
	s_mov_b32 m0, s41
	v_readlane_b32 s37, v251, 56
	global_load_lds_dwordx4 v[30:31], off
	v_lshl_add_u64 v[30:31], v[14:15], 0, s[48:49]
	s_mov_b32 m0, s42
	s_nop 0
	global_load_lds_dwordx4 v[30:31], off
	ds_read_b128 v[116:119], v39
	ds_read_b128 v[120:123], v39 offset:2048
	ds_read_b128 v[124:127], v39 offset:4096
	ds_read_b128 v[128:131], v39 offset:6144
	ds_read_b128 v[132:135], v34
	ds_read_b128 v[136:139], v34 offset:2048
	ds_read_b128 v[164:167], v34 offset:8192
	ds_read_b128 v[168:171], v34 offset:10240
	ds_read_b128 v[172:175], v42
	ds_read_b128 v[184:187], v42 offset:2048
	ds_read_b128 v[222:225], v42 offset:4096
	ds_read_b128 v[226:229], v42 offset:6144
	ds_read_b128 v[230:233], v43
	ds_read_b128 v[234:237], v43 offset:2048
	ds_read_b128 v[238:241], v43 offset:8192
	ds_read_b128 v[242:245], v43 offset:10240
	s_waitcnt lgkmcnt(8)
; DEV f32x4 mma_step(bf16x8 a, bf16x8 b, f32x4 c) { return MFMA(a, b, c); }
; template <class FragT, class AccT>
; DEV void gemm_core_t(const char* __restrict__ A, size_t lda_bytes, const char* __restrict__ Bt, size_t ldb_bytes, int kbytes,
;                      int m0, int n0, int Sshift, int dl, char* smem, AccT (&acc)[4][4]) {
;     ...
;   for (int kt = 0; kt < nk; ++kt) {
;     const unsigned so = (unsigned)(kt & 1) * 32768u;
;     char* nxt = smem + ((kt + 1) & 1) * 32768;
;     if (kt + 1 < nk) {
; #pragma unroll
;       for (int u = 0; u < 4; ++u) {
;         __builtin_amdgcn_global_load_lds((const unsigned*)(ap[u] + (size_t)(kt + 1) * 128), (unsigned*)(nxt + (wid * 4 + u) * 1024 + lane * 16), 16, 0, 0);
;         __builtin_amdgcn_global_load_lds((const unsigned*)(bp[u] + (size_t)(kt + 1) * 128), (unsigned*)(nxt + 16384 + (wid * 4 + u) * 1024 + lane * 16), 16, 0, 0);
;       }
;     }
;     FragT xa[2][4], wb[2][4];
;     asm volatile(
;         "ds_read_b128 %0, %16\n\t"
;         "ds_read_b128 %1, %16 offset:2048\n\t"
;         "ds_read_b128 %2, %16 offset:4096\n\t"
;         "ds_read_b128 %3, %16 offset:6144\n\t"
;         "ds_read_b128 %4, %18\n\t"
;         "ds_read_b128 %5, %18 offset:2048\n\t"
;         "ds_read_b128 %6, %18 offset:8192\n\t"
;         "ds_read_b128 %7, %18 offset:10240\n\t"
;         "ds_read_b128 %8, %17\n\t"
;         "ds_read_b128 %9, %17 offset:2048\n\t"
;         "ds_read_b128 %10, %17 offset:4096\n\t"
;         "ds_read_b128 %11, %17 offset:6144\n\t"
;         "ds_read_b128 %12, %19\n\t"
;         "ds_read_b128 %13, %19 offset:2048\n\t"
;         "ds_read_b128 %14, %19 offset:8192\n\t"
;         "ds_read_b128 %15, %19 offset:10240\n\t"
;         "s_waitcnt lgkmcnt(8)"
;         : "=&v"(xa[0][0]), "=&v"(xa[0][1]), "=&v"(xa[0][2]), "=&v"(xa[0][3]), "=&v"(wb[0][0]), "=&v"(wb[0][1]), "=&v"(wb[0][2]),
;           "=&v"(wb[0][3]), "=&v"(xa[1][0]), "=&v"(xa[1][1]), "=&v"(xa[1][2]), "=&v"(xa[1][3]), "=&v"(wb[1][0]), "=&v"(wb[1][1]),
;           "=&v"(wb[1][2]), "=&v"(wb[1][3])
;         : "v"(a0 + so), "v"((a0 ^ 64u) + so), "v"(b0 + so), "v"((b0 ^ 64u) + so)
;         : "memory");
;     __builtin_amdgcn_s_setprio(1);
; #pragma unroll
;     for (int i = 0; i < 4; ++i)
; #pragma unroll
;       for (int j = 0; j < 4; ++j) acc[i][j] = mma_step(wb[0][j], xa[0][i], acc[i][j]);
;     asm volatile("s_waitcnt lgkmcnt(0)"
	s_setprio 1
	v_mfma_f32_16x16x32_bf16 v[104:107], v[132:135], v[116:119], v[104:107]
	v_mfma_f32_16x16x32_bf16 v[140:143], v[136:139], v[116:119], v[140:143]
	v_mfma_f32_16x16x32_bf16 v[144:147], v[164:167], v[116:119], v[144:147]
	v_mfma_f32_16x16x32_bf16 v[26:29], v[168:171], v[116:119], v[26:29]
	v_mfma_f32_16x16x32_bf16 v[108:111], v[132:135], v[120:123], v[108:111]
	v_mfma_f32_16x16x32_bf16 v[116:119], v[136:139], v[120:123], v[148:151]
	v_mfma_f32_16x16x32_bf16 v[148:151], v[164:167], v[120:123], v[152:155]
	v_mfma_f32_16x16x32_bf16 v[66:69], v[168:171], v[120:123], v[66:69]
	v_mfma_f32_16x16x32_bf16 v[112:115], v[132:135], v[124:127], v[112:115]
	v_mfma_f32_16x16x32_bf16 v[120:123], v[136:139], v[124:127], v[156:159]
	v_mfma_f32_16x16x32_bf16 v[152:155], v[164:167], v[124:127], v[160:163]
	v_mfma_f32_16x16x32_bf16 v[84:87], v[168:171], v[124:127], v[84:87]
	v_mfma_f32_16x16x32_bf16 v[92:95], v[132:135], v[128:131], v[92:95]
	v_mfma_f32_16x16x32_bf16 v[96:99], v[136:139], v[128:131], v[96:99]
	v_mfma_f32_16x16x32_bf16 v[100:103], v[164:167], v[128:131], v[100:103]
	v_mfma_f32_16x16x32_bf16 v[88:91], v[168:171], v[128:131], v[88:91]
	s_waitcnt lgkmcnt(0)
	s_nop 0
	v_mfma_f32_16x16x32_bf16 v[104:107], v[230:233], v[172:175], v[104:107]
	v_mfma_f32_16x16x32_bf16 v[124:127], v[234:237], v[172:175], v[140:143]
	v_mfma_f32_16x16x32_bf16 v[128:131], v[238:241], v[172:175], v[144:147]
	v_mfma_f32_16x16x32_bf16 v[26:29], v[242:245], v[172:175], v[26:29]
	v_mfma_f32_16x16x32_bf16 v[108:111], v[230:233], v[184:187], v[108:111]
	v_mfma_f32_16x16x32_bf16 v[116:119], v[234:237], v[184:187], v[116:119]
	v_mfma_f32_16x16x32_bf16 v[132:135], v[238:241], v[184:187], v[148:151]
	v_mfma_f32_16x16x32_bf16 v[66:69], v[242:245], v[184:187], v[66:69]
	v_mfma_f32_16x16x32_bf16 v[112:115], v[230:233], v[222:225], v[112:115]
	v_mfma_f32_16x16x32_bf16 v[120:123], v[234:237], v[222:225], v[120:123]
	v_mfma_f32_16x16x32_bf16 v[136:139], v[238:241], v[222:225], v[152:155]
	v_mfma_f32_16x16x32_bf16 v[84:87], v[242:245], v[222:225], v[84:87]
	v_mfma_f32_16x16x32_bf16 v[92:95], v[230:233], v[226:229], v[92:95]
	v_mfma_f32_16x16x32_bf16 v[96:99], v[234:237], v[226:229], v[96:99]
	v_mfma_f32_16x16x32_bf16 v[100:103], v[238:241], v[226:229], v[100:103]
	v_mfma_f32_16x16x32_bf16 v[88:91], v[242:245], v[226:229], v[88:91]
	s_setprio 0
	s_mov_b64 s[36:37], 0x180
	s_mov_b32 m0, s31
	v_lshl_add_u64 v[0:1], v[0:1], 0, s[36:37]
	s_waitcnt vmcnt(0)
	s_waitcnt vmcnt(0) lgkmcnt(0)
	s_barrier
	global_load_lds_dwordx4 v[0:1], off
	v_lshl_add_u64 v[0:1], v[2:3], 0, s[36:37]
	s_mov_b32 m0, s5
	s_movk_i32 s31, 0x70
	global_load_lds_dwordx4 v[0:1], off
	v_lshl_add_u64 v[0:1], v[4:5], 0, s[36:37]
	s_mov_b32 m0, s6
	s_nop 0
	global_load_lds_dwordx4 v[0:1], off
	v_lshl_add_u64 v[0:1], v[6:7], 0, s[36:37]
	s_mov_b32 m0, s14
	s_nop 0
	global_load_lds_dwordx4 v[0:1], off
	v_lshl_add_u64 v[0:1], v[8:9], 0, s[36:37]
	s_mov_b32 m0, s15
	s_nop 0
	global_load_lds_dwordx4 v[0:1], off
	v_lshl_add_u64 v[0:1], v[10:11], 0, s[36:37]
	s_mov_b32 m0, s18
	s_nop 0
	global_load_lds_dwordx4 v[0:1], off
	v_lshl_add_u64 v[0:1], v[12:13], 0, s[36:37]
	s_mov_b32 m0, s19
	s_nop 0
	global_load_lds_dwordx4 v[0:1], off
	v_lshl_add_u64 v[0:1], v[14:15], 0, s[36:37]
	s_mov_b32 m0, s24
	s_nop 0
	global_load_lds_dwordx4 v[0:1], off
	ds_read_b128 v[0:3], v24
	ds_read_b128 v[4:7], v24 offset:2048
	ds_read_b128 v[8:11], v24 offset:4096
	ds_read_b128 v[12:15], v24 offset:6144
	ds_read_b128 v[140:143], v25
	ds_read_b128 v[144:147], v25 offset:2048
	ds_read_b128 v[148:151], v25 offset:8192
	ds_read_b128 v[152:155], v25 offset:10240
	ds_read_b128 v[156:159], v35
	ds_read_b128 v[160:163], v35 offset:2048
	ds_read_b128 v[164:167], v35 offset:4096
	ds_read_b128 v[168:171], v35 offset:6144
	ds_read_b128 v[172:175], v38
	ds_read_b128 v[184:187], v38 offset:2048
	ds_read_b128 v[222:225], v38 offset:8192
	ds_read_b128 v[226:229], v38 offset:10240
	s_waitcnt lgkmcnt(8)
	s_setprio 1
	v_mfma_f32_16x16x32_bf16 v[104:107], v[140:143], v[0:3], v[104:107]
	v_mfma_f32_16x16x32_bf16 v[124:127], v[144:147], v[0:3], v[124:127]
	v_mfma_f32_16x16x32_bf16 v[128:131], v[148:151], v[0:3], v[128:131]
	v_mfma_f32_16x16x32_bf16 v[0:3], v[152:155], v[0:3], v[26:29]
	v_mfma_f32_16x16x32_bf16 v[24:27], v[140:143], v[4:7], v[108:111]
	v_mfma_f32_16x16x32_bf16 v[28:31], v[144:147], v[4:7], v[116:119]
	v_mfma_f32_16x16x32_bf16 v[108:111], v[148:151], v[4:7], v[132:135]
	v_mfma_f32_16x16x32_bf16 v[4:7], v[152:155], v[4:7], v[66:69]
	v_mfma_f32_16x16x32_bf16 v[66:69], v[140:143], v[8:11], v[112:115]
	v_mfma_f32_16x16x32_bf16 v[112:115], v[144:147], v[8:11], v[120:123]
	v_mfma_f32_16x16x32_bf16 v[116:119], v[148:151], v[8:11], v[136:139]
	v_mfma_f32_16x16x32_bf16 v[8:11], v[152:155], v[8:11], v[84:87]
	v_mfma_f32_16x16x32_bf16 v[84:87], v[140:143], v[12:15], v[92:95]
	v_mfma_f32_16x16x32_bf16 v[92:95], v[144:147], v[12:15], v[96:99]
	v_mfma_f32_16x16x32_bf16 v[96:99], v[148:151], v[12:15], v[100:103]
	v_mfma_f32_16x16x32_bf16 v[12:15], v[152:155], v[12:15], v[88:91]
	s_waitcnt lgkmcnt(0)
	s_nop 0
	v_mfma_f32_16x16x32_bf16 v[88:91], v[172:175], v[156:159], v[104:107]
	v_mfma_f32_16x16x32_bf16 v[100:103], v[184:187], v[156:159], v[124:127]
	v_mfma_f32_16x16x32_bf16 v[104:107], v[222:225], v[156:159], v[128:131]
	v_mfma_f32_16x16x32_bf16 v[0:3], v[226:229], v[156:159], v[0:3]
	v_mfma_f32_16x16x32_bf16 v[24:27], v[172:175], v[160:163], v[24:27]
	v_mfma_f32_16x16x32_bf16 v[28:31], v[184:187], v[160:163], v[28:31]
	v_mfma_f32_16x16x32_bf16 v[108:111], v[222:225], v[160:163], v[108:111]
	v_mfma_f32_16x16x32_bf16 v[4:7], v[226:229], v[160:163], v[4:7]
	v_mfma_f32_16x16x32_bf16 v[66:69], v[172:175], v[164:167], v[66:69]
	v_mfma_f32_16x16x32_bf16 v[112:115], v[184:187], v[164:167], v[112:115]
	v_mfma_f32_16x16x32_bf16 v[116:119], v[222:225], v[164:167], v[116:119]
	v_mfma_f32_16x16x32_bf16 v[8:11], v[226:229], v[164:167], v[8:11]
	v_mfma_f32_16x16x32_bf16 v[84:87], v[172:175], v[168:171], v[84:87]
	v_mfma_f32_16x16x32_bf16 v[92:95], v[184:187], v[168:171], v[92:95]
	v_mfma_f32_16x16x32_bf16 v[96:99], v[222:225], v[168:171], v[96:99]
	v_mfma_f32_16x16x32_bf16 v[12:15], v[226:229], v[168:171], v[12:15]
	s_setprio 0
	s_waitcnt vmcnt(0)
	s_waitcnt vmcnt(0) lgkmcnt(0)
	s_barrier
; DEV float bflo(unsigned u) { return __uint_as_float(u << 16); }
; DEV float bfhi(unsigned u) { return __uint_as_float(u & 0xffff0000u); }
; DEV f32x4 mma_step(bf16x8 a, bf16x8 b, f32x4 c) { return MFMA(a, b, c); }
; DEV i32x4 mma_step(i32x4 a, i32x4 b, i32x4 c) { return __builtin_amdgcn_mfma_i32_16x16x64_i8(a, b, c, 0, 0, 0); }
; template <class FragT, class AccT>
; DEV void gemm_core_t(const char* __restrict__ A, size_t lda_bytes, const char* __restrict__ Bt, size_t ldb_bytes, int kbytes,
;                      int m0, int n0, int Sshift, int dl, char* smem, AccT (&acc)[4][4]) {
;     ...
;     for (int i = 0; i < 4; ++i)
; #pragma unroll
;       for (int j = 0; j < 4; ++j) acc[i][j] = mma_step(wb[0][j], xa[0][i], acc[i][j]);
;     asm volatile("s_waitcnt lgkmcnt(0)"
;                  : "+v"(xa[1][0]), "+v"(xa[1][1]), "+v"(xa[1][2]), "+v"(xa[1][3]), "+v"(wb[1][0]), "+v"(wb[1][1]), "+v"(wb[1][2]),
;                    "+v"(wb[1][3]), "+v"(acc[0][0]), "+v"(acc[0][1]), "+v"(acc[0][2]), "+v"(acc[0][3]), "+v"(acc[1][0]),
;                    "+v"(acc[1][1]), "+v"(acc[1][2]), "+v"(acc[1][3]), "+v"(acc[2][0]), "+v"(acc[2][1]), "+v"(acc[2][2]),
;                    "+v"(acc[2][3]), "+v"(acc[3][0]), "+v"(acc[3][1]), "+v"(acc[3][2]), "+v"(acc[3][3])
;                  :
;                  : "memory");
; #pragma unroll
;     for (int i = 0; i < 4; ++i)
; #pragma unroll
;       for (int j = 0; j < 4; ++j) acc[i][j] = mma_step(wb[1][j], xa[1][i], acc[i][j]);
; __device__ __forceinline__ void phase_gemm45(PREF P, char* smem, int which) {
;     ...
;       for (int i = 0; i < 4; ++i)
; #pragma unroll
;         for (int j = 0; j < 4; ++j) {
;           const int row = m0 + wm * 64 + i * 16 + l15, col = n0 + (j & 1) * 16 + wn * 32 + (j >> 1) * 64 + q * 4;
;           f32x4 v;
;           v[0] = bflo(part[i][j][0]) * acc[i][j][0]; v[1] = bfhi(part[i][j][0]) * acc[i][j][1];
;           v[2] = bflo(part[i][j][1]) * acc[i][j][2]; v[3] = bfhi(part[i][j][1]) * acc[i][j][3];
;           acc[i][j] = v;
;         }
	ds_read_b128 v[120:123], v39
	ds_read_b128 v[124:127], v39 offset:2048
	ds_read_b128 v[128:131], v39 offset:4096
	ds_read_b128 v[132:135], v39 offset:6144
	ds_read_b128 v[136:139], v34
	ds_read_b128 v[140:143], v34 offset:2048
	ds_read_b128 v[144:147], v34 offset:8192
	ds_read_b128 v[148:151], v34 offset:10240
	ds_read_b128 v[152:155], v42
	ds_read_b128 v[156:159], v42 offset:2048
	ds_read_b128 v[160:163], v42 offset:4096
	ds_read_b128 v[164:167], v42 offset:6144
	ds_read_b128 v[168:171], v43
	ds_read_b128 v[172:175], v43 offset:2048
	ds_read_b128 v[184:187], v43 offset:8192
	ds_read_b128 v[222:225], v43 offset:10240
	s_waitcnt lgkmcnt(8)
	s_setprio 1
	v_mfma_f32_16x16x32_bf16 v[88:91], v[136:139], v[120:123], v[88:91]
	v_mfma_f32_16x16x32_bf16 v[100:103], v[140:143], v[120:123], v[100:103]
	v_mfma_f32_16x16x32_bf16 v[104:107], v[144:147], v[120:123], v[104:107]
	v_mfma_f32_16x16x32_bf16 v[0:3], v[148:151], v[120:123], v[0:3]
	v_mfma_f32_16x16x32_bf16 v[24:27], v[136:139], v[124:127], v[24:27]
	v_mfma_f32_16x16x32_bf16 v[28:31], v[140:143], v[124:127], v[28:31]
	v_mfma_f32_16x16x32_bf16 v[108:111], v[144:147], v[124:127], v[108:111]
	v_mfma_f32_16x16x32_bf16 v[4:7], v[148:151], v[124:127], v[4:7]
	v_mfma_f32_16x16x32_bf16 v[66:69], v[136:139], v[128:131], v[66:69]
	v_mfma_f32_16x16x32_bf16 v[112:115], v[140:143], v[128:131], v[112:115]
	v_mfma_f32_16x16x32_bf16 v[116:119], v[144:147], v[128:131], v[116:119]
	v_mfma_f32_16x16x32_bf16 v[8:11], v[148:151], v[128:131], v[8:11]
	v_mfma_f32_16x16x32_bf16 v[84:87], v[136:139], v[132:135], v[84:87]
	v_mfma_f32_16x16x32_bf16 v[92:95], v[140:143], v[132:135], v[92:95]
	v_mfma_f32_16x16x32_bf16 v[96:99], v[144:147], v[132:135], v[96:99]
	v_mfma_f32_16x16x32_bf16 v[12:15], v[148:151], v[132:135], v[12:15]
	s_waitcnt lgkmcnt(0)
	s_nop 0
	v_mfma_f32_16x16x32_bf16 v[88:91], v[168:171], v[152:155], v[88:91]
	v_mfma_f32_16x16x32_bf16 v[100:103], v[172:175], v[152:155], v[100:103]
	v_mfma_f32_16x16x32_bf16 v[104:107], v[184:187], v[152:155], v[104:107]
	v_mfma_f32_16x16x32_bf16 v[0:3], v[222:225], v[152:155], v[0:3]
	v_mfma_f32_16x16x32_bf16 v[24:27], v[168:171], v[156:159], v[24:27]
	v_mfma_f32_16x16x32_bf16 v[28:31], v[172:175], v[156:159], v[28:31]
	v_mfma_f32_16x16x32_bf16 v[108:111], v[184:187], v[156:159], v[108:111]
	v_mfma_f32_16x16x32_bf16 v[4:7], v[222:225], v[156:159], v[4:7]
	v_mfma_f32_16x16x32_bf16 v[66:69], v[168:171], v[160:163], v[66:69]
	v_mfma_f32_16x16x32_bf16 v[112:115], v[172:175], v[160:163], v[112:115]
	v_mfma_f32_16x16x32_bf16 v[116:119], v[184:187], v[160:163], v[116:119]
	v_mfma_f32_16x16x32_bf16 v[8:11], v[222:225], v[160:163], v[8:11]
	v_mfma_f32_16x16x32_bf16 v[84:87], v[168:171], v[164:167], v[84:87]
	v_mfma_f32_16x16x32_bf16 v[92:95], v[172:175], v[164:167], v[92:95]
	v_mfma_f32_16x16x32_bf16 v[96:99], v[184:187], v[164:167], v[96:99]
	v_mfma_f32_16x16x32_bf16 v[12:15], v[222:225], v[164:167], v[12:15]
	s_setprio 0
	s_waitcnt vmcnt(0)
	v_lshlrev_b32_e32 v58, 16, v64
	v_and_b32_e32 v59, 0xffff0000, v64
	v_pk_mul_f32 v[0:1], v[0:1], v[58:59]
	v_lshlrev_b32_e32 v58, 16, v65
	v_and_b32_e32 v59, 0xffff0000, v65
	v_pk_mul_f32 v[2:3], v[2:3], v[58:59]
	v_lshlrev_b32_e32 v58, 16, v60
	v_and_b32_e32 v59, 0xffff0000, v60
	v_pk_mul_f32 v[24:25], v[24:25], v[58:59]
	v_lshlrev_b32_e32 v58, 16, v61
	v_and_b32_e32 v59, 0xffff0000, v61
	v_pk_mul_f32 v[26:27], v[26:27], v[58:59]
	v_lshlrev_b32_e32 v58, 16, v56
	v_and_b32_e32 v59, 0xffff0000, v56
	v_pk_mul_f32 v[28:29], v[28:29], v[58:59]
	v_lshlrev_b32_e32 v58, 16, v48
	v_and_b32_e32 v59, 0xffff0000, v48
	v_lshlrev_b32_e32 v48, 16, v49
	v_and_b32_e32 v49, 0xffff0000, v49
	v_pk_mul_f32 v[6:7], v[6:7], v[48:49]
	v_lshlrev_b32_e32 v48, 16, v44
	v_and_b32_e32 v49, 0xffff0000, v44
	v_lshlrev_b32_e32 v34, 16, v72
	v_and_b32_e32 v35, 0xffff0000, v72
	v_lshlrev_b32_e32 v38, 16, v73
	v_and_b32_e32 v39, 0xffff0000, v73
	v_pk_mul_f32 v[48:49], v[66:67], v[48:49]
	v_lshlrev_b32_e32 v66, 16, v18
	v_and_b32_e32 v67, 0xffff0000, v18
	v_pk_mul_f32 v[34:35], v[88:89], v[34:35]
	v_pk_mul_f32 v[38:39], v[90:91], v[38:39]
	v_lshlrev_b32_e32 v44, 16, v45
	v_and_b32_e32 v45, 0xffff0000, v45
	v_pk_mul_f32 v[12:13], v[12:13], v[66:67]
	v_lshlrev_b32_e32 v18, 16, v19
	v_and_b32_e32 v19, 0xffff0000, v19
	v_mov_b32_e32 v66, v188
	s_barrier
; DEV int tid_() { int t = threadIdx.x; asm volatile("" : "+v"(t)); return t; }
; DEV float bflo(unsigned u) { return __uint_as_float(u << 16); }
; DEV float bfhi(unsigned u) { return __uint_as_float(u & 0xffff0000u); }
; #define P (*launderP(lp))
; DEV void stage_tile_bf16(char* smem, const f32x4 (&v)[4][4], u16* buf, int ld, int m0, int col0) {
;   const int tid = tid_(), lane = tid & 63, wid = tid >> 6, wm = wid >> 1, wn = wid & 1, l15 = lane & 15, q = lane >> 4;
; #pragma unroll
;   for (int i = 0; i < 4; ++i)
; #pragma unroll
;     for (int j = 0; j < 4; ++j) {
;       const int rl = wm * 64 + i * 16 + l15, cl = (j & 1) * 16 + wn * 32 + (j >> 1) * 64 + q * 4;
;       u32x2 o; o.x = pack2(v[i][j][0], v[i][j][1]); o.y = pack2(v[i][j][2], v[i][j][3]);
;       *(u32x2*)(smem + rl * 272 + cl * 2) = o;
;     }
;   __syncthreads();
; __device__ __forceinline__ void phase_gemm45(PREF P, char* smem, int which) {
;     ...
;       for (int i = 0; i < 4; ++i)
; #pragma unroll
;         for (int j = 0; j < 4; ++j) {
;           const int row = m0 + wm * 64 + i * 16 + l15, col = n0 + (j & 1) * 16 + wn * 32 + (j >> 1) * 64 + q * 4;
;           f32x4 v;
;           v[0] = bflo(part[i][j][0]) * acc[i][j][0]; v[1] = bfhi(part[i][j][0]) * acc[i][j][1];
;           v[2] = bflo(part[i][j][1]) * acc[i][j][2]; v[3] = bfhi(part[i][j][1]) * acc[i][j][3];
;           acc[i][j] = v;
;         }
;       stage_tile_bf16(smem, acc, P.peb, 2048, m0, n0);
	v_lshlrev_b32_e32 v42, 16, v74
	v_and_b32_e32 v43, 0xffff0000, v74
	v_lshlrev_b32_e32 v46, 16, v75
	v_and_b32_e32 v47, 0xffff0000, v75
	v_pk_mul_f32 v[44:45], v[68:69], v[44:45]
	v_pk_mul_f32 v[14:15], v[14:15], v[18:19]
	ds_read_b64 v[18:19], v80 offset:360
	s_mov_b32 s5, 0xfffffc0
	v_and_b32_e32 v67, 15, v66
	v_lshrrev_b32_e32 v68, 1, v66
	v_cvt_pk_bf16_f32 v34, v34, v35
	v_cvt_pk_bf16_f32 v35, v38, v39
	v_and_b32_e32 v38, 64, v66
	v_pk_mul_f32 v[42:43], v[100:101], v[42:43]
	v_pk_mul_f32 v[46:47], v[102:103], v[46:47]
	v_lshlrev_b32_e32 v50, 16, v76
	v_and_b32_e32 v51, 0xffff0000, v76
	v_lshlrev_b32_e32 v54, 16, v77
	v_and_b32_e32 v55, 0xffff0000, v77
	v_and_or_b32 v69, v68, s5, v67
	v_and_or_b32 v38, v68, 24, v38
	v_pk_mul_f32 v[50:51], v[104:105], v[50:51]
	v_pk_mul_f32 v[54:55], v[106:107], v[54:55]
	v_lshlrev_b32_e32 v56, 16, v57
	v_and_b32_e32 v57, 0xffff0000, v57
	v_mad_u64_u32 v[38:39], s[14:15], v69, s11, v[38:39]
	v_cvt_pk_bf16_f32 v42, v42, v43
	v_cvt_pk_bf16_f32 v43, v46, v47
	v_pk_mul_f32 v[30:31], v[30:31], v[56:57]
	v_lshlrev_b32_e32 v56, 16, v52
	v_and_b32_e32 v57, 0xffff0000, v52
	v_lshlrev_b32_e32 v52, 16, v53
	v_and_b32_e32 v53, 0xffff0000, v53
	ds_write2_b64 v38, v[34:35], v[42:43] offset1:4
	v_cvt_pk_bf16_f32 v34, v50, v51
	v_cvt_pk_bf16_f32 v35, v54, v55
	v_cvt_pk_bf16_f32 v0, v0, v1
	v_cvt_pk_bf16_f32 v1, v2, v3
	v_pk_mul_f32 v[56:57], v[108:109], v[56:57]
	v_pk_mul_f32 v[52:53], v[110:111], v[52:53]
	v_pk_mul_f32 v[4:5], v[4:5], v[58:59]
	v_lshlrev_b32_e32 v58, 16, v40
	v_and_b32_e32 v59, 0xffff0000, v40
	v_lshlrev_b32_e32 v40, 16, v41
	v_and_b32_e32 v41, 0xffff0000, v41
	ds_write2_b64 v38, v[34:35], v[0:1] offset0:16 offset1:20
	v_cvt_pk_bf16_f32 v0, v24, v25
	v_cvt_pk_bf16_f32 v1, v26, v27
	v_cvt_pk_bf16_f32 v2, v28, v29
	v_cvt_pk_bf16_f32 v3, v30, v31
	v_add_u32_e32 v24, 0x1000, v38
	v_pk_mul_f32 v[58:59], v[112:113], v[58:59]
	v_pk_mul_f32 v[40:41], v[114:115], v[40:41]
	v_lshlrev_b32_e32 v60, 16, v36
	v_and_b32_e32 v61, 0xffff0000, v36
	v_lshlrev_b32_e32 v36, 16, v37
	v_and_b32_e32 v37, 0xffff0000, v37
	v_lshlrev_b32_e32 v62, 16, v32
	v_and_b32_e32 v63, 0xffff0000, v32
	v_lshlrev_b32_e32 v32, 16, v33
	v_and_b32_e32 v33, 0xffff0000, v33
	ds_write2_b64 v24, v[0:1], v[2:3] offset0:32 offset1:36
	v_cvt_pk_bf16_f32 v0, v56, v57
	v_cvt_pk_bf16_f32 v1, v52, v53
	v_cvt_pk_bf16_f32 v2, v4, v5
	v_cvt_pk_bf16_f32 v3, v6, v7
	v_pk_mul_f32 v[60:61], v[116:117], v[60:61]
	v_pk_mul_f32 v[36:37], v[118:119], v[36:37]
	v_pk_mul_f32 v[8:9], v[8:9], v[62:63]
	v_pk_mul_f32 v[10:11], v[10:11], v[32:33]
	v_lshlrev_b32_e32 v32, 16, v20
	v_and_b32_e32 v33, 0xffff0000, v20
	v_lshlrev_b32_e32 v20, 16, v21
	v_and_b32_e32 v21, 0xffff0000, v21
	v_lshlrev_b32_e32 v62, 16, v22
	v_and_b32_e32 v63, 0xffff0000, v22
	v_lshlrev_b32_e32 v22, 16, v23
	v_and_b32_e32 v23, 0xffff0000, v23
	ds_write2_b64 v24, v[0:1], v[2:3] offset0:48 offset1:52
	v_cvt_pk_bf16_f32 v0, v48, v49
	v_cvt_pk_bf16_f32 v1, v44, v45
	v_cvt_pk_bf16_f32 v2, v58, v59
	v_cvt_pk_bf16_f32 v3, v40, v41
	v_add_u32_e32 v4, 0x2000, v38
	v_pk_mul_f32 v[32:33], v[84:85], v[32:33]
	v_pk_mul_f32 v[20:21], v[86:87], v[20:21]
	v_pk_mul_f32 v[62:63], v[92:93], v[62:63]
	v_pk_mul_f32 v[22:23], v[94:95], v[22:23]
	v_lshlrev_b32_e32 v64, 16, v16
	v_and_b32_e32 v65, 0xffff0000, v16
	v_lshlrev_b32_e32 v16, 16, v17
	v_and_b32_e32 v17, 0xffff0000, v17
	ds_write2_b64 v4, v[0:1], v[2:3] offset0:64 offset1:68
	v_cvt_pk_bf16_f32 v0, v60, v61
	v_cvt_pk_bf16_f32 v1, v36, v37
	v_cvt_pk_bf16_f32 v2, v8, v9
	v_cvt_pk_bf16_f32 v3, v10, v11
	v_pk_mul_f32 v[64:65], v[96:97], v[64:65]
	v_pk_mul_f32 v[16:17], v[98:99], v[16:17]
	ds_write2_b64 v4, v[0:1], v[2:3] offset0:80 offset1:84
	v_cvt_pk_bf16_f32 v0, v32, v33
	v_cvt_pk_bf16_f32 v1, v20, v21
	v_cvt_pk_bf16_f32 v2, v62, v63
	v_cvt_pk_bf16_f32 v3, v22, v23
	v_add_u32_e32 v4, 0x3000, v38
	ds_write2_b64 v4, v[0:1], v[2:3] offset0:96 offset1:100
	v_cvt_pk_bf16_f32 v0, v64, v65
	v_cvt_pk_bf16_f32 v1, v16, v17
	v_cvt_pk_bf16_f32 v2, v12, v13
	v_cvt_pk_bf16_f32 v3, v14, v15
	s_ashr_i32 s5, s4, 31
	ds_write2_b64 v4, v[0:1], v[2:3] offset0:112 offset1:116
	v_lshlrev_b32_e32 v180, 4, v67
	s_waitcnt lgkmcnt(8)
	v_lshl_add_u64 v[0:1], s[4:5], 1, v[18:19]
	v_ashrrev_i32_e32 v6, 4, v66
	v_lshl_add_u64 v[4:5], v[0:1], 0, v[180:181]
	v_mad_u64_u32 v[0:1], s[4:5], v6, s11, v[180:181]
	s_waitcnt lgkmcnt(0)
	s_barrier
; DEV void stage_tile_bf16(char* smem, const f32x4 (&v)[4][4], u16* buf, int ld, int m0, int col0) {
;     ...
; #pragma unroll
;   for (int k = 0; k < 8; ++k) {
;     const int chunk = tid + 256 * k, rl = chunk >> 4, c16 = chunk & 15;
;     u32x4 d = *(const u32x4*)(smem + rl * 272 + c16 * 16);
;     *(u32x4*)(buf + (size_t)(m0 + rl) * ld + col0 + c16 * 8) = d;
;   }
	ds_read_b128 v[0:3], v0
	v_add_u32_e32 v6, s17, v6
	v_ashrrev_i32_e32 v7, 31, v6
	v_lshlrev_b64 v[6:7], 12, v[6:7]
	v_lshl_add_u64 v[6:7], v[4:5], 0, v[6:7]
	s_waitcnt lgkmcnt(0)
	flat_store_dwordx4 v[6:7], v[0:3]
	s_nop 1
	v_add_u32_e32 v0, 0x100, v66
	v_ashrrev_i32_e32 v6, 4, v0
	v_mad_u64_u32 v[0:1], s[4:5], v6, s11, v[180:181]
	ds_read_b128 v[0:3], v0
	v_add_u32_e32 v6, s17, v6
	v_ashrrev_i32_e32 v7, 31, v6
	v_lshlrev_b64 v[6:7], 12, v[6:7]
	v_lshl_add_u64 v[6:7], v[4:5], 0, v[6:7]
	s_waitcnt lgkmcnt(0)
	flat_store_dwordx4 v[6:7], v[0:3]
	s_nop 1
	v_add_u32_e32 v0, 0x200, v66
	v_ashrrev_i32_e32 v6, 4, v0
	v_mad_u64_u32 v[0:1], s[4:5], v6, s11, v[180:181]
	ds_read_b128 v[0:3], v0
	v_add_u32_e32 v6, s17, v6
	v_ashrrev_i32_e32 v7, 31, v6
	v_lshlrev_b64 v[6:7], 12, v[6:7]
	v_lshl_add_u64 v[6:7], v[4:5], 0, v[6:7]
	s_waitcnt lgkmcnt(0)
	flat_store_dwordx4 v[6:7], v[0:3]
	s_nop 1
	v_add_u32_e32 v0, 0x300, v66
	v_ashrrev_i32_e32 v6, 4, v0
	v_mad_u64_u32 v[0:1], s[4:5], v6, s11, v[180:181]
	ds_read_b128 v[0:3], v0
	v_add_u32_e32 v6, s17, v6
	v_ashrrev_i32_e32 v7, 31, v6
	v_lshlrev_b64 v[6:7], 12, v[6:7]
	v_lshl_add_u64 v[6:7], v[4:5], 0, v[6:7]
	s_waitcnt lgkmcnt(0)
	flat_store_dwordx4 v[6:7], v[0:3]
	s_nop 1
	v_add_u32_e32 v0, 0x400, v66
	v_ashrrev_i32_e32 v6, 4, v0
	v_mad_u64_u32 v[0:1], s[4:5], v6, s11, v[180:181]
	ds_read_b128 v[0:3], v0
	v_add_u32_e32 v6, s17, v6
	v_ashrrev_i32_e32 v7, 31, v6
	v_lshlrev_b64 v[6:7], 12, v[6:7]
	v_lshl_add_u64 v[6:7], v[4:5], 0, v[6:7]
	s_waitcnt lgkmcnt(0)
	flat_store_dwordx4 v[6:7], v[0:3]
	s_nop 1
	v_add_u32_e32 v0, 0x500, v66
	v_ashrrev_i32_e32 v6, 4, v0
	v_mad_u64_u32 v[0:1], s[4:5], v6, s11, v[180:181]
	ds_read_b128 v[0:3], v0
	v_add_u32_e32 v6, s17, v6
	v_ashrrev_i32_e32 v7, 31, v6
	v_lshlrev_b64 v[6:7], 12, v[6:7]
	v_lshl_add_u64 v[6:7], v[4:5], 0, v[6:7]
	s_waitcnt lgkmcnt(0)
	flat_store_dwordx4 v[6:7], v[0:3]
	s_nop 1
	v_add_u32_e32 v0, 0x600, v66
	v_ashrrev_i32_e32 v6, 4, v0
	v_mad_u64_u32 v[0:1], s[4:5], v6, s11, v[180:181]
	ds_read_b128 v[0:3], v0
	v_add_u32_e32 v6, s17, v6
	v_ashrrev_i32_e32 v7, 31, v6
	v_lshlrev_b64 v[6:7], 12, v[6:7]
	v_lshl_add_u64 v[6:7], v[4:5], 0, v[6:7]
	s_waitcnt lgkmcnt(0)
	flat_store_dwordx4 v[6:7], v[0:3]
	s_nop 1
	v_add_u32_e32 v0, 0x700, v66
	v_ashrrev_i32_e32 v6, 4, v0
	v_mad_u64_u32 v[0:1], s[4:5], v6, s11, v[180:181]
	ds_read_b128 v[0:3], v0
	v_add_u32_e32 v6, s17, v6
	v_ashrrev_i32_e32 v7, 31, v6
	v_lshlrev_b64 v[6:7], 12, v[6:7]
	v_lshl_add_u64 v[4:5], v[4:5], 0, v[6:7]
	v_readlane_b32 s4, v251, 6
	s_waitcnt lgkmcnt(0)
	flat_store_dwordx4 v[4:5], v[0:3]
	s_add_i32 s16, s4, s16
	s_cmpk_gt_i32 s16, 0x3ff
	v_readlane_b32 s5, v251, 7
	s_cbranch_scc0 .LBB0_623
	s_branch .LBB0_616

; DEV int tid_() { int t = threadIdx.x; asm volatile("" : "+v"(t)); return t; }
; DEV int rowmap(int p, int Sshift, int dl) {
;   int seq = p >> Sshift, pp = p & ((1 << Sshift) - 1);
;   int Lshift = Sshift - dl;
;   int r = pp >> Lshift, l = pp & ((1 << Lshift) - 1);
;   return (seq << Sshift) + (l << dl) + r;
; }
; template <class FragT, class AccT>
; DEV void gemm_core_t(const char* __restrict__ A, size_t lda_bytes, const char* __restrict__ Bt, size_t ldb_bytes, int kbytes,
;                      int m0, int n0, int Sshift, int dl, char* smem, AccT (&acc)[4][4]) {
;   const int tid = tid_(), lane = tid & 63, wid = tid >> 6, wm = wid >> 1, wn = wid & 1;
;   const int l15 = lane & 15, q = lane >> 4;
;   const int srow = lane >> 3, schunk = (lane & 7) ^ (lane >> 3);
;   const char* ap[4];
;   const char* bp[4];
; #pragma unroll
;   for (int u = 0; u < 4; ++u) {
;     int r = (wid * 4 + u) * 8 + srow;
;     int ar = rowmap(m0 + r, Sshift, dl);
;     ap[u] = A + (size_t)ar * lda_bytes + schunk * 16;
;     bp[u] = Bt + (size_t)(n0 + r) * ldb_bytes + schunk * 16;
;   }
; #pragma unroll
;   for (int i = 0; i < 4; ++i)
; #pragma unroll
;     for (int j = 0; j < 4; ++j) acc[i][j] = AccT{0, 0, 0, 0};
;   const int nk = kbytes >> 7;
;   __syncthreads();
; #pragma unroll
;   for (int u = 0; u < 4; ++u) {
;     __builtin_amdgcn_global_load_lds((const unsigned*)ap[u], (unsigned*)(smem + (wid * 4 + u) * 1024 + lane * 16), 16, 0, 0);
;     __builtin_amdgcn_global_load_lds((const unsigned*)bp[u], (unsigned*)(smem + 16384 + (wid * 4 + u) * 1024 + lane * 16), 16, 0, 0);
;   }
;   const unsigned sbase = (unsigned)(unsigned long)((__attribute__((address_space(3))) char*)smem);
;   const unsigned sq0 = (unsigned)((q ^ (l15 & 7)) << 4);
;   const unsigned a0 = sbase + (unsigned)((wm * 64 + l15) * 128) + sq0;
;   const unsigned b0 = sbase + 16384u + (unsigned)((wn * 32 + l15) * 128) + sq0;
;   asm volatile("s_waitcnt vmcnt(0)" ::: "memory");
;   __syncthreads();
.LBB0_733:
	v_mov_b32_e32 v30, v188
	ds_read2_b64 v[0:3], v79 offset0:57 offset1:58
	s_lshl_b32 s18, s18, 7
	v_ashrrev_i32_e32 v32, 6, v30
	v_bfe_u32 v33, v30, 3, 3
	v_lshlrev_b32_e32 v34, 5, v32
	s_lshl_b32 s17, s17, 10
	s_and_b32 s18, s18, 0x380
	v_or_b32_e32 v26, v34, v33
	s_or_b32 s36, s18, s17
	s_sub_i32 s17, s31, s6
	v_or_b32_e32 v18, 8, v26
	v_or_b32_e32 v24, 16, v26
	v_or_b32_e32 v28, 24, v26
	s_lshl_b32 s37, -1, s17
	v_add_u32_e32 v8, s36, v26
	v_mov_b32_e32 v27, s51
	v_add_u32_e32 v12, s40, v26
	v_add_u32_e32 v14, s36, v18
	v_add_u32_e32 v20, s36, v24
	v_add_u32_e32 v26, s36, v28
	v_bitop3_b32 v10, v8, s37, v27 bitop3:0x20
	v_bitop3_b32 v16, v14, s37, v27 bitop3:0x20
	v_bitop3_b32 v22, v20, s37, v27 bitop3:0x20
	v_and_b32_e32 v29, s51, v26
	v_bitop3_b32 v27, v26, s37, v27 bitop3:0x20
	v_bitop3_b32 v4, v33, v30, 7 bitop3:0x78
	v_add_u32_e32 v18, s40, v18
	v_add_u32_e32 v24, s40, v24
	v_lshrrev_b32_e32 v29, s17, v29
	v_and_b32_e32 v26, s50, v26
	v_lshlrev_b32_e32 v27, s6, v27
	v_add_u32_e32 v28, s40, v28
	v_lshlrev_b32_e32 v180, 4, v4
	v_and_b32_e32 v9, s51, v8
	v_ashrrev_i32_e32 v13, 31, v12
	v_ashrrev_i32_e32 v19, 31, v18
	v_ashrrev_i32_e32 v25, 31, v24
	v_add3_u32 v26, v29, v26, v27
	v_ashrrev_i32_e32 v29, 31, v28
	s_waitcnt lgkmcnt(0)
	v_lshl_add_u64 v[6:7], v[2:3], 0, v[180:181]
	v_lshrrev_b32_e32 v9, s17, v9
	v_and_b32_e32 v8, s50, v8
	v_lshlrev_b32_e32 v10, s6, v10
	v_lshlrev_b64 v[12:13], 11, v[12:13]
	v_lshlrev_b64 v[18:19], 11, v[18:19]
	v_lshlrev_b64 v[24:25], 11, v[24:25]
	v_lshlrev_b64 v[28:29], 11, v[28:29]
	v_and_b32_e32 v31, 63, v30
	v_add3_u32 v8, v9, v8, v10
	v_lshl_add_u64 v[12:13], v[6:7], 0, v[12:13]
	v_lshl_add_u64 v[18:19], v[6:7], 0, v[18:19]
	v_lshl_add_u64 v[24:25], v[6:7], 0, v[24:25]
	v_lshl_add_u64 v[6:7], v[6:7], 0, v[28:29]
	v_lshlrev_b32_e32 v28, 12, v32
	v_ashrrev_i32_e32 v9, 31, v8
	v_lshl_or_b32 v81, v31, 4, v28
	s_not_b32 s18, s37
	v_lshl_add_u64 v[4:5], v[0:1], 0, v[180:181]
	v_lshlrev_b64 v[8:9], 11, v[8:9]
	v_and_b32_e32 v15, s51, v14
	v_readfirstlane_b32 s37, v81
	v_lshl_add_u64 v[10:11], v[4:5], 0, v[8:9]
	v_lshrrev_b32_e32 v15, s17, v15
	v_and_b32_e32 v14, s50, v14
	v_lshlrev_b32_e32 v16, s6, v16
	s_mov_b32 m0, s37
	v_add3_u32 v14, v15, v14, v16
	v_and_b32_e32 v21, s51, v20
	s_barrier
	global_load_lds_dwordx4 v[10:11], off
	v_add_u32_e32 v10, 0x4000, v81
	v_ashrrev_i32_e32 v15, 31, v14
	v_lshrrev_b32_e32 v21, s17, v21
	v_and_b32_e32 v20, s50, v20
	v_lshlrev_b32_e32 v22, s6, v22
	v_readfirstlane_b32 s37, v10
	v_or_b32_e32 v10, 0x400, v81
	v_lshlrev_b64 v[14:15], 11, v[14:15]
	v_add3_u32 v20, v21, v20, v22
	s_mov_b32 m0, s37
	v_readfirstlane_b32 s37, v10
	v_add_u32_e32 v10, 0x4400, v81
	v_lshl_add_u64 v[16:17], v[4:5], 0, v[14:15]
	v_ashrrev_i32_e32 v21, 31, v20
	global_load_lds_dwordx4 v[12:13], off
	s_mov_b32 m0, s37
	v_readfirstlane_b32 s37, v10
	v_or_b32_e32 v10, 0x800, v81
	v_lshlrev_b64 v[20:21], 11, v[20:21]
	global_load_lds_dwordx4 v[16:17], off
	s_mov_b32 m0, s37
	v_readfirstlane_b32 s37, v10
	v_add_u32_e32 v10, 0x4800, v81
	v_lshl_add_u64 v[22:23], v[4:5], 0, v[20:21]
	v_ashrrev_i32_e32 v27, 31, v26
	global_load_lds_dwordx4 v[18:19], off
	s_mov_b32 m0, s37
	v_readfirstlane_b32 s37, v10
	v_or_b32_e32 v10, 0xc00, v81
	v_lshlrev_b64 v[26:27], 11, v[26:27]
	global_load_lds_dwordx4 v[22:23], off
	s_mov_b32 m0, s37
	v_readfirstlane_b32 s37, v10
	v_lshl_add_u64 v[4:5], v[4:5], 0, v[26:27]
	global_load_lds_dwordx4 v[24:25], off
	s_mov_b32 m0, s37
	s_mulk_i32 s19, 0x980
	global_load_lds_dwordx4 v[4:5], off
	v_add_u32_e32 v4, 0x4c00, v81
	v_lshlrev_b32_e32 v5, 4, v30
	v_readfirstlane_b32 s37, v4
	s_mov_b32 m0, s37
	v_and_b32_e32 v4, 15, v30
	global_load_lds_dwordx4 v[6:7], off
	v_lshrrev_b32_e32 v6, 1, v30
	s_mov_b32 s37, 0x1ffffc0
	v_bitop3_b32 v5, v31, s56, v5 bitop3:0x48
	v_and_or_b32 v6, v6, s37, v4
	v_and_or_b32 v4, v34, 32, v4
	s_lshl_b32 s37, s41, 7
	v_lshl_or_b32 v4, v4, 7, v5
	s_add_i32 s37, s37, s19
	v_or_b32_e32 v85, 0x4000, v4
	v_bitop3_b32 v86, v4, 64, v219 bitop3:0x36
	v_or_b32_e32 v4, s37, v33
	v_lshlrev_b32_e32 v6, 7, v6
	v_add_u32_e32 v4, v4, v34
	v_or_b32_e32 v84, v5, v6
	v_bitop3_b32 v87, v5, 64, v6 bitop3:0x36
	v_or_b32_e32 v6, 24, v4
	v_ashrrev_i32_e32 v7, 31, v6
	s_mov_b64 s[44:45], 0x80
	v_lshlrev_b64 v[6:7], 11, v[6:7]
	v_lshl_add_u64 v[2:3], v[2:3], 0, s[44:45]
	v_or_b32_e32 v6, v6, v180
	v_lshl_add_u64 v[64:65], v[2:3], 0, v[6:7]
	v_or_b32_e32 v6, 16, v4
	v_ashrrev_i32_e32 v7, 31, v6
	v_lshlrev_b64 v[6:7], 11, v[6:7]
	v_or_b32_e32 v6, v6, v180
	v_lshl_add_u64 v[68:69], v[2:3], 0, v[6:7]
	v_or_b32_e32 v6, 8, v4
	v_ashrrev_i32_e32 v7, 31, v6
	v_ashrrev_i32_e32 v5, 31, v4
	s_waitcnt vmcnt(0)
; DEV f32x4 mma_step(bf16x8 a, bf16x8 b, f32x4 c) { return MFMA(a, b, c); }
; template <class FragT, class AccT>
; DEV void gemm_core_t(const char* __restrict__ A, size_t lda_bytes, const char* __restrict__ Bt, size_t ldb_bytes, int kbytes,
;                      int m0, int n0, int Sshift, int dl, char* smem, AccT (&acc)[4][4]) {
;     ...
;   for (int kt = 0; kt < nk; ++kt) {
;     const unsigned so = (unsigned)(kt & 1) * 32768u;
;     char* nxt = smem + ((kt + 1) & 1) * 32768;
;     if (kt + 1 < nk) {
; #pragma unroll
;       for (int u = 0; u < 4; ++u) {
;         __builtin_amdgcn_global_load_lds((const unsigned*)(ap[u] + (size_t)(kt + 1) * 128), (unsigned*)(nxt + (wid * 4 + u) * 1024 + lane * 16), 16, 0, 0);
;         __builtin_amdgcn_global_load_lds((const unsigned*)(bp[u] + (size_t)(kt + 1) * 128), (unsigned*)(nxt + 16384 + (wid * 4 + u) * 1024 + lane * 16), 16, 0, 0);
;       }
;     }
;     FragT xa[2][4], wb[2][4];
;     asm volatile(
;         "ds_read_b128 %0, %16\n\t"
;         "ds_read_b128 %1, %16 offset:2048\n\t"
;         "ds_read_b128 %2, %16 offset:4096\n\t"
;         "ds_read_b128 %3, %16 offset:6144\n\t"
;         "ds_read_b128 %4, %18\n\t"
;         "ds_read_b128 %5, %18 offset:2048\n\t"
;         "ds_read_b128 %6, %18 offset:8192\n\t"
;         "ds_read_b128 %7, %18 offset:10240\n\t"
;         "ds_read_b128 %8, %17\n\t"
;         "ds_read_b128 %9, %17 offset:2048\n\t"
;         "ds_read_b128 %10, %17 offset:4096\n\t"
;         "ds_read_b128 %11, %17 offset:6144\n\t"
;         "ds_read_b128 %12, %19\n\t"
;         "ds_read_b128 %13, %19 offset:2048\n\t"
;         "ds_read_b128 %14, %19 offset:8192\n\t"
;         "ds_read_b128 %15, %19 offset:10240\n\t"
;         "s_waitcnt lgkmcnt(8)"
;         : "=&v"(xa[0][0]), "=&v"(xa[0][1]), "=&v"(xa[0][2]), "=&v"(xa[0][3]), "=&v"(wb[0][0]), "=&v"(wb[0][1]), "=&v"(wb[0][2]),
;           "=&v"(wb[0][3]), "=&v"(xa[1][0]), "=&v"(xa[1][1]), "=&v"(xa[1][2]), "=&v"(xa[1][3]), "=&v"(wb[1][0]), "=&v"(wb[1][1]),
;           "=&v"(wb[1][2]), "=&v"(wb[1][3])
;         : "v"(a0 + so), "v"((a0 ^ 64u) + so), "v"(b0 + so), "v"((b0 ^ 64u) + so)
;         : "memory");
;     __builtin_amdgcn_s_setprio(1);
; #pragma unroll
;     for (int i = 0; i < 4; ++i)
; #pragma unroll
;       for (int j = 0; j < 4; ++j) acc[i][j] = mma_step(wb[0][j], xa[0][i], acc[i][j]);
;     asm volatile("s_waitcnt lgkmcnt(0)"
	v_lshl_add_u64 v[0:1], v[0:1], 0, s[44:45]
	v_or_b32_e32 v26, v26, v180
	v_or_b32_e32 v20, v20, v180
	v_lshlrev_b64 v[6:7], 11, v[6:7]
	v_or_b32_e32 v14, v14, v180
	v_lshlrev_b64 v[4:5], 11, v[4:5]
	v_or_b32_e32 v8, v8, v180
	v_lshl_add_u64 v[66:67], v[0:1], 0, v[26:27]
	v_lshl_add_u64 v[70:71], v[0:1], 0, v[20:21]
	v_or_b32_e32 v6, v6, v180
	v_lshl_add_u64 v[74:75], v[0:1], 0, v[14:15]
	v_or_b32_e32 v4, v4, v180
	v_lshl_add_u64 v[82:83], v[0:1], 0, v[8:9]
	v_mov_b32_e32 v0, 0
	v_lshl_add_u64 v[72:73], v[2:3], 0, v[6:7]
	v_lshl_add_u64 v[76:77], v[2:3], 0, v[4:5]
	s_mov_b64 s[44:45], 0
	s_mov_b32 s19, 0x8000
	v_mov_b32_e32 v1, v0
	v_mov_b32_e32 v2, v0
	v_mov_b32_e32 v3, v0
	v_mov_b32_e32 v4, v0
	v_mov_b32_e32 v5, v0
	v_mov_b32_e32 v6, v0
	v_mov_b32_e32 v7, v0
	v_mov_b32_e32 v8, v0
	v_mov_b32_e32 v9, v0
	v_mov_b32_e32 v10, v0
	v_mov_b32_e32 v11, v0
	v_mov_b32_e32 v12, v0
	v_mov_b32_e32 v13, v0
	v_mov_b32_e32 v14, v0
	v_mov_b32_e32 v15, v0
	v_mov_b32_e32 v16, v0
	v_mov_b32_e32 v17, v0
	v_mov_b32_e32 v18, v0
	v_mov_b32_e32 v19, v0
	v_mov_b32_e32 v20, v0
	v_mov_b32_e32 v21, v0
	v_mov_b32_e32 v22, v0
	v_mov_b32_e32 v23, v0
	v_mov_b32_e32 v24, v0
	v_mov_b32_e32 v25, v0
	v_mov_b32_e32 v26, v0
	v_mov_b32_e32 v27, v0
	v_mov_b32_e32 v28, v0
	v_mov_b32_e32 v29, v0
	v_mov_b32_e32 v30, v0
	v_mov_b32_e32 v31, v0
	v_mov_b32_e32 v32, v0
	v_mov_b32_e32 v33, v0
	v_mov_b32_e32 v34, v0
	v_mov_b32_e32 v35, v0
	v_mov_b32_e32 v36, v0
	v_mov_b32_e32 v37, v0
	v_mov_b32_e32 v38, v0
	v_mov_b32_e32 v39, v0
	v_mov_b32_e32 v40, v0
	v_mov_b32_e32 v41, v0
	v_mov_b32_e32 v42, v0
	v_mov_b32_e32 v43, v0
	v_mov_b32_e32 v44, v0
	v_mov_b32_e32 v45, v0
	v_mov_b32_e32 v46, v0
	v_mov_b32_e32 v47, v0
	v_mov_b32_e32 v48, v0
	v_mov_b32_e32 v49, v0
	v_mov_b32_e32 v50, v0
	v_mov_b32_e32 v51, v0
	v_mov_b32_e32 v52, v0
	v_mov_b32_e32 v53, v0
	v_mov_b32_e32 v54, v0
	v_mov_b32_e32 v55, v0
	v_mov_b32_e32 v56, v0
	v_mov_b32_e32 v57, v0
	v_mov_b32_e32 v58, v0
	v_mov_b32_e32 v59, v0
	v_mov_b32_e32 v60, v0
	v_mov_b32_e32 v61, v0
	v_mov_b32_e32 v62, v0
	v_mov_b32_e32 v63, v0
	v_readfirstlane_b32 s64, v82
	v_readfirstlane_b32 s65, v83
	v_readfirstlane_b32 s66, v76
	v_readfirstlane_b32 s67, v77
	v_readfirstlane_b32 s62, v81
	s_sub_u32 s64, s64, 0x80000000
	s_subb_u32 s65, s65, 0
	s_sub_u32 s66, s66, 0x80000000
	s_subb_u32 s67, s67, 0
	v_subrev_u32_e32 v82, s64, v82
	v_subrev_u32_e32 v76, s66, v76
	v_subrev_u32_e32 v74, s64, v74
	v_subrev_u32_e32 v72, s66, v72
	v_subrev_u32_e32 v70, s64, v70
	v_subrev_u32_e32 v68, s66, v68
	v_subrev_u32_e32 v66, s64, v66
	v_subrev_u32_e32 v64, s66, v64
	s_waitcnt vmcnt(0) lgkmcnt(0)
	s_barrier
.LBB0_734:
	s_add_i32 s37, s19, 0xffff8000
	s_and_b32 s37, s37, 0x8000
	v_add_u32_e32 v92, s37, v84
	v_add_u32_e32 v93, s37, v87
	v_or_b32_e32 v99, s37, v85
	v_or_b32_e32 v160, s37, v86
	s_and_b32 s37, s19, 0x8000
	s_add_i32 s37, s37, s62
	s_mov_b32 m0, s37
	ds_read_b128 v[88:91], v92
	global_load_lds_dwordx4 v82, s[64:65]
	ds_read_b128 v[100:103], v92 offset:2048
	s_add_i32 m0, s37, 0x4000
	ds_read_b128 v[104:107], v92 offset:4096
	global_load_lds_dwordx4 v76, s[66:67]
	ds_read_b128 v[108:111], v92 offset:6144
	s_add_i32 m0, s37, 0x400
	ds_read_b128 v[112:115], v99
	global_load_lds_dwordx4 v74, s[64:65]
	ds_read_b128 v[116:119], v99 offset:2048
	s_add_i32 m0, s37, 0x4400
	ds_read_b128 v[120:123], v99 offset:8192
	global_load_lds_dwordx4 v72, s[66:67]
	ds_read_b128 v[124:127], v99 offset:10240
	s_add_i32 m0, s37, 0x800
	ds_read_b128 v[128:131], v93
	global_load_lds_dwordx4 v70, s[64:65]
	ds_read_b128 v[132:135], v93 offset:2048
	s_add_i32 m0, s37, 0x4800
	ds_read_b128 v[136:139], v93 offset:4096
	global_load_lds_dwordx4 v68, s[66:67]
	ds_read_b128 v[140:143], v93 offset:6144
	s_add_i32 m0, s37, 0xc00
	ds_read_b128 v[144:147], v160
	global_load_lds_dwordx4 v66, s[64:65]
	ds_read_b128 v[148:151], v160 offset:2048
	s_add_i32 m0, s37, 0x4c00
	ds_read_b128 v[152:155], v160 offset:8192
	global_load_lds_dwordx4 v64, s[66:67]
	ds_read_b128 v[156:159], v160 offset:10240
	s_waitcnt lgkmcnt(8)
	s_setprio 1
	v_mfma_i32_16x16x64_i8 v[60:63], v[112:115], v[88:91], v[60:63]
	v_mfma_i32_16x16x64_i8 v[56:59], v[116:119], v[88:91], v[56:59]
	v_mfma_i32_16x16x64_i8 v[52:55], v[120:123], v[88:91], v[52:55]
	v_mfma_i32_16x16x64_i8 v[48:51], v[124:127], v[88:91], v[48:51]
	v_mfma_i32_16x16x64_i8 v[44:47], v[112:115], v[100:103], v[44:47]
	v_mfma_i32_16x16x64_i8 v[40:43], v[116:119], v[100:103], v[40:43]
	v_mfma_i32_16x16x64_i8 v[36:39], v[120:123], v[100:103], v[36:39]
	v_mfma_i32_16x16x64_i8 v[32:35], v[124:127], v[100:103], v[32:35]
	v_mfma_i32_16x16x64_i8 v[28:31], v[112:115], v[104:107], v[28:31]
	v_mfma_i32_16x16x64_i8 v[24:27], v[116:119], v[104:107], v[24:27]
	v_mfma_i32_16x16x64_i8 v[20:23], v[120:123], v[104:107], v[20:23]
	v_mfma_i32_16x16x64_i8 v[16:19], v[124:127], v[104:107], v[16:19]
	v_mfma_i32_16x16x64_i8 v[12:15], v[112:115], v[108:111], v[12:15]
	v_mfma_i32_16x16x64_i8 v[8:11], v[116:119], v[108:111], v[8:11]
	v_mfma_i32_16x16x64_i8 v[4:7], v[120:123], v[108:111], v[4:7]
	v_mfma_i32_16x16x64_i8 v[0:3], v[124:127], v[108:111], v[0:3]
	s_waitcnt lgkmcnt(0)
	s_nop 0
	v_mfma_i32_16x16x64_i8 v[60:63], v[144:147], v[128:131], v[60:63]
	v_mfma_i32_16x16x64_i8 v[56:59], v[148:151], v[128:131], v[56:59]
	v_mfma_i32_16x16x64_i8 v[52:55], v[152:155], v[128:131], v[52:55]
	v_mfma_i32_16x16x64_i8 v[48:51], v[156:159], v[128:131], v[48:51]
	v_mfma_i32_16x16x64_i8 v[44:47], v[144:147], v[132:135], v[44:47]
	v_mfma_i32_16x16x64_i8 v[40:43], v[148:151], v[132:135], v[40:43]
	v_mfma_i32_16x16x64_i8 v[36:39], v[152:155], v[132:135], v[36:39]
	v_mfma_i32_16x16x64_i8 v[32:35], v[156:159], v[132:135], v[32:35]
	v_mfma_i32_16x16x64_i8 v[28:31], v[144:147], v[136:139], v[28:31]
	v_mfma_i32_16x16x64_i8 v[24:27], v[148:151], v[136:139], v[24:27]
	v_mfma_i32_16x16x64_i8 v[20:23], v[152:155], v[136:139], v[20:23]
	v_mfma_i32_16x16x64_i8 v[16:19], v[156:159], v[136:139], v[16:19]
	v_mfma_i32_16x16x64_i8 v[12:15], v[144:147], v[140:143], v[12:15]
	v_mfma_i32_16x16x64_i8 v[8:11], v[148:151], v[140:143], v[8:11]
	v_mfma_i32_16x16x64_i8 v[4:7], v[152:155], v[140:143], v[4:7]
	v_mfma_i32_16x16x64_i8 v[0:3], v[156:159], v[140:143], v[0:3]
	s_setprio 0
	s_waitcnt vmcnt(0)
	s_add_u32 s44, s44, 0x80
	s_addc_u32 s45, s45, 0
	s_add_u32 s64, s64, 0x80
	s_addc_u32 s65, s65, 0
	s_add_u32 s66, s66, 0x80
	s_addc_u32 s67, s67, 0
	s_add_i32 s19, s19, 0x8000
	s_cmpk_lg_i32 s44, 0x780
	s_waitcnt vmcnt(0) lgkmcnt(0)
	s_barrier
; template <class FragT, class AccT>
; DEV void gemm_core_t(const char* __restrict__ A, size_t lda_bytes, const char* __restrict__ Bt, size_t ldb_bytes, int kbytes,
;                      int m0, int n0, int Sshift, int dl, char* smem, AccT (&acc)[4][4]) {
;     ...
;     asm volatile(
;         "ds_read_b128 %0, %16\n\t"
;         "ds_read_b128 %1, %16 offset:2048\n\t"
;         "ds_read_b128 %2, %16 offset:4096\n\t"
;         "ds_read_b128 %3, %16 offset:6144\n\t"
;         "ds_read_b128 %4, %18\n\t"
;         "ds_read_b128 %5, %18 offset:2048\n\t"
;         "ds_read_b128 %6, %18 offset:8192\n\t"
;         "ds_read_b128 %7, %18 offset:10240\n\t"
;         "ds_read_b128 %8, %17\n\t"
;         "ds_read_b128 %9, %17 offset:2048\n\t"
;         "ds_read_b128 %10, %17 offset:4096\n\t"
;         "ds_read_b128 %11, %17 offset:6144\n\t"
;         "ds_read_b128 %12, %19\n\t"
;         "ds_read_b128 %13, %19 offset:2048\n\t"
;         "ds_read_b128 %14, %19 offset:8192\n\t"
;         "ds_read_b128 %15, %19 offset:10240\n\t"
;         "s_waitcnt lgkmcnt(8)"
;         : "=&v"(xa[0][0]), "=&v"(xa[0][1]), "=&v"(xa[0][2]), "=&v"(xa[0][3]), "=&v"(wb[0][0]), "=&v"(wb[0][1]), "=&v"(wb[0][2]),
;           "=&v"(wb[0][3]), "=&v"(xa[1][0]), "=&v"(xa[1][1]), "=&v"(xa[1][2]), "=&v"(xa[1][3]), "=&v"(wb[1][0]), "=&v"(wb[1][1]),
;           "=&v"(wb[1][2]), "=&v"(wb[1][3])
;         : "v"(a0 + so), "v"((a0 ^ 64u) + so), "v"(b0 + so), "v"((b0 ^ 64u) + so)
;         : "memory");
;     __builtin_amdgcn_s_setprio(1);
; #pragma unroll
;     for (int i = 0; i < 4; ++i)
; #pragma unroll
;       for (int j = 0; j < 4; ++j) acc[i][j] = mma_step(wb[0][j], xa[0][i], acc[i][j]);
;     asm volatile("s_waitcnt lgkmcnt(0)"
;                  : "+v"(xa[1][0]), "+v"(xa[1][1]), "+v"(xa[1][2]), "+v"(xa[1][3]), "+v"(wb[1][0]), "+v"(wb[1][1]), "+v"(wb[1][2]),
;                    "+v"(wb[1][3]), "+v"(acc[0][0]), "+v"(acc[0][1]), "+v"(acc[0][2]), "+v"(acc[0][3]), "+v"(acc[1][0]),
;                    "+v"(acc[1][1]), "+v"(acc[1][2]), "+v"(acc[1][3]), "+v"(acc[2][0]), "+v"(acc[2][1]), "+v"(acc[2][2]),
;                    "+v"(acc[2][3]), "+v"(acc[3][0]), "+v"(acc[3][1]), "+v"(acc[3][2]), "+v"(acc[3][3])
;                  :
;                  : "memory");
; #pragma unroll
;     for (int i = 0; i < 4; ++i)
; #pragma unroll
;       for (int j = 0; j < 4; ++j) acc[i][j] = mma_step(wb[1][j], xa[1][i], acc[i][j]);
	s_cbranch_scc1 .LBB0_734
	v_add_u32_e32 v76, 0x8000, v84
	v_add_u32_e32 v77, 0x8000, v87
	v_or_b32_e32 v81, 0x8000, v85
	v_or_b32_e32 v99, 0x8000, v86
	ds_read_b128 v[64:67], v76
	ds_read_b128 v[68:71], v76 offset:2048
	ds_read_b128 v[72:75], v76 offset:4096
	ds_read_b128 v[82:85], v76 offset:6144
	ds_read_b128 v[86:89], v81
	ds_read_b128 v[90:93], v81 offset:2048
	ds_read_b128 v[100:103], v81 offset:8192
	ds_read_b128 v[104:107], v81 offset:10240
	ds_read_b128 v[108:111], v77
	ds_read_b128 v[112:115], v77 offset:2048
	ds_read_b128 v[116:119], v77 offset:4096
	ds_read_b128 v[120:123], v77 offset:6144
	ds_read_b128 v[124:127], v99
	ds_read_b128 v[128:131], v99 offset:2048
	ds_read_b128 v[132:135], v99 offset:8192
	ds_read_b128 v[136:139], v99 offset:10240
	s_waitcnt lgkmcnt(8)
	s_setprio 1
	v_mfma_i32_16x16x64_i8 v[60:63], v[86:89], v[64:67], v[60:63]
	v_mfma_i32_16x16x64_i8 v[56:59], v[90:93], v[64:67], v[56:59]
	v_mfma_i32_16x16x64_i8 v[52:55], v[100:103], v[64:67], v[52:55]
	v_mfma_i32_16x16x64_i8 v[48:51], v[104:107], v[64:67], v[48:51]
	v_mfma_i32_16x16x64_i8 v[64:67], v[86:89], v[68:71], v[44:47]
	v_mfma_i32_16x16x64_i8 v[40:43], v[90:93], v[68:71], v[40:43]
	v_mfma_i32_16x16x64_i8 v[36:39], v[100:103], v[68:71], v[36:39]
	v_mfma_i32_16x16x64_i8 v[32:35], v[104:107], v[68:71], v[32:35]
	v_mfma_i32_16x16x64_i8 v[68:71], v[86:89], v[72:75], v[28:31]
	v_mfma_i32_16x16x64_i8 v[24:27], v[90:93], v[72:75], v[24:27]
	v_mfma_i32_16x16x64_i8 v[20:23], v[100:103], v[72:75], v[20:23]
	v_mfma_i32_16x16x64_i8 v[16:19], v[104:107], v[72:75], v[16:19]
	v_mfma_i32_16x16x64_i8 v[74:77], v[86:89], v[82:85], v[12:15]
	v_mfma_i32_16x16x64_i8 v[8:11], v[90:93], v[82:85], v[8:11]
	v_mfma_i32_16x16x64_i8 v[86:89], v[100:103], v[82:85], v[4:7]
	v_mfma_i32_16x16x64_i8 v[82:85], v[104:107], v[82:85], v[0:3]
	s_waitcnt lgkmcnt(0)
	s_nop 0
	v_mfma_i32_16x16x64_i8 v[56:59], v[128:131], v[108:111], v[56:59]
	v_mfma_i32_16x16x64_i8 v[140:143], v[132:135], v[108:111], v[52:55]
	v_mfma_i32_16x16x64_i8 v[46:49], v[136:139], v[108:111], v[48:51]
	v_mfma_i32_16x16x64_i8 v[52:55], v[124:127], v[112:115], v[64:67]
	v_mfma_i32_16x16x64_i8 v[40:43], v[128:131], v[112:115], v[40:43]
	v_mfma_i32_16x16x64_i8 v[36:39], v[132:135], v[112:115], v[36:39]
	v_mfma_i32_16x16x64_i8 v[30:33], v[136:139], v[112:115], v[32:35]
	v_mfma_i32_16x16x64_i8 v[24:27], v[128:131], v[116:119], v[24:27]
	v_mfma_i32_16x16x64_i8 v[20:23], v[132:135], v[116:119], v[20:23]
	v_mfma_i32_16x16x64_i8 v[14:17], v[136:139], v[116:119], v[16:19]
	v_mfma_i32_16x16x64_i8 v[4:7], v[124:127], v[120:123], v[74:77]
	v_mfma_i32_16x16x64_i8 v[0:3], v[128:131], v[120:123], v[8:11]
	v_mfma_i32_16x16x64_i8 v[8:11], v[136:139], v[120:123], v[82:85]
	v_mfma_i32_16x16x64_i8 v[102:105], v[124:127], v[108:111], v[60:63]
	v_mfma_i32_16x16x64_i8 v[70:73], v[124:127], v[116:119], v[68:71]
	v_mfma_i32_16x16x64_i8 v[62:65], v[132:135], v[120:123], v[86:89]
	s_setprio 0
	s_waitcnt vmcnt(0)
	s_barrier
	s_nop 0
	ds_read2_b64 v[84:87], v79 offset0:52 offset1:53
	v_add_u32_e32 v28, s36, v94
	v_mov_b32_e32 v29, s51
	v_and_b32_e32 v101, s51, v28
	v_bitop3_b32 v19, v28, s18, v29 bitop3:0x80
	v_lshrrev_b32_e32 v18, s17, v101
	v_and_b32_e32 v34, s50, v28
	v_lshlrev_b32_e32 v19, s6, v19
	v_add3_u32 v18, v18, v34, v19
	v_ashrrev_i32_e32 v19, 31, v18
	s_waitcnt lgkmcnt(0)
	v_lshl_add_u64 v[18:19], v[18:19], 2, v[84:85]
	flat_load_dword v82, v[18:19]
	v_or_b32_e32 v18, 16, v28
	v_bitop3_b32 v100, v28, s51, 16 bitop3:0xc8
	v_bitop3_b32 v18, v18, s18, v29 bitop3:0x80
	s_ashr_i32 s41, s40, 31
	v_lshrrev_b32_e32 v19, s17, v100
	v_lshlrev_b32_e32 v18, s6, v18
	v_lshl_add_u64 v[12:13], s[40:41], 2, v[86:87]
	v_mov_b32_e32 v81, v181
	v_add3_u32 v18, v19, v34, v18
	v_lshl_add_u64 v[12:13], v[12:13], 0, v[80:81]
	v_ashrrev_i32_e32 v19, 31, v18
	v_lshlrev_b32_e32 v180, 2, v78
	v_lshl_add_u64 v[18:19], v[18:19], 2, v[84:85]
	v_lshl_add_u64 v[12:13], v[12:13], 0, v[180:181]
	flat_load_dword v114, v[18:19]
	flat_load_dwordx4 v[106:109], v[12:13]
	flat_load_dwordx4 v[110:113], v[12:13] offset:256
	flat_load_dwordx4 v[74:77], v[12:13] offset:64
	flat_load_dwordx4 v[66:69], v[12:13] offset:320
	v_or_b32_e32 v12, 32, v28
	v_bitop3_b32 v99, v28, s51, 32 bitop3:0xc8
	v_bitop3_b32 v12, v12, s18, v29 bitop3:0x80
	v_lshrrev_b32_e32 v13, s17, v99
	v_lshlrev_b32_e32 v12, s6, v12
	v_add3_u32 v12, v13, v34, v12
	v_ashrrev_i32_e32 v13, 31, v12
	v_lshl_add_u64 v[12:13], v[12:13], 2, v[84:85]
	flat_load_dword v116, v[12:13]
	v_or_b32_e32 v12, 48, v28
	v_bitop3_b32 v81, v28, s51, 48 bitop3:0xc8
	v_bitop3_b32 v12, v12, s18, v29 bitop3:0x80
	v_lshrrev_b32_e32 v18, s17, v81
	v_lshlrev_b32_e32 v12, s6, v12
	v_add3_u32 v18, v18, v34, v12
	v_ashrrev_i32_e32 v19, 31, v18
	v_lshl_add_u64 v[18:19], v[18:19], 2, v[84:85]
	flat_load_dword v118, v[18:19]
	v_cvt_f32_i32_e32 v19, v143
	v_cvt_f32_i32_e32 v18, v105
	v_cvt_f32_i32_e32 v29, v48
	v_cvt_f32_i32_e32 v28, v58
	v_cvt_f32_i32_e32 v13, v142
	v_cvt_f32_i32_e32 v12, v104
	v_cvt_f32_i32_e32 v35, v49
	v_cvt_f32_i32_e32 v34, v59
	v_cvt_f32_i32_e32 v49, v32
	v_cvt_f32_i32_e32 v33, v33
	v_cvt_f32_i32_e32 v32, v43
	v_cvt_f32_i32_e32 v59, v22
	v_cvt_f32_i32_e32 v58, v72
	v_cvt_f32_i32_e32 v45, v38
	v_cvt_f32_i32_e32 v44, v54
	v_cvt_f32_i32_e32 v38, v55
	v_cvt_f32_i32_e32 v48, v42
	v_cvt_f32_i32_e32 v5, v5
	v_cvt_f32_i32_e32 v4, v4
	v_cvt_f32_i32_e32 v25, v25
	v_cvt_f32_i32_e32 v24, v24
	v_cvt_f32_i32_e32 v15, v15
	v_cvt_f32_i32_e32 v14, v14
	v_cvt_f32_i32_e32 v31, v31
	v_cvt_f32_i32_e32 v30, v30
	v_cvt_f32_i32_e32 v1, v1
	v_cvt_f32_i32_e32 v0, v0
	v_cvt_f32_i32_e32 v39, v39
	v_cvt_f32_i32_e32 v11, v11
	s_andn2_b64 vcc, exec, s[14:15]
	s_waitcnt vmcnt(0) lgkmcnt(0)
; #define P (*launderP(lp))
; __device__ __forceinline__ void phase_gemm1(PREF P, int slab, char* smem) {
;     ...
; #pragma unroll
;       for (int i = 0; i < 4; ++i) {
;         const float sxr = P.sx[rowmap(m0 + wm * 64 + i * 16 + l15, Sshift, dl)];
; #pragma unroll
;         for (int j = 0; j < 4; ++j) {
;           const float4 swc = *(const float4*)(P.sw + n0 + (j & 1) * 16 + wn * 32 + (j >> 1) * 64 + q * 4);
;           acc[i][j][0] = (float)iacc[i][j][0] * sxr * swc.x; acc[i][j][1] = (float)iacc[i][j][1] * sxr * swc.y;
;           acc[i][j][2] = (float)iacc[i][j][2] * sxr * swc.z; acc[i][j][3] = (float)iacc[i][j][3] * sxr * swc.w;
;         }
;       }
;     }
;     if (region <= 1) {
	v_pk_mul_f32 v[18:19], v[82:83], v[18:19] op_sel_hi:[0,1]
	v_pk_mul_f32 v[28:29], v[82:83], v[28:29] op_sel_hi:[0,1]
	v_pk_mul_f32 v[12:13], v[82:83], v[12:13] op_sel_hi:[0,1]
	v_pk_mul_f32 v[34:35], v[82:83], v[34:35] op_sel_hi:[0,1]
	v_mov_b32_e32 v84, v108
	v_mov_b32_e32 v85, v112
	v_mov_b32_e32 v112, v109
	v_mov_b32_e32 v104, v76
	v_mov_b32_e32 v105, v68
	v_pk_mul_f32 v[54:55], v[18:19], v[112:113]
	v_cvt_f32_i32_e32 v19, v23
	v_cvt_f32_i32_e32 v18, v73
	v_pk_mul_f32 v[42:43], v[28:29], v[104:105]
	v_cvt_f32_i32_e32 v29, v16
	v_cvt_f32_i32_e32 v28, v26
	v_mov_b32_e32 v68, v77
	v_pk_mul_f32 v[88:89], v[12:13], v[84:85]
	v_pk_mul_f32 v[12:13], v[114:115], v[32:33] op_sel_hi:[0,1]
	v_pk_mul_f32 v[50:51], v[34:35], v[68:69]
	v_pk_mul_f32 v[34:35], v[68:69], v[12:13]
	v_pk_mul_f32 v[12:13], v[116:117], v[58:59] op_sel_hi:[0,1]
	v_pk_mul_f32 v[86:87], v[84:85], v[12:13]
	v_pk_mul_f32 v[12:13], v[116:117], v[18:19] op_sel_hi:[0,1]
	v_pk_mul_f32 v[22:23], v[112:113], v[12:13]
	v_pk_mul_f32 v[12:13], v[116:117], v[28:29] op_sel_hi:[0,1]
	v_pk_mul_f32 v[76:77], v[104:105], v[12:13]
	v_cvt_f32_i32_e32 v13, v17
	v_cvt_f32_i32_e32 v12, v27
	v_cvt_f32_i32_e32 v17, v103
	v_cvt_f32_i32_e32 v16, v102
	v_cvt_f32_i32_e32 v27, v141
	v_cvt_f32_i32_e32 v26, v140
	v_cvt_f32_i32_e32 v29, v37
	v_cvt_f32_i32_e32 v28, v36
	v_pk_mul_f32 v[12:13], v[116:117], v[12:13] op_sel_hi:[0,1]
	v_pk_mul_f32 v[18:19], v[68:69], v[12:13]
	v_pk_mul_f32 v[12:13], v[82:83], v[16:17] op_sel_hi:[0,1]
	v_pk_mul_f32 v[16:17], v[82:83], v[26:27] op_sel_hi:[0,1]
	v_cvt_f32_i32_e32 v27, v53
	v_cvt_f32_i32_e32 v26, v52
	v_pk_mul_f32 v[52:53], v[16:17], v[110:111]
	v_pk_mul_f32 v[16:17], v[114:115], v[28:29] op_sel_hi:[0,1]
	v_pk_mul_f32 v[36:37], v[110:111], v[16:17]
	v_cvt_f32_i32_e32 v17, v21
	v_cvt_f32_i32_e32 v16, v20
	v_pk_mul_f32 v[44:45], v[114:115], v[44:45] op_sel_hi:[0,1]
	v_pk_mul_f32 v[60:61], v[106:107], v[12:13]
	v_pk_mul_f32 v[12:13], v[114:115], v[26:27] op_sel_hi:[0,1]
	v_pk_mul_f32 v[92:93], v[84:85], v[44:45]
	v_pk_mul_f32 v[44:45], v[106:107], v[12:13]
	v_cvt_f32_i32_e32 v13, v71
	v_cvt_f32_i32_e32 v12, v70
	v_pk_mul_f32 v[16:17], v[116:117], v[16:17] op_sel_hi:[0,1]
	v_pk_mul_f32 v[20:21], v[110:111], v[16:17]
	v_cvt_f32_i32_e32 v17, v63
	v_cvt_f32_i32_e32 v16, v62
	v_cvt_f32_i32_e32 v27, v64
	v_cvt_f32_i32_e32 v26, v6
	v_pk_mul_f32 v[12:13], v[116:117], v[12:13] op_sel_hi:[0,1]
	v_pk_mul_f32 v[4:5], v[118:119], v[4:5] op_sel_hi:[0,1]
	v_pk_mul_f32 v[28:29], v[106:107], v[12:13]
	v_pk_mul_f32 v[12:13], v[106:107], v[4:5]
	v_pk_mul_f32 v[4:5], v[118:119], v[16:17] op_sel_hi:[0,1]
	v_pk_mul_f32 v[16:17], v[118:119], v[26:27] op_sel_hi:[0,1]
	v_pk_mul_f32 v[84:85], v[84:85], v[16:17]
	v_cvt_f32_i32_e32 v17, v65
	v_cvt_f32_i32_e32 v16, v7
	v_cvt_f32_i32_e32 v27, v57
	v_cvt_f32_i32_e32 v26, v56
	v_cvt_f32_i32_e32 v33, v47
	v_cvt_f32_i32_e32 v32, v46
	v_pk_mul_f32 v[6:7], v[118:119], v[16:17] op_sel_hi:[0,1]
	v_pk_mul_f32 v[16:17], v[82:83], v[26:27] op_sel_hi:[0,1]
	v_pk_mul_f32 v[56:57], v[16:17], v[74:75]
	v_pk_mul_f32 v[26:27], v[82:83], v[32:33] op_sel_hi:[0,1]
	v_cvt_f32_i32_e32 v33, v41
	v_cvt_f32_i32_e32 v32, v40
	v_pk_mul_f32 v[48:49], v[114:115], v[48:49] op_sel_hi:[0,1]
	v_pk_mul_f32 v[14:15], v[116:117], v[14:15] op_sel_hi:[0,1]
	v_pk_mul_f32 v[90:91], v[104:105], v[48:49]
	v_pk_mul_f32 v[16:17], v[114:115], v[32:33] op_sel_hi:[0,1]
	v_pk_mul_f32 v[40:41], v[74:75], v[16:17]
	v_pk_mul_f32 v[16:17], v[116:117], v[24:25] op_sel_hi:[0,1]
	v_pk_mul_f32 v[48:49], v[26:27], v[66:67]
	v_pk_mul_f32 v[26:27], v[114:115], v[30:31] op_sel_hi:[0,1]
	v_pk_mul_f32 v[24:25], v[74:75], v[16:17]
	v_pk_mul_f32 v[16:17], v[66:67], v[14:15]
	v_cvt_f32_i32_e32 v15, v10
	v_cvt_f32_i32_e32 v14, v2
	v_pk_mul_f32 v[32:33], v[66:67], v[26:27]
	v_cvt_f32_i32_e32 v27, v9
	v_cvt_f32_i32_e32 v26, v8
	v_cvt_f32_i32_e32 v10, v3
	v_pk_mul_f32 v[0:1], v[118:119], v[0:1] op_sel_hi:[0,1]
	v_pk_mul_f32 v[2:3], v[118:119], v[14:15] op_sel_hi:[0,1]
	v_pk_mul_f32 v[38:39], v[114:115], v[38:39] op_sel_hi:[0,1]
	v_pk_mul_f32 v[8:9], v[74:75], v[0:1]
	v_pk_mul_f32 v[0:1], v[118:119], v[26:27] op_sel_hi:[0,1]
	v_pk_mul_f32 v[82:83], v[104:105], v[2:3]
	v_pk_mul_f32 v[2:3], v[118:119], v[10:11] op_sel_hi:[0,1]
	v_pk_mul_f32 v[38:39], v[112:113], v[38:39]
	v_pk_mul_f32 v[4:5], v[110:111], v[4:5]
	v_pk_mul_f32 v[6:7], v[112:113], v[6:7]
	v_pk_mul_f32 v[0:1], v[66:67], v[0:1]
	v_pk_mul_f32 v[2:3], v[68:69], v[2:3]
	s_cbranch_vccnz .LBB0_737
; #define P (*launderP(lp))
; __device__ __forceinline__ void phase_gemm1(PREF P, int slab, char* smem) {
;     ...
;     if (region <= 1) {
; #pragma unroll
;       for (int i = 0; i < 4; ++i) {
;         const int row = m0 + wm * 64 + i * 16 + l15;
;         const float s = (float)(row & ((1 << Sshift) - 1));
; #pragma unroll
;         for (int jj = 0; jj < 2; ++jj)
; #pragma unroll
;           for (int r = 0; r < 4; ++r) {
;             const int d = jj * 16 + wn * 32 + q * 4 + r;
;             float fr = __builtin_amdgcn_fractf(s * P.ropec[d]);
;             float cs = __builtin_amdgcn_cosf(fr), sn = __builtin_amdgcn_sinf(fr);
;             float t1 = acc[i][jj][r], t2 = acc[i][jj + 2][r];
;             float o1 = t1 * cs - t2 * sn, o2 = t1 * sn + t2 * cs;
;             if (region == 1) { o1 *= QK_SCALE; o2 *= QK_SCALE; }
;             acc[i][jj][r] = o1;
;             acc[i][jj + 2][r] = o2;
;           }
;       }
;     }
	ds_read2_b32 v[10:11], v96 offset0:134 offset1:135
	v_cvt_f32_u32_e32 v26, v101
	v_mov_b32_e32 v30, v60
	v_mov_b32_e32 v31, v52
	v_mov_b32_e32 v46, v61
	s_waitcnt lgkmcnt(0)
	v_mul_f32_e32 v14, v10, v26
	v_fract_f32_e32 v15, v14
	v_cos_f32_e32 v14, v15
	v_sin_f32_e32 v15, v15
	v_mov_b32_e32 v47, v53
	v_pk_mul_f32 v[30:31], v[30:31], v[14:15]
	s_nop 0
	v_sub_f32_e32 v27, v30, v31
	v_mul_f32_e32 v30, 0x3db504f3, v27
	v_cndmask_b32_e64 v62, v27, v30, s[42:43]
	v_mul_f32_e32 v27, v11, v26
	v_fract_f32_e32 v27, v27
	v_cos_f32_e32 v30, v27
	v_sin_f32_e32 v31, v27
	s_nop 0
	v_pk_mul_f32 v[46:47], v[46:47], v[30:31]
	s_nop 0
	v_sub_f32_e32 v27, v46, v47
	v_mov_b32_e32 v46, v15
	v_mov_b32_e32 v15, v30
	v_mov_b32_e32 v47, v31
	v_pk_mul_f32 v[14:15], v[52:53], v[14:15]
	v_mul_f32_e32 v63, 0x3db504f3, v27
	v_pk_fma_f32 v[14:15], v[60:61], v[46:47], v[14:15]
	v_cndmask_b32_e64 v63, v27, v63, s[42:43]
	v_pk_mul_f32 v[30:31], v[14:15], s[12:13] op_sel_hi:[1,0]
	v_mov_b32_e32 v52, v57
	v_cndmask_b32_e64 v59, v15, v31, s[42:43]
	v_cndmask_b32_e64 v58, v14, v30, s[42:43]
	ds_read2_b32 v[14:15], v96 offset0:136 offset1:137
	v_mov_b32_e32 v53, v49
	s_waitcnt lgkmcnt(0)
	v_mul_f32_e32 v27, v14, v26
	v_fract_f32_e32 v27, v27
	v_cos_f32_e32 v30, v27
	v_sin_f32_e32 v31, v27
	s_nop 0
	v_pk_mul_f32 v[46:47], v[88:89], v[30:31]
	s_nop 0
	v_sub_f32_e32 v27, v46, v47
	v_mov_b32_e32 v46, v31
	v_mov_b32_e32 v47, v30
	v_pk_mul_f32 v[30:31], v[88:89], v[46:47]
	ds_read2_b32 v[88:89], v96 offset0:150 offset1:151
	v_add_f32_e32 v30, v30, v31
	v_mul_f32_e32 v31, 0x3db504f3, v27
	v_cndmask_b32_e64 v64, v27, v31, s[42:43]
	v_mul_f32_e32 v27, v15, v26
	v_mul_f32_e32 v46, 0x3db504f3, v30
	v_fract_f32_e32 v27, v27
	v_cndmask_b32_e64 v60, v30, v46, s[42:43]
	v_cos_f32_e32 v30, v27
	v_sin_f32_e32 v31, v27
	s_nop 0
	v_pk_mul_f32 v[46:47], v[54:55], v[30:31]
	s_nop 0
	v_sub_f32_e32 v27, v46, v47
	v_mov_b32_e32 v46, v31
	v_mov_b32_e32 v47, v30
	v_pk_mul_f32 v[30:31], v[54:55], v[46:47]
	v_mov_b32_e32 v47, v48
	v_add_f32_e32 v30, v30, v31
	v_mul_f32_e32 v31, 0x3db504f3, v27
	v_cndmask_b32_e64 v65, v27, v31, s[42:43]
	s_waitcnt lgkmcnt(0)
	v_mul_f32_e32 v27, v88, v26
	v_mul_f32_e32 v46, 0x3db504f3, v30
	v_fract_f32_e32 v27, v27
	v_cndmask_b32_e64 v61, v30, v46, s[42:43]
	v_cos_f32_e32 v30, v27
	v_sin_f32_e32 v31, v27
	v_mov_b32_e32 v46, v56
	v_pk_mul_f32 v[46:47], v[46:47], v[30:31]
	s_nop 0
	v_sub_f32_e32 v27, v46, v47
	v_mul_f32_e32 v46, 0x3db504f3, v27
	v_cndmask_b32_e64 v66, v27, v46, s[42:43]
	v_mul_f32_e32 v27, v89, v26
	v_fract_f32_e32 v27, v27
	v_cos_f32_e32 v46, v27
	v_sin_f32_e32 v47, v27
	s_nop 0
	v_pk_mul_f32 v[52:53], v[52:53], v[46:47]
	s_nop 0
	v_sub_f32_e32 v27, v52, v53
	v_mov_b32_e32 v52, v31
	v_mov_b32_e32 v31, v46
	v_mov_b32_e32 v53, v47
	v_pk_mul_f32 v[30:31], v[48:49], v[30:31]
	v_mul_f32_e32 v54, 0x3db504f3, v27
	v_pk_fma_f32 v[30:31], v[56:57], v[52:53], v[30:31]
	ds_read2_b32 v[56:57], v96 offset0:152 offset1:153
	v_cndmask_b32_e64 v67, v27, v54, s[42:43]
	v_pk_mul_f32 v[46:47], v[30:31], s[12:13] op_sel_hi:[1,0]
	s_waitcnt lgkmcnt(0)
	v_mul_f32_e32 v27, v56, v26
	v_fract_f32_e32 v27, v27
	v_cndmask_b32_e64 v53, v31, v47, s[42:43]
	v_cndmask_b32_e64 v52, v30, v46, s[42:43]
	v_cos_f32_e32 v30, v27
	v_sin_f32_e32 v31, v27
	v_mul_f32_e32 v26, v57, v26
	v_pk_mul_f32 v[46:47], v[42:43], v[30:31]
	s_nop 0
	v_sub_f32_e32 v27, v46, v47
	v_mov_b32_e32 v46, v31
	v_mov_b32_e32 v47, v30
	v_pk_mul_f32 v[30:31], v[42:43], v[46:47]
	v_mov_b32_e32 v43, v37
	v_add_f32_e32 v30, v30, v31
	v_mul_f32_e32 v31, 0x3db504f3, v27
	v_cndmask_b32_e64 v68, v27, v31, s[42:43]
	v_fract_f32_e32 v27, v26
	v_cos_f32_e32 v26, v27
	v_sin_f32_e32 v27, v27
	v_mul_f32_e32 v42, 0x3db504f3, v30
	v_cndmask_b32_e64 v54, v30, v42, s[42:43]
	v_pk_mul_f32 v[30:31], v[50:51], v[26:27]
	s_nop 0
	v_sub_f32_e32 v42, v30, v31
	v_mov_b32_e32 v30, v27
	v_mov_b32_e32 v31, v26
	v_pk_mul_f32 v[26:27], v[50:51], v[30:31]
	v_cvt_f32_u32_e32 v50, v100
	v_add_f32_e32 v26, v26, v27
	v_mul_f32_e32 v30, 0x3db504f3, v26
	v_mul_f32_e32 v27, 0x3db504f3, v42
	v_cndmask_b32_e64 v55, v26, v30, s[42:43]
	v_mul_f32_e32 v26, v10, v50
	v_cndmask_b32_e64 v69, v42, v27, s[42:43]
	v_fract_f32_e32 v27, v26
	v_cos_f32_e32 v26, v27
	v_sin_f32_e32 v27, v27
	v_mov_b32_e32 v30, v44
	v_mov_b32_e32 v31, v36
	v_mov_b32_e32 v42, v45
	v_pk_mul_f32 v[30:31], v[30:31], v[26:27]
	s_nop 0
	v_sub_f32_e32 v30, v30, v31
	v_mul_f32_e32 v31, 0x3db504f3, v30
	v_cndmask_b32_e64 v46, v30, v31, s[42:43]
	v_mul_f32_e32 v30, v11, v50
	v_fract_f32_e32 v31, v30
	v_cos_f32_e32 v30, v31
	v_sin_f32_e32 v31, v31
	s_nop 0
	v_pk_mul_f32 v[42:43], v[42:43], v[30:31]
	s_nop 0
	v_sub_f32_e32 v47, v42, v43
	v_mov_b32_e32 v42, v27
	v_mov_b32_e32 v27, v30
	v_mov_b32_e32 v43, v31
	v_pk_mul_f32 v[26:27], v[36:37], v[26:27]
	v_mul_f32_e32 v48, 0x3db504f3, v47
	v_pk_fma_f32 v[26:27], v[44:45], v[42:43], v[26:27]
	v_cndmask_b32_e64 v47, v47, v48, s[42:43]
	v_pk_mul_f32 v[30:31], v[26:27], s[12:13] op_sel_hi:[1,0]
	v_mov_b32_e32 v37, v33
	v_cndmask_b32_e64 v42, v26, v30, s[42:43]
	v_mul_f32_e32 v26, v14, v50
	v_cndmask_b32_e64 v43, v27, v31, s[42:43]
	v_fract_f32_e32 v27, v26
	v_cos_f32_e32 v26, v27
	v_sin_f32_e32 v27, v27
	s_nop 0
	v_pk_mul_f32 v[30:31], v[92:93], v[26:27]
	s_nop 0
	v_sub_f32_e32 v36, v30, v31
	v_mov_b32_e32 v30, v27
	v_mov_b32_e32 v31, v26
	v_pk_mul_f32 v[26:27], v[92:93], v[30:31]
	s_nop 0
	v_add_f32_e32 v26, v26, v27
	v_mul_f32_e32 v30, 0x3db504f3, v26
	v_mul_f32_e32 v27, 0x3db504f3, v36
	v_cndmask_b32_e64 v44, v26, v30, s[42:43]
	v_mul_f32_e32 v26, v15, v50
	v_cndmask_b32_e64 v48, v36, v27, s[42:43]
	v_fract_f32_e32 v27, v26
	v_cos_f32_e32 v26, v27
; #define P (*launderP(lp))
; __device__ __forceinline__ void phase_gemm1(PREF P, int slab, char* smem) {
;     ...
;     if (region <= 1) {
; #pragma unroll
;       for (int i = 0; i < 4; ++i) {
;         const int row = m0 + wm * 64 + i * 16 + l15;
;         const float s = (float)(row & ((1 << Sshift) - 1));
; #pragma unroll
;         for (int jj = 0; jj < 2; ++jj)
; #pragma unroll
;           for (int r = 0; r < 4; ++r) {
;             const int d = jj * 16 + wn * 32 + q * 4 + r;
;             float fr = __builtin_amdgcn_fractf(s * P.ropec[d]);
;             float cs = __builtin_amdgcn_cosf(fr), sn = __builtin_amdgcn_sinf(fr);
;             float t1 = acc[i][jj][r], t2 = acc[i][jj + 2][r];
;             float o1 = t1 * cs - t2 * sn, o2 = t1 * sn + t2 * cs;
;             if (region == 1) { o1 *= QK_SCALE; o2 *= QK_SCALE; }
;             acc[i][jj][r] = o1;
;             acc[i][jj + 2][r] = o2;
;           }
;       }
;     }
	v_sin_f32_e32 v27, v27
	s_nop 0
	v_pk_mul_f32 v[30:31], v[38:39], v[26:27]
	s_nop 0
	v_sub_f32_e32 v36, v30, v31
	v_mov_b32_e32 v30, v27
	v_mov_b32_e32 v31, v26
	v_pk_mul_f32 v[26:27], v[38:39], v[30:31]
	v_mov_b32_e32 v31, v32
	v_add_f32_e32 v26, v26, v27
	v_mul_f32_e32 v30, 0x3db504f3, v26
	v_mul_f32_e32 v27, 0x3db504f3, v36
	v_cndmask_b32_e64 v45, v26, v30, s[42:43]
	v_mul_f32_e32 v26, v88, v50
	v_cndmask_b32_e64 v49, v36, v27, s[42:43]
	v_fract_f32_e32 v27, v26
	v_cos_f32_e32 v26, v27
	v_sin_f32_e32 v27, v27
	v_mov_b32_e32 v30, v40
	v_mov_b32_e32 v36, v41
	v_pk_mul_f32 v[30:31], v[30:31], v[26:27]
	s_nop 0
	v_sub_f32_e32 v30, v30, v31
	v_mul_f32_e32 v31, 0x3db504f3, v30
	v_cndmask_b32_e64 v70, v30, v31, s[42:43]
	v_mul_f32_e32 v30, v89, v50
	v_fract_f32_e32 v31, v30
	v_cos_f32_e32 v30, v31
	v_sin_f32_e32 v31, v31
	s_nop 0
	v_pk_mul_f32 v[36:37], v[36:37], v[30:31]
	s_nop 0
	v_sub_f32_e32 v38, v36, v37
	v_mov_b32_e32 v36, v27
	v_mov_b32_e32 v27, v30
	v_mov_b32_e32 v37, v31
	v_pk_mul_f32 v[26:27], v[32:33], v[26:27]
	v_mul_f32_e32 v39, 0x3db504f3, v38
	v_pk_fma_f32 v[26:27], v[40:41], v[36:37], v[26:27]
	v_cndmask_b32_e64 v71, v38, v39, s[42:43]
	v_pk_mul_f32 v[30:31], v[26:27], s[12:13] op_sel_hi:[1,0]
	v_cvt_f32_u32_e32 v40, v99
	v_cndmask_b32_e64 v36, v26, v30, s[42:43]
	v_mul_f32_e32 v26, v56, v50
	v_cndmask_b32_e64 v37, v27, v31, s[42:43]
	v_fract_f32_e32 v27, v26
	v_cos_f32_e32 v26, v27
	v_sin_f32_e32 v27, v27
	s_nop 0
	v_pk_mul_f32 v[30:31], v[90:91], v[26:27]
	s_nop 0
	v_sub_f32_e32 v32, v30, v31
	v_mov_b32_e32 v30, v27
	v_mov_b32_e32 v31, v26
	v_pk_mul_f32 v[26:27], v[90:91], v[30:31]
	s_nop 0
	v_add_f32_e32 v26, v26, v27
	v_mul_f32_e32 v30, 0x3db504f3, v26
	v_mul_f32_e32 v27, 0x3db504f3, v32
	v_cndmask_b32_e64 v38, v26, v30, s[42:43]
	v_mul_f32_e32 v26, v57, v50
	v_cndmask_b32_e64 v72, v32, v27, s[42:43]
	v_fract_f32_e32 v27, v26
	v_cos_f32_e32 v26, v27
	v_sin_f32_e32 v27, v27
	s_nop 0
	v_pk_mul_f32 v[30:31], v[34:35], v[26:27]
	s_nop 0
	v_sub_f32_e32 v32, v30, v31
	v_mov_b32_e32 v30, v27
	v_mov_b32_e32 v31, v26
	v_pk_mul_f32 v[26:27], v[34:35], v[30:31]
	v_mov_b32_e32 v31, v20
	v_add_f32_e32 v26, v26, v27
	v_mul_f32_e32 v30, 0x3db504f3, v26
	v_mul_f32_e32 v27, 0x3db504f3, v32
	v_cndmask_b32_e64 v39, v26, v30, s[42:43]
	v_mul_f32_e32 v26, v10, v40
	v_cndmask_b32_e64 v73, v32, v27, s[42:43]
	v_fract_f32_e32 v27, v26
	v_cos_f32_e32 v26, v27
	v_sin_f32_e32 v27, v27
	v_mov_b32_e32 v30, v28
	v_mov_b32_e32 v34, v29
	v_mov_b32_e32 v35, v21
	v_pk_mul_f32 v[30:31], v[30:31], v[26:27]
	s_nop 0
	v_sub_f32_e32 v30, v30, v31
	v_mul_f32_e32 v31, 0x3db504f3, v30
	v_cndmask_b32_e64 v30, v30, v31, s[42:43]
	v_mul_f32_e32 v31, v11, v40
	v_fract_f32_e32 v31, v31
	v_cos_f32_e32 v32, v31
	v_sin_f32_e32 v33, v31
	s_nop 0
	v_pk_mul_f32 v[34:35], v[34:35], v[32:33]
	s_nop 0
	v_sub_f32_e32 v31, v34, v35
	v_mov_b32_e32 v34, v27
	v_mov_b32_e32 v27, v32
	v_mov_b32_e32 v35, v33
	v_pk_mul_f32 v[20:21], v[20:21], v[26:27]
	v_mul_f32_e32 v41, 0x3db504f3, v31
	v_pk_fma_f32 v[20:21], v[28:29], v[34:35], v[20:21]
	v_cndmask_b32_e64 v31, v31, v41, s[42:43]
	v_pk_mul_f32 v[26:27], v[20:21], s[12:13] op_sel_hi:[1,0]
	s_nop 0
	v_cndmask_b32_e64 v26, v20, v26, s[42:43]
	v_mul_f32_e32 v20, v14, v40
	v_cndmask_b32_e64 v27, v21, v27, s[42:43]
	v_fract_f32_e32 v21, v20
	v_cos_f32_e32 v20, v21
	v_sin_f32_e32 v21, v21
	s_nop 0
	v_pk_mul_f32 v[28:29], v[86:87], v[20:21]
	s_nop 0
	v_sub_f32_e32 v32, v28, v29
	v_mov_b32_e32 v28, v21
	v_mov_b32_e32 v29, v20
	v_pk_mul_f32 v[20:21], v[86:87], v[28:29]
	s_nop 0
	v_add_f32_e32 v20, v20, v21
	v_mul_f32_e32 v28, 0x3db504f3, v20
	v_mul_f32_e32 v21, 0x3db504f3, v32
	v_cndmask_b32_e64 v28, v20, v28, s[42:43]
	v_mul_f32_e32 v20, v15, v40
	v_cndmask_b32_e64 v32, v32, v21, s[42:43]
	v_fract_f32_e32 v21, v20
	v_cos_f32_e32 v20, v21
	v_sin_f32_e32 v21, v21
	s_nop 0
	v_pk_mul_f32 v[34:35], v[22:23], v[20:21]
	s_nop 0
	v_sub_f32_e32 v33, v34, v35
	v_mov_b32_e32 v34, v21
	v_mov_b32_e32 v35, v20
	v_pk_mul_f32 v[20:21], v[22:23], v[34:35]
	v_mov_b32_e32 v23, v16
	v_add_f32_e32 v20, v20, v21
	v_mul_f32_e32 v22, 0x3db504f3, v20
	v_mul_f32_e32 v21, 0x3db504f3, v33
	v_cndmask_b32_e64 v29, v20, v22, s[42:43]
	v_mul_f32_e32 v20, v88, v40
	v_cndmask_b32_e64 v33, v33, v21, s[42:43]
	v_fract_f32_e32 v21, v20
	v_cos_f32_e32 v20, v21
	v_sin_f32_e32 v21, v21
	v_mov_b32_e32 v22, v24
	v_mov_b32_e32 v34, v25
	v_mov_b32_e32 v35, v17
	v_pk_mul_f32 v[22:23], v[22:23], v[20:21]
	s_nop 0
	v_sub_f32_e32 v22, v22, v23
	v_mul_f32_e32 v23, 0x3db504f3, v22
	v_cndmask_b32_e64 v74, v22, v23, s[42:43]
	v_mul_f32_e32 v22, v89, v40
	v_fract_f32_e32 v23, v22
	v_cos_f32_e32 v22, v23
	v_sin_f32_e32 v23, v23
	s_nop 0
	v_pk_mul_f32 v[34:35], v[34:35], v[22:23]
	s_nop 0
	v_sub_f32_e32 v41, v34, v35
	v_mov_b32_e32 v34, v21
	v_mov_b32_e32 v21, v22
	v_mov_b32_e32 v35, v23
	v_pk_mul_f32 v[16:17], v[16:17], v[20:21]
	v_mul_f32_e32 v50, 0x3db504f3, v41
	v_pk_fma_f32 v[16:17], v[24:25], v[34:35], v[16:17]
	v_cndmask_b32_e64 v75, v41, v50, s[42:43]
	v_pk_mul_f32 v[20:21], v[16:17], s[12:13] op_sel_hi:[1,0]
	s_nop 0
	v_cndmask_b32_e64 v20, v16, v20, s[42:43]
	v_mul_f32_e32 v16, v56, v40
	v_cndmask_b32_e64 v21, v17, v21, s[42:43]
	v_fract_f32_e32 v17, v16
	v_cos_f32_e32 v16, v17
	v_sin_f32_e32 v17, v17
	s_nop 0
	v_pk_mul_f32 v[22:23], v[76:77], v[16:17]
	s_nop 0
	v_sub_f32_e32 v24, v22, v23
	v_mov_b32_e32 v22, v17
	v_mov_b32_e32 v23, v16
	v_pk_mul_f32 v[16:17], v[76:77], v[22:23]
	s_nop 0
	v_add_f32_e32 v16, v16, v17
; #define P (*launderP(lp))
; __device__ __forceinline__ void phase_gemm1(PREF P, int slab, char* smem) {
;     ...
;     if (region <= 1) {
; #pragma unroll
;       for (int i = 0; i < 4; ++i) {
;         const int row = m0 + wm * 64 + i * 16 + l15;
;         const float s = (float)(row & ((1 << Sshift) - 1));
; #pragma unroll
;         for (int jj = 0; jj < 2; ++jj)
; #pragma unroll
;           for (int r = 0; r < 4; ++r) {
;             const int d = jj * 16 + wn * 32 + q * 4 + r;
;             float fr = __builtin_amdgcn_fractf(s * P.ropec[d]);
;             float cs = __builtin_amdgcn_cosf(fr), sn = __builtin_amdgcn_sinf(fr);
;             float t1 = acc[i][jj][r], t2 = acc[i][jj + 2][r];
;             float o1 = t1 * cs - t2 * sn, o2 = t1 * sn + t2 * cs;
;             if (region == 1) { o1 *= QK_SCALE; o2 *= QK_SCALE; }
;             acc[i][jj][r] = o1;
;             acc[i][jj + 2][r] = o2;
;           }
;       }
;     }
	v_mul_f32_e32 v22, 0x3db504f3, v16
	v_mul_f32_e32 v17, 0x3db504f3, v24
	v_cndmask_b32_e64 v22, v16, v22, s[42:43]
	v_mul_f32_e32 v16, v57, v40
	v_cndmask_b32_e64 v76, v24, v17, s[42:43]
	v_fract_f32_e32 v17, v16
	v_cos_f32_e32 v16, v17
	v_sin_f32_e32 v17, v17
	s_nop 0
	v_pk_mul_f32 v[24:25], v[18:19], v[16:17]
	s_nop 0
	v_sub_f32_e32 v34, v24, v25
	v_mov_b32_e32 v24, v17
	v_mov_b32_e32 v25, v16
	v_pk_mul_f32 v[16:17], v[18:19], v[24:25]
	v_mov_b32_e32 v24, v13
	v_add_f32_e32 v16, v16, v17
	v_mul_f32_e32 v17, 0x3db504f3, v34
	v_cndmask_b32_e64 v77, v34, v17, s[42:43]
	v_cvt_f32_u32_e32 v34, v81
	v_mul_f32_e32 v18, 0x3db504f3, v16
	v_cndmask_b32_e64 v23, v16, v18, s[42:43]
	v_mov_b32_e32 v16, v12
	v_mul_f32_e32 v10, v10, v34
	v_fract_f32_e32 v10, v10
	v_cos_f32_e32 v18, v10
	v_sin_f32_e32 v19, v10
	v_mov_b32_e32 v17, v4
	v_mov_b32_e32 v25, v5
	v_pk_mul_f32 v[16:17], v[16:17], v[18:19]
	s_nop 0
	v_sub_f32_e32 v10, v16, v17
	v_mul_f32_e32 v16, 0x3db504f3, v10
	v_cndmask_b32_e64 v16, v10, v16, s[42:43]
	v_mul_f32_e32 v10, v11, v34
	v_fract_f32_e32 v11, v10
	v_cos_f32_e32 v10, v11
	v_sin_f32_e32 v11, v11
	s_nop 0
	v_pk_mul_f32 v[24:25], v[24:25], v[10:11]
	s_nop 0
	v_sub_f32_e32 v17, v24, v25
	v_mov_b32_e32 v24, v19
	v_mov_b32_e32 v19, v10
	v_mov_b32_e32 v25, v11
	v_pk_mul_f32 v[4:5], v[4:5], v[18:19]
	v_mul_f32_e32 v35, 0x3db504f3, v17
	v_pk_fma_f32 v[4:5], v[12:13], v[24:25], v[4:5]
	v_cndmask_b32_e64 v17, v17, v35, s[42:43]
	v_pk_mul_f32 v[10:11], v[4:5], s[12:13] op_sel_hi:[1,0]
	s_nop 0
	v_cndmask_b32_e64 v10, v4, v10, s[42:43]
	v_mul_f32_e32 v4, v14, v34
	v_cndmask_b32_e64 v11, v5, v11, s[42:43]
	v_fract_f32_e32 v5, v4
	v_cos_f32_e32 v4, v5
	v_sin_f32_e32 v5, v5
	s_nop 0
	v_pk_mul_f32 v[12:13], v[84:85], v[4:5]
	s_nop 0
	v_sub_f32_e32 v14, v12, v13
	v_mov_b32_e32 v12, v5
	v_mov_b32_e32 v13, v4
	v_pk_mul_f32 v[4:5], v[84:85], v[12:13]
	s_nop 0
	v_add_f32_e32 v4, v4, v5
	v_mul_f32_e32 v12, 0x3db504f3, v4
	v_mul_f32_e32 v5, 0x3db504f3, v14
	v_cndmask_b32_e64 v12, v4, v12, s[42:43]
	v_mul_f32_e32 v4, v15, v34
	v_cndmask_b32_e64 v18, v14, v5, s[42:43]
	v_fract_f32_e32 v5, v4
	v_cos_f32_e32 v4, v5
	v_sin_f32_e32 v5, v5
	s_nop 0
	v_pk_mul_f32 v[14:15], v[6:7], v[4:5]
	s_nop 0
	v_sub_f32_e32 v19, v14, v15
	v_mov_b32_e32 v14, v5
	v_mov_b32_e32 v15, v4
	v_pk_mul_f32 v[4:5], v[6:7], v[14:15]
	v_mov_b32_e32 v7, v0
	v_add_f32_e32 v4, v4, v5
	v_mul_f32_e32 v6, 0x3db504f3, v4
	v_mul_f32_e32 v5, 0x3db504f3, v19
	v_cndmask_b32_e64 v13, v4, v6, s[42:43]
	v_mul_f32_e32 v4, v88, v34
	v_cndmask_b32_e64 v19, v19, v5, s[42:43]
	v_fract_f32_e32 v5, v4
	v_cos_f32_e32 v4, v5
	v_sin_f32_e32 v5, v5
	v_mov_b32_e32 v6, v8
	v_mov_b32_e32 v14, v9
	v_mov_b32_e32 v15, v1
	v_pk_mul_f32 v[6:7], v[6:7], v[4:5]
	s_nop 0
	v_sub_f32_e32 v6, v6, v7
	v_mul_f32_e32 v7, 0x3db504f3, v6
	v_cndmask_b32_e64 v84, v6, v7, s[42:43]
	v_mul_f32_e32 v6, v89, v34
	v_fract_f32_e32 v7, v6
	v_cos_f32_e32 v6, v7
	v_sin_f32_e32 v7, v7
	s_nop 0
	v_pk_mul_f32 v[14:15], v[14:15], v[6:7]
	s_nop 0
	v_sub_f32_e32 v24, v14, v15
	v_mov_b32_e32 v14, v5
	v_mov_b32_e32 v5, v6
	v_mov_b32_e32 v15, v7
	v_pk_mul_f32 v[0:1], v[0:1], v[4:5]
	v_mul_f32_e32 v25, 0x3db504f3, v24
	v_pk_fma_f32 v[0:1], v[8:9], v[14:15], v[0:1]
	v_cndmask_b32_e64 v85, v24, v25, s[42:43]
	v_pk_mul_f32 v[4:5], v[0:1], s[12:13] op_sel_hi:[1,0]
	s_nop 0
	v_cndmask_b32_e64 v4, v0, v4, s[42:43]
	v_mul_f32_e32 v0, v56, v34
	v_cndmask_b32_e64 v5, v1, v5, s[42:43]
	v_fract_f32_e32 v1, v0
	v_cos_f32_e32 v0, v1
	v_sin_f32_e32 v1, v1
	s_nop 0
	v_pk_mul_f32 v[6:7], v[82:83], v[0:1]
	s_nop 0
	v_sub_f32_e32 v8, v6, v7
	v_mov_b32_e32 v6, v1
	v_mov_b32_e32 v7, v0
	v_pk_mul_f32 v[0:1], v[82:83], v[6:7]
	s_nop 0
	v_add_f32_e32 v0, v0, v1
	v_mul_f32_e32 v6, 0x3db504f3, v0
	v_mul_f32_e32 v1, 0x3db504f3, v8
	v_cndmask_b32_e64 v6, v0, v6, s[42:43]
	v_mul_f32_e32 v0, v57, v34
	v_cndmask_b32_e64 v86, v8, v1, s[42:43]
	v_fract_f32_e32 v1, v0
	v_cos_f32_e32 v0, v1
	v_sin_f32_e32 v1, v1
	s_nop 0
	v_pk_mul_f32 v[8:9], v[2:3], v[0:1]
	s_nop 0
	v_sub_f32_e32 v14, v8, v9
	v_mov_b32_e32 v8, v1
	v_mov_b32_e32 v9, v0
	v_pk_mul_f32 v[0:1], v[2:3], v[8:9]
	s_nop 0
	v_add_f32_e32 v0, v0, v1
	v_mul_f32_e32 v1, 0x3db504f3, v14
	v_mul_f32_e32 v2, 0x3db504f3, v0
	v_cndmask_b32_e64 v7, v0, v2, s[42:43]
	v_cndmask_b32_e64 v87, v14, v1, s[42:43]
	v_mov_b64_e32 v[0:1], v[4:5]
	v_mov_b64_e32 v[2:3], v[6:7]
	v_mov_b64_e32 v[4:5], v[10:11]
	v_mov_b64_e32 v[6:7], v[12:13]
	v_mov_b64_e32 v[12:13], v[16:17]
	v_mov_b64_e32 v[14:15], v[18:19]
	v_mov_b64_e32 v[16:17], v[20:21]
	v_mov_b64_e32 v[18:19], v[22:23]
	v_mov_b64_e32 v[20:21], v[26:27]
	v_mov_b64_e32 v[22:23], v[28:29]
	v_mov_b64_e32 v[28:29], v[30:31]
	v_mov_b64_e32 v[30:31], v[32:33]
	v_mov_b64_e32 v[32:33], v[36:37]
	v_mov_b64_e32 v[34:35], v[38:39]
	v_mov_b64_e32 v[36:37], v[42:43]
	v_mov_b64_e32 v[38:39], v[44:45]
	v_mov_b64_e32 v[44:45], v[46:47]
	v_mov_b64_e32 v[46:47], v[48:49]
	v_mov_b64_e32 v[48:49], v[52:53]
	v_mov_b64_e32 v[50:51], v[54:55]
	v_mov_b64_e32 v[52:53], v[58:59]
	v_mov_b64_e32 v[8:9], v[84:85]
	v_mov_b64_e32 v[24:25], v[74:75]
	v_mov_b64_e32 v[40:41], v[70:71]
	v_mov_b64_e32 v[54:55], v[60:61]
	v_mov_b64_e32 v[56:57], v[66:67]
	v_mov_b64_e32 v[60:61], v[62:63]
	v_mov_b64_e32 v[10:11], v[86:87]
	v_mov_b64_e32 v[26:27], v[76:77]
	v_mov_b64_e32 v[42:43], v[72:73]
	v_mov_b64_e32 v[58:59], v[68:69]
	v_mov_b64_e32 v[62:63], v[64:65]
	s_cmp_lt_i32 s16, 3
	s_mov_b64 s[14:15], -1
	s_cbranch_scc1 .LBB0_751
	s_branch .LBB0_738
